# speedup vs baseline: 1.0143x; 1.0116x over previous
; #define SCHED() __builtin_amdgcn_sched_barrier(0)
; #define LGKM(n) asm volatile("s_waitcnt lgkmcnt(%0)" ::"n"(n) : "memory")
; #define STAGE_A(b, h, kt) STAGE_AX(Ag, b, h, kt)
; #define STAGE_B(b, h, kt) STAGE_BX(Bg, b, h, kt)
; #define LDA(b, h) do { const unsigned pa_ = lds0 + SLOTA(b, h) + wr * 8192 + laneoff; _Pragma("unroll") for (int m = 0; m < 4; ++m)   \
;       _Pragma("unroll") for (int k = 0; k < 2; ++k) DSR(At[m][k], pa_, m * 2048 + k * 1024); } while (0)
; #define LDB(dst, b, h) do { const unsigned pb_ = lds0 + SLOTB(b, h) + wc * 4096 + laneoff; _Pragma("unroll") for (int n = 0; n < 2; ++n) \
;       _Pragma("unroll") for (int k = 0; k < 2; ++k) DSR(dst[n][k], pb_, n * 2048 + k * 1024); } while (0)
; #define BAR __builtin_amdgcn_s_barrier()
; #define LGKM(n) asm volatile("s_waitcnt lgkmcnt(%0)" ::"n"(n) : "memory")
; template <int EPI, bool SWP> ...
;     ...
;     LDB(B0, 0, 0); LDA(0, 0); STAGE_A(1, 1, t + 1);
;     LGKM(8); BAR; LGKM(0); SCHED(); MMA(0, 0, B0); BAR; SCHED();
;     LDB(B1, 0, 1); STAGE_B(0, 0, t + 2);
;     BAR; LGKM(0); SCHED(); MMA(0, 1, B1); BAR; SCHED();
;     LDA(0, 1); STAGE_A(0, 0, t + 2);
;     BAR; LGKM(0); SCHED(); MMA(1, 0, B0); BAR; SCHED();
.LBB0_81:
	ds_read_b128 v[128:131], v219 offset:0
	ds_read_b128 v[132:135], v219 offset:0x400
	ds_read_b128 v[136:139], v219 offset:0x800
	ds_read_b128 v[140:143], v219 offset:0xc00
	ds_read_b128 v[144:147], v220 offset:0
	ds_read_b128 v[148:151], v220 offset:0x400
	ds_read_b128 v[152:155], v220 offset:0x800
	ds_read_b128 v[156:159], v220 offset:0xc00
	ds_read_b128 v[160:163], v220 offset:0x1000
	ds_read_b128 v[164:167], v220 offset:0x1400
	ds_read_b128 v[168:171], v220 offset:0x1800
	v_lshl_add_u64 v[192:193], s[76:77], 0, v[210:211]
	s_mov_b32 m0, s79
	ds_read_b128 v[172:175], v220 offset:0x1c00
	v_lshl_add_u64 v[176:177], v[192:193], 0, s[44:45]
	global_load_lds_dwordx4 v[176:177], off
	v_lshl_add_u64 v[176:177], v[192:193], 0, s[48:49]
	s_mov_b32 m0, s80
	s_nop 0
	global_load_lds_dwordx4 v[176:177], off
	s_waitcnt lgkmcnt(8)
	s_barrier
	s_waitcnt lgkmcnt(0)
	v_mfma_f32_16x16x32_bf16 v[124:127], v[128:131], v[144:147], v[124:127]
	v_mfma_f32_16x16x32_bf16 v[120:123], v[136:139], v[144:147], v[120:123]
	v_mfma_f32_16x16x32_bf16 v[116:119], v[128:131], v[152:155], v[116:119]
	v_mfma_f32_16x16x32_bf16 v[112:115], v[136:139], v[152:155], v[112:115]
	v_mfma_f32_16x16x32_bf16 v[108:111], v[128:131], v[160:163], v[108:111]
	v_mfma_f32_16x16x32_bf16 v[104:107], v[136:139], v[160:163], v[104:107]
	v_mfma_f32_16x16x32_bf16 v[100:103], v[128:131], v[168:171], v[100:103]
	v_mfma_f32_16x16x32_bf16 v[96:99], v[136:139], v[168:171], v[96:99]
	v_mfma_f32_16x16x32_bf16 v[124:127], v[132:135], v[148:151], v[124:127]
	v_mfma_f32_16x16x32_bf16 v[120:123], v[140:143], v[148:151], v[120:123]
	v_mfma_f32_16x16x32_bf16 v[116:119], v[132:135], v[156:159], v[116:119]
	v_mfma_f32_16x16x32_bf16 v[112:115], v[140:143], v[156:159], v[112:115]
	v_mfma_f32_16x16x32_bf16 v[108:111], v[132:135], v[164:167], v[108:111]
	v_mfma_f32_16x16x32_bf16 v[104:107], v[140:143], v[164:167], v[104:107]
	v_mfma_f32_16x16x32_bf16 v[100:103], v[132:135], v[172:175], v[100:103]
	v_mfma_f32_16x16x32_bf16 v[96:99], v[140:143], v[172:175], v[96:99]
	s_barrier
	ds_read_b128 v[176:179], v221 offset:0
	ds_read_b128 v[180:183], v221 offset:0x400
	ds_read_b128 v[184:187], v221 offset:0x800
	v_lshl_add_u64 v[194:195], s[74:75], 0, v[210:211]
	s_mov_b64 s[84:85], 0x30100100
	s_mov_b32 m0, s19
	ds_read_b128 v[188:191], v221 offset:0xc00
	v_lshl_add_u64 v[196:197], v[194:195], 0, s[84:85]
	s_mov_b64 s[84:85], 0x30140100
	global_load_lds_dwordx4 v[196:197], off
	v_lshl_add_u64 v[196:197], v[194:195], 0, s[84:85]
	s_mov_b32 m0, s30
	s_nop 0
	global_load_lds_dwordx4 v[196:197], off
	s_barrier
	s_waitcnt lgkmcnt(0)
	v_mfma_f32_16x16x32_bf16 v[92:95], v[176:179], v[144:147], v[92:95]
	v_mfma_f32_16x16x32_bf16 v[88:91], v[184:187], v[144:147], v[88:91]
	v_mfma_f32_16x16x32_bf16 v[84:87], v[176:179], v[152:155], v[84:87]
	v_mfma_f32_16x16x32_bf16 v[80:83], v[184:187], v[152:155], v[80:83]
	v_mfma_f32_16x16x32_bf16 v[76:79], v[176:179], v[160:163], v[76:79]
	v_mfma_f32_16x16x32_bf16 v[72:75], v[184:187], v[160:163], v[72:75]
	v_mfma_f32_16x16x32_bf16 v[68:71], v[176:179], v[168:171], v[68:71]
	v_mfma_f32_16x16x32_bf16 v[64:67], v[184:187], v[168:171], v[64:67]
	v_mfma_f32_16x16x32_bf16 v[92:95], v[180:183], v[148:151], v[92:95]
	v_mfma_f32_16x16x32_bf16 v[88:91], v[188:191], v[148:151], v[88:91]
	v_mfma_f32_16x16x32_bf16 v[84:87], v[180:183], v[156:159], v[84:87]
	v_mfma_f32_16x16x32_bf16 v[80:83], v[188:191], v[156:159], v[80:83]
	v_mfma_f32_16x16x32_bf16 v[76:79], v[180:183], v[164:167], v[76:79]
	v_mfma_f32_16x16x32_bf16 v[72:75], v[188:191], v[164:167], v[72:75]
	v_mfma_f32_16x16x32_bf16 v[68:71], v[180:183], v[172:175], v[68:71]
	v_mfma_f32_16x16x32_bf16 v[64:67], v[188:191], v[172:175], v[64:67]
	s_barrier
	ds_read_b128 v[144:147], v222 offset:0
	ds_read_b128 v[148:151], v222 offset:0x400
	ds_read_b128 v[152:155], v222 offset:0x800
	ds_read_b128 v[156:159], v222 offset:0xc00
	ds_read_b128 v[160:163], v222 offset:0x1000
	ds_read_b128 v[164:167], v222 offset:0x1400
	ds_read_b128 v[168:171], v222 offset:0x1800
	s_mov_b64 s[84:85], 0x100
	s_mov_b32 m0, s3
	ds_read_b128 v[172:175], v222 offset:0x1c00
	v_lshl_add_u64 v[196:197], v[192:193], 0, s[84:85]
	s_mov_b64 s[84:85], 0x40100
	global_load_lds_dwordx4 v[196:197], off
	v_lshl_add_u64 v[196:197], v[192:193], 0, s[84:85]
	s_mov_b32 m0, s31
	s_nop 0
	global_load_lds_dwordx4 v[196:197], off
	s_barrier
	s_waitcnt lgkmcnt(0)
	v_mfma_f32_16x16x32_bf16 v[60:63], v[128:131], v[144:147], v[60:63]
	v_mfma_f32_16x16x32_bf16 v[56:59], v[136:139], v[144:147], v[56:59]
	v_mfma_f32_16x16x32_bf16 v[52:55], v[128:131], v[152:155], v[52:55]
	v_mfma_f32_16x16x32_bf16 v[48:51], v[136:139], v[152:155], v[48:51]
	v_mfma_f32_16x16x32_bf16 v[44:47], v[128:131], v[160:163], v[44:47]
	v_mfma_f32_16x16x32_bf16 v[40:43], v[136:139], v[160:163], v[40:43]
	v_mfma_f32_16x16x32_bf16 v[36:39], v[128:131], v[168:171], v[36:39]
	v_mfma_f32_16x16x32_bf16 v[32:35], v[136:139], v[168:171], v[32:35]
	v_mfma_f32_16x16x32_bf16 v[60:63], v[132:135], v[148:151], v[60:63]
	v_mfma_f32_16x16x32_bf16 v[56:59], v[140:143], v[148:151], v[56:59]
	v_mfma_f32_16x16x32_bf16 v[52:55], v[132:135], v[156:159], v[52:55]
	v_mfma_f32_16x16x32_bf16 v[48:51], v[140:143], v[156:159], v[48:51]
	v_mfma_f32_16x16x32_bf16 v[44:47], v[132:135], v[164:167], v[44:47]
	v_mfma_f32_16x16x32_bf16 v[40:43], v[140:143], v[164:167], v[40:43]
	v_mfma_f32_16x16x32_bf16 v[36:39], v[132:135], v[172:175], v[36:39]
	v_mfma_f32_16x16x32_bf16 v[32:35], v[140:143], v[172:175], v[32:35]
	s_barrier
; #define WAIT_V(n) asm volatile("s_waitcnt vmcnt(%0)" ::"n"(n) : "memory")
; #define SCHED() __builtin_amdgcn_sched_barrier(0)
; #define LGKM(n) asm volatile("s_waitcnt lgkmcnt(%0)" ::"n"(n) : "memory")
; #define STAGE_A(b, h, kt) STAGE_AX(Ag, b, h, kt)
; #define STAGE_B(b, h, kt) STAGE_BX(Bg, b, h, kt)
; #define LDA(b, h) do { const unsigned pa_ = lds0 + SLOTA(b, h) + wr * 8192 + laneoff; _Pragma("unroll") for (int m = 0; m < 4; ++m)   \
;       _Pragma("unroll") for (int k = 0; k < 2; ++k) DSR(At[m][k], pa_, m * 2048 + k * 1024); } while (0)
; #define LDB(dst, b, h) do { const unsigned pb_ = lds0 + SLOTB(b, h) + wc * 4096 + laneoff; _Pragma("unroll") for (int n = 0; n < 2; ++n) \
;       _Pragma("unroll") for (int k = 0; k < 2; ++k) DSR(dst[n][k], pb_, n * 2048 + k * 1024); } while (0)
; #define BAR __builtin_amdgcn_s_barrier()
; #define LGKM(n) asm volatile("s_waitcnt lgkmcnt(%0)" ::"n"(n) : "memory")
; template <int EPI, bool SWP> ...
;     ...
;     STAGE_B(0, 1, t + 2);
;     WAIT_V(6); BAR; SCHED(); MMA(1, 1, B1); BAR; SCHED();
;     LDB(B0, 1, 0); LDA(1, 0); STAGE_A(0, 1, t + 2);
;     LGKM(8); BAR; LGKM(0); SCHED(); MMA(0, 0, B0); BAR; SCHED();
;     LDB(B1, 1, 1); STAGE_B(1, 0, t + 3);
;     BAR; LGKM(0); SCHED(); MMA(0, 1, B1); BAR; SCHED();
;     LDA(1, 1); STAGE_A(1, 0, t + 3);
	s_mov_b64 s[84:85], 0x30180100
	s_mov_b32 m0, s50
	v_lshl_add_u64 v[128:129], v[194:195], 0, s[84:85]
	s_mov_b64 s[84:85], 0x301c0100
	global_load_lds_dwordx4 v[128:129], off
	v_lshl_add_u64 v[128:129], v[194:195], 0, s[84:85]
	s_mov_b32 m0, s51
	s_nop 0
	global_load_lds_dwordx4 v[128:129], off
	s_waitcnt vmcnt(6)
	s_barrier
	v_mfma_f32_16x16x32_bf16 v[28:31], v[176:179], v[144:147], v[28:31]
	v_mfma_f32_16x16x32_bf16 v[24:27], v[184:187], v[144:147], v[24:27]
	v_mfma_f32_16x16x32_bf16 v[20:23], v[176:179], v[152:155], v[20:23]
	v_mfma_f32_16x16x32_bf16 v[16:19], v[184:187], v[152:155], v[16:19]
	v_mfma_f32_16x16x32_bf16 v[12:15], v[176:179], v[160:163], v[12:15]
	v_mfma_f32_16x16x32_bf16 v[8:11], v[184:187], v[160:163], v[8:11]
	v_mfma_f32_16x16x32_bf16 v[4:7], v[176:179], v[168:171], v[4:7]
	v_mfma_f32_16x16x32_bf16 v[0:3], v[184:187], v[168:171], v[0:3]
	v_mfma_f32_16x16x32_bf16 v[28:31], v[180:183], v[148:151], v[28:31]
	v_mfma_f32_16x16x32_bf16 v[24:27], v[188:191], v[148:151], v[24:27]
	v_mfma_f32_16x16x32_bf16 v[20:23], v[180:183], v[156:159], v[20:23]
	v_mfma_f32_16x16x32_bf16 v[16:19], v[188:191], v[156:159], v[16:19]
	v_mfma_f32_16x16x32_bf16 v[12:15], v[180:183], v[164:167], v[12:15]
	v_mfma_f32_16x16x32_bf16 v[8:11], v[188:191], v[164:167], v[8:11]
	v_mfma_f32_16x16x32_bf16 v[4:7], v[180:183], v[172:175], v[4:7]
	v_mfma_f32_16x16x32_bf16 v[0:3], v[188:191], v[172:175], v[0:3]
	s_barrier
	ds_read_b128 v[128:131], v223 offset:0
	ds_read_b128 v[132:135], v223 offset:0x400
	ds_read_b128 v[136:139], v223 offset:0x800
	ds_read_b128 v[140:143], v223 offset:0xc00
	ds_read_b128 v[144:147], v224 offset:0
	ds_read_b128 v[148:151], v224 offset:0x400
	ds_read_b128 v[152:155], v224 offset:0x800
	ds_read_b128 v[156:159], v224 offset:0xc00
	ds_read_b128 v[160:163], v224 offset:0x1000
	ds_read_b128 v[164:167], v224 offset:0x1400
	ds_read_b128 v[168:171], v224 offset:0x1800
	s_mov_b64 s[84:85], 0x80100
	s_mov_b32 m0, s64
	ds_read_b128 v[172:175], v224 offset:0x1c00
	v_lshl_add_u64 v[176:177], v[192:193], 0, s[84:85]
	s_mov_b64 s[84:85], 0xc0100
	global_load_lds_dwordx4 v[176:177], off
	v_lshl_add_u64 v[176:177], v[192:193], 0, s[84:85]
	s_mov_b32 m0, s65
	s_nop 0
	global_load_lds_dwordx4 v[176:177], off
	s_waitcnt lgkmcnt(8)
	s_barrier
	s_waitcnt lgkmcnt(0)
	v_mfma_f32_16x16x32_bf16 v[124:127], v[128:131], v[144:147], v[124:127]
	v_mfma_f32_16x16x32_bf16 v[120:123], v[136:139], v[144:147], v[120:123]
	v_mfma_f32_16x16x32_bf16 v[116:119], v[128:131], v[152:155], v[116:119]
	v_mfma_f32_16x16x32_bf16 v[112:115], v[136:139], v[152:155], v[112:115]
	v_mfma_f32_16x16x32_bf16 v[108:111], v[128:131], v[160:163], v[108:111]
	v_mfma_f32_16x16x32_bf16 v[104:107], v[136:139], v[160:163], v[104:107]
	v_mfma_f32_16x16x32_bf16 v[100:103], v[128:131], v[168:171], v[100:103]
	v_mfma_f32_16x16x32_bf16 v[96:99], v[136:139], v[168:171], v[96:99]
	v_mfma_f32_16x16x32_bf16 v[124:127], v[132:135], v[148:151], v[124:127]
	v_mfma_f32_16x16x32_bf16 v[120:123], v[140:143], v[148:151], v[120:123]
	v_mfma_f32_16x16x32_bf16 v[116:119], v[132:135], v[156:159], v[116:119]
	v_mfma_f32_16x16x32_bf16 v[112:115], v[140:143], v[156:159], v[112:115]
	v_mfma_f32_16x16x32_bf16 v[108:111], v[132:135], v[164:167], v[108:111]
	v_mfma_f32_16x16x32_bf16 v[104:107], v[140:143], v[164:167], v[104:107]
	v_mfma_f32_16x16x32_bf16 v[100:103], v[132:135], v[172:175], v[100:103]
	v_mfma_f32_16x16x32_bf16 v[96:99], v[140:143], v[172:175], v[96:99]
	s_barrier
	ds_read_b128 v[176:179], v225 offset:0
	ds_read_b128 v[180:183], v225 offset:0x400
	ds_read_b128 v[184:187], v225 offset:0x800
	s_mov_b64 s[84:85], 0x30100180
	s_add_i32 s83, s3, 0x18000
	ds_read_b128 v[188:191], v225 offset:0xc00
	v_lshl_add_u64 v[196:197], v[194:195], 0, s[84:85]
	s_mov_b32 m0, s83
	s_mov_b64 s[84:85], 0x30140180
	global_load_lds_dwordx4 v[196:197], off
	v_lshl_add_u64 v[196:197], v[194:195], 0, s[84:85]
	s_mov_b32 m0, s66
	s_nop 0
	global_load_lds_dwordx4 v[196:197], off
	s_barrier
	s_waitcnt lgkmcnt(0)
	v_mfma_f32_16x16x32_bf16 v[92:95], v[176:179], v[144:147], v[92:95]
	v_mfma_f32_16x16x32_bf16 v[88:91], v[184:187], v[144:147], v[88:91]
	v_mfma_f32_16x16x32_bf16 v[84:87], v[176:179], v[152:155], v[84:87]
	v_mfma_f32_16x16x32_bf16 v[80:83], v[184:187], v[152:155], v[80:83]
	v_mfma_f32_16x16x32_bf16 v[76:79], v[176:179], v[160:163], v[76:79]
	v_mfma_f32_16x16x32_bf16 v[72:75], v[184:187], v[160:163], v[72:75]
	v_mfma_f32_16x16x32_bf16 v[68:71], v[176:179], v[168:171], v[68:71]
	v_mfma_f32_16x16x32_bf16 v[64:67], v[184:187], v[168:171], v[64:67]
	v_mfma_f32_16x16x32_bf16 v[92:95], v[180:183], v[148:151], v[92:95]
	v_mfma_f32_16x16x32_bf16 v[88:91], v[188:191], v[148:151], v[88:91]
	v_mfma_f32_16x16x32_bf16 v[84:87], v[180:183], v[156:159], v[84:87]
	v_mfma_f32_16x16x32_bf16 v[80:83], v[188:191], v[156:159], v[80:83]
	v_mfma_f32_16x16x32_bf16 v[76:79], v[180:183], v[164:167], v[76:79]
	v_mfma_f32_16x16x32_bf16 v[72:75], v[188:191], v[164:167], v[72:75]
	v_mfma_f32_16x16x32_bf16 v[68:71], v[180:183], v[172:175], v[68:71]
	v_mfma_f32_16x16x32_bf16 v[64:67], v[188:191], v[172:175], v[64:67]
	s_barrier
	ds_read_b128 v[144:147], v226 offset:0
	ds_read_b128 v[148:151], v226 offset:0x400
	ds_read_b128 v[152:155], v226 offset:0x800
	ds_read_b128 v[156:159], v226 offset:0xc00
	ds_read_b128 v[160:163], v226 offset:0x1000
	ds_read_b128 v[164:167], v226 offset:0x1400
	s_mov_b64 s[84:85], 0x180
	ds_read_b128 v[168:171], v226 offset:0x1800
	v_lshl_add_u64 v[196:197], v[192:193], 0, s[84:85]
	s_add_i32 s84, s3, 0x8000
	ds_read_b128 v[172:175], v226 offset:0x1c00
	s_mov_b32 m0, s84
	s_mov_b64 s[86:87], 0x40180
	global_load_lds_dwordx4 v[196:197], off
	v_lshl_add_u64 v[192:193], v[192:193], 0, s[86:87]
	s_mov_b32 m0, s67
	s_nop 0
	global_load_lds_dwordx4 v[192:193], off
	s_barrier
; #define WAIT_V(n) asm volatile("s_waitcnt vmcnt(%0)" ::"n"(n) : "memory")
; #define SCHED() __builtin_amdgcn_sched_barrier(0)
; #define LGKM(n) asm volatile("s_waitcnt lgkmcnt(%0)" ::"n"(n) : "memory")
; #define STAGE_A(b, h, kt) STAGE_AX(Ag, b, h, kt)
; #define STAGE_B(b, h, kt) STAGE_BX(Bg, b, h, kt)
; #define LDA(b, h) do { const unsigned pa_ = lds0 + SLOTA(b, h) + wr * 8192 + laneoff; _Pragma("unroll") for (int m = 0; m < 4; ++m)   \
;       _Pragma("unroll") for (int k = 0; k < 2; ++k) DSR(At[m][k], pa_, m * 2048 + k * 1024); } while (0)
; #define LDB(dst, b, h) do { const unsigned pb_ = lds0 + SLOTB(b, h) + wc * 4096 + laneoff; _Pragma("unroll") for (int n = 0; n < 2; ++n) \
;       _Pragma("unroll") for (int k = 0; k < 2; ++k) DSR(dst[n][k], pb_, n * 2048 + k * 1024); } while (0)
; #define BAR __builtin_amdgcn_s_barrier()
; #define LGKM(n) asm volatile("s_waitcnt lgkmcnt(%0)" ::"n"(n) : "memory")
; template <int EPI, bool SWP> ...
;     ...
;     BAR; LGKM(0); SCHED(); MMA(1, 0, B0); BAR; SCHED();
;     STAGE_B(1, 1, t + 3);
;     WAIT_V(6); BAR; SCHED(); MMA(1, 1, B1); BAR; SCHED();
;   }
;   { LDB(B0, 0, 0); LDA(0, 0); STAGE_A(1, 1, nt - 1);
	s_waitcnt lgkmcnt(0)
	v_mfma_f32_16x16x32_bf16 v[60:63], v[128:131], v[144:147], v[60:63]
	v_mfma_f32_16x16x32_bf16 v[56:59], v[136:139], v[144:147], v[56:59]
	v_mfma_f32_16x16x32_bf16 v[52:55], v[128:131], v[152:155], v[52:55]
	v_mfma_f32_16x16x32_bf16 v[48:51], v[136:139], v[152:155], v[48:51]
	v_mfma_f32_16x16x32_bf16 v[44:47], v[128:131], v[160:163], v[44:47]
	v_mfma_f32_16x16x32_bf16 v[40:43], v[136:139], v[160:163], v[40:43]
	v_mfma_f32_16x16x32_bf16 v[36:39], v[128:131], v[168:171], v[36:39]
	v_mfma_f32_16x16x32_bf16 v[32:35], v[136:139], v[168:171], v[32:35]
	v_mfma_f32_16x16x32_bf16 v[60:63], v[132:135], v[148:151], v[60:63]
	v_mfma_f32_16x16x32_bf16 v[56:59], v[140:143], v[148:151], v[56:59]
	v_mfma_f32_16x16x32_bf16 v[52:55], v[132:135], v[156:159], v[52:55]
	v_mfma_f32_16x16x32_bf16 v[48:51], v[140:143], v[156:159], v[48:51]
	v_mfma_f32_16x16x32_bf16 v[44:47], v[132:135], v[164:167], v[44:47]
	v_mfma_f32_16x16x32_bf16 v[40:43], v[140:143], v[164:167], v[40:43]
	v_mfma_f32_16x16x32_bf16 v[36:39], v[132:135], v[172:175], v[36:39]
	v_mfma_f32_16x16x32_bf16 v[32:35], v[140:143], v[172:175], v[32:35]
	s_barrier
	s_mov_b64 s[86:87], 0x30180180
	s_add_i32 s85, s3, 0x1c000
	v_lshl_add_u64 v[128:129], v[194:195], 0, s[86:87]
	s_mov_b32 m0, s85
	s_mov_b64 s[86:87], 0x301c0180
	global_load_lds_dwordx4 v[128:129], off
	v_lshl_add_u64 v[128:129], v[194:195], 0, s[86:87]
	s_mov_b32 m0, s78
	s_nop 0
	global_load_lds_dwordx4 v[128:129], off
	s_waitcnt vmcnt(6)
	s_barrier
	v_mfma_f32_16x16x32_bf16 v[28:31], v[176:179], v[144:147], v[28:31]
	v_mfma_f32_16x16x32_bf16 v[24:27], v[184:187], v[144:147], v[24:27]
	v_mfma_f32_16x16x32_bf16 v[20:23], v[176:179], v[152:155], v[20:23]
	v_mfma_f32_16x16x32_bf16 v[16:19], v[184:187], v[152:155], v[16:19]
	v_mfma_f32_16x16x32_bf16 v[12:15], v[176:179], v[160:163], v[12:15]
	v_mfma_f32_16x16x32_bf16 v[8:11], v[184:187], v[160:163], v[8:11]
	v_mfma_f32_16x16x32_bf16 v[4:7], v[176:179], v[168:171], v[4:7]
	v_mfma_f32_16x16x32_bf16 v[0:3], v[184:187], v[168:171], v[0:3]
	v_mfma_f32_16x16x32_bf16 v[28:31], v[180:183], v[148:151], v[28:31]
	v_mfma_f32_16x16x32_bf16 v[24:27], v[188:191], v[148:151], v[24:27]
	v_mfma_f32_16x16x32_bf16 v[20:23], v[180:183], v[156:159], v[20:23]
	v_mfma_f32_16x16x32_bf16 v[16:19], v[188:191], v[156:159], v[16:19]
	v_mfma_f32_16x16x32_bf16 v[12:15], v[180:183], v[164:167], v[12:15]
	v_mfma_f32_16x16x32_bf16 v[8:11], v[188:191], v[164:167], v[8:11]
	v_mfma_f32_16x16x32_bf16 v[4:7], v[180:183], v[172:175], v[4:7]
	v_mfma_f32_16x16x32_bf16 v[0:3], v[188:191], v[172:175], v[0:3]
	s_add_i32 s15, s15, 2
	s_add_u32 s74, s74, 0x100
	s_addc_u32 s75, s75, 0
	s_add_u32 s76, s76, 0x100
	s_addc_u32 s77, s77, 0
	s_cmp_gt_u32 s15, 27
	s_barrier
	s_cbranch_scc0 .LBB0_81
	ds_read_b128 v[136:139], v219 offset:0
	ds_read_b128 v[140:143], v219 offset:0x400
	ds_read_b128 v[144:147], v219 offset:0x800
	ds_read_b128 v[148:151], v219 offset:0xc00
	ds_read_b128 v[128:131], v220 offset:0
	ds_read_b128 v[132:135], v220 offset:0x400
	ds_read_b128 v[152:155], v220 offset:0x800
	ds_read_b128 v[156:159], v220 offset:0xc00
	ds_read_b128 v[160:163], v220 offset:0x1000
	ds_read_b128 v[164:167], v220 offset:0x1400
	v_lshl_add_u64 v[176:177], s[72:73], 0, v[208:209]
	ds_read_b128 v[168:171], v220 offset:0x1800
	s_mov_b64 s[72:73], 0x80f80
	s_mov_b32 m0, s79
	ds_read_b128 v[172:175], v220 offset:0x1c00
	v_lshl_add_u64 v[178:179], v[176:177], 0, s[72:73]
	s_mov_b64 s[72:73], 0xc0f80
	global_load_lds_dwordx4 v[178:179], off
	v_lshl_add_u64 v[176:177], v[176:177], 0, s[72:73]
	s_mov_b32 m0, s80
	s_ashr_i32 s15, s14, 31
	global_load_lds_dwordx4 v[176:177], off
	s_lshl_b64 s[72:73], s[14:15], 20
	s_add_u32 s72, s56, s72
	s_addc_u32 s73, s57, s73
	s_ashr_i32 s61, s60, 31
	s_barrier
	s_waitcnt lgkmcnt(0)
	s_lshl_b64 s[74:75], s[60:61], 20
	s_add_u32 s74, s10, s74
	s_addc_u32 s75, s11, s75
	v_mfma_f32_16x16x32_bf16 v[124:127], v[136:139], v[128:131], v[124:127]
	v_mfma_f32_16x16x32_bf16 v[120:123], v[144:147], v[128:131], v[120:123]
	v_mfma_f32_16x16x32_bf16 v[116:119], v[136:139], v[152:155], v[116:119]
	v_mfma_f32_16x16x32_bf16 v[112:115], v[144:147], v[152:155], v[112:115]
	v_mfma_f32_16x16x32_bf16 v[108:111], v[136:139], v[160:163], v[108:111]
	v_mfma_f32_16x16x32_bf16 v[104:107], v[144:147], v[160:163], v[104:107]
	v_mfma_f32_16x16x32_bf16 v[100:103], v[136:139], v[168:171], v[100:103]
	v_mfma_f32_16x16x32_bf16 v[96:99], v[144:147], v[168:171], v[96:99]
	v_mfma_f32_16x16x32_bf16 v[124:127], v[140:143], v[132:135], v[124:127]
	v_mfma_f32_16x16x32_bf16 v[120:123], v[148:151], v[132:135], v[120:123]
	v_mfma_f32_16x16x32_bf16 v[116:119], v[140:143], v[156:159], v[116:119]
	v_mfma_f32_16x16x32_bf16 v[112:115], v[148:151], v[156:159], v[112:115]
	v_mfma_f32_16x16x32_bf16 v[176:179], v[140:143], v[164:167], v[108:111]
	v_mfma_f32_16x16x32_bf16 v[180:183], v[148:151], v[164:167], v[104:107]
	v_mfma_f32_16x16x32_bf16 v[100:103], v[140:143], v[172:175], v[100:103]
	v_mfma_f32_16x16x32_bf16 v[96:99], v[148:151], v[172:175], v[96:99]
	s_barrier
	ds_read_b128 v[104:107], v221 offset:0
	ds_read_b128 v[108:111], v221 offset:0x400
	ds_read_b128 v[184:187], v221 offset:0x800
	ds_read_b128 v[188:191], v221 offset:0xc00
	s_barrier
; #define WAIT_V(n) asm volatile("s_waitcnt vmcnt(%0)" ::"n"(n) : "memory")
; #define SCHED() __builtin_amdgcn_sched_barrier(0)
; #define LGKM(n) asm volatile("s_waitcnt lgkmcnt(%0)" ::"n"(n) : "memory")
; #define LDA(b, h) do { const unsigned pa_ = lds0 + SLOTA(b, h) + wr * 8192 + laneoff; _Pragma("unroll") for (int m = 0; m < 4; ++m)   \
;       _Pragma("unroll") for (int k = 0; k < 2; ++k) DSR(At[m][k], pa_, m * 2048 + k * 1024); } while (0)
; #define LDB(dst, b, h) do { const unsigned pb_ = lds0 + SLOTB(b, h) + wc * 4096 + laneoff; _Pragma("unroll") for (int n = 0; n < 2; ++n) \
;       _Pragma("unroll") for (int k = 0; k < 2; ++k) DSR(dst[n][k], pb_, n * 2048 + k * 1024); } while (0)
; #define BAR __builtin_amdgcn_s_barrier()
; #define LGKM(n) asm volatile("s_waitcnt lgkmcnt(%0)" ::"n"(n) : "memory")
; template <int EPI, bool SWP> ...
;     ...
;     LDB(B1, 0, 1); BAR; LGKM(0); SCHED(); MMA(0, 1, B1); BAR; SCHED();
;     LDA(0, 1); WAIT_V(4); BAR; LGKM(0); SCHED(); MMA(1, 0, B0); MMA(1, 1, B1); BAR; SCHED(); }
;   { LDB(B0, 1, 0); LDA(1, 0); WAIT_V(2); BAR; LGKM(0); SCHED(); MMA(0, 0, B0); BAR; SCHED();
	s_waitcnt lgkmcnt(0)
	v_mfma_f32_16x16x32_bf16 v[92:95], v[104:107], v[128:131], v[92:95]
	v_mfma_f32_16x16x32_bf16 v[88:91], v[184:187], v[128:131], v[88:91]
	v_mfma_f32_16x16x32_bf16 v[84:87], v[104:107], v[152:155], v[84:87]
	v_mfma_f32_16x16x32_bf16 v[80:83], v[184:187], v[152:155], v[80:83]
	v_mfma_f32_16x16x32_bf16 v[76:79], v[104:107], v[160:163], v[76:79]
	v_mfma_f32_16x16x32_bf16 v[72:75], v[184:187], v[160:163], v[72:75]
	v_mfma_f32_16x16x32_bf16 v[68:71], v[104:107], v[168:171], v[68:71]
	v_mfma_f32_16x16x32_bf16 v[64:67], v[184:187], v[168:171], v[64:67]
	v_mfma_f32_16x16x32_bf16 v[192:195], v[108:111], v[132:135], v[92:95]
	v_mfma_f32_16x16x32_bf16 v[196:199], v[188:191], v[132:135], v[88:91]
	v_mfma_f32_16x16x32_bf16 v[84:87], v[108:111], v[156:159], v[84:87]
	v_mfma_f32_16x16x32_bf16 v[80:83], v[188:191], v[156:159], v[80:83]
	v_mfma_f32_16x16x32_bf16 v[200:203], v[108:111], v[164:167], v[76:79]
	v_mfma_f32_16x16x32_bf16 v[204:207], v[188:191], v[164:167], v[72:75]
	v_mfma_f32_16x16x32_bf16 v[68:71], v[108:111], v[172:175], v[68:71]
	v_mfma_f32_16x16x32_bf16 v[64:67], v[188:191], v[172:175], v[64:67]
	s_barrier
	ds_read_b128 v[72:75], v222 offset:0
	ds_read_b128 v[76:79], v222 offset:0x400
	ds_read_b128 v[88:91], v222 offset:0x800
	ds_read_b128 v[92:95], v222 offset:0xc00
	ds_read_b128 v[152:155], v222 offset:0x1000
	ds_read_b128 v[156:159], v222 offset:0x1400
	ds_read_b128 v[160:163], v222 offset:0x1800
	ds_read_b128 v[164:167], v222 offset:0x1c00
	s_waitcnt vmcnt(4)
	s_barrier
	s_waitcnt lgkmcnt(0)
	v_mfma_f32_16x16x32_bf16 v[60:63], v[136:139], v[72:75], v[60:63]
	v_mfma_f32_16x16x32_bf16 v[56:59], v[144:147], v[72:75], v[56:59]
	v_mfma_f32_16x16x32_bf16 v[52:55], v[136:139], v[88:91], v[52:55]
	v_mfma_f32_16x16x32_bf16 v[48:51], v[144:147], v[88:91], v[48:51]
	v_mfma_f32_16x16x32_bf16 v[44:47], v[136:139], v[152:155], v[44:47]
	v_mfma_f32_16x16x32_bf16 v[40:43], v[144:147], v[152:155], v[40:43]
	v_mfma_f32_16x16x32_bf16 v[36:39], v[136:139], v[160:163], v[36:39]
	v_mfma_f32_16x16x32_bf16 v[32:35], v[144:147], v[160:163], v[32:35]
	v_mfma_f32_16x16x32_bf16 v[60:63], v[140:143], v[76:79], v[60:63]
	v_mfma_f32_16x16x32_bf16 v[56:59], v[148:151], v[76:79], v[56:59]
	v_mfma_f32_16x16x32_bf16 v[52:55], v[140:143], v[92:95], v[52:55]
	v_mfma_f32_16x16x32_bf16 v[48:51], v[148:151], v[92:95], v[48:51]
	v_mfma_f32_16x16x32_bf16 v[128:131], v[140:143], v[156:159], v[44:47]
	v_mfma_f32_16x16x32_bf16 v[132:135], v[148:151], v[156:159], v[40:43]
	v_mfma_f32_16x16x32_bf16 v[36:39], v[140:143], v[164:167], v[36:39]
	v_mfma_f32_16x16x32_bf16 v[32:35], v[148:151], v[164:167], v[32:35]
	v_mfma_f32_16x16x32_bf16 v[28:31], v[104:107], v[72:75], v[28:31]
	v_mfma_f32_16x16x32_bf16 v[24:27], v[184:187], v[72:75], v[24:27]
	v_mfma_f32_16x16x32_bf16 v[20:23], v[104:107], v[88:91], v[20:23]
	v_mfma_f32_16x16x32_bf16 v[16:19], v[184:187], v[88:91], v[16:19]
	v_mfma_f32_16x16x32_bf16 v[12:15], v[104:107], v[152:155], v[12:15]
	v_mfma_f32_16x16x32_bf16 v[8:11], v[184:187], v[152:155], v[8:11]
	v_mfma_f32_16x16x32_bf16 v[4:7], v[104:107], v[160:163], v[4:7]
	v_mfma_f32_16x16x32_bf16 v[0:3], v[184:187], v[160:163], v[0:3]
	v_mfma_f32_16x16x32_bf16 v[136:139], v[108:111], v[76:79], v[28:31]
	v_mfma_f32_16x16x32_bf16 v[140:143], v[188:191], v[76:79], v[24:27]
	v_mfma_f32_16x16x32_bf16 v[20:23], v[108:111], v[92:95], v[20:23]
	v_mfma_f32_16x16x32_bf16 v[16:19], v[188:191], v[92:95], v[16:19]
	v_mfma_f32_16x16x32_bf16 v[144:147], v[108:111], v[156:159], v[12:15]
	v_mfma_f32_16x16x32_bf16 v[148:151], v[188:191], v[156:159], v[8:11]
	v_mfma_f32_16x16x32_bf16 v[4:7], v[108:111], v[164:167], v[4:7]
	v_mfma_f32_16x16x32_bf16 v[0:3], v[188:191], v[164:167], v[0:3]
	s_barrier
	ds_read_b128 v[8:11], v223 offset:0
	ds_read_b128 v[12:15], v223 offset:0x400
	ds_read_b128 v[152:155], v223 offset:0x800
	ds_read_b128 v[156:159], v223 offset:0xc00
	ds_read_b128 v[24:27], v224 offset:0
	ds_read_b128 v[28:31], v224 offset:0x400
	ds_read_b128 v[40:43], v224 offset:0x800
	ds_read_b128 v[44:47], v224 offset:0xc00
	ds_read_b128 v[184:187], v224 offset:0x1000
	ds_read_b128 v[188:191], v224 offset:0x1400
	ds_read_b128 v[212:215], v224 offset:0x1800
	ds_read_b128 v[236:239], v224 offset:0x1c00
	s_waitcnt vmcnt(2)
	s_barrier
; #define WAIT_V(n) asm volatile("s_waitcnt vmcnt(%0)" ::"n"(n) : "memory")
; #define SCHED() __builtin_amdgcn_sched_barrier(0)
; #define LGKM(n) asm volatile("s_waitcnt lgkmcnt(%0)" ::"n"(n) : "memory")
; #define STAGE_AX(AG, b, h, kt) do { _Pragma("unroll") for (int i = 0; i < 2; ++i)                                    \
;       __builtin_amdgcn_global_load_lds((const unsigned*)(((AG) + ((size_t)(kt) * (BK * 2) + (size_t)((h) * 2 + i) * 128 * lda)) + aoff), \
;                                        (unsigned*)(shm + SLOTA(b, h) + wid * 1024 + i * 8192), 16, 0, 0); } while (0)
; #define STAGE_BX(BG, b, h, kt) do { _Pragma("unroll") for (int i = 0; i < 2; ++i)                                    \
;       __builtin_amdgcn_global_load_lds((const unsigned*)(((BG) + ((size_t)(kt) * (BK * 2) + (size_t)((h) * 2 + i) * 128 * K)) + boff),   \
;                                        (unsigned*)(shm + SLOTB(b, h) + wid * 1024 + i * 8192), 16, 0, 0); } while (0)
; #define LDA(b, h) do { const unsigned pa_ = lds0 + SLOTA(b, h) + wr * 8192 + laneoff; _Pragma("unroll") for (int m = 0; m < 4; ++m)   \
;       _Pragma("unroll") for (int k = 0; k < 2; ++k) DSR(At[m][k], pa_, m * 2048 + k * 1024); } while (0)
; #define LDB(dst, b, h) do { const unsigned pb_ = lds0 + SLOTB(b, h) + wc * 4096 + laneoff; _Pragma("unroll") for (int n = 0; n < 2; ++n) \
;       _Pragma("unroll") for (int k = 0; k < 2; ++k) DSR(dst[n][k], pb_, n * 2048 + k * 1024); } while (0)
; #define BAR __builtin_amdgcn_s_barrier()
; #define LGKM(n) asm volatile("s_waitcnt lgkmcnt(%0)" ::"n"(n) : "memory")
; template <int EPI, bool SWP> ...
;     ...
;   { LDB(B0, 1, 0); LDA(1, 0); WAIT_V(2); BAR; LGKM(0); SCHED(); MMA(0, 0, B0); BAR; SCHED();
;     LDB(B1, 1, 1); WAIT_V(0); BAR; LGKM(0); SCHED(); MMA(0, 1, B1); BAR; SCHED();
;     LDA(1, 1);
;     if (has_next) { STAGE_BX(Bg_n, 0, 0, 0); STAGE_AX(Ag_n, 0, 0, 0); STAGE_BX(Bg_n, 0, 1, 0); STAGE_AX(Ag_n, 0, 1, 0); }
	s_waitcnt lgkmcnt(0)
	v_mfma_f32_16x16x32_bf16 v[72:75], v[8:11], v[24:27], v[124:127]
	v_mfma_f32_16x16x32_bf16 v[124:127], v[12:15], v[28:31], v[72:75]
	v_mfma_f32_16x16x32_bf16 v[72:75], v[152:155], v[24:27], v[120:123]
	v_mfma_f32_16x16x32_bf16 v[120:123], v[156:159], v[28:31], v[72:75]
	v_mfma_f32_16x16x32_bf16 v[72:75], v[8:11], v[40:43], v[116:119]
	v_mfma_f32_16x16x32_bf16 v[108:111], v[12:15], v[44:47], v[72:75]
	v_mfma_f32_16x16x32_bf16 v[72:75], v[152:155], v[40:43], v[112:115]
	v_mfma_f32_16x16x32_bf16 v[104:107], v[156:159], v[44:47], v[72:75]
	v_mfma_f32_16x16x32_bf16 v[72:75], v[8:11], v[184:187], v[176:179]
	v_mfma_f32_16x16x32_bf16 v[92:95], v[12:15], v[188:191], v[72:75]
	v_mfma_f32_16x16x32_bf16 v[72:75], v[152:155], v[184:187], v[180:183]
	v_mfma_f32_16x16x32_bf16 v[88:91], v[156:159], v[188:191], v[72:75]
	v_mfma_f32_16x16x32_bf16 v[72:75], v[8:11], v[212:215], v[100:103]
	v_mfma_f32_16x16x32_bf16 v[76:79], v[12:15], v[236:239], v[72:75]
	v_mfma_f32_16x16x32_bf16 v[72:75], v[152:155], v[212:215], v[96:99]
	v_mfma_f32_16x16x32_bf16 v[72:75], v[156:159], v[236:239], v[72:75]
	s_barrier
	ds_read_b128 v[160:163], v225 offset:0
	ds_read_b128 v[164:167], v225 offset:0x400
	ds_read_b128 v[168:171], v225 offset:0x800
	ds_read_b128 v[172:175], v225 offset:0xc00
	s_waitcnt vmcnt(0)
	s_barrier
	s_waitcnt lgkmcnt(0)
	v_mfma_f32_16x16x32_bf16 v[96:99], v[160:163], v[24:27], v[192:195]
	v_mfma_f32_16x16x32_bf16 v[24:27], v[168:171], v[24:27], v[196:199]
	v_mfma_f32_16x16x32_bf16 v[112:115], v[172:175], v[28:31], v[24:27]
	v_mfma_f32_16x16x32_bf16 v[24:27], v[160:163], v[40:43], v[84:87]
	v_mfma_f32_16x16x32_bf16 v[100:103], v[164:167], v[44:47], v[24:27]
	v_mfma_f32_16x16x32_bf16 v[24:27], v[168:171], v[40:43], v[80:83]
	v_mfma_f32_16x16x32_bf16 v[116:119], v[164:167], v[28:31], v[96:99]
	v_mfma_f32_16x16x32_bf16 v[96:99], v[172:175], v[44:47], v[24:27]
	v_mfma_f32_16x16x32_bf16 v[24:27], v[160:163], v[184:187], v[200:203]
	v_mfma_f32_16x16x32_bf16 v[84:87], v[164:167], v[188:191], v[24:27]
	v_mfma_f32_16x16x32_bf16 v[24:27], v[168:171], v[184:187], v[204:207]
	v_mfma_f32_16x16x32_bf16 v[80:83], v[172:175], v[188:191], v[24:27]
	v_mfma_f32_16x16x32_bf16 v[24:27], v[160:163], v[212:215], v[68:71]
	v_mfma_f32_16x16x32_bf16 v[68:71], v[164:167], v[236:239], v[24:27]
	v_mfma_f32_16x16x32_bf16 v[24:27], v[168:171], v[212:215], v[64:67]
	v_mfma_f32_16x16x32_bf16 v[64:67], v[172:175], v[236:239], v[24:27]
	s_barrier
	ds_read_b128 v[200:203], v226 offset:0
	ds_read_b128 v[204:207], v226 offset:0x400
	ds_read_b128 v[192:195], v226 offset:0x800
	ds_read_b128 v[196:199], v226 offset:0xc00
	ds_read_b128 v[184:187], v226 offset:0x1000
	ds_read_b128 v[188:191], v226 offset:0x1400
	ds_read_b128 v[176:179], v226 offset:0x1800
	ds_read_b128 v[180:183], v226 offset:0x1c00
	s_and_b64 vcc, exec, s[70:71]
	v_lshl_add_u64 v[212:213], s[74:75], 0, v[208:209]
	v_lshl_add_u64 v[214:215], s[72:73], 0, v[208:209]
	s_cbranch_vccz .LBB0_84
	s_mov_b32 m0, s19
	v_lshl_add_u64 v[24:25], v[212:213], 0, s[22:23]
	global_load_lds_dwordx4 v[212:213], off
	s_mov_b32 m0, s30
	s_nop 0
	global_load_lds_dwordx4 v[24:25], off
	s_mov_b32 m0, s3
	v_lshl_add_u64 v[24:25], v[214:215], 0, s[22:23]
	global_load_lds_dwordx4 v[214:215], off
	s_mov_b32 m0, s31
	s_nop 0
	global_load_lds_dwordx4 v[24:25], off
	v_lshl_add_u64 v[24:25], v[212:213], 0, s[24:25]
	s_mov_b32 m0, s50
	s_nop 0
	global_load_lds_dwordx4 v[24:25], off
	v_lshl_add_u64 v[24:25], v[212:213], 0, s[26:27]
	s_mov_b32 m0, s51
	s_nop 0
	global_load_lds_dwordx4 v[24:25], off
	v_lshl_add_u64 v[24:25], v[214:215], 0, s[24:25]
	s_mov_b32 m0, s64
	s_nop 0
	global_load_lds_dwordx4 v[24:25], off
	v_lshl_add_u64 v[24:25], v[214:215], 0, s[26:27]
	s_mov_b32 m0, s65
	s_nop 0
	global_load_lds_dwordx4 v[24:25], off

; #define WAIT_V(n) asm volatile("s_waitcnt vmcnt(%0)" ::"n"(n) : "memory")
; #define SCHED() __builtin_amdgcn_sched_barrier(0)
; #define LGKM(n) asm volatile("s_waitcnt lgkmcnt(%0)" ::"n"(n) : "memory")
; #define STAGE_A(b, h, kt) STAGE_AX(Ag, b, h, kt)
; #define STAGE_B(b, h, kt) STAGE_BX(Bg, b, h, kt)
; #define LDA(b, h) do { const unsigned pa_ = lds0 + SLOTA(b, h) + wr * 8192 + laneoff; _Pragma("unroll") for (int m = 0; m < 4; ++m)   \
;       _Pragma("unroll") for (int k = 0; k < 2; ++k) DSR(At[m][k], pa_, m * 2048 + k * 1024); } while (0)
; #define LDB(dst, b, h) do { const unsigned pb_ = lds0 + SLOTB(b, h) + wc * 4096 + laneoff; _Pragma("unroll") for (int n = 0; n < 2; ++n) \
;       _Pragma("unroll") for (int k = 0; k < 2; ++k) DSR(dst[n][k], pb_, n * 2048 + k * 1024); } while (0)
; #define BAR __builtin_amdgcn_s_barrier()
; #define LGKM(n) asm volatile("s_waitcnt lgkmcnt(%0)" ::"n"(n) : "memory")
; template <int EPI, bool SWP> ...
;     ...
;     LDB(B0, 0, 0); LDA(0, 0); STAGE_A(1, 1, t + 1);
;     LGKM(8); BAR; LGKM(0); SCHED(); MMA(0, 0, B0); BAR; SCHED();
;     LDB(B1, 0, 1); STAGE_B(0, 0, t + 2);
;     BAR; LGKM(0); SCHED(); MMA(0, 1, B1); BAR; SCHED();
;     LDA(0, 1); STAGE_A(0, 0, t + 2);
;     BAR; LGKM(0); SCHED(); MMA(1, 0, B0); BAR; SCHED();
;     STAGE_B(0, 1, t + 2);
;     WAIT_V(6); BAR; SCHED(); MMA(1, 1, B1); BAR; SCHED();
.LBB0_123:
	ds_read_b128 v[130:133], v201 offset:0
	ds_read_b128 v[134:137], v201 offset:0x400
	ds_read_b128 v[138:141], v201 offset:0x800
	ds_read_b128 v[142:145], v201 offset:0xc00
	ds_read_b128 v[146:149], v202 offset:0
	ds_read_b128 v[150:153], v202 offset:0x400
	ds_read_b128 v[154:157], v202 offset:0x800
	ds_read_b128 v[158:161], v202 offset:0xc00
	ds_read_b128 v[162:165], v202 offset:0x1000
	ds_read_b128 v[166:169], v202 offset:0x1400
	ds_read_b128 v[170:173], v202 offset:0x1800
	v_lshl_add_u64 v[190:191], s[58:59], 0, v[194:195]
	s_mov_b64 s[70:71], 0xf260080
	s_add_i32 s74, s3, 0xc000
	ds_read_b128 v[174:177], v202 offset:0x1c00
	v_lshl_add_u64 v[178:179], v[190:191], 0, s[70:71]
	s_mov_b32 m0, s74
	s_mov_b64 s[70:71], 0xf310080
	global_load_lds_dwordx4 v[178:179], off
	v_lshl_add_u64 v[178:179], v[190:191], 0, s[70:71]
	s_mov_b32 m0, s61
	s_nop 0
	global_load_lds_dwordx4 v[178:179], off
	s_waitcnt lgkmcnt(8)
	s_barrier
	s_waitcnt lgkmcnt(0)
	v_mfma_f32_16x16x32_bf16 v[124:127], v[130:133], v[146:149], v[124:127]
	v_mfma_f32_16x16x32_bf16 v[120:123], v[138:141], v[146:149], v[120:123]
	v_mfma_f32_16x16x32_bf16 v[116:119], v[130:133], v[154:157], v[116:119]
	v_mfma_f32_16x16x32_bf16 v[112:115], v[138:141], v[154:157], v[112:115]
	v_mfma_f32_16x16x32_bf16 v[108:111], v[130:133], v[162:165], v[108:111]
	v_mfma_f32_16x16x32_bf16 v[104:107], v[138:141], v[162:165], v[104:107]
	v_mfma_f32_16x16x32_bf16 v[100:103], v[130:133], v[170:173], v[100:103]
	v_mfma_f32_16x16x32_bf16 v[96:99], v[138:141], v[170:173], v[96:99]
	v_mfma_f32_16x16x32_bf16 v[124:127], v[134:137], v[150:153], v[124:127]
	v_mfma_f32_16x16x32_bf16 v[120:123], v[142:145], v[150:153], v[120:123]
	v_mfma_f32_16x16x32_bf16 v[116:119], v[134:137], v[158:161], v[116:119]
	v_mfma_f32_16x16x32_bf16 v[112:115], v[142:145], v[158:161], v[112:115]
	v_mfma_f32_16x16x32_bf16 v[108:111], v[134:137], v[166:169], v[108:111]
	v_mfma_f32_16x16x32_bf16 v[104:107], v[142:145], v[166:169], v[104:107]
	v_mfma_f32_16x16x32_bf16 v[100:103], v[134:137], v[174:177], v[100:103]
	v_mfma_f32_16x16x32_bf16 v[96:99], v[142:145], v[174:177], v[96:99]
	s_barrier
	ds_read_b128 v[178:181], v203 offset:0
	ds_read_b128 v[182:185], v203 offset:0x400
	ds_read_b128 v[186:189], v203 offset:0x800
	v_lshl_add_u64 v[220:221], s[10:11], 0, v[194:195]
	s_mov_b64 s[70:71], 0x32d00100
	s_mov_b32 m0, s17
	ds_read_b128 v[196:199], v203 offset:0xc00
	v_lshl_add_u64 v[222:223], v[220:221], 0, s[70:71]
	s_mov_b64 s[70:71], 0x32db0100
	global_load_lds_dwordx4 v[222:223], off
	v_lshl_add_u64 v[222:223], v[220:221], 0, s[70:71]
	s_mov_b32 m0, s18
	s_nop 0
	global_load_lds_dwordx4 v[222:223], off
	s_barrier
	s_waitcnt lgkmcnt(0)
	v_mfma_f32_16x16x32_bf16 v[92:95], v[178:181], v[146:149], v[92:95]
	v_mfma_f32_16x16x32_bf16 v[88:91], v[186:189], v[146:149], v[88:91]
	v_mfma_f32_16x16x32_bf16 v[84:87], v[178:181], v[154:157], v[84:87]
	v_mfma_f32_16x16x32_bf16 v[80:83], v[186:189], v[154:157], v[80:83]
	v_mfma_f32_16x16x32_bf16 v[76:79], v[178:181], v[162:165], v[76:79]
	v_mfma_f32_16x16x32_bf16 v[72:75], v[186:189], v[162:165], v[72:75]
	v_mfma_f32_16x16x32_bf16 v[68:71], v[178:181], v[170:173], v[68:71]
	v_mfma_f32_16x16x32_bf16 v[64:67], v[186:189], v[170:173], v[64:67]
	v_mfma_f32_16x16x32_bf16 v[92:95], v[182:185], v[150:153], v[92:95]
	v_mfma_f32_16x16x32_bf16 v[88:91], v[196:199], v[150:153], v[88:91]
	v_mfma_f32_16x16x32_bf16 v[84:87], v[182:185], v[158:161], v[84:87]
	v_mfma_f32_16x16x32_bf16 v[80:83], v[196:199], v[158:161], v[80:83]
	v_mfma_f32_16x16x32_bf16 v[76:79], v[182:185], v[166:169], v[76:79]
	v_mfma_f32_16x16x32_bf16 v[72:75], v[196:199], v[166:169], v[72:75]
	v_mfma_f32_16x16x32_bf16 v[68:71], v[182:185], v[174:177], v[68:71]
	v_mfma_f32_16x16x32_bf16 v[64:67], v[196:199], v[174:177], v[64:67]
	s_barrier
	ds_read_b128 v[146:149], v204 offset:0
	ds_read_b128 v[150:153], v204 offset:0x400
	ds_read_b128 v[154:157], v204 offset:0x800
	ds_read_b128 v[158:161], v204 offset:0xc00
	ds_read_b128 v[162:165], v204 offset:0x1000
	ds_read_b128 v[166:169], v204 offset:0x1400
	ds_read_b128 v[170:173], v204 offset:0x1800
	s_mov_b64 s[70:71], 0xf100100
	s_mov_b32 m0, s3
	ds_read_b128 v[174:177], v204 offset:0x1c00
	v_lshl_add_u64 v[222:223], v[190:191], 0, s[70:71]
	s_mov_b64 s[70:71], 0xf1b0100
	global_load_lds_dwordx4 v[222:223], off
	v_lshl_add_u64 v[222:223], v[190:191], 0, s[70:71]
	s_mov_b32 m0, s19
	s_nop 0
	global_load_lds_dwordx4 v[222:223], off
	s_barrier
	s_waitcnt lgkmcnt(0)
	v_mfma_f32_16x16x32_bf16 v[60:63], v[130:133], v[146:149], v[60:63]
	v_mfma_f32_16x16x32_bf16 v[56:59], v[138:141], v[146:149], v[56:59]
	v_mfma_f32_16x16x32_bf16 v[52:55], v[130:133], v[154:157], v[52:55]
	v_mfma_f32_16x16x32_bf16 v[48:51], v[138:141], v[154:157], v[48:51]
	v_mfma_f32_16x16x32_bf16 v[44:47], v[130:133], v[162:165], v[44:47]
	v_mfma_f32_16x16x32_bf16 v[40:43], v[138:141], v[162:165], v[40:43]
	v_mfma_f32_16x16x32_bf16 v[36:39], v[130:133], v[170:173], v[36:39]
	v_mfma_f32_16x16x32_bf16 v[32:35], v[138:141], v[170:173], v[32:35]
	v_mfma_f32_16x16x32_bf16 v[60:63], v[134:137], v[150:153], v[60:63]
	v_mfma_f32_16x16x32_bf16 v[56:59], v[142:145], v[150:153], v[56:59]
	v_mfma_f32_16x16x32_bf16 v[52:55], v[134:137], v[158:161], v[52:55]
	v_mfma_f32_16x16x32_bf16 v[48:51], v[142:145], v[158:161], v[48:51]
	v_mfma_f32_16x16x32_bf16 v[44:47], v[134:137], v[166:169], v[44:47]
	v_mfma_f32_16x16x32_bf16 v[40:43], v[142:145], v[166:169], v[40:43]
	v_mfma_f32_16x16x32_bf16 v[36:39], v[134:137], v[174:177], v[36:39]
	v_mfma_f32_16x16x32_bf16 v[32:35], v[142:145], v[174:177], v[32:35]
	s_barrier
; #define WAIT_V(n) asm volatile("s_waitcnt vmcnt(%0)" ::"n"(n) : "memory")
; #define SCHED() __builtin_amdgcn_sched_barrier(0)
; #define LGKM(n) asm volatile("s_waitcnt lgkmcnt(%0)" ::"n"(n) : "memory")
; #define STAGE_A(b, h, kt) STAGE_AX(Ag, b, h, kt)
; #define STAGE_B(b, h, kt) STAGE_BX(Bg, b, h, kt)
; #define LDA(b, h) do { const unsigned pa_ = lds0 + SLOTA(b, h) + wr * 8192 + laneoff; _Pragma("unroll") for (int m = 0; m < 4; ++m)   \
;       _Pragma("unroll") for (int k = 0; k < 2; ++k) DSR(At[m][k], pa_, m * 2048 + k * 1024); } while (0)
; #define LDB(dst, b, h) do { const unsigned pb_ = lds0 + SLOTB(b, h) + wc * 4096 + laneoff; _Pragma("unroll") for (int n = 0; n < 2; ++n) \
;       _Pragma("unroll") for (int k = 0; k < 2; ++k) DSR(dst[n][k], pb_, n * 2048 + k * 1024); } while (0)
; #define BAR __builtin_amdgcn_s_barrier()
; #define LGKM(n) asm volatile("s_waitcnt lgkmcnt(%0)" ::"n"(n) : "memory")
; template <int EPI, bool SWP> ...
;     ...
;     WAIT_V(6); BAR; SCHED(); MMA(1, 1, B1); BAR; SCHED();
;     LDB(B0, 1, 0); LDA(1, 0); STAGE_A(0, 1, t + 2);
;     LGKM(8); BAR; LGKM(0); SCHED(); MMA(0, 0, B0); BAR; SCHED();
;     LDB(B1, 1, 1); STAGE_B(1, 0, t + 3);
;     BAR; LGKM(0); SCHED(); MMA(0, 1, B1); BAR; SCHED();
;     LDA(1, 1); STAGE_A(1, 0, t + 3);
	s_mov_b64 s[70:71], 0x32e60100
	s_add_i32 s69, s3, 0x14000
	v_lshl_add_u64 v[130:131], v[220:221], 0, s[70:71]
	s_mov_b32 m0, s69
	s_mov_b64 s[70:71], 0x32f10100
	global_load_lds_dwordx4 v[130:131], off
	v_lshl_add_u64 v[130:131], v[220:221], 0, s[70:71]
	s_mov_b32 m0, s30
	s_nop 0
	global_load_lds_dwordx4 v[130:131], off
	s_waitcnt vmcnt(6)
	s_barrier
	v_mfma_f32_16x16x32_bf16 v[28:31], v[178:181], v[146:149], v[28:31]
	v_mfma_f32_16x16x32_bf16 v[24:27], v[186:189], v[146:149], v[24:27]
	v_mfma_f32_16x16x32_bf16 v[20:23], v[178:181], v[154:157], v[20:23]
	v_mfma_f32_16x16x32_bf16 v[16:19], v[186:189], v[154:157], v[16:19]
	v_mfma_f32_16x16x32_bf16 v[12:15], v[178:181], v[162:165], v[12:15]
	v_mfma_f32_16x16x32_bf16 v[8:11], v[186:189], v[162:165], v[8:11]
	v_mfma_f32_16x16x32_bf16 v[4:7], v[178:181], v[170:173], v[4:7]
	v_mfma_f32_16x16x32_bf16 v[0:3], v[186:189], v[170:173], v[0:3]
	v_mfma_f32_16x16x32_bf16 v[28:31], v[182:185], v[150:153], v[28:31]
	v_mfma_f32_16x16x32_bf16 v[24:27], v[196:199], v[150:153], v[24:27]
	v_mfma_f32_16x16x32_bf16 v[20:23], v[182:185], v[158:161], v[20:23]
	v_mfma_f32_16x16x32_bf16 v[16:19], v[196:199], v[158:161], v[16:19]
	v_mfma_f32_16x16x32_bf16 v[12:15], v[182:185], v[166:169], v[12:15]
	v_mfma_f32_16x16x32_bf16 v[8:11], v[196:199], v[166:169], v[8:11]
	v_mfma_f32_16x16x32_bf16 v[4:7], v[182:185], v[174:177], v[4:7]
	v_mfma_f32_16x16x32_bf16 v[0:3], v[196:199], v[174:177], v[0:3]
	s_barrier
	ds_read_b128 v[130:133], v205 offset:0
	ds_read_b128 v[134:137], v205 offset:0x400
	ds_read_b128 v[138:141], v205 offset:0x800
	ds_read_b128 v[142:145], v205 offset:0xc00
	ds_read_b128 v[146:149], v206 offset:0
	ds_read_b128 v[150:153], v206 offset:0x400
	ds_read_b128 v[154:157], v206 offset:0x800
	ds_read_b128 v[158:161], v206 offset:0xc00
	ds_read_b128 v[162:165], v206 offset:0x1000
	ds_read_b128 v[166:169], v206 offset:0x1400
	s_mov_b64 s[70:71], 0xf260100
	ds_read_b128 v[170:173], v206 offset:0x1800
	v_lshl_add_u64 v[178:179], v[190:191], 0, s[70:71]
	s_add_i32 s71, s3, 0x4000
	ds_read_b128 v[174:177], v206 offset:0x1c00
	s_mov_b32 m0, s71
	s_mov_b64 s[72:73], 0xf310100
	global_load_lds_dwordx4 v[178:179], off
	v_lshl_add_u64 v[178:179], v[190:191], 0, s[72:73]
	s_mov_b32 m0, s31
	s_nop 0
	global_load_lds_dwordx4 v[178:179], off
	s_waitcnt lgkmcnt(8)
	s_barrier
	s_waitcnt lgkmcnt(0)
	v_mfma_f32_16x16x32_bf16 v[124:127], v[130:133], v[146:149], v[124:127]
	v_mfma_f32_16x16x32_bf16 v[120:123], v[138:141], v[146:149], v[120:123]
	v_mfma_f32_16x16x32_bf16 v[116:119], v[130:133], v[154:157], v[116:119]
	v_mfma_f32_16x16x32_bf16 v[112:115], v[138:141], v[154:157], v[112:115]
	v_mfma_f32_16x16x32_bf16 v[108:111], v[130:133], v[162:165], v[108:111]
	v_mfma_f32_16x16x32_bf16 v[104:107], v[138:141], v[162:165], v[104:107]
	v_mfma_f32_16x16x32_bf16 v[100:103], v[130:133], v[170:173], v[100:103]
	v_mfma_f32_16x16x32_bf16 v[96:99], v[138:141], v[170:173], v[96:99]
	v_mfma_f32_16x16x32_bf16 v[124:127], v[134:137], v[150:153], v[124:127]
	v_mfma_f32_16x16x32_bf16 v[120:123], v[142:145], v[150:153], v[120:123]
	v_mfma_f32_16x16x32_bf16 v[116:119], v[134:137], v[158:161], v[116:119]
	v_mfma_f32_16x16x32_bf16 v[112:115], v[142:145], v[158:161], v[112:115]
	v_mfma_f32_16x16x32_bf16 v[108:111], v[134:137], v[166:169], v[108:111]
	v_mfma_f32_16x16x32_bf16 v[104:107], v[142:145], v[166:169], v[104:107]
	v_mfma_f32_16x16x32_bf16 v[100:103], v[134:137], v[174:177], v[100:103]
	v_mfma_f32_16x16x32_bf16 v[96:99], v[142:145], v[174:177], v[96:99]
	s_barrier
	ds_read_b128 v[178:181], v207 offset:0
	ds_read_b128 v[182:185], v207 offset:0x400
	ds_read_b128 v[186:189], v207 offset:0x800
	s_mov_b64 s[72:73], 0x32d00180
	s_add_i32 s70, s3, 0x18000
	ds_read_b128 v[196:199], v207 offset:0xc00
	v_lshl_add_u64 v[222:223], v[220:221], 0, s[72:73]
	s_mov_b32 m0, s70
	s_mov_b64 s[72:73], 0x32db0180
	global_load_lds_dwordx4 v[222:223], off
	v_lshl_add_u64 v[222:223], v[220:221], 0, s[72:73]
	s_mov_b32 m0, s50
	s_nop 0
	global_load_lds_dwordx4 v[222:223], off
	s_barrier
	s_waitcnt lgkmcnt(0)
	v_mfma_f32_16x16x32_bf16 v[92:95], v[178:181], v[146:149], v[92:95]
	v_mfma_f32_16x16x32_bf16 v[88:91], v[186:189], v[146:149], v[88:91]
	v_mfma_f32_16x16x32_bf16 v[84:87], v[178:181], v[154:157], v[84:87]
	v_mfma_f32_16x16x32_bf16 v[80:83], v[186:189], v[154:157], v[80:83]
	v_mfma_f32_16x16x32_bf16 v[76:79], v[178:181], v[162:165], v[76:79]
	v_mfma_f32_16x16x32_bf16 v[72:75], v[186:189], v[162:165], v[72:75]
	v_mfma_f32_16x16x32_bf16 v[68:71], v[178:181], v[170:173], v[68:71]
	v_mfma_f32_16x16x32_bf16 v[64:67], v[186:189], v[170:173], v[64:67]
	v_mfma_f32_16x16x32_bf16 v[92:95], v[182:185], v[150:153], v[92:95]
	v_mfma_f32_16x16x32_bf16 v[88:91], v[196:199], v[150:153], v[88:91]
	v_mfma_f32_16x16x32_bf16 v[84:87], v[182:185], v[158:161], v[84:87]
	v_mfma_f32_16x16x32_bf16 v[80:83], v[196:199], v[158:161], v[80:83]
	v_mfma_f32_16x16x32_bf16 v[76:79], v[182:185], v[166:169], v[76:79]
	v_mfma_f32_16x16x32_bf16 v[72:75], v[196:199], v[166:169], v[72:75]
	v_mfma_f32_16x16x32_bf16 v[68:71], v[182:185], v[174:177], v[68:71]
	v_mfma_f32_16x16x32_bf16 v[64:67], v[196:199], v[174:177], v[64:67]
	s_barrier
	ds_read_b128 v[146:149], v208 offset:0
	ds_read_b128 v[150:153], v208 offset:0x400
	ds_read_b128 v[154:157], v208 offset:0x800
	ds_read_b128 v[158:161], v208 offset:0xc00
	ds_read_b128 v[162:165], v208 offset:0x1000
	ds_read_b128 v[166:169], v208 offset:0x1400
	s_mov_b64 s[72:73], 0xf100180
	ds_read_b128 v[170:173], v208 offset:0x1800
	v_lshl_add_u64 v[222:223], v[190:191], 0, s[72:73]
	s_add_i32 s72, s3, 0x8000
	ds_read_b128 v[174:177], v208 offset:0x1c00
	s_mov_b32 m0, s72
	s_mov_b64 s[76:77], 0xf1b0180
	global_load_lds_dwordx4 v[222:223], off
	v_lshl_add_u64 v[190:191], v[190:191], 0, s[76:77]
	s_mov_b32 m0, s51
	s_nop 0
	global_load_lds_dwordx4 v[190:191], off
	s_barrier
; #define WAIT_V(n) asm volatile("s_waitcnt vmcnt(%0)" ::"n"(n) : "memory")
; #define SCHED() __builtin_amdgcn_sched_barrier(0)
; #define LGKM(n) asm volatile("s_waitcnt lgkmcnt(%0)" ::"n"(n) : "memory")
; #define STAGE_A(b, h, kt) STAGE_AX(Ag, b, h, kt)
; #define STAGE_B(b, h, kt) STAGE_BX(Bg, b, h, kt)
; #define LDA(b, h) do { const unsigned pa_ = lds0 + SLOTA(b, h) + wr * 8192 + laneoff; _Pragma("unroll") for (int m = 0; m < 4; ++m)   \
;       _Pragma("unroll") for (int k = 0; k < 2; ++k) DSR(At[m][k], pa_, m * 2048 + k * 1024); } while (0)
; #define LDB(dst, b, h) do { const unsigned pb_ = lds0 + SLOTB(b, h) + wc * 4096 + laneoff; _Pragma("unroll") for (int n = 0; n < 2; ++n) \
;       _Pragma("unroll") for (int k = 0; k < 2; ++k) DSR(dst[n][k], pb_, n * 2048 + k * 1024); } while (0)
; #define BAR __builtin_amdgcn_s_barrier()
; #define LGKM(n) asm volatile("s_waitcnt lgkmcnt(%0)" ::"n"(n) : "memory")
; template <int EPI, bool SWP> ...
;     ...
;     BAR; LGKM(0); SCHED(); MMA(1, 0, B0); BAR; SCHED();
;     STAGE_B(1, 1, t + 3);
;     WAIT_V(6); BAR; SCHED(); MMA(1, 1, B1); BAR; SCHED();
;   }
;   { LDB(B0, 0, 0); LDA(0, 0); STAGE_A(1, 1, nt - 1);
;     BAR; LGKM(0); SCHED(); MMA(0, 0, B0); BAR; SCHED();
;     LDB(B1, 0, 1); BAR; LGKM(0); SCHED(); MMA(0, 1, B1); BAR; SCHED();
	s_waitcnt lgkmcnt(0)
	v_mfma_f32_16x16x32_bf16 v[60:63], v[130:133], v[146:149], v[60:63]
	v_mfma_f32_16x16x32_bf16 v[56:59], v[138:141], v[146:149], v[56:59]
	v_mfma_f32_16x16x32_bf16 v[52:55], v[130:133], v[154:157], v[52:55]
	v_mfma_f32_16x16x32_bf16 v[48:51], v[138:141], v[154:157], v[48:51]
	v_mfma_f32_16x16x32_bf16 v[44:47], v[130:133], v[162:165], v[44:47]
	v_mfma_f32_16x16x32_bf16 v[40:43], v[138:141], v[162:165], v[40:43]
	v_mfma_f32_16x16x32_bf16 v[36:39], v[130:133], v[170:173], v[36:39]
	v_mfma_f32_16x16x32_bf16 v[32:35], v[138:141], v[170:173], v[32:35]
	v_mfma_f32_16x16x32_bf16 v[60:63], v[134:137], v[150:153], v[60:63]
	v_mfma_f32_16x16x32_bf16 v[56:59], v[142:145], v[150:153], v[56:59]
	v_mfma_f32_16x16x32_bf16 v[52:55], v[134:137], v[158:161], v[52:55]
	v_mfma_f32_16x16x32_bf16 v[48:51], v[142:145], v[158:161], v[48:51]
	v_mfma_f32_16x16x32_bf16 v[44:47], v[134:137], v[166:169], v[44:47]
	v_mfma_f32_16x16x32_bf16 v[40:43], v[142:145], v[166:169], v[40:43]
	v_mfma_f32_16x16x32_bf16 v[36:39], v[134:137], v[174:177], v[36:39]
	v_mfma_f32_16x16x32_bf16 v[32:35], v[142:145], v[174:177], v[32:35]
	s_barrier
	s_mov_b64 s[76:77], 0x32e60180
	s_add_i32 s73, s3, 0x1c000
	v_lshl_add_u64 v[130:131], v[220:221], 0, s[76:77]
	s_mov_b32 m0, s73
	s_mov_b64 s[76:77], 0x32f10180
	global_load_lds_dwordx4 v[130:131], off
	v_lshl_add_u64 v[130:131], v[220:221], 0, s[76:77]
	s_mov_b32 m0, s60
	s_nop 0
	global_load_lds_dwordx4 v[130:131], off
	s_waitcnt vmcnt(6)
	s_barrier
	v_mfma_f32_16x16x32_bf16 v[28:31], v[178:181], v[146:149], v[28:31]
	v_mfma_f32_16x16x32_bf16 v[24:27], v[186:189], v[146:149], v[24:27]
	v_mfma_f32_16x16x32_bf16 v[20:23], v[178:181], v[154:157], v[20:23]
	v_mfma_f32_16x16x32_bf16 v[16:19], v[186:189], v[154:157], v[16:19]
	v_mfma_f32_16x16x32_bf16 v[12:15], v[178:181], v[162:165], v[12:15]
	v_mfma_f32_16x16x32_bf16 v[8:11], v[186:189], v[162:165], v[8:11]
	v_mfma_f32_16x16x32_bf16 v[4:7], v[178:181], v[170:173], v[4:7]
	v_mfma_f32_16x16x32_bf16 v[0:3], v[186:189], v[170:173], v[0:3]
	v_mfma_f32_16x16x32_bf16 v[28:31], v[182:185], v[150:153], v[28:31]
	v_mfma_f32_16x16x32_bf16 v[24:27], v[196:199], v[150:153], v[24:27]
	v_mfma_f32_16x16x32_bf16 v[20:23], v[182:185], v[158:161], v[20:23]
	v_mfma_f32_16x16x32_bf16 v[16:19], v[196:199], v[158:161], v[16:19]
	v_mfma_f32_16x16x32_bf16 v[12:15], v[182:185], v[166:169], v[12:15]
	v_mfma_f32_16x16x32_bf16 v[8:11], v[196:199], v[166:169], v[8:11]
	v_mfma_f32_16x16x32_bf16 v[4:7], v[182:185], v[174:177], v[4:7]
	v_mfma_f32_16x16x32_bf16 v[0:3], v[196:199], v[174:177], v[0:3]
	s_add_i32 s68, s68, 2
	s_add_u32 s10, s10, 0x100
	s_addc_u32 s11, s11, 0
	s_add_u32 s58, s58, 0x100
	s_addc_u32 s59, s59, 0
	s_cmpk_gt_u32 s68, 0x53
	s_barrier
	s_cbranch_scc0 .LBB0_123
	ds_read_b128 v[130:133], v201 offset:0
	ds_read_b128 v[134:137], v201 offset:0x400
	ds_read_b128 v[138:141], v201 offset:0x800
	ds_read_b128 v[142:145], v201 offset:0xc00
	ds_read_b128 v[146:149], v202 offset:0
	ds_read_b128 v[150:153], v202 offset:0x400
	ds_read_b128 v[154:157], v202 offset:0x800
	ds_read_b128 v[158:161], v202 offset:0xc00
	ds_read_b128 v[162:165], v202 offset:0x1000
	ds_read_b128 v[166:169], v202 offset:0x1400
	ds_read_b128 v[170:173], v202 offset:0x1800
	s_mov_b64 s[10:11], 0x162b80
	s_mov_b32 m0, s74
	ds_read_b128 v[174:177], v202 offset:0x1c00
	v_lshl_add_u64 v[178:179], v[128:129], 0, s[10:11]
	s_mov_b64 s[10:11], 0x212b80
	global_load_lds_dwordx4 v[178:179], off
	v_lshl_add_u64 v[128:129], v[128:129], 0, s[10:11]
	s_mov_b32 m0, s61
	s_mul_i32 s10, s63, 0x2c0000
	global_load_lds_dwordx4 v[128:129], off
	s_mul_hi_i32 s11, s63, 0x2c0000
	s_add_u32 s10, s46, s10
	s_barrier
	s_waitcnt lgkmcnt(0)
	s_addc_u32 s11, s47, s11
	s_mul_i32 s58, s64, 0x2c0000
	s_mul_hi_i32 s59, s64, 0x2c0000
	s_add_u32 s58, s12, s58
	s_addc_u32 s59, s13, s59
	v_mfma_f32_16x16x32_bf16 v[124:127], v[130:133], v[146:149], v[124:127]
	v_mfma_f32_16x16x32_bf16 v[120:123], v[138:141], v[146:149], v[120:123]
	v_mfma_f32_16x16x32_bf16 v[116:119], v[130:133], v[154:157], v[116:119]
	v_mfma_f32_16x16x32_bf16 v[112:115], v[138:141], v[154:157], v[112:115]
	v_mfma_f32_16x16x32_bf16 v[108:111], v[130:133], v[162:165], v[108:111]
	v_mfma_f32_16x16x32_bf16 v[104:107], v[138:141], v[162:165], v[104:107]
	v_mfma_f32_16x16x32_bf16 v[100:103], v[130:133], v[170:173], v[100:103]
	v_mfma_f32_16x16x32_bf16 v[96:99], v[138:141], v[170:173], v[96:99]
	v_mfma_f32_16x16x32_bf16 v[124:127], v[134:137], v[150:153], v[124:127]
	v_mfma_f32_16x16x32_bf16 v[120:123], v[142:145], v[150:153], v[120:123]
	v_mfma_f32_16x16x32_bf16 v[116:119], v[134:137], v[158:161], v[116:119]
	v_mfma_f32_16x16x32_bf16 v[112:115], v[142:145], v[158:161], v[112:115]
	v_mfma_f32_16x16x32_bf16 v[108:111], v[134:137], v[166:169], v[108:111]
	v_mfma_f32_16x16x32_bf16 v[104:107], v[142:145], v[166:169], v[104:107]
	v_mfma_f32_16x16x32_bf16 v[100:103], v[134:137], v[174:177], v[100:103]
	v_mfma_f32_16x16x32_bf16 v[96:99], v[142:145], v[174:177], v[96:99]
	s_barrier
	ds_read_b128 v[178:181], v203 offset:0
	ds_read_b128 v[182:185], v203 offset:0x400
	ds_read_b128 v[186:189], v203 offset:0x800
	ds_read_b128 v[196:199], v203 offset:0xc00
	s_barrier
; #define WAIT_V(n) asm volatile("s_waitcnt vmcnt(%0)" ::"n"(n) : "memory")
; #define SCHED() __builtin_amdgcn_sched_barrier(0)
; #define LGKM(n) asm volatile("s_waitcnt lgkmcnt(%0)" ::"n"(n) : "memory")
; #define LDA(b, h) do { const unsigned pa_ = lds0 + SLOTA(b, h) + wr * 8192 + laneoff; _Pragma("unroll") for (int m = 0; m < 4; ++m)   \
;       _Pragma("unroll") for (int k = 0; k < 2; ++k) DSR(At[m][k], pa_, m * 2048 + k * 1024); } while (0)
; #define LDB(dst, b, h) do { const unsigned pb_ = lds0 + SLOTB(b, h) + wc * 4096 + laneoff; _Pragma("unroll") for (int n = 0; n < 2; ++n) \
;       _Pragma("unroll") for (int k = 0; k < 2; ++k) DSR(dst[n][k], pb_, n * 2048 + k * 1024); } while (0)
; #define BAR __builtin_amdgcn_s_barrier()
; #define LGKM(n) asm volatile("s_waitcnt lgkmcnt(%0)" ::"n"(n) : "memory")
; template <int EPI, bool SWP> ...
;     ...
;     LDB(B1, 0, 1); BAR; LGKM(0); SCHED(); MMA(0, 1, B1); BAR; SCHED();
;     LDA(0, 1); WAIT_V(4); BAR; LGKM(0); SCHED(); MMA(1, 0, B0); MMA(1, 1, B1); BAR; SCHED(); }
;   { LDB(B0, 1, 0); LDA(1, 0); WAIT_V(2); BAR; LGKM(0); SCHED(); MMA(0, 0, B0); BAR; SCHED();
	s_waitcnt lgkmcnt(0)
	v_mfma_f32_16x16x32_bf16 v[92:95], v[178:181], v[146:149], v[92:95]
	v_mfma_f32_16x16x32_bf16 v[88:91], v[186:189], v[146:149], v[88:91]
	v_mfma_f32_16x16x32_bf16 v[84:87], v[178:181], v[154:157], v[84:87]
	v_mfma_f32_16x16x32_bf16 v[80:83], v[186:189], v[154:157], v[80:83]
	v_mfma_f32_16x16x32_bf16 v[76:79], v[178:181], v[162:165], v[76:79]
	v_mfma_f32_16x16x32_bf16 v[72:75], v[186:189], v[162:165], v[72:75]
	v_mfma_f32_16x16x32_bf16 v[68:71], v[178:181], v[170:173], v[68:71]
	v_mfma_f32_16x16x32_bf16 v[64:67], v[186:189], v[170:173], v[64:67]
	v_mfma_f32_16x16x32_bf16 v[92:95], v[182:185], v[150:153], v[92:95]
	v_mfma_f32_16x16x32_bf16 v[88:91], v[196:199], v[150:153], v[88:91]
	v_mfma_f32_16x16x32_bf16 v[84:87], v[182:185], v[158:161], v[84:87]
	v_mfma_f32_16x16x32_bf16 v[80:83], v[196:199], v[158:161], v[80:83]
	v_mfma_f32_16x16x32_bf16 v[76:79], v[182:185], v[166:169], v[76:79]
	v_mfma_f32_16x16x32_bf16 v[72:75], v[196:199], v[166:169], v[72:75]
	v_mfma_f32_16x16x32_bf16 v[68:71], v[182:185], v[174:177], v[68:71]
	v_mfma_f32_16x16x32_bf16 v[64:67], v[196:199], v[174:177], v[64:67]
	s_barrier
	ds_read_b128 v[146:149], v204 offset:0
	ds_read_b128 v[150:153], v204 offset:0x400
	ds_read_b128 v[154:157], v204 offset:0x800
	ds_read_b128 v[158:161], v204 offset:0xc00
	ds_read_b128 v[162:165], v204 offset:0x1000
	ds_read_b128 v[166:169], v204 offset:0x1400
	ds_read_b128 v[170:173], v204 offset:0x1800
	ds_read_b128 v[174:177], v204 offset:0x1c00
	s_waitcnt vmcnt(4)
	s_barrier
	s_waitcnt lgkmcnt(0)
	v_mfma_f32_16x16x32_bf16 v[60:63], v[130:133], v[146:149], v[60:63]
	v_mfma_f32_16x16x32_bf16 v[56:59], v[138:141], v[146:149], v[56:59]
	v_mfma_f32_16x16x32_bf16 v[52:55], v[130:133], v[154:157], v[52:55]
	v_mfma_f32_16x16x32_bf16 v[48:51], v[138:141], v[154:157], v[48:51]
	v_mfma_f32_16x16x32_bf16 v[44:47], v[130:133], v[162:165], v[44:47]
	v_mfma_f32_16x16x32_bf16 v[40:43], v[138:141], v[162:165], v[40:43]
	v_mfma_f32_16x16x32_bf16 v[36:39], v[130:133], v[170:173], v[36:39]
	v_mfma_f32_16x16x32_bf16 v[32:35], v[138:141], v[170:173], v[32:35]
	v_mfma_f32_16x16x32_bf16 v[60:63], v[134:137], v[150:153], v[60:63]
	v_mfma_f32_16x16x32_bf16 v[56:59], v[142:145], v[150:153], v[56:59]
	v_mfma_f32_16x16x32_bf16 v[52:55], v[134:137], v[158:161], v[52:55]
	v_mfma_f32_16x16x32_bf16 v[48:51], v[142:145], v[158:161], v[48:51]
	v_mfma_f32_16x16x32_bf16 v[44:47], v[134:137], v[166:169], v[44:47]
	v_mfma_f32_16x16x32_bf16 v[40:43], v[142:145], v[166:169], v[40:43]
	v_mfma_f32_16x16x32_bf16 v[36:39], v[134:137], v[174:177], v[36:39]
	v_mfma_f32_16x16x32_bf16 v[32:35], v[142:145], v[174:177], v[32:35]
	v_mfma_f32_16x16x32_bf16 v[28:31], v[178:181], v[146:149], v[28:31]
	v_mfma_f32_16x16x32_bf16 v[24:27], v[186:189], v[146:149], v[24:27]
	v_mfma_f32_16x16x32_bf16 v[20:23], v[178:181], v[154:157], v[20:23]
	v_mfma_f32_16x16x32_bf16 v[16:19], v[186:189], v[154:157], v[16:19]
	v_mfma_f32_16x16x32_bf16 v[12:15], v[178:181], v[162:165], v[12:15]
	v_mfma_f32_16x16x32_bf16 v[8:11], v[186:189], v[162:165], v[8:11]
	v_mfma_f32_16x16x32_bf16 v[4:7], v[178:181], v[170:173], v[4:7]
	v_mfma_f32_16x16x32_bf16 v[0:3], v[186:189], v[170:173], v[0:3]
	v_mfma_f32_16x16x32_bf16 v[28:31], v[182:185], v[150:153], v[28:31]
	v_mfma_f32_16x16x32_bf16 v[24:27], v[196:199], v[150:153], v[24:27]
	v_mfma_f32_16x16x32_bf16 v[20:23], v[182:185], v[158:161], v[20:23]
	v_mfma_f32_16x16x32_bf16 v[16:19], v[196:199], v[158:161], v[16:19]
	v_mfma_f32_16x16x32_bf16 v[12:15], v[182:185], v[166:169], v[12:15]
	v_mfma_f32_16x16x32_bf16 v[8:11], v[196:199], v[166:169], v[8:11]
	v_mfma_f32_16x16x32_bf16 v[4:7], v[182:185], v[174:177], v[4:7]
	v_mfma_f32_16x16x32_bf16 v[0:3], v[196:199], v[174:177], v[0:3]
	s_barrier
	ds_read_b128 v[128:131], v205 offset:0
	ds_read_b128 v[132:135], v205 offset:0x400
	ds_read_b128 v[136:139], v205 offset:0x800
	ds_read_b128 v[140:143], v205 offset:0xc00
	ds_read_b128 v[160:163], v206 offset:0
	ds_read_b128 v[164:167], v206 offset:0x400
	ds_read_b128 v[168:171], v206 offset:0x800
	ds_read_b128 v[172:175], v206 offset:0xc00
	ds_read_b128 v[176:179], v206 offset:0x1000
	ds_read_b128 v[180:183], v206 offset:0x1400
	ds_read_b128 v[184:187], v206 offset:0x1800
	ds_read_b128 v[188:191], v206 offset:0x1c00
	s_waitcnt vmcnt(2)
	s_barrier
; #define WAIT_V(n) asm volatile("s_waitcnt vmcnt(%0)" ::"n"(n) : "memory")
; #define SCHED() __builtin_amdgcn_sched_barrier(0)
; #define LGKM(n) asm volatile("s_waitcnt lgkmcnt(%0)" ::"n"(n) : "memory")
; #define STAGE_AX(AG, b, h, kt) do { _Pragma("unroll") for (int i = 0; i < 2; ++i)                                    \
;       __builtin_amdgcn_global_load_lds((const unsigned*)(((AG) + ((size_t)(kt) * (BK * 2) + (size_t)((h) * 2 + i) * 128 * lda)) + aoff), \
;                                        (unsigned*)(shm + SLOTA(b, h) + wid * 1024 + i * 8192), 16, 0, 0); } while (0)
; #define STAGE_BX(BG, b, h, kt) do { _Pragma("unroll") for (int i = 0; i < 2; ++i)                                    \
;       __builtin_amdgcn_global_load_lds((const unsigned*)(((BG) + ((size_t)(kt) * (BK * 2) + (size_t)((h) * 2 + i) * 128 * K)) + boff),   \
;                                        (unsigned*)(shm + SLOTB(b, h) + wid * 1024 + i * 8192), 16, 0, 0); } while (0)
; #define LDA(b, h) do { const unsigned pa_ = lds0 + SLOTA(b, h) + wr * 8192 + laneoff; _Pragma("unroll") for (int m = 0; m < 4; ++m)   \
;       _Pragma("unroll") for (int k = 0; k < 2; ++k) DSR(At[m][k], pa_, m * 2048 + k * 1024); } while (0)
; #define LDB(dst, b, h) do { const unsigned pb_ = lds0 + SLOTB(b, h) + wc * 4096 + laneoff; _Pragma("unroll") for (int n = 0; n < 2; ++n) \
;       _Pragma("unroll") for (int k = 0; k < 2; ++k) DSR(dst[n][k], pb_, n * 2048 + k * 1024); } while (0)
; #define BAR __builtin_amdgcn_s_barrier()
; #define LGKM(n) asm volatile("s_waitcnt lgkmcnt(%0)" ::"n"(n) : "memory")
; template <int EPI, bool SWP> ...
;     ...
;   { LDB(B0, 1, 0); LDA(1, 0); WAIT_V(2); BAR; LGKM(0); SCHED(); MMA(0, 0, B0); BAR; SCHED();
;     LDB(B1, 1, 1); WAIT_V(0); BAR; LGKM(0); SCHED(); MMA(0, 1, B1); BAR; SCHED();
;     LDA(1, 1);
;     if (has_next) { STAGE_BX(Bg_n, 0, 0, 0); STAGE_AX(Ag_n, 0, 0, 0); STAGE_BX(Bg_n, 0, 1, 0); STAGE_AX(Ag_n, 0, 1, 0); }
	s_waitcnt lgkmcnt(0)
	v_mfma_f32_16x16x32_bf16 v[124:127], v[128:131], v[160:163], v[124:127]
	v_mfma_f32_16x16x32_bf16 v[120:123], v[136:139], v[160:163], v[120:123]
	v_mfma_f32_16x16x32_bf16 v[116:119], v[128:131], v[168:171], v[116:119]
	v_mfma_f32_16x16x32_bf16 v[112:115], v[136:139], v[168:171], v[112:115]
	v_mfma_f32_16x16x32_bf16 v[108:111], v[128:131], v[176:179], v[108:111]
	v_mfma_f32_16x16x32_bf16 v[104:107], v[136:139], v[176:179], v[104:107]
	v_mfma_f32_16x16x32_bf16 v[100:103], v[128:131], v[184:187], v[100:103]
	v_mfma_f32_16x16x32_bf16 v[96:99], v[136:139], v[184:187], v[96:99]
	v_mfma_f32_16x16x32_bf16 v[124:127], v[132:135], v[164:167], v[124:127]
	v_mfma_f32_16x16x32_bf16 v[120:123], v[140:143], v[164:167], v[120:123]
	v_mfma_f32_16x16x32_bf16 v[116:119], v[132:135], v[172:175], v[116:119]
	v_mfma_f32_16x16x32_bf16 v[112:115], v[140:143], v[172:175], v[112:115]
	v_mfma_f32_16x16x32_bf16 v[108:111], v[132:135], v[180:183], v[108:111]
	v_mfma_f32_16x16x32_bf16 v[104:107], v[140:143], v[180:183], v[104:107]
	v_mfma_f32_16x16x32_bf16 v[100:103], v[132:135], v[188:191], v[100:103]
	v_mfma_f32_16x16x32_bf16 v[96:99], v[140:143], v[188:191], v[96:99]
	s_barrier
	ds_read_b128 v[144:147], v207 offset:0
	ds_read_b128 v[148:151], v207 offset:0x400
	ds_read_b128 v[152:155], v207 offset:0x800
	ds_read_b128 v[156:159], v207 offset:0xc00
	s_waitcnt vmcnt(0)
	s_barrier
	s_waitcnt lgkmcnt(0)
	v_mfma_f32_16x16x32_bf16 v[92:95], v[144:147], v[160:163], v[92:95]
	v_mfma_f32_16x16x32_bf16 v[88:91], v[152:155], v[160:163], v[88:91]
	v_mfma_f32_16x16x32_bf16 v[84:87], v[144:147], v[168:171], v[84:87]
	v_mfma_f32_16x16x32_bf16 v[80:83], v[152:155], v[168:171], v[80:83]
	v_mfma_f32_16x16x32_bf16 v[76:79], v[144:147], v[176:179], v[76:79]
	v_mfma_f32_16x16x32_bf16 v[72:75], v[152:155], v[176:179], v[72:75]
	v_mfma_f32_16x16x32_bf16 v[68:71], v[144:147], v[184:187], v[68:71]
	v_mfma_f32_16x16x32_bf16 v[64:67], v[152:155], v[184:187], v[64:67]
	v_mfma_f32_16x16x32_bf16 v[92:95], v[148:151], v[164:167], v[92:95]
	v_mfma_f32_16x16x32_bf16 v[88:91], v[156:159], v[164:167], v[88:91]
	v_mfma_f32_16x16x32_bf16 v[84:87], v[148:151], v[172:175], v[84:87]
	v_mfma_f32_16x16x32_bf16 v[80:83], v[156:159], v[172:175], v[80:83]
	v_mfma_f32_16x16x32_bf16 v[76:79], v[148:151], v[180:183], v[76:79]
	v_mfma_f32_16x16x32_bf16 v[72:75], v[156:159], v[180:183], v[72:75]
	v_mfma_f32_16x16x32_bf16 v[68:71], v[148:151], v[188:191], v[68:71]
	v_mfma_f32_16x16x32_bf16 v[64:67], v[156:159], v[188:191], v[64:67]
	s_barrier
	ds_read_b128 v[184:187], v208 offset:0
	ds_read_b128 v[188:191], v208 offset:0x400
	ds_read_b128 v[176:179], v208 offset:0x800
	ds_read_b128 v[180:183], v208 offset:0xc00
	ds_read_b128 v[168:171], v208 offset:0x1000
	ds_read_b128 v[172:175], v208 offset:0x1400
	ds_read_b128 v[160:163], v208 offset:0x1800
	ds_read_b128 v[164:167], v208 offset:0x1c00
	s_and_b64 vcc, exec, s[48:49]
	v_lshl_add_u64 v[196:197], s[58:59], 0, v[192:193]
	v_lshl_add_u64 v[198:199], s[10:11], 0, v[192:193]
	s_cbranch_vccz .LBB0_126
	s_mov_b32 m0, s17
	v_lshl_add_u64 v[220:221], v[196:197], 0, s[14:15]
	global_load_lds_dwordx4 v[196:197], off
	s_mov_b32 m0, s18
	s_nop 0
	global_load_lds_dwordx4 v[220:221], off
	s_mov_b32 m0, s3
	v_lshl_add_u64 v[220:221], v[198:199], 0, s[14:15]
	global_load_lds_dwordx4 v[198:199], off
	s_mov_b32 m0, s19
	s_nop 0
	global_load_lds_dwordx4 v[220:221], off
	v_lshl_add_u64 v[220:221], v[196:197], 0, s[20:21]
	s_mov_b32 m0, s69
	s_nop 0
	global_load_lds_dwordx4 v[220:221], off
	v_lshl_add_u64 v[220:221], v[196:197], 0, s[22:23]
	s_mov_b32 m0, s30
	s_nop 0
	global_load_lds_dwordx4 v[220:221], off
	v_lshl_add_u64 v[220:221], v[198:199], 0, s[20:21]
	s_mov_b32 m0, s71
	s_nop 0
	global_load_lds_dwordx4 v[220:221], off
	v_lshl_add_u64 v[220:221], v[198:199], 0, s[22:23]
	s_mov_b32 m0, s31
	s_nop 0
	global_load_lds_dwordx4 v[220:221], off

; #define WAIT_V(n) asm volatile("s_waitcnt vmcnt(%0)" ::"n"(n) : "memory")
; #define SCHED() __builtin_amdgcn_sched_barrier(0)
; #define LGKM(n) asm volatile("s_waitcnt lgkmcnt(%0)" ::"n"(n) : "memory")
; #define STAGE_A(b, h, kt) STAGE_AX(Ag, b, h, kt)
; #define STAGE_B(b, h, kt) STAGE_BX(Bg, b, h, kt)
; #define LDA(b, h) do { const unsigned pa_ = lds0 + SLOTA(b, h) + wr * 8192 + laneoff; _Pragma("unroll") for (int m = 0; m < 4; ++m)   \
;       _Pragma("unroll") for (int k = 0; k < 2; ++k) DSR(At[m][k], pa_, m * 2048 + k * 1024); } while (0)
; #define LDB(dst, b, h) do { const unsigned pb_ = lds0 + SLOTB(b, h) + wc * 4096 + laneoff; _Pragma("unroll") for (int n = 0; n < 2; ++n) \
;       _Pragma("unroll") for (int k = 0; k < 2; ++k) DSR(dst[n][k], pb_, n * 2048 + k * 1024); } while (0)
; #define BAR __builtin_amdgcn_s_barrier()
; #define LGKM(n) asm volatile("s_waitcnt lgkmcnt(%0)" ::"n"(n) : "memory")
; template <int EPI, bool SWP> ...
;     ...
;     LDB(B0, 0, 0); LDA(0, 0); STAGE_A(1, 1, t + 1);
;     LGKM(8); BAR; LGKM(0); SCHED(); MMA(0, 0, B0); BAR; SCHED();
;     LDB(B1, 0, 1); STAGE_B(0, 0, t + 2);
;     BAR; LGKM(0); SCHED(); MMA(0, 1, B1); BAR; SCHED();
;     LDA(0, 1); STAGE_A(0, 0, t + 2);
;     BAR; LGKM(0); SCHED(); MMA(1, 0, B0); BAR; SCHED();
;     STAGE_B(0, 1, t + 2);
;     WAIT_V(6); BAR; SCHED(); MMA(1, 1, B1); BAR; SCHED();
.LBB0_197:
	ds_read_b128 v[128:131], v203 offset:0
	ds_read_b128 v[132:135], v203 offset:0x400
	ds_read_b128 v[136:139], v203 offset:0x800
	ds_read_b128 v[140:143], v203 offset:0xc00
	ds_read_b128 v[144:147], v204 offset:0
	ds_read_b128 v[148:151], v204 offset:0x400
	ds_read_b128 v[152:155], v204 offset:0x800
	ds_read_b128 v[156:159], v204 offset:0xc00
	ds_read_b128 v[160:163], v204 offset:0x1000
	ds_read_b128 v[164:167], v204 offset:0x1400
	ds_read_b128 v[168:171], v204 offset:0x1800
	v_lshl_add_u64 v[200:201], s[12:13], 0, v[196:197]
	s_add_i32 vcc_lo, s69, 0xc000
	ds_read_b128 v[172:175], v204 offset:0x1c00
	v_lshl_add_u64 v[176:177], v[200:201], 0, s[80:81]
	s_mov_b32 m0, vcc_lo
	s_nop 0
	global_load_lds_dwordx4 v[176:177], off
	v_lshl_add_u64 v[176:177], v[200:201], 0, s[82:83]
	s_mov_b32 m0, s17
	s_nop 0
	global_load_lds_dwordx4 v[176:177], off
	s_waitcnt lgkmcnt(8)
	s_barrier
	s_waitcnt lgkmcnt(0)
	v_mfma_f32_16x16x32_bf16 v[124:127], v[128:131], v[144:147], v[124:127]
	v_mfma_f32_16x16x32_bf16 v[120:123], v[136:139], v[144:147], v[120:123]
	v_mfma_f32_16x16x32_bf16 v[116:119], v[128:131], v[152:155], v[116:119]
	v_mfma_f32_16x16x32_bf16 v[112:115], v[136:139], v[152:155], v[112:115]
	v_mfma_f32_16x16x32_bf16 v[108:111], v[128:131], v[160:163], v[108:111]
	v_mfma_f32_16x16x32_bf16 v[104:107], v[136:139], v[160:163], v[104:107]
	v_mfma_f32_16x16x32_bf16 v[100:103], v[128:131], v[168:171], v[100:103]
	v_mfma_f32_16x16x32_bf16 v[96:99], v[136:139], v[168:171], v[96:99]
	v_mfma_f32_16x16x32_bf16 v[124:127], v[132:135], v[148:151], v[124:127]
	v_mfma_f32_16x16x32_bf16 v[120:123], v[140:143], v[148:151], v[120:123]
	v_mfma_f32_16x16x32_bf16 v[116:119], v[132:135], v[156:159], v[116:119]
	v_mfma_f32_16x16x32_bf16 v[112:115], v[140:143], v[156:159], v[112:115]
	v_mfma_f32_16x16x32_bf16 v[108:111], v[132:135], v[164:167], v[108:111]
	v_mfma_f32_16x16x32_bf16 v[104:107], v[140:143], v[164:167], v[104:107]
	v_mfma_f32_16x16x32_bf16 v[100:103], v[132:135], v[172:175], v[100:103]
	v_mfma_f32_16x16x32_bf16 v[96:99], v[140:143], v[172:175], v[96:99]
	s_barrier
	ds_read_b128 v[176:179], v205 offset:0
	ds_read_b128 v[180:183], v205 offset:0x400
	ds_read_b128 v[184:187], v205 offset:0x800
	v_lshl_add_u64 v[224:225], s[6:7], 0, v[196:197]
	s_mov_b32 m0, s68
	ds_read_b128 v[188:191], v205 offset:0xc00
	v_lshl_add_u64 v[226:227], v[224:225], 0, s[84:85]
	global_load_lds_dwordx4 v[226:227], off
	v_lshl_add_u64 v[226:227], v[224:225], 0, s[86:87]
	s_mov_b32 m0, s64
	s_nop 0
	global_load_lds_dwordx4 v[226:227], off
	s_barrier
	s_waitcnt lgkmcnt(0)
	v_mfma_f32_16x16x32_bf16 v[92:95], v[176:179], v[144:147], v[92:95]
	v_mfma_f32_16x16x32_bf16 v[88:91], v[184:187], v[144:147], v[88:91]
	v_mfma_f32_16x16x32_bf16 v[84:87], v[176:179], v[152:155], v[84:87]
	v_mfma_f32_16x16x32_bf16 v[80:83], v[184:187], v[152:155], v[80:83]
	v_mfma_f32_16x16x32_bf16 v[76:79], v[176:179], v[160:163], v[76:79]
	v_mfma_f32_16x16x32_bf16 v[72:75], v[184:187], v[160:163], v[72:75]
	v_mfma_f32_16x16x32_bf16 v[68:71], v[176:179], v[168:171], v[68:71]
	v_mfma_f32_16x16x32_bf16 v[64:67], v[184:187], v[168:171], v[64:67]
	v_mfma_f32_16x16x32_bf16 v[92:95], v[180:183], v[148:151], v[92:95]
	v_mfma_f32_16x16x32_bf16 v[88:91], v[188:191], v[148:151], v[88:91]
	v_mfma_f32_16x16x32_bf16 v[84:87], v[180:183], v[156:159], v[84:87]
	v_mfma_f32_16x16x32_bf16 v[80:83], v[188:191], v[156:159], v[80:83]
	v_mfma_f32_16x16x32_bf16 v[76:79], v[180:183], v[164:167], v[76:79]
	v_mfma_f32_16x16x32_bf16 v[72:75], v[188:191], v[164:167], v[72:75]
	v_mfma_f32_16x16x32_bf16 v[68:71], v[180:183], v[172:175], v[68:71]
	v_mfma_f32_16x16x32_bf16 v[64:67], v[188:191], v[172:175], v[64:67]
	s_barrier
	ds_read_b128 v[144:147], v206 offset:0
	ds_read_b128 v[148:151], v206 offset:0x400
	ds_read_b128 v[152:155], v206 offset:0x800
	ds_read_b128 v[156:159], v206 offset:0xc00
	ds_read_b128 v[160:163], v206 offset:0x1000
	ds_read_b128 v[164:167], v206 offset:0x1400
	ds_read_b128 v[168:171], v206 offset:0x1800
	s_mov_b32 m0, s69
	ds_read_b128 v[172:175], v206 offset:0x1c00
	v_lshl_add_u64 v[226:227], v[200:201], 0, s[88:89]
	global_load_lds_dwordx4 v[226:227], off
	v_lshl_add_u64 v[226:227], v[200:201], 0, s[90:91]
	s_mov_b32 m0, s65
	s_nop 0
	global_load_lds_dwordx4 v[226:227], off
	s_barrier
	s_waitcnt lgkmcnt(0)
	v_mfma_f32_16x16x32_bf16 v[60:63], v[128:131], v[144:147], v[60:63]
	v_mfma_f32_16x16x32_bf16 v[56:59], v[136:139], v[144:147], v[56:59]
	v_mfma_f32_16x16x32_bf16 v[52:55], v[128:131], v[152:155], v[52:55]
	v_mfma_f32_16x16x32_bf16 v[48:51], v[136:139], v[152:155], v[48:51]
	v_mfma_f32_16x16x32_bf16 v[44:47], v[128:131], v[160:163], v[44:47]
	v_mfma_f32_16x16x32_bf16 v[40:43], v[136:139], v[160:163], v[40:43]
	v_mfma_f32_16x16x32_bf16 v[36:39], v[128:131], v[168:171], v[36:39]
	v_mfma_f32_16x16x32_bf16 v[32:35], v[136:139], v[168:171], v[32:35]
	v_mfma_f32_16x16x32_bf16 v[60:63], v[132:135], v[148:151], v[60:63]
	v_mfma_f32_16x16x32_bf16 v[56:59], v[140:143], v[148:151], v[56:59]
	v_mfma_f32_16x16x32_bf16 v[52:55], v[132:135], v[156:159], v[52:55]
	v_mfma_f32_16x16x32_bf16 v[48:51], v[140:143], v[156:159], v[48:51]
	v_mfma_f32_16x16x32_bf16 v[44:47], v[132:135], v[164:167], v[44:47]
	v_mfma_f32_16x16x32_bf16 v[40:43], v[140:143], v[164:167], v[40:43]
	v_mfma_f32_16x16x32_bf16 v[36:39], v[132:135], v[172:175], v[36:39]
	v_mfma_f32_16x16x32_bf16 v[32:35], v[140:143], v[172:175], v[32:35]
	s_barrier
	s_add_i32 s23, s69, 0x14000
	v_lshl_add_u64 v[128:129], v[224:225], 0, s[92:93]
	s_mov_b32 m0, s23
	s_nop 0
	global_load_lds_dwordx4 v[128:129], off
	v_lshl_add_u64 v[128:129], v[224:225], 0, s[94:95]
	s_mov_b32 m0, s50
	s_nop 0
	global_load_lds_dwordx4 v[128:129], off
	s_waitcnt vmcnt(6)
	s_barrier
; #define WAIT_V(n) asm volatile("s_waitcnt vmcnt(%0)" ::"n"(n) : "memory")
; #define SCHED() __builtin_amdgcn_sched_barrier(0)
; #define LGKM(n) asm volatile("s_waitcnt lgkmcnt(%0)" ::"n"(n) : "memory")
; #define STAGE_A(b, h, kt) STAGE_AX(Ag, b, h, kt)
; #define STAGE_B(b, h, kt) STAGE_BX(Bg, b, h, kt)
; #define LDA(b, h) do { const unsigned pa_ = lds0 + SLOTA(b, h) + wr * 8192 + laneoff; _Pragma("unroll") for (int m = 0; m < 4; ++m)   \
;       _Pragma("unroll") for (int k = 0; k < 2; ++k) DSR(At[m][k], pa_, m * 2048 + k * 1024); } while (0)
; #define LDB(dst, b, h) do { const unsigned pb_ = lds0 + SLOTB(b, h) + wc * 4096 + laneoff; _Pragma("unroll") for (int n = 0; n < 2; ++n) \
;       _Pragma("unroll") for (int k = 0; k < 2; ++k) DSR(dst[n][k], pb_, n * 2048 + k * 1024); } while (0)
; #define BAR __builtin_amdgcn_s_barrier()
; #define LGKM(n) asm volatile("s_waitcnt lgkmcnt(%0)" ::"n"(n) : "memory")
; template <int EPI, bool SWP> ...
;     ...
;     WAIT_V(6); BAR; SCHED(); MMA(1, 1, B1); BAR; SCHED();
;     LDB(B0, 1, 0); LDA(1, 0); STAGE_A(0, 1, t + 2);
;     LGKM(8); BAR; LGKM(0); SCHED(); MMA(0, 0, B0); BAR; SCHED();
;     LDB(B1, 1, 1); STAGE_B(1, 0, t + 3);
;     BAR; LGKM(0); SCHED(); MMA(0, 1, B1); BAR; SCHED();
;     LDA(1, 1); STAGE_A(1, 0, t + 3);
	v_mfma_f32_16x16x32_bf16 v[28:31], v[176:179], v[144:147], v[28:31]
	v_mfma_f32_16x16x32_bf16 v[24:27], v[184:187], v[144:147], v[24:27]
	v_mfma_f32_16x16x32_bf16 v[20:23], v[176:179], v[152:155], v[20:23]
	v_mfma_f32_16x16x32_bf16 v[16:19], v[184:187], v[152:155], v[16:19]
	v_mfma_f32_16x16x32_bf16 v[12:15], v[176:179], v[160:163], v[12:15]
	v_mfma_f32_16x16x32_bf16 v[8:11], v[184:187], v[160:163], v[8:11]
	v_mfma_f32_16x16x32_bf16 v[4:7], v[176:179], v[168:171], v[4:7]
	v_mfma_f32_16x16x32_bf16 v[0:3], v[184:187], v[168:171], v[0:3]
	v_mfma_f32_16x16x32_bf16 v[28:31], v[180:183], v[148:151], v[28:31]
	v_mfma_f32_16x16x32_bf16 v[24:27], v[188:191], v[148:151], v[24:27]
	v_mfma_f32_16x16x32_bf16 v[20:23], v[180:183], v[156:159], v[20:23]
	v_mfma_f32_16x16x32_bf16 v[16:19], v[188:191], v[156:159], v[16:19]
	v_mfma_f32_16x16x32_bf16 v[12:15], v[180:183], v[164:167], v[12:15]
	v_mfma_f32_16x16x32_bf16 v[8:11], v[188:191], v[164:167], v[8:11]
	v_mfma_f32_16x16x32_bf16 v[4:7], v[180:183], v[172:175], v[4:7]
	v_mfma_f32_16x16x32_bf16 v[0:3], v[188:191], v[172:175], v[0:3]
	s_barrier
	ds_read_b128 v[128:131], v207 offset:0
	ds_read_b128 v[132:135], v207 offset:0x400
	ds_read_b128 v[136:139], v207 offset:0x800
	ds_read_b128 v[140:143], v207 offset:0xc00
	ds_read_b128 v[144:147], v208 offset:0
	ds_read_b128 v[148:151], v208 offset:0x400
	ds_read_b128 v[152:155], v208 offset:0x800
	ds_read_b128 v[156:159], v208 offset:0xc00
	ds_read_b128 v[160:163], v208 offset:0x1000
	ds_read_b128 v[164:167], v208 offset:0x1400
	ds_read_b128 v[168:171], v208 offset:0x1800
	s_add_i32 s29, s69, 0x4000
	ds_read_b128 v[172:175], v208 offset:0x1c00
	v_lshl_add_u64 v[176:177], v[200:201], 0, s[96:97]
	s_mov_b32 m0, s29
	s_nop 0
	global_load_lds_dwordx4 v[176:177], off
	v_lshl_add_u64 v[176:177], v[200:201], 0, s[44:45]
	s_mov_b32 m0, s51
	s_nop 0
	global_load_lds_dwordx4 v[176:177], off
	s_waitcnt lgkmcnt(8)
	s_barrier
	s_waitcnt lgkmcnt(0)
	v_mfma_f32_16x16x32_bf16 v[124:127], v[128:131], v[144:147], v[124:127]
	v_mfma_f32_16x16x32_bf16 v[120:123], v[136:139], v[144:147], v[120:123]
	v_mfma_f32_16x16x32_bf16 v[116:119], v[128:131], v[152:155], v[116:119]
	v_mfma_f32_16x16x32_bf16 v[112:115], v[136:139], v[152:155], v[112:115]
	v_mfma_f32_16x16x32_bf16 v[108:111], v[128:131], v[160:163], v[108:111]
	v_mfma_f32_16x16x32_bf16 v[104:107], v[136:139], v[160:163], v[104:107]
	v_mfma_f32_16x16x32_bf16 v[100:103], v[128:131], v[168:171], v[100:103]
	v_mfma_f32_16x16x32_bf16 v[96:99], v[136:139], v[168:171], v[96:99]
	v_mfma_f32_16x16x32_bf16 v[124:127], v[132:135], v[148:151], v[124:127]
	v_mfma_f32_16x16x32_bf16 v[120:123], v[140:143], v[148:151], v[120:123]
	v_mfma_f32_16x16x32_bf16 v[116:119], v[132:135], v[156:159], v[116:119]
	v_mfma_f32_16x16x32_bf16 v[112:115], v[140:143], v[156:159], v[112:115]
	v_mfma_f32_16x16x32_bf16 v[108:111], v[132:135], v[164:167], v[108:111]
	v_mfma_f32_16x16x32_bf16 v[104:107], v[140:143], v[164:167], v[104:107]
	v_mfma_f32_16x16x32_bf16 v[100:103], v[132:135], v[172:175], v[100:103]
	v_mfma_f32_16x16x32_bf16 v[96:99], v[140:143], v[172:175], v[96:99]
	s_barrier
	ds_read_b128 v[176:179], v209 offset:0
	ds_read_b128 v[180:183], v209 offset:0x400
	ds_read_b128 v[184:187], v209 offset:0x800
	s_add_i32 s25, s69, 0x18000
	ds_read_b128 v[188:191], v209 offset:0xc00
	v_lshl_add_u64 v[226:227], v[224:225], 0, s[58:59]
	s_mov_b32 m0, s25
	s_nop 0
	global_load_lds_dwordx4 v[226:227], off
	v_lshl_add_u64 v[226:227], v[224:225], 0, s[60:61]
	s_mov_b32 m0, s66
	s_nop 0
	global_load_lds_dwordx4 v[226:227], off
	s_barrier
	s_waitcnt lgkmcnt(0)
	v_mfma_f32_16x16x32_bf16 v[92:95], v[176:179], v[144:147], v[92:95]
	v_mfma_f32_16x16x32_bf16 v[88:91], v[184:187], v[144:147], v[88:91]
	v_mfma_f32_16x16x32_bf16 v[84:87], v[176:179], v[152:155], v[84:87]
	v_mfma_f32_16x16x32_bf16 v[80:83], v[184:187], v[152:155], v[80:83]
	v_mfma_f32_16x16x32_bf16 v[76:79], v[176:179], v[160:163], v[76:79]
	v_mfma_f32_16x16x32_bf16 v[72:75], v[184:187], v[160:163], v[72:75]
	v_mfma_f32_16x16x32_bf16 v[68:71], v[176:179], v[168:171], v[68:71]
	v_mfma_f32_16x16x32_bf16 v[64:67], v[184:187], v[168:171], v[64:67]
	v_mfma_f32_16x16x32_bf16 v[92:95], v[180:183], v[148:151], v[92:95]
	v_mfma_f32_16x16x32_bf16 v[88:91], v[188:191], v[148:151], v[88:91]
	v_mfma_f32_16x16x32_bf16 v[84:87], v[180:183], v[156:159], v[84:87]
	v_mfma_f32_16x16x32_bf16 v[80:83], v[188:191], v[156:159], v[80:83]
	v_mfma_f32_16x16x32_bf16 v[76:79], v[180:183], v[164:167], v[76:79]
	v_mfma_f32_16x16x32_bf16 v[72:75], v[188:191], v[164:167], v[72:75]
	v_mfma_f32_16x16x32_bf16 v[68:71], v[180:183], v[172:175], v[68:71]
	v_mfma_f32_16x16x32_bf16 v[64:67], v[188:191], v[172:175], v[64:67]
	s_barrier
	ds_read_b128 v[144:147], v210 offset:0
	ds_read_b128 v[148:151], v210 offset:0x400
	ds_read_b128 v[152:155], v210 offset:0x800
	ds_read_b128 v[156:159], v210 offset:0xc00
	ds_read_b128 v[160:163], v210 offset:0x1000
	ds_read_b128 v[164:167], v210 offset:0x1400
	ds_read_b128 v[168:171], v210 offset:0x1800
	s_add_i32 s48, s69, 0x8000
	ds_read_b128 v[172:175], v210 offset:0x1c00
	v_lshl_add_u64 v[226:227], v[200:201], 0, s[0:1]
	s_mov_b32 m0, s48
	v_lshl_add_u64 v[200:201], v[200:201], 0, s[4:5]
	global_load_lds_dwordx4 v[226:227], off
	s_mov_b32 m0, s67
	s_nop 0
	global_load_lds_dwordx4 v[200:201], off
	s_barrier
; #define WAIT_V(n) asm volatile("s_waitcnt vmcnt(%0)" ::"n"(n) : "memory")
; #define SCHED() __builtin_amdgcn_sched_barrier(0)
; #define LGKM(n) asm volatile("s_waitcnt lgkmcnt(%0)" ::"n"(n) : "memory")
; #define STAGE_A(b, h, kt) STAGE_AX(Ag, b, h, kt)
; #define STAGE_B(b, h, kt) STAGE_BX(Bg, b, h, kt)
; #define LDA(b, h) do { const unsigned pa_ = lds0 + SLOTA(b, h) + wr * 8192 + laneoff; _Pragma("unroll") for (int m = 0; m < 4; ++m)   \
;       _Pragma("unroll") for (int k = 0; k < 2; ++k) DSR(At[m][k], pa_, m * 2048 + k * 1024); } while (0)
; #define LDB(dst, b, h) do { const unsigned pb_ = lds0 + SLOTB(b, h) + wc * 4096 + laneoff; _Pragma("unroll") for (int n = 0; n < 2; ++n) \
;       _Pragma("unroll") for (int k = 0; k < 2; ++k) DSR(dst[n][k], pb_, n * 2048 + k * 1024); } while (0)
; #define BAR __builtin_amdgcn_s_barrier()
; #define LGKM(n) asm volatile("s_waitcnt lgkmcnt(%0)" ::"n"(n) : "memory")
; template <int EPI, bool SWP> ...
;     ...
;     BAR; LGKM(0); SCHED(); MMA(1, 0, B0); BAR; SCHED();
;     STAGE_B(1, 1, t + 3);
;     WAIT_V(6); BAR; SCHED(); MMA(1, 1, B1); BAR; SCHED();
;   }
;   { LDB(B0, 0, 0); LDA(0, 0); STAGE_A(1, 1, nt - 1);
;     BAR; LGKM(0); SCHED(); MMA(0, 0, B0); BAR; SCHED();
;     LDB(B1, 0, 1); BAR; LGKM(0); SCHED(); MMA(0, 1, B1); BAR; SCHED();
	s_waitcnt lgkmcnt(0)
	v_mfma_f32_16x16x32_bf16 v[60:63], v[128:131], v[144:147], v[60:63]
	v_mfma_f32_16x16x32_bf16 v[56:59], v[136:139], v[144:147], v[56:59]
	v_mfma_f32_16x16x32_bf16 v[52:55], v[128:131], v[152:155], v[52:55]
	v_mfma_f32_16x16x32_bf16 v[48:51], v[136:139], v[152:155], v[48:51]
	v_mfma_f32_16x16x32_bf16 v[44:47], v[128:131], v[160:163], v[44:47]
	v_mfma_f32_16x16x32_bf16 v[40:43], v[136:139], v[160:163], v[40:43]
	v_mfma_f32_16x16x32_bf16 v[36:39], v[128:131], v[168:171], v[36:39]
	v_mfma_f32_16x16x32_bf16 v[32:35], v[136:139], v[168:171], v[32:35]
	v_mfma_f32_16x16x32_bf16 v[60:63], v[132:135], v[148:151], v[60:63]
	v_mfma_f32_16x16x32_bf16 v[56:59], v[140:143], v[148:151], v[56:59]
	v_mfma_f32_16x16x32_bf16 v[52:55], v[132:135], v[156:159], v[52:55]
	v_mfma_f32_16x16x32_bf16 v[48:51], v[140:143], v[156:159], v[48:51]
	v_mfma_f32_16x16x32_bf16 v[44:47], v[132:135], v[164:167], v[44:47]
	v_mfma_f32_16x16x32_bf16 v[40:43], v[140:143], v[164:167], v[40:43]
	v_mfma_f32_16x16x32_bf16 v[36:39], v[132:135], v[172:175], v[36:39]
	v_mfma_f32_16x16x32_bf16 v[32:35], v[140:143], v[172:175], v[32:35]
	s_barrier
	s_add_i32 s49, s69, 0x1c000
	v_lshl_add_u64 v[128:129], v[224:225], 0, s[34:35]
	s_mov_b32 m0, s49
	s_nop 0
	global_load_lds_dwordx4 v[128:129], off
	v_lshl_add_u64 v[128:129], v[224:225], 0, s[14:15]
	s_mov_b32 m0, s16
	s_nop 0
	global_load_lds_dwordx4 v[128:129], off
	s_waitcnt vmcnt(6)
	s_barrier
	v_mfma_f32_16x16x32_bf16 v[28:31], v[176:179], v[144:147], v[28:31]
	v_mfma_f32_16x16x32_bf16 v[24:27], v[184:187], v[144:147], v[24:27]
	v_mfma_f32_16x16x32_bf16 v[20:23], v[176:179], v[152:155], v[20:23]
	v_mfma_f32_16x16x32_bf16 v[16:19], v[184:187], v[152:155], v[16:19]
	v_mfma_f32_16x16x32_bf16 v[12:15], v[176:179], v[160:163], v[12:15]
	v_mfma_f32_16x16x32_bf16 v[8:11], v[184:187], v[160:163], v[8:11]
	v_mfma_f32_16x16x32_bf16 v[4:7], v[176:179], v[168:171], v[4:7]
	v_mfma_f32_16x16x32_bf16 v[0:3], v[184:187], v[168:171], v[0:3]
	v_mfma_f32_16x16x32_bf16 v[28:31], v[180:183], v[148:151], v[28:31]
	v_mfma_f32_16x16x32_bf16 v[24:27], v[188:191], v[148:151], v[24:27]
	v_mfma_f32_16x16x32_bf16 v[20:23], v[180:183], v[156:159], v[20:23]
	v_mfma_f32_16x16x32_bf16 v[16:19], v[188:191], v[156:159], v[16:19]
	v_mfma_f32_16x16x32_bf16 v[12:15], v[180:183], v[164:167], v[12:15]
	v_mfma_f32_16x16x32_bf16 v[8:11], v[188:191], v[164:167], v[8:11]
	v_mfma_f32_16x16x32_bf16 v[4:7], v[180:183], v[172:175], v[4:7]
	v_mfma_f32_16x16x32_bf16 v[0:3], v[188:191], v[172:175], v[0:3]
	s_add_i32 s9, s9, 2
	s_add_u32 s6, s6, 0x100
	s_addc_u32 s7, s7, 0
	s_add_u32 s12, s12, 0x100
	s_addc_u32 s13, s13, 0
	s_cmp_gt_u32 s9, 27
	s_barrier
	s_cbranch_scc0 .LBB0_197
	ds_read_b128 v[128:131], v203 offset:0
	ds_read_b128 v[132:135], v203 offset:0x400
	ds_read_b128 v[136:139], v203 offset:0x800
	ds_read_b128 v[140:143], v203 offset:0xc00
	ds_read_b128 v[144:147], v204 offset:0
	ds_read_b128 v[148:151], v204 offset:0x400
	ds_read_b128 v[152:155], v204 offset:0x800
	ds_read_b128 v[156:159], v204 offset:0xc00
	ds_read_b128 v[160:163], v204 offset:0x1000
	ds_read_b128 v[164:167], v204 offset:0x1400
	v_lshl_add_u64 v[176:177], s[76:77], 0, v[192:193]
	ds_read_b128 v[168:171], v204 offset:0x1800
	s_mov_b64 s[6:7], 0x80f80
	s_mov_b32 m0, vcc_lo
	ds_read_b128 v[172:175], v204 offset:0x1c00
	v_lshl_add_u64 v[178:179], v[176:177], 0, s[6:7]
	s_mov_b64 s[6:7], 0xc0f80
	global_load_lds_dwordx4 v[178:179], off
	v_lshl_add_u64 v[176:177], v[176:177], 0, s[6:7]
	s_mov_b32 m0, s17
	s_nop 0
	global_load_lds_dwordx4 v[176:177], off
	s_barrier
	s_waitcnt lgkmcnt(0)
	v_mfma_f32_16x16x32_bf16 v[124:127], v[128:131], v[144:147], v[124:127]
	v_mfma_f32_16x16x32_bf16 v[120:123], v[136:139], v[144:147], v[120:123]
	v_mfma_f32_16x16x32_bf16 v[116:119], v[128:131], v[152:155], v[116:119]
	v_mfma_f32_16x16x32_bf16 v[112:115], v[136:139], v[152:155], v[112:115]
	v_mfma_f32_16x16x32_bf16 v[108:111], v[128:131], v[160:163], v[108:111]
	v_mfma_f32_16x16x32_bf16 v[104:107], v[136:139], v[160:163], v[104:107]
	v_mfma_f32_16x16x32_bf16 v[100:103], v[128:131], v[168:171], v[100:103]
	v_mfma_f32_16x16x32_bf16 v[96:99], v[136:139], v[168:171], v[96:99]
	v_mfma_f32_16x16x32_bf16 v[124:127], v[132:135], v[148:151], v[124:127]
	v_mfma_f32_16x16x32_bf16 v[120:123], v[140:143], v[148:151], v[120:123]
	v_mfma_f32_16x16x32_bf16 v[116:119], v[132:135], v[156:159], v[116:119]
	v_mfma_f32_16x16x32_bf16 v[112:115], v[140:143], v[156:159], v[112:115]
	v_mfma_f32_16x16x32_bf16 v[108:111], v[132:135], v[164:167], v[108:111]
	v_mfma_f32_16x16x32_bf16 v[104:107], v[140:143], v[164:167], v[104:107]
	v_mfma_f32_16x16x32_bf16 v[100:103], v[132:135], v[172:175], v[100:103]
	v_mfma_f32_16x16x32_bf16 v[96:99], v[140:143], v[172:175], v[96:99]
	s_barrier
	ds_read_b128 v[176:179], v205 offset:0
	ds_read_b128 v[180:183], v205 offset:0x400
	ds_read_b128 v[184:187], v205 offset:0x800
	ds_read_b128 v[188:191], v205 offset:0xc00
	s_barrier
	s_waitcnt lgkmcnt(0)
	v_mfma_f32_16x16x32_bf16 v[92:95], v[176:179], v[144:147], v[92:95]
	v_mfma_f32_16x16x32_bf16 v[88:91], v[184:187], v[144:147], v[88:91]
	v_mfma_f32_16x16x32_bf16 v[84:87], v[176:179], v[152:155], v[84:87]
	v_mfma_f32_16x16x32_bf16 v[80:83], v[184:187], v[152:155], v[80:83]
	v_mfma_f32_16x16x32_bf16 v[76:79], v[176:179], v[160:163], v[76:79]
	v_mfma_f32_16x16x32_bf16 v[72:75], v[184:187], v[160:163], v[72:75]
	v_mfma_f32_16x16x32_bf16 v[68:71], v[176:179], v[168:171], v[68:71]
	v_mfma_f32_16x16x32_bf16 v[64:67], v[184:187], v[168:171], v[64:67]
	v_mfma_f32_16x16x32_bf16 v[92:95], v[180:183], v[148:151], v[92:95]
	v_mfma_f32_16x16x32_bf16 v[88:91], v[188:191], v[148:151], v[88:91]
	v_mfma_f32_16x16x32_bf16 v[84:87], v[180:183], v[156:159], v[84:87]
	v_mfma_f32_16x16x32_bf16 v[80:83], v[188:191], v[156:159], v[80:83]
	v_mfma_f32_16x16x32_bf16 v[76:79], v[180:183], v[164:167], v[76:79]
	v_mfma_f32_16x16x32_bf16 v[72:75], v[188:191], v[164:167], v[72:75]
	v_mfma_f32_16x16x32_bf16 v[68:71], v[180:183], v[172:175], v[68:71]
	v_mfma_f32_16x16x32_bf16 v[64:67], v[188:191], v[172:175], v[64:67]
	s_barrier
; #define WAIT_V(n) asm volatile("s_waitcnt vmcnt(%0)" ::"n"(n) : "memory")
; #define SCHED() __builtin_amdgcn_sched_barrier(0)
; #define LGKM(n) asm volatile("s_waitcnt lgkmcnt(%0)" ::"n"(n) : "memory")
; #define LDA(b, h) do { const unsigned pa_ = lds0 + SLOTA(b, h) + wr * 8192 + laneoff; _Pragma("unroll") for (int m = 0; m < 4; ++m)   \
;       _Pragma("unroll") for (int k = 0; k < 2; ++k) DSR(At[m][k], pa_, m * 2048 + k * 1024); } while (0)
; #define LDB(dst, b, h) do { const unsigned pb_ = lds0 + SLOTB(b, h) + wc * 4096 + laneoff; _Pragma("unroll") for (int n = 0; n < 2; ++n) \
;       _Pragma("unroll") for (int k = 0; k < 2; ++k) DSR(dst[n][k], pb_, n * 2048 + k * 1024); } while (0)
; #define BAR __builtin_amdgcn_s_barrier()
; #define LGKM(n) asm volatile("s_waitcnt lgkmcnt(%0)" ::"n"(n) : "memory")
; template <int EPI, bool SWP> ...
;     ...
;     LDA(0, 1); WAIT_V(4); BAR; LGKM(0); SCHED(); MMA(1, 0, B0); MMA(1, 1, B1); BAR; SCHED(); }
;   { LDB(B0, 1, 0); LDA(1, 0); WAIT_V(2); BAR; LGKM(0); SCHED(); MMA(0, 0, B0); BAR; SCHED();
	ds_read_b128 v[144:147], v206 offset:0
	ds_read_b128 v[148:151], v206 offset:0x400
	ds_read_b128 v[152:155], v206 offset:0x800
	ds_read_b128 v[156:159], v206 offset:0xc00
	ds_read_b128 v[160:163], v206 offset:0x1000
	ds_read_b128 v[164:167], v206 offset:0x1400
	ds_read_b128 v[168:171], v206 offset:0x1800
	ds_read_b128 v[172:175], v206 offset:0x1c00
	s_waitcnt vmcnt(4)
	s_barrier
	s_waitcnt lgkmcnt(0)
	v_mfma_f32_16x16x32_bf16 v[60:63], v[128:131], v[144:147], v[60:63]
	v_mfma_f32_16x16x32_bf16 v[56:59], v[136:139], v[144:147], v[56:59]
	v_mfma_f32_16x16x32_bf16 v[52:55], v[128:131], v[152:155], v[52:55]
	v_mfma_f32_16x16x32_bf16 v[48:51], v[136:139], v[152:155], v[48:51]
	v_mfma_f32_16x16x32_bf16 v[44:47], v[128:131], v[160:163], v[44:47]
	v_mfma_f32_16x16x32_bf16 v[40:43], v[136:139], v[160:163], v[40:43]
	v_mfma_f32_16x16x32_bf16 v[36:39], v[128:131], v[168:171], v[36:39]
	v_mfma_f32_16x16x32_bf16 v[32:35], v[136:139], v[168:171], v[32:35]
	v_mfma_f32_16x16x32_bf16 v[60:63], v[132:135], v[148:151], v[60:63]
	v_mfma_f32_16x16x32_bf16 v[56:59], v[140:143], v[148:151], v[56:59]
	v_mfma_f32_16x16x32_bf16 v[52:55], v[132:135], v[156:159], v[52:55]
	v_mfma_f32_16x16x32_bf16 v[48:51], v[140:143], v[156:159], v[48:51]
	v_mfma_f32_16x16x32_bf16 v[44:47], v[132:135], v[164:167], v[44:47]
	v_mfma_f32_16x16x32_bf16 v[40:43], v[140:143], v[164:167], v[40:43]
	v_mfma_f32_16x16x32_bf16 v[36:39], v[132:135], v[172:175], v[36:39]
	v_mfma_f32_16x16x32_bf16 v[32:35], v[140:143], v[172:175], v[32:35]
	v_mfma_f32_16x16x32_bf16 v[28:31], v[176:179], v[144:147], v[28:31]
	v_mfma_f32_16x16x32_bf16 v[24:27], v[184:187], v[144:147], v[24:27]
	v_mfma_f32_16x16x32_bf16 v[20:23], v[176:179], v[152:155], v[20:23]
	v_mfma_f32_16x16x32_bf16 v[16:19], v[184:187], v[152:155], v[16:19]
	v_mfma_f32_16x16x32_bf16 v[12:15], v[176:179], v[160:163], v[12:15]
	v_mfma_f32_16x16x32_bf16 v[8:11], v[184:187], v[160:163], v[8:11]
	v_mfma_f32_16x16x32_bf16 v[4:7], v[176:179], v[168:171], v[4:7]
	v_mfma_f32_16x16x32_bf16 v[0:3], v[184:187], v[168:171], v[0:3]
	v_mfma_f32_16x16x32_bf16 v[28:31], v[180:183], v[148:151], v[28:31]
	v_mfma_f32_16x16x32_bf16 v[24:27], v[188:191], v[148:151], v[24:27]
	v_mfma_f32_16x16x32_bf16 v[20:23], v[180:183], v[156:159], v[20:23]
	v_mfma_f32_16x16x32_bf16 v[16:19], v[188:191], v[156:159], v[16:19]
	v_mfma_f32_16x16x32_bf16 v[12:15], v[180:183], v[164:167], v[12:15]
	v_mfma_f32_16x16x32_bf16 v[8:11], v[188:191], v[164:167], v[8:11]
	v_mfma_f32_16x16x32_bf16 v[4:7], v[180:183], v[172:175], v[4:7]
	v_mfma_f32_16x16x32_bf16 v[0:3], v[188:191], v[172:175], v[0:3]
	s_barrier
	ds_read_b128 v[128:131], v207 offset:0
	ds_read_b128 v[132:135], v207 offset:0x400
	ds_read_b128 v[136:139], v207 offset:0x800
	ds_read_b128 v[140:143], v207 offset:0xc00
	ds_read_b128 v[160:163], v208 offset:0
	ds_read_b128 v[164:167], v208 offset:0x400
	ds_read_b128 v[168:171], v208 offset:0x800
	ds_read_b128 v[172:175], v208 offset:0xc00
	ds_read_b128 v[176:179], v208 offset:0x1000
	ds_read_b128 v[180:183], v208 offset:0x1400
	ds_read_b128 v[184:187], v208 offset:0x1800
	ds_read_b128 v[188:191], v208 offset:0x1c00
	s_waitcnt vmcnt(2)
	s_barrier
; #define WAIT_V(n) asm volatile("s_waitcnt vmcnt(%0)" ::"n"(n) : "memory")
; #define SCHED() __builtin_amdgcn_sched_barrier(0)
; #define LGKM(n) asm volatile("s_waitcnt lgkmcnt(%0)" ::"n"(n) : "memory")
; #define STAGE_AX(AG, b, h, kt) do { _Pragma("unroll") for (int i = 0; i < 2; ++i)                                    \
;       __builtin_amdgcn_global_load_lds((const unsigned*)(((AG) + ((size_t)(kt) * (BK * 2) + (size_t)((h) * 2 + i) * 128 * lda)) + aoff), \
;                                        (unsigned*)(shm + SLOTA(b, h) + wid * 1024 + i * 8192), 16, 0, 0); } while (0)
; #define STAGE_BX(BG, b, h, kt) do { _Pragma("unroll") for (int i = 0; i < 2; ++i)                                    \
;       __builtin_amdgcn_global_load_lds((const unsigned*)(((BG) + ((size_t)(kt) * (BK * 2) + (size_t)((h) * 2 + i) * 128 * K)) + boff),   \
;                                        (unsigned*)(shm + SLOTB(b, h) + wid * 1024 + i * 8192), 16, 0, 0); } while (0)
; #define LDA(b, h) do { const unsigned pa_ = lds0 + SLOTA(b, h) + wr * 8192 + laneoff; _Pragma("unroll") for (int m = 0; m < 4; ++m)   \
;       _Pragma("unroll") for (int k = 0; k < 2; ++k) DSR(At[m][k], pa_, m * 2048 + k * 1024); } while (0)
; #define LDB(dst, b, h) do { const unsigned pb_ = lds0 + SLOTB(b, h) + wc * 4096 + laneoff; _Pragma("unroll") for (int n = 0; n < 2; ++n) \
;       _Pragma("unroll") for (int k = 0; k < 2; ++k) DSR(dst[n][k], pb_, n * 2048 + k * 1024); } while (0)
; #define BAR __builtin_amdgcn_s_barrier()
; #define LGKM(n) asm volatile("s_waitcnt lgkmcnt(%0)" ::"n"(n) : "memory")
; template <int EPI, bool SWP> ...
;     ...
;   { LDB(B0, 1, 0); LDA(1, 0); WAIT_V(2); BAR; LGKM(0); SCHED(); MMA(0, 0, B0); BAR; SCHED();
;     LDB(B1, 1, 1); WAIT_V(0); BAR; LGKM(0); SCHED(); MMA(0, 1, B1); BAR; SCHED();
;     LDA(1, 1);
;     if (has_next) { STAGE_BX(Bg_n, 0, 0, 0); STAGE_AX(Ag_n, 0, 0, 0); STAGE_BX(Bg_n, 0, 1, 0); STAGE_AX(Ag_n, 0, 1, 0); }
	s_waitcnt lgkmcnt(0)
	v_mfma_f32_16x16x32_bf16 v[124:127], v[128:131], v[160:163], v[124:127]
	v_mfma_f32_16x16x32_bf16 v[120:123], v[136:139], v[160:163], v[120:123]
	v_mfma_f32_16x16x32_bf16 v[116:119], v[128:131], v[168:171], v[116:119]
	v_mfma_f32_16x16x32_bf16 v[112:115], v[136:139], v[168:171], v[112:115]
	v_mfma_f32_16x16x32_bf16 v[108:111], v[128:131], v[176:179], v[108:111]
	v_mfma_f32_16x16x32_bf16 v[104:107], v[136:139], v[176:179], v[104:107]
	v_mfma_f32_16x16x32_bf16 v[100:103], v[128:131], v[184:187], v[100:103]
	v_mfma_f32_16x16x32_bf16 v[96:99], v[136:139], v[184:187], v[96:99]
	v_mfma_f32_16x16x32_bf16 v[124:127], v[132:135], v[164:167], v[124:127]
	v_mfma_f32_16x16x32_bf16 v[120:123], v[140:143], v[164:167], v[120:123]
	v_mfma_f32_16x16x32_bf16 v[116:119], v[132:135], v[172:175], v[116:119]
	v_mfma_f32_16x16x32_bf16 v[112:115], v[140:143], v[172:175], v[112:115]
	v_mfma_f32_16x16x32_bf16 v[108:111], v[132:135], v[180:183], v[108:111]
	v_mfma_f32_16x16x32_bf16 v[104:107], v[140:143], v[180:183], v[104:107]
	v_mfma_f32_16x16x32_bf16 v[100:103], v[132:135], v[188:191], v[100:103]
	v_mfma_f32_16x16x32_bf16 v[96:99], v[140:143], v[188:191], v[96:99]
	s_barrier
	ds_read_b128 v[144:147], v209 offset:0
	ds_read_b128 v[148:151], v209 offset:0x400
	ds_read_b128 v[152:155], v209 offset:0x800
	ds_read_b128 v[156:159], v209 offset:0xc00
	s_waitcnt vmcnt(0)
	s_barrier
	s_waitcnt lgkmcnt(0)
	v_mfma_f32_16x16x32_bf16 v[92:95], v[144:147], v[160:163], v[92:95]
	v_mfma_f32_16x16x32_bf16 v[88:91], v[152:155], v[160:163], v[88:91]
	v_mfma_f32_16x16x32_bf16 v[84:87], v[144:147], v[168:171], v[84:87]
	v_mfma_f32_16x16x32_bf16 v[80:83], v[152:155], v[168:171], v[80:83]
	v_mfma_f32_16x16x32_bf16 v[76:79], v[144:147], v[176:179], v[76:79]
	v_mfma_f32_16x16x32_bf16 v[72:75], v[152:155], v[176:179], v[72:75]
	v_mfma_f32_16x16x32_bf16 v[68:71], v[144:147], v[184:187], v[68:71]
	v_mfma_f32_16x16x32_bf16 v[64:67], v[152:155], v[184:187], v[64:67]
	v_mfma_f32_16x16x32_bf16 v[92:95], v[148:151], v[164:167], v[92:95]
	v_mfma_f32_16x16x32_bf16 v[88:91], v[156:159], v[164:167], v[88:91]
	v_mfma_f32_16x16x32_bf16 v[84:87], v[148:151], v[172:175], v[84:87]
	v_mfma_f32_16x16x32_bf16 v[80:83], v[156:159], v[172:175], v[80:83]
	v_mfma_f32_16x16x32_bf16 v[76:79], v[148:151], v[180:183], v[76:79]
	v_mfma_f32_16x16x32_bf16 v[72:75], v[156:159], v[180:183], v[72:75]
	v_mfma_f32_16x16x32_bf16 v[68:71], v[148:151], v[188:191], v[68:71]
	v_mfma_f32_16x16x32_bf16 v[64:67], v[156:159], v[188:191], v[64:67]
	s_barrier
	ds_read_b128 v[184:187], v210 offset:0
	ds_read_b128 v[188:191], v210 offset:0x400
	ds_read_b128 v[176:179], v210 offset:0x800
	ds_read_b128 v[180:183], v210 offset:0xc00
	ds_read_b128 v[168:171], v210 offset:0x1000
	ds_read_b128 v[172:175], v210 offset:0x1400
	ds_read_b128 v[160:163], v210 offset:0x1800
	ds_read_b128 v[164:167], v210 offset:0x1c00
	s_and_b64 vcc, exec, s[70:71]
	s_cbranch_vccz .LBB0_200
	s_mov_b32 m0, s68
	v_lshl_add_u64 v[200:201], s[74:75], 0, v[192:193]
	s_mov_b64 s[6:7], 0x40000
	global_load_lds_dwordx4 v[200:201], off
	v_lshl_add_u64 v[224:225], v[200:201], 0, s[6:7]
	s_mov_b32 m0, s64
	s_mov_b64 s[12:13], 0xc0000
	global_load_lds_dwordx4 v[224:225], off
	v_lshl_add_u64 v[224:225], s[72:73], 0, v[192:193]
	s_mov_b32 m0, s69
	v_lshl_add_u64 v[226:227], v[224:225], 0, s[6:7]
	global_load_lds_dwordx4 v[224:225], off
	s_mov_b32 m0, s65
	s_mov_b64 s[6:7], 0x80000
	global_load_lds_dwordx4 v[226:227], off
	v_lshl_add_u64 v[226:227], v[200:201], 0, s[6:7]
	s_mov_b32 m0, s23
	v_lshl_add_u64 v[200:201], v[200:201], 0, s[12:13]
	global_load_lds_dwordx4 v[226:227], off
	s_mov_b32 m0, s50
	s_nop 0
	global_load_lds_dwordx4 v[200:201], off
	v_lshl_add_u64 v[200:201], v[224:225], 0, s[6:7]
	s_mov_b32 m0, s29
	s_nop 0
	global_load_lds_dwordx4 v[200:201], off
	v_lshl_add_u64 v[200:201], v[224:225], 0, s[12:13]
	s_mov_b32 m0, s51
	s_nop 0
	global_load_lds_dwordx4 v[200:201], off

; #define WAIT_V(n) asm volatile("s_waitcnt vmcnt(%0)" ::"n"(n) : "memory")
; #define SCHED() __builtin_amdgcn_sched_barrier(0)
; #define LGKM(n) asm volatile("s_waitcnt lgkmcnt(%0)" ::"n"(n) : "memory")
; #define STAGE_A(b, h, kt) STAGE_AX(Ag, b, h, kt)
; #define STAGE_B(b, h, kt) STAGE_BX(Bg, b, h, kt)
; #define LDA(b, h) do { const unsigned pa_ = lds0 + SLOTA(b, h) + wr * 8192 + laneoff; _Pragma("unroll") for (int m = 0; m < 4; ++m)   \
;       _Pragma("unroll") for (int k = 0; k < 2; ++k) DSR(At[m][k], pa_, m * 2048 + k * 1024); } while (0)
; #define LDB(dst, b, h) do { const unsigned pb_ = lds0 + SLOTB(b, h) + wc * 4096 + laneoff; _Pragma("unroll") for (int n = 0; n < 2; ++n) \
;       _Pragma("unroll") for (int k = 0; k < 2; ++k) DSR(dst[n][k], pb_, n * 2048 + k * 1024); } while (0)
; #define BAR __builtin_amdgcn_s_barrier()
; #define LGKM(n) asm volatile("s_waitcnt lgkmcnt(%0)" ::"n"(n) : "memory")
; template <int EPI, bool SWP> ...
;     ...
;     LDB(B0, 0, 0); LDA(0, 0); STAGE_A(1, 1, t + 1);
;     LGKM(8); BAR; LGKM(0); SCHED(); MMA(0, 0, B0); BAR; SCHED();
;     LDB(B1, 0, 1); STAGE_B(0, 0, t + 2);
;     BAR; LGKM(0); SCHED(); MMA(0, 1, B1); BAR; SCHED();
;     LDA(0, 1); STAGE_A(0, 0, t + 2);
;     BAR; LGKM(0); SCHED(); MMA(1, 0, B0); BAR; SCHED();
;     STAGE_B(0, 1, t + 2);
;     WAIT_V(6); BAR; SCHED(); MMA(1, 1, B1); BAR; SCHED();
.LBB0_269:
	ds_read_b128 v[128:131], v203 offset:0
	ds_read_b128 v[132:135], v203 offset:0x400
	ds_read_b128 v[136:139], v203 offset:0x800
	ds_read_b128 v[140:143], v203 offset:0xc00
	ds_read_b128 v[144:147], v204 offset:0
	ds_read_b128 v[148:151], v204 offset:0x400
	ds_read_b128 v[152:155], v204 offset:0x800
	ds_read_b128 v[156:159], v204 offset:0xc00
	ds_read_b128 v[160:163], v204 offset:0x1000
	ds_read_b128 v[164:167], v204 offset:0x1400
	ds_read_b128 v[168:171], v204 offset:0x1800
	v_lshl_add_u64 v[198:199], s[10:11], 0, v[196:197]
	s_add_i32 s29, s69, 0xc000
	ds_read_b128 v[172:175], v204 offset:0x1c00
	v_lshl_add_u64 v[176:177], v[198:199], 0, s[80:81]
	s_mov_b32 m0, s29
	s_nop 0
	global_load_lds_dwordx4 v[176:177], off
	v_lshl_add_u64 v[176:177], v[198:199], 0, s[82:83]
	s_mov_b32 m0, s17
	s_nop 0
	global_load_lds_dwordx4 v[176:177], off
	s_waitcnt lgkmcnt(8)
	s_barrier
	s_waitcnt lgkmcnt(0)
	v_mfma_f32_16x16x32_bf16 v[124:127], v[144:147], v[128:131], v[124:127]
	v_mfma_f32_16x16x32_bf16 v[120:123], v[144:147], v[136:139], v[120:123]
	v_mfma_f32_16x16x32_bf16 v[116:119], v[152:155], v[128:131], v[116:119]
	v_mfma_f32_16x16x32_bf16 v[112:115], v[152:155], v[136:139], v[112:115]
	v_mfma_f32_16x16x32_bf16 v[108:111], v[160:163], v[128:131], v[108:111]
	v_mfma_f32_16x16x32_bf16 v[104:107], v[160:163], v[136:139], v[104:107]
	v_mfma_f32_16x16x32_bf16 v[100:103], v[168:171], v[128:131], v[100:103]
	v_mfma_f32_16x16x32_bf16 v[96:99], v[168:171], v[136:139], v[96:99]
	v_mfma_f32_16x16x32_bf16 v[124:127], v[148:151], v[132:135], v[124:127]
	v_mfma_f32_16x16x32_bf16 v[120:123], v[148:151], v[140:143], v[120:123]
	v_mfma_f32_16x16x32_bf16 v[116:119], v[156:159], v[132:135], v[116:119]
	v_mfma_f32_16x16x32_bf16 v[112:115], v[156:159], v[140:143], v[112:115]
	v_mfma_f32_16x16x32_bf16 v[108:111], v[164:167], v[132:135], v[108:111]
	v_mfma_f32_16x16x32_bf16 v[104:107], v[164:167], v[140:143], v[104:107]
	v_mfma_f32_16x16x32_bf16 v[100:103], v[172:175], v[132:135], v[100:103]
	v_mfma_f32_16x16x32_bf16 v[96:99], v[172:175], v[140:143], v[96:99]
	s_barrier
	ds_read_b128 v[176:179], v205 offset:0
	ds_read_b128 v[180:183], v205 offset:0x400
	ds_read_b128 v[184:187], v205 offset:0x800
	v_lshl_add_u64 v[200:201], s[6:7], 0, v[196:197]
	s_mov_b32 m0, s68
	ds_read_b128 v[188:191], v205 offset:0xc00
	v_lshl_add_u64 v[226:227], v[200:201], 0, s[84:85]
	global_load_lds_dwordx4 v[226:227], off
	v_lshl_add_u64 v[226:227], v[200:201], 0, s[86:87]
	s_mov_b32 m0, s64
	s_nop 0
	global_load_lds_dwordx4 v[226:227], off
	s_barrier
	s_waitcnt lgkmcnt(0)
	v_mfma_f32_16x16x32_bf16 v[92:95], v[144:147], v[176:179], v[92:95]
	v_mfma_f32_16x16x32_bf16 v[88:91], v[144:147], v[184:187], v[88:91]
	v_mfma_f32_16x16x32_bf16 v[84:87], v[152:155], v[176:179], v[84:87]
	v_mfma_f32_16x16x32_bf16 v[80:83], v[152:155], v[184:187], v[80:83]
	v_mfma_f32_16x16x32_bf16 v[76:79], v[160:163], v[176:179], v[76:79]
	v_mfma_f32_16x16x32_bf16 v[72:75], v[160:163], v[184:187], v[72:75]
	v_mfma_f32_16x16x32_bf16 v[68:71], v[168:171], v[176:179], v[68:71]
	v_mfma_f32_16x16x32_bf16 v[64:67], v[168:171], v[184:187], v[64:67]
	v_mfma_f32_16x16x32_bf16 v[92:95], v[148:151], v[180:183], v[92:95]
	v_mfma_f32_16x16x32_bf16 v[88:91], v[148:151], v[188:191], v[88:91]
	v_mfma_f32_16x16x32_bf16 v[84:87], v[156:159], v[180:183], v[84:87]
	v_mfma_f32_16x16x32_bf16 v[80:83], v[156:159], v[188:191], v[80:83]
	v_mfma_f32_16x16x32_bf16 v[76:79], v[164:167], v[180:183], v[76:79]
	v_mfma_f32_16x16x32_bf16 v[72:75], v[164:167], v[188:191], v[72:75]
	v_mfma_f32_16x16x32_bf16 v[68:71], v[172:175], v[180:183], v[68:71]
	v_mfma_f32_16x16x32_bf16 v[64:67], v[172:175], v[188:191], v[64:67]
	s_barrier
	ds_read_b128 v[144:147], v206 offset:0
	ds_read_b128 v[148:151], v206 offset:0x400
	ds_read_b128 v[152:155], v206 offset:0x800
	ds_read_b128 v[156:159], v206 offset:0xc00
	ds_read_b128 v[160:163], v206 offset:0x1000
	ds_read_b128 v[164:167], v206 offset:0x1400
	ds_read_b128 v[168:171], v206 offset:0x1800
	s_mov_b32 m0, s69
	ds_read_b128 v[172:175], v206 offset:0x1c00
	v_lshl_add_u64 v[226:227], v[198:199], 0, s[88:89]
	global_load_lds_dwordx4 v[226:227], off
	v_lshl_add_u64 v[226:227], v[198:199], 0, s[90:91]
	s_mov_b32 m0, s65
	s_nop 0
	global_load_lds_dwordx4 v[226:227], off
	s_barrier
	s_waitcnt lgkmcnt(0)
	v_mfma_f32_16x16x32_bf16 v[60:63], v[144:147], v[128:131], v[60:63]
	v_mfma_f32_16x16x32_bf16 v[56:59], v[144:147], v[136:139], v[56:59]
	v_mfma_f32_16x16x32_bf16 v[52:55], v[152:155], v[128:131], v[52:55]
	v_mfma_f32_16x16x32_bf16 v[48:51], v[152:155], v[136:139], v[48:51]
	v_mfma_f32_16x16x32_bf16 v[44:47], v[160:163], v[128:131], v[44:47]
	v_mfma_f32_16x16x32_bf16 v[40:43], v[160:163], v[136:139], v[40:43]
	v_mfma_f32_16x16x32_bf16 v[36:39], v[168:171], v[128:131], v[36:39]
	v_mfma_f32_16x16x32_bf16 v[32:35], v[168:171], v[136:139], v[32:35]
	v_mfma_f32_16x16x32_bf16 v[60:63], v[148:151], v[132:135], v[60:63]
	v_mfma_f32_16x16x32_bf16 v[56:59], v[148:151], v[140:143], v[56:59]
	v_mfma_f32_16x16x32_bf16 v[52:55], v[156:159], v[132:135], v[52:55]
	v_mfma_f32_16x16x32_bf16 v[48:51], v[156:159], v[140:143], v[48:51]
	v_mfma_f32_16x16x32_bf16 v[44:47], v[164:167], v[132:135], v[44:47]
	v_mfma_f32_16x16x32_bf16 v[40:43], v[164:167], v[140:143], v[40:43]
	v_mfma_f32_16x16x32_bf16 v[36:39], v[172:175], v[132:135], v[36:39]
	v_mfma_f32_16x16x32_bf16 v[32:35], v[172:175], v[140:143], v[32:35]
	s_barrier
	s_add_i32 s9, s69, 0x14000
	v_lshl_add_u64 v[128:129], v[200:201], 0, s[92:93]
	s_mov_b32 m0, s9
	s_nop 0
	global_load_lds_dwordx4 v[128:129], off
	v_lshl_add_u64 v[128:129], v[200:201], 0, s[94:95]
	s_mov_b32 m0, s50
	s_nop 0
	global_load_lds_dwordx4 v[128:129], off
	s_waitcnt vmcnt(6)
	s_barrier
; #define WAIT_V(n) asm volatile("s_waitcnt vmcnt(%0)" ::"n"(n) : "memory")
; #define SCHED() __builtin_amdgcn_sched_barrier(0)
; #define LGKM(n) asm volatile("s_waitcnt lgkmcnt(%0)" ::"n"(n) : "memory")
; #define STAGE_A(b, h, kt) STAGE_AX(Ag, b, h, kt)
; #define STAGE_B(b, h, kt) STAGE_BX(Bg, b, h, kt)
; #define LDA(b, h) do { const unsigned pa_ = lds0 + SLOTA(b, h) + wr * 8192 + laneoff; _Pragma("unroll") for (int m = 0; m < 4; ++m)   \
;       _Pragma("unroll") for (int k = 0; k < 2; ++k) DSR(At[m][k], pa_, m * 2048 + k * 1024); } while (0)
; #define LDB(dst, b, h) do { const unsigned pb_ = lds0 + SLOTB(b, h) + wc * 4096 + laneoff; _Pragma("unroll") for (int n = 0; n < 2; ++n) \
;       _Pragma("unroll") for (int k = 0; k < 2; ++k) DSR(dst[n][k], pb_, n * 2048 + k * 1024); } while (0)
; #define BAR __builtin_amdgcn_s_barrier()
; #define LGKM(n) asm volatile("s_waitcnt lgkmcnt(%0)" ::"n"(n) : "memory")
; template <int EPI, bool SWP> ...
;     ...
;     WAIT_V(6); BAR; SCHED(); MMA(1, 1, B1); BAR; SCHED();
;     LDB(B0, 1, 0); LDA(1, 0); STAGE_A(0, 1, t + 2);
;     LGKM(8); BAR; LGKM(0); SCHED(); MMA(0, 0, B0); BAR; SCHED();
;     LDB(B1, 1, 1); STAGE_B(1, 0, t + 3);
;     BAR; LGKM(0); SCHED(); MMA(0, 1, B1); BAR; SCHED();
;     LDA(1, 1); STAGE_A(1, 0, t + 3);
	v_mfma_f32_16x16x32_bf16 v[28:31], v[144:147], v[176:179], v[28:31]
	v_mfma_f32_16x16x32_bf16 v[24:27], v[144:147], v[184:187], v[24:27]
	v_mfma_f32_16x16x32_bf16 v[20:23], v[152:155], v[176:179], v[20:23]
	v_mfma_f32_16x16x32_bf16 v[16:19], v[152:155], v[184:187], v[16:19]
	v_mfma_f32_16x16x32_bf16 v[12:15], v[160:163], v[176:179], v[12:15]
	v_mfma_f32_16x16x32_bf16 v[8:11], v[160:163], v[184:187], v[8:11]
	v_mfma_f32_16x16x32_bf16 v[4:7], v[168:171], v[176:179], v[4:7]
	v_mfma_f32_16x16x32_bf16 v[0:3], v[168:171], v[184:187], v[0:3]
	v_mfma_f32_16x16x32_bf16 v[28:31], v[148:151], v[180:183], v[28:31]
	v_mfma_f32_16x16x32_bf16 v[24:27], v[148:151], v[188:191], v[24:27]
	v_mfma_f32_16x16x32_bf16 v[20:23], v[156:159], v[180:183], v[20:23]
	v_mfma_f32_16x16x32_bf16 v[16:19], v[156:159], v[188:191], v[16:19]
	v_mfma_f32_16x16x32_bf16 v[12:15], v[164:167], v[180:183], v[12:15]
	v_mfma_f32_16x16x32_bf16 v[8:11], v[164:167], v[188:191], v[8:11]
	v_mfma_f32_16x16x32_bf16 v[4:7], v[172:175], v[180:183], v[4:7]
	v_mfma_f32_16x16x32_bf16 v[0:3], v[172:175], v[188:191], v[0:3]
	s_barrier
	ds_read_b128 v[128:131], v207 offset:0
	ds_read_b128 v[132:135], v207 offset:0x400
	ds_read_b128 v[136:139], v207 offset:0x800
	ds_read_b128 v[140:143], v207 offset:0xc00
	ds_read_b128 v[144:147], v208 offset:0
	ds_read_b128 v[148:151], v208 offset:0x400
	ds_read_b128 v[152:155], v208 offset:0x800
	ds_read_b128 v[156:159], v208 offset:0xc00
	ds_read_b128 v[160:163], v208 offset:0x1000
	ds_read_b128 v[164:167], v208 offset:0x1400
	ds_read_b128 v[168:171], v208 offset:0x1800
	s_add_i32 s13, s69, 0x4000
	ds_read_b128 v[172:175], v208 offset:0x1c00
	v_lshl_add_u64 v[176:177], v[198:199], 0, s[96:97]
	s_mov_b32 m0, s13
	s_nop 0
	global_load_lds_dwordx4 v[176:177], off
	v_lshl_add_u64 v[176:177], v[198:199], 0, s[44:45]
	s_mov_b32 m0, s51
	s_nop 0
	global_load_lds_dwordx4 v[176:177], off
	s_waitcnt lgkmcnt(8)
	s_barrier
	s_waitcnt lgkmcnt(0)
	v_mfma_f32_16x16x32_bf16 v[124:127], v[144:147], v[128:131], v[124:127]
	v_mfma_f32_16x16x32_bf16 v[120:123], v[144:147], v[136:139], v[120:123]
	v_mfma_f32_16x16x32_bf16 v[116:119], v[152:155], v[128:131], v[116:119]
	v_mfma_f32_16x16x32_bf16 v[112:115], v[152:155], v[136:139], v[112:115]
	v_mfma_f32_16x16x32_bf16 v[108:111], v[160:163], v[128:131], v[108:111]
	v_mfma_f32_16x16x32_bf16 v[104:107], v[160:163], v[136:139], v[104:107]
	v_mfma_f32_16x16x32_bf16 v[100:103], v[168:171], v[128:131], v[100:103]
	v_mfma_f32_16x16x32_bf16 v[96:99], v[168:171], v[136:139], v[96:99]
	v_mfma_f32_16x16x32_bf16 v[124:127], v[148:151], v[132:135], v[124:127]
	v_mfma_f32_16x16x32_bf16 v[120:123], v[148:151], v[140:143], v[120:123]
	v_mfma_f32_16x16x32_bf16 v[116:119], v[156:159], v[132:135], v[116:119]
	v_mfma_f32_16x16x32_bf16 v[112:115], v[156:159], v[140:143], v[112:115]
	v_mfma_f32_16x16x32_bf16 v[108:111], v[164:167], v[132:135], v[108:111]
	v_mfma_f32_16x16x32_bf16 v[104:107], v[164:167], v[140:143], v[104:107]
	v_mfma_f32_16x16x32_bf16 v[100:103], v[172:175], v[132:135], v[100:103]
	v_mfma_f32_16x16x32_bf16 v[96:99], v[172:175], v[140:143], v[96:99]
	s_barrier
	ds_read_b128 v[176:179], v209 offset:0
	ds_read_b128 v[180:183], v209 offset:0x400
	ds_read_b128 v[184:187], v209 offset:0x800
	s_add_i32 s12, s69, 0x18000
	ds_read_b128 v[188:191], v209 offset:0xc00
	v_lshl_add_u64 v[226:227], v[200:201], 0, s[58:59]
	s_mov_b32 m0, s12
	s_nop 0
	global_load_lds_dwordx4 v[226:227], off
	v_lshl_add_u64 v[226:227], v[200:201], 0, s[60:61]
	s_mov_b32 m0, s66
	s_nop 0
	global_load_lds_dwordx4 v[226:227], off
	s_barrier
	s_waitcnt lgkmcnt(0)
	v_mfma_f32_16x16x32_bf16 v[92:95], v[144:147], v[176:179], v[92:95]
	v_mfma_f32_16x16x32_bf16 v[88:91], v[144:147], v[184:187], v[88:91]
	v_mfma_f32_16x16x32_bf16 v[84:87], v[152:155], v[176:179], v[84:87]
	v_mfma_f32_16x16x32_bf16 v[80:83], v[152:155], v[184:187], v[80:83]
	v_mfma_f32_16x16x32_bf16 v[76:79], v[160:163], v[176:179], v[76:79]
	v_mfma_f32_16x16x32_bf16 v[72:75], v[160:163], v[184:187], v[72:75]
	v_mfma_f32_16x16x32_bf16 v[68:71], v[168:171], v[176:179], v[68:71]
	v_mfma_f32_16x16x32_bf16 v[64:67], v[168:171], v[184:187], v[64:67]
	v_mfma_f32_16x16x32_bf16 v[92:95], v[148:151], v[180:183], v[92:95]
	v_mfma_f32_16x16x32_bf16 v[88:91], v[148:151], v[188:191], v[88:91]
	v_mfma_f32_16x16x32_bf16 v[84:87], v[156:159], v[180:183], v[84:87]
	v_mfma_f32_16x16x32_bf16 v[80:83], v[156:159], v[188:191], v[80:83]
	v_mfma_f32_16x16x32_bf16 v[76:79], v[164:167], v[180:183], v[76:79]
	v_mfma_f32_16x16x32_bf16 v[72:75], v[164:167], v[188:191], v[72:75]
	v_mfma_f32_16x16x32_bf16 v[68:71], v[172:175], v[180:183], v[68:71]
	v_mfma_f32_16x16x32_bf16 v[64:67], v[172:175], v[188:191], v[64:67]
	s_barrier
	ds_read_b128 v[144:147], v210 offset:0
	ds_read_b128 v[148:151], v210 offset:0x400
	ds_read_b128 v[152:155], v210 offset:0x800
	ds_read_b128 v[156:159], v210 offset:0xc00
	ds_read_b128 v[160:163], v210 offset:0x1000
	ds_read_b128 v[164:167], v210 offset:0x1400
	ds_read_b128 v[168:171], v210 offset:0x1800
	s_add_i32 s23, s69, 0x8000
	ds_read_b128 v[172:175], v210 offset:0x1c00
	v_lshl_add_u64 v[226:227], v[198:199], 0, s[0:1]
	s_mov_b32 m0, s23
	v_lshl_add_u64 v[198:199], v[198:199], 0, s[4:5]
	global_load_lds_dwordx4 v[226:227], off
	s_mov_b32 m0, s67
	s_nop 0
	global_load_lds_dwordx4 v[198:199], off
	s_barrier
; #define WAIT_V(n) asm volatile("s_waitcnt vmcnt(%0)" ::"n"(n) : "memory")
; #define SCHED() __builtin_amdgcn_sched_barrier(0)
; #define LGKM(n) asm volatile("s_waitcnt lgkmcnt(%0)" ::"n"(n) : "memory")
; #define STAGE_A(b, h, kt) STAGE_AX(Ag, b, h, kt)
; #define STAGE_B(b, h, kt) STAGE_BX(Bg, b, h, kt)
; #define LDA(b, h) do { const unsigned pa_ = lds0 + SLOTA(b, h) + wr * 8192 + laneoff; _Pragma("unroll") for (int m = 0; m < 4; ++m)   \
;       _Pragma("unroll") for (int k = 0; k < 2; ++k) DSR(At[m][k], pa_, m * 2048 + k * 1024); } while (0)
; #define LDB(dst, b, h) do { const unsigned pb_ = lds0 + SLOTB(b, h) + wc * 4096 + laneoff; _Pragma("unroll") for (int n = 0; n < 2; ++n) \
;       _Pragma("unroll") for (int k = 0; k < 2; ++k) DSR(dst[n][k], pb_, n * 2048 + k * 1024); } while (0)
; #define BAR __builtin_amdgcn_s_barrier()
; #define LGKM(n) asm volatile("s_waitcnt lgkmcnt(%0)" ::"n"(n) : "memory")
; template <int EPI, bool SWP> ...
;     ...
;     BAR; LGKM(0); SCHED(); MMA(1, 0, B0); BAR; SCHED();
;     STAGE_B(1, 1, t + 3);
;     WAIT_V(6); BAR; SCHED(); MMA(1, 1, B1); BAR; SCHED();
;   }
;   { LDB(B0, 0, 0); LDA(0, 0); STAGE_A(1, 1, nt - 1);
;     BAR; LGKM(0); SCHED(); MMA(0, 0, B0); BAR; SCHED();
;     LDB(B1, 0, 1); BAR; LGKM(0); SCHED(); MMA(0, 1, B1); BAR; SCHED();
	s_waitcnt lgkmcnt(0)
	v_mfma_f32_16x16x32_bf16 v[60:63], v[144:147], v[128:131], v[60:63]
	v_mfma_f32_16x16x32_bf16 v[56:59], v[144:147], v[136:139], v[56:59]
	v_mfma_f32_16x16x32_bf16 v[52:55], v[152:155], v[128:131], v[52:55]
	v_mfma_f32_16x16x32_bf16 v[48:51], v[152:155], v[136:139], v[48:51]
	v_mfma_f32_16x16x32_bf16 v[44:47], v[160:163], v[128:131], v[44:47]
	v_mfma_f32_16x16x32_bf16 v[40:43], v[160:163], v[136:139], v[40:43]
	v_mfma_f32_16x16x32_bf16 v[36:39], v[168:171], v[128:131], v[36:39]
	v_mfma_f32_16x16x32_bf16 v[32:35], v[168:171], v[136:139], v[32:35]
	v_mfma_f32_16x16x32_bf16 v[60:63], v[148:151], v[132:135], v[60:63]
	v_mfma_f32_16x16x32_bf16 v[56:59], v[148:151], v[140:143], v[56:59]
	v_mfma_f32_16x16x32_bf16 v[52:55], v[156:159], v[132:135], v[52:55]
	v_mfma_f32_16x16x32_bf16 v[48:51], v[156:159], v[140:143], v[48:51]
	v_mfma_f32_16x16x32_bf16 v[44:47], v[164:167], v[132:135], v[44:47]
	v_mfma_f32_16x16x32_bf16 v[40:43], v[164:167], v[140:143], v[40:43]
	v_mfma_f32_16x16x32_bf16 v[36:39], v[172:175], v[132:135], v[36:39]
	v_mfma_f32_16x16x32_bf16 v[32:35], v[172:175], v[140:143], v[32:35]
	s_barrier
	s_add_i32 s25, s69, 0x1c000
	v_lshl_add_u64 v[128:129], v[200:201], 0, s[34:35]
	s_mov_b32 m0, s25
	s_nop 0
	global_load_lds_dwordx4 v[128:129], off
	v_lshl_add_u64 v[128:129], v[200:201], 0, s[14:15]
	s_mov_b32 m0, s16
	s_nop 0
	global_load_lds_dwordx4 v[128:129], off
	s_waitcnt vmcnt(6)
	s_barrier
	v_mfma_f32_16x16x32_bf16 v[28:31], v[144:147], v[176:179], v[28:31]
	v_mfma_f32_16x16x32_bf16 v[24:27], v[144:147], v[184:187], v[24:27]
	v_mfma_f32_16x16x32_bf16 v[20:23], v[152:155], v[176:179], v[20:23]
	v_mfma_f32_16x16x32_bf16 v[16:19], v[152:155], v[184:187], v[16:19]
	v_mfma_f32_16x16x32_bf16 v[12:15], v[160:163], v[176:179], v[12:15]
	v_mfma_f32_16x16x32_bf16 v[8:11], v[160:163], v[184:187], v[8:11]
	v_mfma_f32_16x16x32_bf16 v[4:7], v[168:171], v[176:179], v[4:7]
	v_mfma_f32_16x16x32_bf16 v[0:3], v[168:171], v[184:187], v[0:3]
	v_mfma_f32_16x16x32_bf16 v[28:31], v[148:151], v[180:183], v[28:31]
	v_mfma_f32_16x16x32_bf16 v[24:27], v[148:151], v[188:191], v[24:27]
	v_mfma_f32_16x16x32_bf16 v[20:23], v[156:159], v[180:183], v[20:23]
	v_mfma_f32_16x16x32_bf16 v[16:19], v[156:159], v[188:191], v[16:19]
	v_mfma_f32_16x16x32_bf16 v[12:15], v[164:167], v[180:183], v[12:15]
	v_mfma_f32_16x16x32_bf16 v[8:11], v[164:167], v[188:191], v[8:11]
	v_mfma_f32_16x16x32_bf16 v[4:7], v[172:175], v[180:183], v[4:7]
	v_mfma_f32_16x16x32_bf16 v[0:3], v[172:175], v[188:191], v[0:3]
	s_add_i32 s8, s8, 2
	s_add_u32 s6, s6, 0x100
	s_addc_u32 s7, s7, 0
	s_add_u32 s10, s10, 0x100
	s_addc_u32 s11, s11, 0
	s_cmp_gt_u32 s8, 27
	s_barrier
	s_cbranch_scc0 .LBB0_269
	ds_read_b128 v[128:131], v203 offset:0
	ds_read_b128 v[132:135], v203 offset:0x400
	ds_read_b128 v[136:139], v203 offset:0x800
	ds_read_b128 v[140:143], v203 offset:0xc00
	ds_read_b128 v[144:147], v204 offset:0
	ds_read_b128 v[148:151], v204 offset:0x400
	ds_read_b128 v[152:155], v204 offset:0x800
	ds_read_b128 v[156:159], v204 offset:0xc00
	ds_read_b128 v[160:163], v204 offset:0x1000
	ds_read_b128 v[164:167], v204 offset:0x1400
	v_lshl_add_u64 v[176:177], s[76:77], 0, v[192:193]
	ds_read_b128 v[168:171], v204 offset:0x1800
	s_mov_b64 s[6:7], 0x80f80
	s_mov_b32 m0, s29
	ds_read_b128 v[172:175], v204 offset:0x1c00
	v_lshl_add_u64 v[178:179], v[176:177], 0, s[6:7]
	s_mov_b64 s[6:7], 0xc0f80
	global_load_lds_dwordx4 v[178:179], off
	v_lshl_add_u64 v[176:177], v[176:177], 0, s[6:7]
	s_mov_b32 m0, s17
	s_nop 0
	global_load_lds_dwordx4 v[176:177], off
	s_barrier
	s_waitcnt lgkmcnt(0)
	v_mfma_f32_16x16x32_bf16 v[124:127], v[144:147], v[128:131], v[124:127]
	v_mfma_f32_16x16x32_bf16 v[120:123], v[144:147], v[136:139], v[120:123]
	v_mfma_f32_16x16x32_bf16 v[116:119], v[152:155], v[128:131], v[116:119]
	v_mfma_f32_16x16x32_bf16 v[112:115], v[152:155], v[136:139], v[112:115]
	v_mfma_f32_16x16x32_bf16 v[108:111], v[160:163], v[128:131], v[108:111]
	v_mfma_f32_16x16x32_bf16 v[104:107], v[160:163], v[136:139], v[104:107]
	v_mfma_f32_16x16x32_bf16 v[100:103], v[168:171], v[128:131], v[100:103]
	v_mfma_f32_16x16x32_bf16 v[96:99], v[168:171], v[136:139], v[96:99]
	v_mfma_f32_16x16x32_bf16 v[124:127], v[148:151], v[132:135], v[124:127]
	v_mfma_f32_16x16x32_bf16 v[120:123], v[148:151], v[140:143], v[120:123]
	v_mfma_f32_16x16x32_bf16 v[116:119], v[156:159], v[132:135], v[116:119]
	v_mfma_f32_16x16x32_bf16 v[112:115], v[156:159], v[140:143], v[112:115]
	v_mfma_f32_16x16x32_bf16 v[108:111], v[164:167], v[132:135], v[108:111]
	v_mfma_f32_16x16x32_bf16 v[104:107], v[164:167], v[140:143], v[104:107]
	v_mfma_f32_16x16x32_bf16 v[100:103], v[172:175], v[132:135], v[100:103]
	v_mfma_f32_16x16x32_bf16 v[96:99], v[172:175], v[140:143], v[96:99]
	s_barrier
	ds_read_b128 v[176:179], v205 offset:0
	ds_read_b128 v[180:183], v205 offset:0x400
	ds_read_b128 v[184:187], v205 offset:0x800
	ds_read_b128 v[188:191], v205 offset:0xc00
	s_barrier
	s_waitcnt lgkmcnt(0)
	v_mfma_f32_16x16x32_bf16 v[92:95], v[144:147], v[176:179], v[92:95]
	v_mfma_f32_16x16x32_bf16 v[88:91], v[144:147], v[184:187], v[88:91]
	v_mfma_f32_16x16x32_bf16 v[84:87], v[152:155], v[176:179], v[84:87]
	v_mfma_f32_16x16x32_bf16 v[80:83], v[152:155], v[184:187], v[80:83]
	v_mfma_f32_16x16x32_bf16 v[76:79], v[160:163], v[176:179], v[76:79]
	v_mfma_f32_16x16x32_bf16 v[72:75], v[160:163], v[184:187], v[72:75]
	v_mfma_f32_16x16x32_bf16 v[68:71], v[168:171], v[176:179], v[68:71]
	v_mfma_f32_16x16x32_bf16 v[64:67], v[168:171], v[184:187], v[64:67]
	v_mfma_f32_16x16x32_bf16 v[92:95], v[148:151], v[180:183], v[92:95]
	v_mfma_f32_16x16x32_bf16 v[88:91], v[148:151], v[188:191], v[88:91]
	v_mfma_f32_16x16x32_bf16 v[84:87], v[156:159], v[180:183], v[84:87]
	v_mfma_f32_16x16x32_bf16 v[80:83], v[156:159], v[188:191], v[80:83]
	v_mfma_f32_16x16x32_bf16 v[76:79], v[164:167], v[180:183], v[76:79]
	v_mfma_f32_16x16x32_bf16 v[72:75], v[164:167], v[188:191], v[72:75]
	v_mfma_f32_16x16x32_bf16 v[68:71], v[172:175], v[180:183], v[68:71]
	v_mfma_f32_16x16x32_bf16 v[160:163], v[172:175], v[188:191], v[64:67]
	s_barrier
; #define WAIT_V(n) asm volatile("s_waitcnt vmcnt(%0)" ::"n"(n) : "memory")
; #define SCHED() __builtin_amdgcn_sched_barrier(0)
; #define LGKM(n) asm volatile("s_waitcnt lgkmcnt(%0)" ::"n"(n) : "memory")
; #define LDA(b, h) do { const unsigned pa_ = lds0 + SLOTA(b, h) + wr * 8192 + laneoff; _Pragma("unroll") for (int m = 0; m < 4; ++m)   \
;       _Pragma("unroll") for (int k = 0; k < 2; ++k) DSR(At[m][k], pa_, m * 2048 + k * 1024); } while (0)
; #define LDB(dst, b, h) do { const unsigned pb_ = lds0 + SLOTB(b, h) + wc * 4096 + laneoff; _Pragma("unroll") for (int n = 0; n < 2; ++n) \
;       _Pragma("unroll") for (int k = 0; k < 2; ++k) DSR(dst[n][k], pb_, n * 2048 + k * 1024); } while (0)
; #define BAR __builtin_amdgcn_s_barrier()
; #define LGKM(n) asm volatile("s_waitcnt lgkmcnt(%0)" ::"n"(n) : "memory")
; template <int EPI, bool SWP> ...
;     ...
;     LDA(0, 1); WAIT_V(4); BAR; LGKM(0); SCHED(); MMA(1, 0, B0); MMA(1, 1, B1); BAR; SCHED(); }
;   { LDB(B0, 1, 0); LDA(1, 0); WAIT_V(2); BAR; LGKM(0); SCHED(); MMA(0, 0, B0); BAR; SCHED();
	ds_read_b128 v[144:147], v206 offset:0
	ds_read_b128 v[148:151], v206 offset:0x400
	ds_read_b128 v[152:155], v206 offset:0x800
	ds_read_b128 v[156:159], v206 offset:0xc00
	ds_read_b128 v[164:167], v206 offset:0x1000
	ds_read_b128 v[168:171], v206 offset:0x1400
	ds_read_b128 v[172:175], v206 offset:0x1800
	ds_read_b128 v[198:201], v206 offset:0x1c00
	s_waitcnt vmcnt(4)
	s_barrier
	s_waitcnt lgkmcnt(0)
	v_mfma_f32_16x16x32_bf16 v[60:63], v[144:147], v[128:131], v[60:63]
	v_mfma_f32_16x16x32_bf16 v[56:59], v[144:147], v[136:139], v[56:59]
	v_mfma_f32_16x16x32_bf16 v[52:55], v[152:155], v[128:131], v[52:55]
	v_mfma_f32_16x16x32_bf16 v[48:51], v[152:155], v[136:139], v[48:51]
	v_mfma_f32_16x16x32_bf16 v[44:47], v[164:167], v[128:131], v[44:47]
	v_mfma_f32_16x16x32_bf16 v[40:43], v[164:167], v[136:139], v[40:43]
	v_mfma_f32_16x16x32_bf16 v[36:39], v[172:175], v[128:131], v[36:39]
	v_mfma_f32_16x16x32_bf16 v[32:35], v[172:175], v[136:139], v[32:35]
	v_mfma_f32_16x16x32_bf16 v[64:67], v[148:151], v[132:135], v[60:63]
	v_mfma_f32_16x16x32_bf16 v[56:59], v[148:151], v[140:143], v[56:59]
	v_mfma_f32_16x16x32_bf16 v[52:55], v[156:159], v[132:135], v[52:55]
	v_mfma_f32_16x16x32_bf16 v[48:51], v[156:159], v[140:143], v[48:51]
	v_mfma_f32_16x16x32_bf16 v[44:47], v[168:171], v[132:135], v[44:47]
	v_mfma_f32_16x16x32_bf16 v[40:43], v[168:171], v[140:143], v[40:43]
	v_mfma_f32_16x16x32_bf16 v[36:39], v[198:201], v[132:135], v[36:39]
	v_mfma_f32_16x16x32_bf16 v[32:35], v[198:201], v[140:143], v[32:35]
	v_mfma_f32_16x16x32_bf16 v[28:31], v[144:147], v[176:179], v[28:31]
	v_mfma_f32_16x16x32_bf16 v[24:27], v[144:147], v[184:187], v[24:27]
	v_mfma_f32_16x16x32_bf16 v[20:23], v[152:155], v[176:179], v[20:23]
	v_mfma_f32_16x16x32_bf16 v[16:19], v[152:155], v[184:187], v[16:19]
	v_mfma_f32_16x16x32_bf16 v[12:15], v[164:167], v[176:179], v[12:15]
	v_mfma_f32_16x16x32_bf16 v[8:11], v[164:167], v[184:187], v[8:11]
	v_mfma_f32_16x16x32_bf16 v[4:7], v[172:175], v[176:179], v[4:7]
	v_mfma_f32_16x16x32_bf16 v[0:3], v[172:175], v[184:187], v[0:3]
	v_mfma_f32_16x16x32_bf16 v[28:31], v[148:151], v[180:183], v[28:31]
	v_mfma_f32_16x16x32_bf16 v[24:27], v[148:151], v[188:191], v[24:27]
	v_mfma_f32_16x16x32_bf16 v[20:23], v[156:159], v[180:183], v[20:23]
	v_mfma_f32_16x16x32_bf16 v[16:19], v[156:159], v[188:191], v[16:19]
	v_mfma_f32_16x16x32_bf16 v[12:15], v[168:171], v[180:183], v[12:15]
	v_mfma_f32_16x16x32_bf16 v[8:11], v[168:171], v[188:191], v[8:11]
	v_mfma_f32_16x16x32_bf16 v[4:7], v[198:201], v[180:183], v[4:7]
	v_mfma_f32_16x16x32_bf16 v[0:3], v[198:201], v[188:191], v[0:3]
	s_barrier
	ds_read_b128 v[128:131], v207 offset:0
	ds_read_b128 v[132:135], v207 offset:0x400
	ds_read_b128 v[136:139], v207 offset:0x800
	ds_read_b128 v[140:143], v207 offset:0xc00
	ds_read_b128 v[60:63], v208 offset:0
	ds_read_b128 v[164:167], v208 offset:0x400
	ds_read_b128 v[168:171], v208 offset:0x800
	ds_read_b128 v[172:175], v208 offset:0xc00
	ds_read_b128 v[176:179], v208 offset:0x1000
	ds_read_b128 v[180:183], v208 offset:0x1400
	ds_read_b128 v[184:187], v208 offset:0x1800
	ds_read_b128 v[188:191], v208 offset:0x1c00
	s_waitcnt vmcnt(2)
	s_barrier
; #define WAIT_V(n) asm volatile("s_waitcnt vmcnt(%0)" ::"n"(n) : "memory")
; #define SCHED() __builtin_amdgcn_sched_barrier(0)
; #define LGKM(n) asm volatile("s_waitcnt lgkmcnt(%0)" ::"n"(n) : "memory")
; #define STAGE_AX(AG, b, h, kt) do { _Pragma("unroll") for (int i = 0; i < 2; ++i)                                    \
;       __builtin_amdgcn_global_load_lds((const unsigned*)(((AG) + ((size_t)(kt) * (BK * 2) + (size_t)((h) * 2 + i) * 128 * lda)) + aoff), \
;                                        (unsigned*)(shm + SLOTA(b, h) + wid * 1024 + i * 8192), 16, 0, 0); } while (0)
; #define STAGE_BX(BG, b, h, kt) do { _Pragma("unroll") for (int i = 0; i < 2; ++i)                                    \
;       __builtin_amdgcn_global_load_lds((const unsigned*)(((BG) + ((size_t)(kt) * (BK * 2) + (size_t)((h) * 2 + i) * 128 * K)) + boff),   \
;                                        (unsigned*)(shm + SLOTB(b, h) + wid * 1024 + i * 8192), 16, 0, 0); } while (0)
; #define LDA(b, h) do { const unsigned pa_ = lds0 + SLOTA(b, h) + wr * 8192 + laneoff; _Pragma("unroll") for (int m = 0; m < 4; ++m)   \
;       _Pragma("unroll") for (int k = 0; k < 2; ++k) DSR(At[m][k], pa_, m * 2048 + k * 1024); } while (0)
; #define LDB(dst, b, h) do { const unsigned pb_ = lds0 + SLOTB(b, h) + wc * 4096 + laneoff; _Pragma("unroll") for (int n = 0; n < 2; ++n) \
;       _Pragma("unroll") for (int k = 0; k < 2; ++k) DSR(dst[n][k], pb_, n * 2048 + k * 1024); } while (0)
; #define BAR __builtin_amdgcn_s_barrier()
; #define LGKM(n) asm volatile("s_waitcnt lgkmcnt(%0)" ::"n"(n) : "memory")
; template <int EPI, bool SWP> ...
;     ...
;   { LDB(B0, 1, 0); LDA(1, 0); WAIT_V(2); BAR; LGKM(0); SCHED(); MMA(0, 0, B0); BAR; SCHED();
;     LDB(B1, 1, 1); WAIT_V(0); BAR; LGKM(0); SCHED(); MMA(0, 1, B1); BAR; SCHED();
;     LDA(1, 1);
;     if (has_next) { STAGE_BX(Bg_n, 0, 0, 0); STAGE_AX(Ag_n, 0, 0, 0); STAGE_BX(Bg_n, 0, 1, 0); STAGE_AX(Ag_n, 0, 1, 0); }
	s_waitcnt lgkmcnt(0)
	v_mfma_f32_16x16x32_bf16 v[124:127], v[60:63], v[128:131], v[124:127]
	v_mfma_f32_16x16x32_bf16 v[120:123], v[60:63], v[136:139], v[120:123]
	v_mfma_f32_16x16x32_bf16 v[116:119], v[168:171], v[128:131], v[116:119]
	v_mfma_f32_16x16x32_bf16 v[112:115], v[168:171], v[136:139], v[112:115]
	v_mfma_f32_16x16x32_bf16 v[108:111], v[176:179], v[128:131], v[108:111]
	v_mfma_f32_16x16x32_bf16 v[104:107], v[176:179], v[136:139], v[104:107]
	v_mfma_f32_16x16x32_bf16 v[100:103], v[184:187], v[128:131], v[100:103]
	v_mfma_f32_16x16x32_bf16 v[96:99], v[184:187], v[136:139], v[96:99]
	v_mfma_f32_16x16x32_bf16 v[124:127], v[164:167], v[132:135], v[124:127]
	v_mfma_f32_16x16x32_bf16 v[120:123], v[164:167], v[140:143], v[120:123]
	v_mfma_f32_16x16x32_bf16 v[116:119], v[172:175], v[132:135], v[116:119]
	v_mfma_f32_16x16x32_bf16 v[112:115], v[172:175], v[140:143], v[112:115]
	v_mfma_f32_16x16x32_bf16 v[108:111], v[180:183], v[132:135], v[108:111]
	v_mfma_f32_16x16x32_bf16 v[104:107], v[180:183], v[140:143], v[104:107]
	v_mfma_f32_16x16x32_bf16 v[100:103], v[188:191], v[132:135], v[100:103]
	v_mfma_f32_16x16x32_bf16 v[96:99], v[188:191], v[140:143], v[96:99]
	s_barrier
	ds_read_b128 v[144:147], v209 offset:0
	ds_read_b128 v[148:151], v209 offset:0x400
	ds_read_b128 v[152:155], v209 offset:0x800
	ds_read_b128 v[156:159], v209 offset:0xc00
	s_waitcnt vmcnt(0)
	s_barrier
	s_waitcnt lgkmcnt(0)
	v_mfma_f32_16x16x32_bf16 v[92:95], v[60:63], v[144:147], v[92:95]
	v_mfma_f32_16x16x32_bf16 v[60:63], v[60:63], v[152:155], v[88:91]
	v_mfma_f32_16x16x32_bf16 v[88:91], v[164:167], v[156:159], v[60:63]
	v_mfma_f32_16x16x32_bf16 v[60:63], v[168:171], v[144:147], v[84:87]
	v_mfma_f32_16x16x32_bf16 v[84:87], v[172:175], v[148:151], v[60:63]
	v_mfma_f32_16x16x32_bf16 v[60:63], v[168:171], v[152:155], v[80:83]
	v_mfma_f32_16x16x32_bf16 v[80:83], v[172:175], v[156:159], v[60:63]
	v_mfma_f32_16x16x32_bf16 v[60:63], v[176:179], v[144:147], v[76:79]
	v_mfma_f32_16x16x32_bf16 v[76:79], v[180:183], v[148:151], v[60:63]
	v_mfma_f32_16x16x32_bf16 v[60:63], v[176:179], v[152:155], v[72:75]
	v_mfma_f32_16x16x32_bf16 v[72:75], v[180:183], v[156:159], v[60:63]
	v_mfma_f32_16x16x32_bf16 v[60:63], v[184:187], v[144:147], v[68:71]
	v_mfma_f32_16x16x32_bf16 v[68:71], v[188:191], v[148:151], v[60:63]
	v_mfma_f32_16x16x32_bf16 v[60:63], v[184:187], v[152:155], v[160:163]
	v_mfma_f32_16x16x32_bf16 v[92:95], v[164:167], v[148:151], v[92:95]
	v_mfma_f32_16x16x32_bf16 v[60:63], v[188:191], v[156:159], v[60:63]
	s_barrier
	ds_read_b128 v[184:187], v210 offset:0
	ds_read_b128 v[188:191], v210 offset:0x400
	ds_read_b128 v[176:179], v210 offset:0x800
	ds_read_b128 v[180:183], v210 offset:0xc00
	ds_read_b128 v[168:171], v210 offset:0x1000
	ds_read_b128 v[172:175], v210 offset:0x1400
	ds_read_b128 v[160:163], v210 offset:0x1800
	ds_read_b128 v[164:167], v210 offset:0x1c00
	s_and_b64 vcc, exec, s[70:71]
	v_lshl_add_u64 v[198:199], s[74:75], 0, v[192:193]
	v_lshl_add_u64 v[200:201], s[72:73], 0, v[192:193]
	s_cbranch_vccz .LBB0_272
	s_mov_b32 m0, s68
	s_mov_b64 s[6:7], 0x40000
	global_load_lds_dwordx4 v[198:199], off
	v_lshl_add_u64 v[226:227], v[198:199], 0, s[6:7]
	s_mov_b32 m0, s64
	s_nop 0
	global_load_lds_dwordx4 v[226:227], off
	s_mov_b32 m0, s69
	v_lshl_add_u64 v[226:227], v[200:201], 0, s[6:7]
	global_load_lds_dwordx4 v[200:201], off
	s_mov_b32 m0, s65
	s_mov_b64 s[6:7], 0x80000
	global_load_lds_dwordx4 v[226:227], off
	v_lshl_add_u64 v[226:227], v[198:199], 0, s[6:7]
	s_mov_b32 m0, s9
	s_mov_b64 s[8:9], 0xc0000
	global_load_lds_dwordx4 v[226:227], off
	v_lshl_add_u64 v[226:227], v[198:199], 0, s[8:9]
	s_mov_b32 m0, s50
	s_nop 0
	global_load_lds_dwordx4 v[226:227], off
	v_lshl_add_u64 v[226:227], v[200:201], 0, s[6:7]
	s_mov_b32 m0, s13
	s_nop 0
	global_load_lds_dwordx4 v[226:227], off
	v_lshl_add_u64 v[226:227], v[200:201], 0, s[8:9]
	s_mov_b32 m0, s51
	s_nop 0
	global_load_lds_dwordx4 v[226:227], off

; #define SCHED() __builtin_amdgcn_sched_barrier(0)
; #define DSR(dst, addr, off) asm volatile("ds_read_b128 %0, %1 offset:%2" : "=&v"(dst) : "v"(addr), "n"(off) : "memory")
; #define LGKM(n) asm volatile("s_waitcnt lgkmcnt(%0)" ::"n"(n) : "memory")
; #define DSR(dst, addr, off) asm volatile("ds_read_b128 %0, %1 offset:%2" : "=&v"(dst) : "v"(addr), "n"(off) : "memory")
; #define LGKM(n) asm volatile("s_waitcnt lgkmcnt(%0)" ::"n"(n) : "memory")
; __device__ __forceinline__ void attn_phase(char* shm, const Params& p, const u16* __restrict__ qb, const u16* __restrict__ kb,
;                                            const u16* __restrict__ vT, u16* __restrict__ attn) {
;     ...
;         const float df = (float)(kt * 64 + u * 32 + 4 * hh - qpos);
;         bf16x8 P[2][2];
;         bf16x8 kf[2], qf[2];
;         DSR(kf[0], kb_ + kL0, u * 8192); DSR(qf[0], qaddr, 0);
; #pragma unroll
;         for (int c = 0; c < 2; ++c) {
;           f32x16 Sx;
; #pragma unroll
;           for (int i = 0; i < 16; ++i) Sx[i] = -sl2 * fabsf(df + (float)((i & 3) + 8 * (i >> 2)));
; #pragma unroll
;           for (int ks = 0; ks < 4; ++ks) {
;             const int f = c * 4 + ks;
;             if (f < 7) {
;               DSR(kf[(f + 1) & 1], kb_ + (kL0 ^ ((((f + 1) >> 2) * 8 + ((f + 1) & 3) * 2) << 4)), u * 8192);
;               DSR(qf[(f + 1) & 1], qaddr, (f + 1) * 1024);
;               LGKM(2);
;             } else LGKM(0);
;             SCHED();
;             Sx = __builtin_amdgcn_mfma_f32_32x32x16_bf16(kf[f & 1], qf[f & 1], Sx, 0, 0, 0);
;             SCHED();
;           }
.LBB0_299:
	v_cvt_f32_i32_e32 v128, v205
	v_add_u32_e32 v160, s44, v188
	ds_read_b128 v[206:209], v160 offset:0
	ds_read_b128 v[210:213], v185 offset:0
	v_add_u32_e32 v214, s44, v190
	ds_read_b128 v[218:221], v214 offset:0
	ds_read_b128 v[222:225], v185 offset:0x400
	v_add_u32_e32 v215, s44, v191
	ds_read_b128 v[242:245], v215 offset:0
	ds_read_b128 v[246:249], v185 offset:0x800
	v_add_f32_e32 v129, 1.0, v128
	v_add_f32_e64 v130, v128, s12
	v_add_f32_e64 v131, v128, s13
	v_add_f32_e64 v132, v128, s14
	v_add_f32_e64 v133, v128, s15
	v_add_f32_e64 v134, v128, s20
	v_add_f32_e64 v135, v128, s21
	v_add_f32_e64 v136, v128, s22
	v_add_f32_e64 v137, v128, s23
	v_add_f32_e64 v138, v128, s24
	v_add_f32_e64 v139, v128, s25
	v_add_f32_e64 v140, v128, s26
	v_add_f32_e64 v141, v128, s27
	v_add_f32_e64 v142, v128, s28
	v_add_f32_e64 v143, v128, s29
	s_add_i32 s0, s44, 0x4000
	v_mul_f32_e64 v142, v178, |v142|
	v_mul_f32_e64 v143, v179, |v143|
	v_mul_f32_e64 v140, v178, |v140|
	v_mul_f32_e64 v141, v179, |v141|
	v_mul_f32_e64 v138, v178, |v138|
	v_mul_f32_e64 v139, v179, |v139|
	v_mul_f32_e64 v136, v178, |v136|
	v_mul_f32_e64 v137, v179, |v137|
	v_mul_f32_e64 v134, v178, |v134|
	v_mul_f32_e64 v135, v179, |v135|
	v_mul_f32_e64 v132, v178, |v132|
	v_mul_f32_e64 v133, v179, |v133|
	v_mul_f32_e64 v130, v178, |v130|
	v_mul_f32_e64 v131, v179, |v131|
	v_mul_f32_e64 v128, v170, |v128|
	v_mul_f32_e64 v129, v171, |v129|
	s_nop 1
	s_waitcnt lgkmcnt(4)
	v_readfirstlane_b32 s88, v128
	s_cmp_gt_u32 s88, 0xc35c0000
	s_cselect_b32 s89, 1, 0
	v_mfma_f32_32x32x16_bf16 v[144:159], v[206:209], v[210:213], v[128:143]
	v_add_u32_e32 v226, s44, v192
	ds_read_b128 v[206:209], v226 offset:0
	ds_read_b128 v[210:213], v185 offset:0xc00
	s_waitcnt lgkmcnt(4)
	v_mfma_f32_32x32x16_bf16 v[144:159], v[218:221], v[222:225], v[144:159]
	v_add_u32_e32 v227, s44, v193
	ds_read_b128 v[218:221], v227 offset:0
	ds_read_b128 v[222:225], v185 offset:0x1000
	s_waitcnt lgkmcnt(4)
	v_mfma_f32_32x32x16_bf16 v[144:159], v[242:245], v[246:249], v[144:159]
	v_add_u32_e32 v229, s44, v194
	ds_read_b128 v[242:245], v229 offset:0
	ds_read_b128 v[246:249], v185 offset:0x1400
	s_waitcnt lgkmcnt(4)
	v_mfma_f32_32x32x16_bf16 v[144:159], v[206:209], v[210:213], v[144:159]
	v_add_u32_e32 v230, s44, v195
	ds_read_b128 v[206:209], v230 offset:0
	ds_read_b128 v[210:213], v185 offset:0x1800
	s_waitcnt lgkmcnt(4)
	v_mfma_f32_32x32x16_bf16 v[128:143], v[218:221], v[222:225], v[128:143]
	v_add_u32_e32 v232, s44, v196
	ds_read_b128 v[218:221], v232 offset:0
	ds_read_b128 v[222:225], v185 offset:0x1c00
	s_waitcnt lgkmcnt(4)
	v_mfma_f32_32x32x16_bf16 v[128:143], v[242:245], v[246:249], v[128:143]
	s_waitcnt lgkmcnt(2)
	v_mfma_f32_32x32x16_bf16 v[128:143], v[206:209], v[210:213], v[128:143]
	s_waitcnt lgkmcnt(0)
	v_mfma_f32_32x32x16_bf16 v[128:143], v[218:221], v[222:225], v[128:143]
	s_nop 3
	s_cmp_eq_u32 s89, 0
	s_cbranch_scc1 .Lattn_exp_normal_0_0
	v_max3_f32 v240, v144, v145, v146
	v_max3_f32 v240, v240, v147, v148
	v_max3_f32 v240, v240, v149, v150
	v_max3_f32 v240, v240, v151, v152
	v_max3_f32 v240, v240, v153, v154
	v_max3_f32 v240, v240, v155, v156
	v_max3_f32 v240, v240, v157, v158
	v_max_f32_e32 v240, v240, v159
	v_cmp_ngt_f32_e32 vcc, 0xc3180000, v240
	s_and_b64 vcc, exec, vcc
	s_cbranch_vccnz .Lattn_exp_normal_0_0
	v_mov_b32_e32 v144, 0
	v_mov_b32_e32 v145, 0
	v_mov_b32_e32 v146, 0
	v_mov_b32_e32 v147, 0
	v_mov_b32_e32 v148, 0
	v_mov_b32_e32 v149, 0
	v_mov_b32_e32 v150, 0
	v_mov_b32_e32 v151, 0
	s_branch .Lattn_exp_done_0_0

; #define SCHED() __builtin_amdgcn_sched_barrier(0)
; #define DSR(dst, addr, off) asm volatile("ds_read_b128 %0, %1 offset:%2" : "=&v"(dst) : "v"(addr), "n"(off) : "memory")
; #define LGKM(n) asm volatile("s_waitcnt lgkmcnt(%0)" ::"n"(n) : "memory")
; #define DSR(dst, addr, off) asm volatile("ds_read_b128 %0, %1 offset:%2" : "=&v"(dst) : "v"(addr), "n"(off) : "memory")
; #define LGKM(n) asm volatile("s_waitcnt lgkmcnt(%0)" ::"n"(n) : "memory")
; __device__ __forceinline__ void attn_phase(char* shm, const Params& p, const u16* __restrict__ qb, const u16* __restrict__ kb,
;                                            const u16* __restrict__ vT, u16* __restrict__ attn) {
;     ...
;         const float df = (float)(kt * 64 + u * 32 + 4 * hh - qpos);
;         bf16x8 P[2][2];
;         bf16x8 kf[2], qf[2];
;         DSR(kf[0], kb_ + kL0, u * 8192); DSR(qf[0], qaddr, 0);
; #pragma unroll
;         for (int c = 0; c < 2; ++c) {
;           f32x16 Sx;
; #pragma unroll
;           for (int i = 0; i < 16; ++i) Sx[i] = -sl2 * fabsf(df + (float)((i & 3) + 8 * (i >> 2)));
; #pragma unroll
;           for (int ks = 0; ks < 4; ++ks) {
;             const int f = c * 4 + ks;
;             if (f < 7) {
;               DSR(kf[(f + 1) & 1], kb_ + (kL0 ^ ((((f + 1) >> 2) * 8 + ((f + 1) & 3) * 2) << 4)), u * 8192);
;               DSR(qf[(f + 1) & 1], qaddr, (f + 1) * 1024);
;               LGKM(2);
;             } else LGKM(0);
;             SCHED();
;             Sx = __builtin_amdgcn_mfma_f32_32x32x16_bf16(kf[f & 1], qf[f & 1], Sx, 0, 0, 0);
;             SCHED();
;           }
.Lattn_pv_zero_0:
	s_waitcnt lgkmcnt(0)
	v_add_u32_e32 v128, 32, v205
	v_cvt_f32_i32_e32 v128, v128
	ds_read_b128 v[206:209], v160 offset:0x2000
	ds_read_b128 v[210:213], v185 offset:0
	ds_read_b128 v[218:221], v214 offset:0x2000
	ds_read_b128 v[222:225], v185 offset:0x400
	ds_read_b128 v[242:245], v215 offset:0x2000
	ds_read_b128 v[246:249], v185 offset:0x800
	v_add_f32_e32 v129, 1.0, v128
	v_add_f32_e64 v130, v128, s12
	v_add_f32_e64 v131, v128, s13
	v_add_f32_e64 v132, v128, s14
	v_add_f32_e64 v133, v128, s15
	v_add_f32_e64 v134, v128, s20
	v_add_f32_e64 v135, v128, s21
	v_add_f32_e64 v136, v128, s22
	v_add_f32_e64 v137, v128, s23
	v_add_f32_e64 v138, v128, s24
	v_add_f32_e64 v139, v128, s25
	v_add_f32_e64 v140, v128, s26
	v_add_f32_e64 v141, v128, s27
	v_add_f32_e64 v142, v128, s28
	v_add_f32_e64 v143, v128, s29
	v_mul_f32_e64 v142, v178, |v142|
	v_mul_f32_e64 v143, v179, |v143|
	v_mul_f32_e64 v140, v178, |v140|
	v_mul_f32_e64 v141, v179, |v141|
	v_mul_f32_e64 v138, v178, |v138|
	v_mul_f32_e64 v139, v179, |v139|
	v_mul_f32_e64 v136, v178, |v136|
	v_mul_f32_e64 v137, v179, |v137|
	v_mul_f32_e64 v134, v178, |v134|
	v_mul_f32_e64 v135, v179, |v135|
	v_mul_f32_e64 v132, v178, |v132|
	v_mul_f32_e64 v133, v179, |v133|
	v_mul_f32_e64 v130, v178, |v130|
	v_mul_f32_e64 v131, v179, |v131|
	v_mul_f32_e64 v128, v170, |v128|
	v_mul_f32_e64 v129, v171, |v129|
	s_nop 1
	s_waitcnt lgkmcnt(4)
	v_readfirstlane_b32 s88, v128
	s_cmp_gt_u32 s88, 0xc35c0000
	s_cselect_b32 s89, 1, 0
	v_mfma_f32_32x32x16_bf16 v[144:159], v[206:209], v[210:213], v[128:143]
	ds_read_b128 v[206:209], v226 offset:0x2000
	ds_read_b128 v[210:213], v185 offset:0xc00
	s_waitcnt lgkmcnt(4)
	v_mfma_f32_32x32x16_bf16 v[144:159], v[218:221], v[222:225], v[144:159]
	ds_read_b128 v[218:221], v227 offset:0x2000
	ds_read_b128 v[222:225], v185 offset:0x1000
	s_waitcnt lgkmcnt(4)
	v_mfma_f32_32x32x16_bf16 v[144:159], v[242:245], v[246:249], v[144:159]
	ds_read_b128 v[242:245], v229 offset:0x2000
	ds_read_b128 v[246:249], v185 offset:0x1400
	s_waitcnt lgkmcnt(4)
	v_mfma_f32_32x32x16_bf16 v[144:159], v[206:209], v[210:213], v[144:159]
	ds_read_b128 v[206:209], v230 offset:0x2000
	ds_read_b128 v[210:213], v185 offset:0x1800
	s_waitcnt lgkmcnt(4)
	v_mfma_f32_32x32x16_bf16 v[128:143], v[218:221], v[222:225], v[128:143]
	ds_read_b128 v[218:221], v232 offset:0x2000
	ds_read_b128 v[222:225], v185 offset:0x1c00
	s_waitcnt lgkmcnt(4)
	v_mfma_f32_32x32x16_bf16 v[128:143], v[242:245], v[246:249], v[128:143]
	s_waitcnt lgkmcnt(2)
	v_mfma_f32_32x32x16_bf16 v[128:143], v[206:209], v[210:213], v[128:143]
	s_waitcnt lgkmcnt(0)
	v_mfma_f32_32x32x16_bf16 v[128:143], v[218:221], v[222:225], v[128:143]
	s_nop 3
	s_cmp_eq_u32 s89, 0
	s_cbranch_scc1 .Lattn_exp_normal_1_0
	v_max3_f32 v240, v144, v145, v146
	v_max3_f32 v240, v240, v147, v148
	v_max3_f32 v240, v240, v149, v150
	v_max3_f32 v240, v240, v151, v152
	v_max3_f32 v240, v240, v153, v154
	v_max3_f32 v240, v240, v155, v156
	v_max3_f32 v240, v240, v157, v158
	v_max_f32_e32 v240, v240, v159
	v_cmp_ngt_f32_e32 vcc, 0xc3180000, v240
	s_and_b64 vcc, exec, vcc
	s_cbranch_vccnz .Lattn_exp_normal_1_0
	v_mov_b32_e32 v144, 0
	v_mov_b32_e32 v145, 0
	v_mov_b32_e32 v146, 0
	v_mov_b32_e32 v147, 0
	v_mov_b32_e32 v148, 0
	v_mov_b32_e32 v149, 0
	v_mov_b32_e32 v150, 0
	v_mov_b32_e32 v151, 0
	s_branch .Lattn_exp_done_1_0

; #define WAIT_V(n) asm volatile("s_waitcnt vmcnt(%0)" ::"n"(n) : "memory")
; #define SCHED() __builtin_amdgcn_sched_barrier(0)
; #define LGKM(n) asm volatile("s_waitcnt lgkmcnt(%0)" ::"n"(n) : "memory")
; #define STAGE_A(b, h, kt) STAGE_AX(Ag, b, h, kt)
; #define STAGE_B(b, h, kt) STAGE_BX(Bg, b, h, kt)
; #define LDA(b, h) do { const unsigned pa_ = lds0 + SLOTA(b, h) + wr * 8192 + laneoff; _Pragma("unroll") for (int m = 0; m < 4; ++m)   \
;       _Pragma("unroll") for (int k = 0; k < 2; ++k) DSR(At[m][k], pa_, m * 2048 + k * 1024); } while (0)
; #define LDB(dst, b, h) do { const unsigned pb_ = lds0 + SLOTB(b, h) + wc * 4096 + laneoff; _Pragma("unroll") for (int n = 0; n < 2; ++n) \
;       _Pragma("unroll") for (int k = 0; k < 2; ++k) DSR(dst[n][k], pb_, n * 2048 + k * 1024); } while (0)
; #define BAR __builtin_amdgcn_s_barrier()
; #define LGKM(n) asm volatile("s_waitcnt lgkmcnt(%0)" ::"n"(n) : "memory")
; template <int EPI, bool SWP> ...
;     ...
;     LDB(B0, 0, 0); LDA(0, 0); STAGE_A(1, 1, t + 1);
;     LGKM(8); BAR; LGKM(0); SCHED(); MMA(0, 0, B0); BAR; SCHED();
;     LDB(B1, 0, 1); STAGE_B(0, 0, t + 2);
;     BAR; LGKM(0); SCHED(); MMA(0, 1, B1); BAR; SCHED();
;     LDA(0, 1); STAGE_A(0, 0, t + 2);
;     BAR; LGKM(0); SCHED(); MMA(1, 0, B0); BAR; SCHED();
;     STAGE_B(0, 1, t + 2);
;     WAIT_V(6); BAR; SCHED(); MMA(1, 1, B1); BAR; SCHED();
.LBB0_354:
	ds_read_b128 v[130:133], v222 offset:0
	ds_read_b128 v[134:137], v222 offset:0x400
	ds_read_b128 v[138:141], v222 offset:0x800
	ds_read_b128 v[142:145], v222 offset:0xc00
	ds_read_b128 v[146:149], v223 offset:0
	ds_read_b128 v[150:153], v223 offset:0x400
	ds_read_b128 v[154:157], v223 offset:0x800
	ds_read_b128 v[158:161], v223 offset:0xc00
	ds_read_b128 v[162:165], v223 offset:0x1000
	ds_read_b128 v[166:169], v223 offset:0x1400
	ds_read_b128 v[170:173], v223 offset:0x1800
	v_lshl_add_u64 v[194:195], s[48:49], 0, v[214:215]
	s_mov_b32 m0, s69
	ds_read_b128 v[174:177], v223 offset:0x1c00
	v_lshl_add_u64 v[178:179], v[194:195], 0, s[22:23]
	global_load_lds_dwordx4 v[178:179], off
	v_lshl_add_u64 v[178:179], v[194:195], 0, s[24:25]
	s_mov_b32 m0, s70
	s_nop 0
	global_load_lds_dwordx4 v[178:179], off
	s_waitcnt lgkmcnt(8)
	s_barrier
	s_waitcnt lgkmcnt(0)
	v_mfma_f32_16x16x32_bf16 v[124:127], v[130:133], v[146:149], v[124:127]
	v_mfma_f32_16x16x32_bf16 v[120:123], v[138:141], v[146:149], v[120:123]
	v_mfma_f32_16x16x32_bf16 v[116:119], v[130:133], v[154:157], v[116:119]
	v_mfma_f32_16x16x32_bf16 v[112:115], v[138:141], v[154:157], v[112:115]
	v_mfma_f32_16x16x32_bf16 v[108:111], v[130:133], v[162:165], v[108:111]
	v_mfma_f32_16x16x32_bf16 v[104:107], v[138:141], v[162:165], v[104:107]
	v_mfma_f32_16x16x32_bf16 v[100:103], v[130:133], v[170:173], v[100:103]
	v_mfma_f32_16x16x32_bf16 v[96:99], v[138:141], v[170:173], v[96:99]
	v_mfma_f32_16x16x32_bf16 v[124:127], v[134:137], v[150:153], v[124:127]
	v_mfma_f32_16x16x32_bf16 v[120:123], v[142:145], v[150:153], v[120:123]
	v_mfma_f32_16x16x32_bf16 v[116:119], v[134:137], v[158:161], v[116:119]
	v_mfma_f32_16x16x32_bf16 v[112:115], v[142:145], v[158:161], v[112:115]
	v_mfma_f32_16x16x32_bf16 v[108:111], v[134:137], v[166:169], v[108:111]
	v_mfma_f32_16x16x32_bf16 v[104:107], v[142:145], v[166:169], v[104:107]
	v_mfma_f32_16x16x32_bf16 v[100:103], v[134:137], v[174:177], v[100:103]
	v_mfma_f32_16x16x32_bf16 v[96:99], v[142:145], v[174:177], v[96:99]
	s_barrier
	ds_read_b128 v[178:181], v224 offset:0
	ds_read_b128 v[182:185], v224 offset:0x400
	ds_read_b128 v[186:189], v224 offset:0x800
	v_lshl_add_u64 v[196:197], s[50:51], 0, v[214:215]
	s_mov_b64 s[58:59], 0xe000100
	s_mov_b32 m0, s16
	ds_read_b128 v[190:193], v224 offset:0xc00
	v_lshl_add_u64 v[198:199], v[196:197], 0, s[58:59]
	s_mov_b64 s[58:59], 0xe020100
	global_load_lds_dwordx4 v[198:199], off
	v_lshl_add_u64 v[198:199], v[196:197], 0, s[58:59]
	s_mov_b32 m0, s17
	s_nop 0
	global_load_lds_dwordx4 v[198:199], off
	s_barrier
	s_waitcnt lgkmcnt(0)
	v_mfma_f32_16x16x32_bf16 v[92:95], v[178:181], v[146:149], v[92:95]
	v_mfma_f32_16x16x32_bf16 v[88:91], v[186:189], v[146:149], v[88:91]
	v_mfma_f32_16x16x32_bf16 v[84:87], v[178:181], v[154:157], v[84:87]
	v_mfma_f32_16x16x32_bf16 v[80:83], v[186:189], v[154:157], v[80:83]
	v_mfma_f32_16x16x32_bf16 v[76:79], v[178:181], v[162:165], v[76:79]
	v_mfma_f32_16x16x32_bf16 v[72:75], v[186:189], v[162:165], v[72:75]
	v_mfma_f32_16x16x32_bf16 v[68:71], v[178:181], v[170:173], v[68:71]
	v_mfma_f32_16x16x32_bf16 v[64:67], v[186:189], v[170:173], v[64:67]
	v_mfma_f32_16x16x32_bf16 v[92:95], v[182:185], v[150:153], v[92:95]
	v_mfma_f32_16x16x32_bf16 v[88:91], v[190:193], v[150:153], v[88:91]
	v_mfma_f32_16x16x32_bf16 v[84:87], v[182:185], v[158:161], v[84:87]
	v_mfma_f32_16x16x32_bf16 v[80:83], v[190:193], v[158:161], v[80:83]
	v_mfma_f32_16x16x32_bf16 v[76:79], v[182:185], v[166:169], v[76:79]
	v_mfma_f32_16x16x32_bf16 v[72:75], v[190:193], v[166:169], v[72:75]
	v_mfma_f32_16x16x32_bf16 v[68:71], v[182:185], v[174:177], v[68:71]
	v_mfma_f32_16x16x32_bf16 v[64:67], v[190:193], v[174:177], v[64:67]
	s_barrier
	ds_read_b128 v[146:149], v225 offset:0
	ds_read_b128 v[150:153], v225 offset:0x400
	ds_read_b128 v[154:157], v225 offset:0x800
	ds_read_b128 v[158:161], v225 offset:0xc00
	ds_read_b128 v[162:165], v225 offset:0x1000
	ds_read_b128 v[166:169], v225 offset:0x1400
	ds_read_b128 v[170:173], v225 offset:0x1800
	s_mov_b64 s[58:59], 0x100
	s_mov_b32 m0, s3
	ds_read_b128 v[174:177], v225 offset:0x1c00
	v_lshl_add_u64 v[198:199], v[194:195], 0, s[58:59]
	s_mov_b64 s[58:59], 0x20100
	global_load_lds_dwordx4 v[198:199], off
	v_lshl_add_u64 v[198:199], v[194:195], 0, s[58:59]
	s_mov_b32 m0, s18
	s_nop 0
	global_load_lds_dwordx4 v[198:199], off
	s_barrier
	s_waitcnt lgkmcnt(0)
	v_mfma_f32_16x16x32_bf16 v[60:63], v[130:133], v[146:149], v[60:63]
	v_mfma_f32_16x16x32_bf16 v[56:59], v[138:141], v[146:149], v[56:59]
	v_mfma_f32_16x16x32_bf16 v[52:55], v[130:133], v[154:157], v[52:55]
	v_mfma_f32_16x16x32_bf16 v[48:51], v[138:141], v[154:157], v[48:51]
	v_mfma_f32_16x16x32_bf16 v[44:47], v[130:133], v[162:165], v[44:47]
	v_mfma_f32_16x16x32_bf16 v[40:43], v[138:141], v[162:165], v[40:43]
	v_mfma_f32_16x16x32_bf16 v[36:39], v[130:133], v[170:173], v[36:39]
	v_mfma_f32_16x16x32_bf16 v[32:35], v[138:141], v[170:173], v[32:35]
	v_mfma_f32_16x16x32_bf16 v[60:63], v[134:137], v[150:153], v[60:63]
	v_mfma_f32_16x16x32_bf16 v[56:59], v[142:145], v[150:153], v[56:59]
	v_mfma_f32_16x16x32_bf16 v[52:55], v[134:137], v[158:161], v[52:55]
	v_mfma_f32_16x16x32_bf16 v[48:51], v[142:145], v[158:161], v[48:51]
	v_mfma_f32_16x16x32_bf16 v[44:47], v[134:137], v[166:169], v[44:47]
	v_mfma_f32_16x16x32_bf16 v[40:43], v[142:145], v[166:169], v[40:43]
	v_mfma_f32_16x16x32_bf16 v[36:39], v[134:137], v[174:177], v[36:39]
	v_mfma_f32_16x16x32_bf16 v[32:35], v[142:145], v[174:177], v[32:35]
	s_barrier
; #define WAIT_V(n) asm volatile("s_waitcnt vmcnt(%0)" ::"n"(n) : "memory")
; #define SCHED() __builtin_amdgcn_sched_barrier(0)
; #define LGKM(n) asm volatile("s_waitcnt lgkmcnt(%0)" ::"n"(n) : "memory")
; #define STAGE_A(b, h, kt) STAGE_AX(Ag, b, h, kt)
; #define STAGE_B(b, h, kt) STAGE_BX(Bg, b, h, kt)
; #define LDA(b, h) do { const unsigned pa_ = lds0 + SLOTA(b, h) + wr * 8192 + laneoff; _Pragma("unroll") for (int m = 0; m < 4; ++m)   \
;       _Pragma("unroll") for (int k = 0; k < 2; ++k) DSR(At[m][k], pa_, m * 2048 + k * 1024); } while (0)
; #define LDB(dst, b, h) do { const unsigned pb_ = lds0 + SLOTB(b, h) + wc * 4096 + laneoff; _Pragma("unroll") for (int n = 0; n < 2; ++n) \
;       _Pragma("unroll") for (int k = 0; k < 2; ++k) DSR(dst[n][k], pb_, n * 2048 + k * 1024); } while (0)
; #define BAR __builtin_amdgcn_s_barrier()
; #define LGKM(n) asm volatile("s_waitcnt lgkmcnt(%0)" ::"n"(n) : "memory")
; template <int EPI, bool SWP> ...
;     ...
;     WAIT_V(6); BAR; SCHED(); MMA(1, 1, B1); BAR; SCHED();
;     LDB(B0, 1, 0); LDA(1, 0); STAGE_A(0, 1, t + 2);
;     LGKM(8); BAR; LGKM(0); SCHED(); MMA(0, 0, B0); BAR; SCHED();
;     LDB(B1, 1, 1); STAGE_B(1, 0, t + 3);
;     BAR; LGKM(0); SCHED(); MMA(0, 1, B1); BAR; SCHED();
;     LDA(1, 1); STAGE_A(1, 0, t + 3);
	s_mov_b64 s[58:59], 0xe040100
	s_mov_b32 m0, s19
	v_lshl_add_u64 v[130:131], v[196:197], 0, s[58:59]
	s_mov_b64 s[58:59], 0xe060100
	global_load_lds_dwordx4 v[130:131], off
	v_lshl_add_u64 v[130:131], v[196:197], 0, s[58:59]
	s_mov_b32 m0, s60
	s_nop 0
	global_load_lds_dwordx4 v[130:131], off
	s_waitcnt vmcnt(6)
	s_barrier
	v_mfma_f32_16x16x32_bf16 v[28:31], v[178:181], v[146:149], v[28:31]
	v_mfma_f32_16x16x32_bf16 v[24:27], v[186:189], v[146:149], v[24:27]
	v_mfma_f32_16x16x32_bf16 v[20:23], v[178:181], v[154:157], v[20:23]
	v_mfma_f32_16x16x32_bf16 v[16:19], v[186:189], v[154:157], v[16:19]
	v_mfma_f32_16x16x32_bf16 v[12:15], v[178:181], v[162:165], v[12:15]
	v_mfma_f32_16x16x32_bf16 v[8:11], v[186:189], v[162:165], v[8:11]
	v_mfma_f32_16x16x32_bf16 v[4:7], v[178:181], v[170:173], v[4:7]
	v_mfma_f32_16x16x32_bf16 v[0:3], v[186:189], v[170:173], v[0:3]
	v_mfma_f32_16x16x32_bf16 v[28:31], v[182:185], v[150:153], v[28:31]
	v_mfma_f32_16x16x32_bf16 v[24:27], v[190:193], v[150:153], v[24:27]
	v_mfma_f32_16x16x32_bf16 v[20:23], v[182:185], v[158:161], v[20:23]
	v_mfma_f32_16x16x32_bf16 v[16:19], v[190:193], v[158:161], v[16:19]
	v_mfma_f32_16x16x32_bf16 v[12:15], v[182:185], v[166:169], v[12:15]
	v_mfma_f32_16x16x32_bf16 v[8:11], v[190:193], v[166:169], v[8:11]
	v_mfma_f32_16x16x32_bf16 v[4:7], v[182:185], v[174:177], v[4:7]
	v_mfma_f32_16x16x32_bf16 v[0:3], v[190:193], v[174:177], v[0:3]
	s_barrier
	ds_read_b128 v[130:133], v226 offset:0
	ds_read_b128 v[134:137], v226 offset:0x400
	ds_read_b128 v[138:141], v226 offset:0x800
	ds_read_b128 v[142:145], v226 offset:0xc00
	ds_read_b128 v[146:149], v227 offset:0
	ds_read_b128 v[150:153], v227 offset:0x400
	ds_read_b128 v[154:157], v227 offset:0x800
	ds_read_b128 v[158:161], v227 offset:0xc00
	ds_read_b128 v[162:165], v227 offset:0x1000
	ds_read_b128 v[166:169], v227 offset:0x1400
	ds_read_b128 v[170:173], v227 offset:0x1800
	s_mov_b64 s[58:59], 0x40100
	s_mov_b32 m0, s61
	ds_read_b128 v[174:177], v227 offset:0x1c00
	v_lshl_add_u64 v[178:179], v[194:195], 0, s[58:59]
	s_mov_b64 s[58:59], 0x60100
	global_load_lds_dwordx4 v[178:179], off
	v_lshl_add_u64 v[178:179], v[194:195], 0, s[58:59]
	s_mov_b32 m0, s62
	s_nop 0
	global_load_lds_dwordx4 v[178:179], off
	s_waitcnt lgkmcnt(8)
	s_barrier
	s_waitcnt lgkmcnt(0)
	v_mfma_f32_16x16x32_bf16 v[124:127], v[130:133], v[146:149], v[124:127]
	v_mfma_f32_16x16x32_bf16 v[120:123], v[138:141], v[146:149], v[120:123]
	v_mfma_f32_16x16x32_bf16 v[116:119], v[130:133], v[154:157], v[116:119]
	v_mfma_f32_16x16x32_bf16 v[112:115], v[138:141], v[154:157], v[112:115]
	v_mfma_f32_16x16x32_bf16 v[108:111], v[130:133], v[162:165], v[108:111]
	v_mfma_f32_16x16x32_bf16 v[104:107], v[138:141], v[162:165], v[104:107]
	v_mfma_f32_16x16x32_bf16 v[100:103], v[130:133], v[170:173], v[100:103]
	v_mfma_f32_16x16x32_bf16 v[96:99], v[138:141], v[170:173], v[96:99]
	v_mfma_f32_16x16x32_bf16 v[124:127], v[134:137], v[150:153], v[124:127]
	v_mfma_f32_16x16x32_bf16 v[120:123], v[142:145], v[150:153], v[120:123]
	v_mfma_f32_16x16x32_bf16 v[116:119], v[134:137], v[158:161], v[116:119]
	v_mfma_f32_16x16x32_bf16 v[112:115], v[142:145], v[158:161], v[112:115]
	v_mfma_f32_16x16x32_bf16 v[108:111], v[134:137], v[166:169], v[108:111]
	v_mfma_f32_16x16x32_bf16 v[104:107], v[142:145], v[166:169], v[104:107]
	v_mfma_f32_16x16x32_bf16 v[100:103], v[134:137], v[174:177], v[100:103]
	v_mfma_f32_16x16x32_bf16 v[96:99], v[142:145], v[174:177], v[96:99]
	s_barrier
	ds_read_b128 v[178:181], v229 offset:0
	ds_read_b128 v[182:185], v229 offset:0x400
	ds_read_b128 v[186:189], v229 offset:0x800
	s_mov_b64 s[58:59], 0xe000180
	s_mov_b32 m0, s63
	ds_read_b128 v[190:193], v229 offset:0xc00
	v_lshl_add_u64 v[198:199], v[196:197], 0, s[58:59]
	s_mov_b64 s[58:59], 0xe020180
	global_load_lds_dwordx4 v[198:199], off
	v_lshl_add_u64 v[198:199], v[196:197], 0, s[58:59]
	s_mov_b32 m0, s64
	s_nop 0
	global_load_lds_dwordx4 v[198:199], off
	s_barrier
	s_waitcnt lgkmcnt(0)
	v_mfma_f32_16x16x32_bf16 v[92:95], v[178:181], v[146:149], v[92:95]
	v_mfma_f32_16x16x32_bf16 v[88:91], v[186:189], v[146:149], v[88:91]
	v_mfma_f32_16x16x32_bf16 v[84:87], v[178:181], v[154:157], v[84:87]
	v_mfma_f32_16x16x32_bf16 v[80:83], v[186:189], v[154:157], v[80:83]
	v_mfma_f32_16x16x32_bf16 v[76:79], v[178:181], v[162:165], v[76:79]
	v_mfma_f32_16x16x32_bf16 v[72:75], v[186:189], v[162:165], v[72:75]
	v_mfma_f32_16x16x32_bf16 v[68:71], v[178:181], v[170:173], v[68:71]
	v_mfma_f32_16x16x32_bf16 v[64:67], v[186:189], v[170:173], v[64:67]
	v_mfma_f32_16x16x32_bf16 v[92:95], v[182:185], v[150:153], v[92:95]
	v_mfma_f32_16x16x32_bf16 v[88:91], v[190:193], v[150:153], v[88:91]
	v_mfma_f32_16x16x32_bf16 v[84:87], v[182:185], v[158:161], v[84:87]
	v_mfma_f32_16x16x32_bf16 v[80:83], v[190:193], v[158:161], v[80:83]
	v_mfma_f32_16x16x32_bf16 v[76:79], v[182:185], v[166:169], v[76:79]
	v_mfma_f32_16x16x32_bf16 v[72:75], v[190:193], v[166:169], v[72:75]
	v_mfma_f32_16x16x32_bf16 v[68:71], v[182:185], v[174:177], v[68:71]
	v_mfma_f32_16x16x32_bf16 v[64:67], v[190:193], v[174:177], v[64:67]
	s_barrier
	ds_read_b128 v[146:149], v230 offset:0
	ds_read_b128 v[150:153], v230 offset:0x400
	ds_read_b128 v[154:157], v230 offset:0x800
	ds_read_b128 v[158:161], v230 offset:0xc00
	ds_read_b128 v[162:165], v230 offset:0x1000
	ds_read_b128 v[166:169], v230 offset:0x1400
	ds_read_b128 v[170:173], v230 offset:0x1800
	s_mov_b64 s[58:59], 0x180
	s_mov_b32 m0, s65
	ds_read_b128 v[174:177], v230 offset:0x1c00
	v_lshl_add_u64 v[198:199], v[194:195], 0, s[58:59]
	s_mov_b64 s[58:59], 0x20180
	global_load_lds_dwordx4 v[198:199], off
	v_lshl_add_u64 v[194:195], v[194:195], 0, s[58:59]
	s_mov_b32 m0, s66
	s_nop 0
	global_load_lds_dwordx4 v[194:195], off
	s_barrier
; #define WAIT_V(n) asm volatile("s_waitcnt vmcnt(%0)" ::"n"(n) : "memory")
; #define SCHED() __builtin_amdgcn_sched_barrier(0)
; #define LGKM(n) asm volatile("s_waitcnt lgkmcnt(%0)" ::"n"(n) : "memory")
; #define STAGE_A(b, h, kt) STAGE_AX(Ag, b, h, kt)
; #define STAGE_B(b, h, kt) STAGE_BX(Bg, b, h, kt)
; #define LDA(b, h) do { const unsigned pa_ = lds0 + SLOTA(b, h) + wr * 8192 + laneoff; _Pragma("unroll") for (int m = 0; m < 4; ++m)   \
;       _Pragma("unroll") for (int k = 0; k < 2; ++k) DSR(At[m][k], pa_, m * 2048 + k * 1024); } while (0)
; #define LDB(dst, b, h) do { const unsigned pb_ = lds0 + SLOTB(b, h) + wc * 4096 + laneoff; _Pragma("unroll") for (int n = 0; n < 2; ++n) \
;       _Pragma("unroll") for (int k = 0; k < 2; ++k) DSR(dst[n][k], pb_, n * 2048 + k * 1024); } while (0)
; #define BAR __builtin_amdgcn_s_barrier()
; #define LGKM(n) asm volatile("s_waitcnt lgkmcnt(%0)" ::"n"(n) : "memory")
; template <int EPI, bool SWP> ...
;     ...
;     BAR; LGKM(0); SCHED(); MMA(1, 0, B0); BAR; SCHED();
;     STAGE_B(1, 1, t + 3);
;     WAIT_V(6); BAR; SCHED(); MMA(1, 1, B1); BAR; SCHED();
;   }
;   { LDB(B0, 0, 0); LDA(0, 0); STAGE_A(1, 1, nt - 1);
;     BAR; LGKM(0); SCHED(); MMA(0, 0, B0); BAR; SCHED();
;     LDB(B1, 0, 1); BAR; LGKM(0); SCHED(); MMA(0, 1, B1); BAR; SCHED();
	s_waitcnt lgkmcnt(0)
	v_mfma_f32_16x16x32_bf16 v[60:63], v[130:133], v[146:149], v[60:63]
	v_mfma_f32_16x16x32_bf16 v[56:59], v[138:141], v[146:149], v[56:59]
	v_mfma_f32_16x16x32_bf16 v[52:55], v[130:133], v[154:157], v[52:55]
	v_mfma_f32_16x16x32_bf16 v[48:51], v[138:141], v[154:157], v[48:51]
	v_mfma_f32_16x16x32_bf16 v[44:47], v[130:133], v[162:165], v[44:47]
	v_mfma_f32_16x16x32_bf16 v[40:43], v[138:141], v[162:165], v[40:43]
	v_mfma_f32_16x16x32_bf16 v[36:39], v[130:133], v[170:173], v[36:39]
	v_mfma_f32_16x16x32_bf16 v[32:35], v[138:141], v[170:173], v[32:35]
	v_mfma_f32_16x16x32_bf16 v[60:63], v[134:137], v[150:153], v[60:63]
	v_mfma_f32_16x16x32_bf16 v[56:59], v[142:145], v[150:153], v[56:59]
	v_mfma_f32_16x16x32_bf16 v[52:55], v[134:137], v[158:161], v[52:55]
	v_mfma_f32_16x16x32_bf16 v[48:51], v[142:145], v[158:161], v[48:51]
	v_mfma_f32_16x16x32_bf16 v[44:47], v[134:137], v[166:169], v[44:47]
	v_mfma_f32_16x16x32_bf16 v[40:43], v[142:145], v[166:169], v[40:43]
	v_mfma_f32_16x16x32_bf16 v[36:39], v[134:137], v[174:177], v[36:39]
	v_mfma_f32_16x16x32_bf16 v[32:35], v[142:145], v[174:177], v[32:35]
	s_barrier
	s_mov_b64 s[58:59], 0xe040180
	s_mov_b32 m0, s67
	v_lshl_add_u64 v[130:131], v[196:197], 0, s[58:59]
	s_mov_b64 s[58:59], 0xe060180
	global_load_lds_dwordx4 v[130:131], off
	v_lshl_add_u64 v[130:131], v[196:197], 0, s[58:59]
	s_mov_b32 m0, s68
	s_nop 0
	global_load_lds_dwordx4 v[130:131], off
	s_waitcnt vmcnt(6)
	s_barrier
	v_mfma_f32_16x16x32_bf16 v[28:31], v[178:181], v[146:149], v[28:31]
	v_mfma_f32_16x16x32_bf16 v[24:27], v[186:189], v[146:149], v[24:27]
	v_mfma_f32_16x16x32_bf16 v[20:23], v[178:181], v[154:157], v[20:23]
	v_mfma_f32_16x16x32_bf16 v[16:19], v[186:189], v[154:157], v[16:19]
	v_mfma_f32_16x16x32_bf16 v[12:15], v[178:181], v[162:165], v[12:15]
	v_mfma_f32_16x16x32_bf16 v[8:11], v[186:189], v[162:165], v[8:11]
	v_mfma_f32_16x16x32_bf16 v[4:7], v[178:181], v[170:173], v[4:7]
	v_mfma_f32_16x16x32_bf16 v[0:3], v[186:189], v[170:173], v[0:3]
	v_mfma_f32_16x16x32_bf16 v[28:31], v[182:185], v[150:153], v[28:31]
	v_mfma_f32_16x16x32_bf16 v[24:27], v[190:193], v[150:153], v[24:27]
	v_mfma_f32_16x16x32_bf16 v[20:23], v[182:185], v[158:161], v[20:23]
	v_mfma_f32_16x16x32_bf16 v[16:19], v[190:193], v[158:161], v[16:19]
	v_mfma_f32_16x16x32_bf16 v[12:15], v[182:185], v[166:169], v[12:15]
	v_mfma_f32_16x16x32_bf16 v[8:11], v[190:193], v[166:169], v[8:11]
	v_mfma_f32_16x16x32_bf16 v[4:7], v[182:185], v[174:177], v[4:7]
	v_mfma_f32_16x16x32_bf16 v[0:3], v[190:193], v[174:177], v[0:3]
	s_add_i32 s35, s35, 2
	s_add_u32 s50, s50, 0x100
	s_addc_u32 s51, s51, 0
	s_add_u32 s48, s48, 0x100
	s_addc_u32 s49, s49, 0
	s_cmp_gt_u32 s35, 11
	s_barrier
	s_cbranch_scc0 .LBB0_354
	ds_read_b128 v[140:143], v222 offset:0
	ds_read_b128 v[144:147], v222 offset:0x400
	ds_read_b128 v[148:151], v222 offset:0x800
	ds_read_b128 v[152:155], v222 offset:0xc00
	ds_read_b128 v[130:133], v223 offset:0
	ds_read_b128 v[134:137], v223 offset:0x400
	ds_read_b128 v[156:159], v223 offset:0x800
	ds_read_b128 v[160:163], v223 offset:0xc00
	ds_read_b128 v[164:167], v223 offset:0x1000
	ds_read_b128 v[168:171], v223 offset:0x1400
	ds_read_b128 v[172:175], v223 offset:0x1800
	s_mov_b64 s[48:49], 0x40780
	s_mov_b32 m0, s69
	ds_read_b128 v[176:179], v223 offset:0x1c00
	v_lshl_add_u64 v[138:139], v[128:129], 0, s[48:49]
	global_load_lds_dwordx4 v[138:139], off
	v_lshl_add_u64 v[128:129], v[128:129], 0, s[26:27]
	s_mov_b32 m0, s70
	s_ashr_i32 s39, s38, 31
	global_load_lds_dwordx4 v[128:129], off
	s_lshl_b64 s[48:49], s[38:39], 19
	s_add_u32 s48, s56, s48
	s_addc_u32 s49, s57, s49
	s_ashr_i32 s35, s34, 31
	s_barrier
	s_waitcnt lgkmcnt(0)
	s_lshl_b64 s[50:51], s[34:35], 19
	v_readlane_b32 s58, v254, 30
	v_readlane_b32 s59, v254, 31
	s_add_u32 s50, s58, s50
	s_addc_u32 s51, s59, s51
	v_mfma_f32_16x16x32_bf16 v[124:127], v[140:143], v[130:133], v[124:127]
	v_mfma_f32_16x16x32_bf16 v[120:123], v[148:151], v[130:133], v[120:123]
	v_mfma_f32_16x16x32_bf16 v[116:119], v[140:143], v[156:159], v[116:119]
	v_mfma_f32_16x16x32_bf16 v[112:115], v[148:151], v[156:159], v[112:115]
	v_mfma_f32_16x16x32_bf16 v[108:111], v[140:143], v[164:167], v[108:111]
	v_mfma_f32_16x16x32_bf16 v[104:107], v[148:151], v[164:167], v[104:107]
	v_mfma_f32_16x16x32_bf16 v[100:103], v[140:143], v[172:175], v[100:103]
	v_mfma_f32_16x16x32_bf16 v[96:99], v[148:151], v[172:175], v[96:99]
	v_mfma_f32_16x16x32_bf16 v[124:127], v[144:147], v[134:137], v[124:127]
	v_mfma_f32_16x16x32_bf16 v[180:183], v[152:155], v[134:137], v[120:123]
	v_mfma_f32_16x16x32_bf16 v[116:119], v[144:147], v[160:163], v[116:119]
	v_mfma_f32_16x16x32_bf16 v[184:187], v[152:155], v[160:163], v[112:115]
	v_mfma_f32_16x16x32_bf16 v[108:111], v[144:147], v[168:171], v[108:111]
	v_mfma_f32_16x16x32_bf16 v[188:191], v[152:155], v[168:171], v[104:107]
	v_mfma_f32_16x16x32_bf16 v[100:103], v[144:147], v[176:179], v[100:103]
	v_mfma_f32_16x16x32_bf16 v[192:195], v[152:155], v[176:179], v[96:99]
	s_barrier
	ds_read_b128 v[96:99], v224 offset:0
	ds_read_b128 v[104:107], v224 offset:0x400
	ds_read_b128 v[112:115], v224 offset:0x800
	ds_read_b128 v[120:123], v224 offset:0xc00
	s_barrier
; #define WAIT_V(n) asm volatile("s_waitcnt vmcnt(%0)" ::"n"(n) : "memory")
; #define SCHED() __builtin_amdgcn_sched_barrier(0)
; #define LGKM(n) asm volatile("s_waitcnt lgkmcnt(%0)" ::"n"(n) : "memory")
; #define LDA(b, h) do { const unsigned pa_ = lds0 + SLOTA(b, h) + wr * 8192 + laneoff; _Pragma("unroll") for (int m = 0; m < 4; ++m)   \
;       _Pragma("unroll") for (int k = 0; k < 2; ++k) DSR(At[m][k], pa_, m * 2048 + k * 1024); } while (0)
; #define LDB(dst, b, h) do { const unsigned pb_ = lds0 + SLOTB(b, h) + wc * 4096 + laneoff; _Pragma("unroll") for (int n = 0; n < 2; ++n) \
;       _Pragma("unroll") for (int k = 0; k < 2; ++k) DSR(dst[n][k], pb_, n * 2048 + k * 1024); } while (0)
; #define BAR __builtin_amdgcn_s_barrier()
; #define LGKM(n) asm volatile("s_waitcnt lgkmcnt(%0)" ::"n"(n) : "memory")
; template <int EPI, bool SWP> ...
;     ...
;     LDA(0, 1); WAIT_V(4); BAR; LGKM(0); SCHED(); MMA(1, 0, B0); MMA(1, 1, B1); BAR; SCHED(); }
;   { LDB(B0, 1, 0); LDA(1, 0); WAIT_V(2); BAR; LGKM(0); SCHED(); MMA(0, 0, B0); BAR; SCHED();
	s_waitcnt lgkmcnt(0)
	v_mfma_f32_16x16x32_bf16 v[92:95], v[96:99], v[130:133], v[92:95]
	v_mfma_f32_16x16x32_bf16 v[88:91], v[112:115], v[130:133], v[88:91]
	v_mfma_f32_16x16x32_bf16 v[84:87], v[96:99], v[156:159], v[84:87]
	v_mfma_f32_16x16x32_bf16 v[80:83], v[112:115], v[156:159], v[80:83]
	v_mfma_f32_16x16x32_bf16 v[76:79], v[96:99], v[164:167], v[76:79]
	v_mfma_f32_16x16x32_bf16 v[72:75], v[112:115], v[164:167], v[72:75]
	v_mfma_f32_16x16x32_bf16 v[68:71], v[96:99], v[172:175], v[68:71]
	v_mfma_f32_16x16x32_bf16 v[64:67], v[112:115], v[172:175], v[64:67]
	v_mfma_f32_16x16x32_bf16 v[92:95], v[104:107], v[134:137], v[92:95]
	v_mfma_f32_16x16x32_bf16 v[196:199], v[120:123], v[134:137], v[88:91]
	v_mfma_f32_16x16x32_bf16 v[84:87], v[104:107], v[160:163], v[84:87]
	v_mfma_f32_16x16x32_bf16 v[200:203], v[120:123], v[160:163], v[80:83]
	v_mfma_f32_16x16x32_bf16 v[76:79], v[104:107], v[168:171], v[76:79]
	v_mfma_f32_16x16x32_bf16 v[204:207], v[120:123], v[168:171], v[72:75]
	v_mfma_f32_16x16x32_bf16 v[68:71], v[104:107], v[176:179], v[68:71]
	v_mfma_f32_16x16x32_bf16 v[176:179], v[120:123], v[176:179], v[64:67]
	s_barrier
	ds_read_b128 v[64:67], v225 offset:0
	ds_read_b128 v[72:75], v225 offset:0x400
	ds_read_b128 v[80:83], v225 offset:0x800
	ds_read_b128 v[88:91], v225 offset:0xc00
	ds_read_b128 v[156:159], v225 offset:0x1000
	ds_read_b128 v[160:163], v225 offset:0x1400
	ds_read_b128 v[164:167], v225 offset:0x1800
	ds_read_b128 v[168:171], v225 offset:0x1c00
	s_waitcnt vmcnt(4)
	s_barrier
	s_waitcnt lgkmcnt(0)
	v_mfma_f32_16x16x32_bf16 v[60:63], v[140:143], v[64:67], v[60:63]
	v_mfma_f32_16x16x32_bf16 v[56:59], v[148:151], v[64:67], v[56:59]
	v_mfma_f32_16x16x32_bf16 v[52:55], v[140:143], v[80:83], v[52:55]
	v_mfma_f32_16x16x32_bf16 v[48:51], v[148:151], v[80:83], v[48:51]
	v_mfma_f32_16x16x32_bf16 v[44:47], v[140:143], v[156:159], v[44:47]
	v_mfma_f32_16x16x32_bf16 v[40:43], v[148:151], v[156:159], v[40:43]
	v_mfma_f32_16x16x32_bf16 v[36:39], v[140:143], v[164:167], v[36:39]
	v_mfma_f32_16x16x32_bf16 v[32:35], v[148:151], v[164:167], v[32:35]
	v_mfma_f32_16x16x32_bf16 v[60:63], v[144:147], v[72:75], v[60:63]
	v_mfma_f32_16x16x32_bf16 v[128:131], v[152:155], v[72:75], v[56:59]
	v_mfma_f32_16x16x32_bf16 v[52:55], v[144:147], v[88:91], v[52:55]
	v_mfma_f32_16x16x32_bf16 v[132:135], v[152:155], v[88:91], v[48:51]
	v_mfma_f32_16x16x32_bf16 v[44:47], v[144:147], v[160:163], v[44:47]
	v_mfma_f32_16x16x32_bf16 v[136:139], v[152:155], v[160:163], v[40:43]
	v_mfma_f32_16x16x32_bf16 v[36:39], v[144:147], v[168:171], v[36:39]
	v_mfma_f32_16x16x32_bf16 v[140:143], v[152:155], v[168:171], v[32:35]
	v_mfma_f32_16x16x32_bf16 v[28:31], v[96:99], v[64:67], v[28:31]
	v_mfma_f32_16x16x32_bf16 v[24:27], v[112:115], v[64:67], v[24:27]
	v_mfma_f32_16x16x32_bf16 v[20:23], v[96:99], v[80:83], v[20:23]
	v_mfma_f32_16x16x32_bf16 v[16:19], v[112:115], v[80:83], v[16:19]
	v_mfma_f32_16x16x32_bf16 v[12:15], v[96:99], v[156:159], v[12:15]
	v_mfma_f32_16x16x32_bf16 v[8:11], v[112:115], v[156:159], v[8:11]
	v_mfma_f32_16x16x32_bf16 v[4:7], v[96:99], v[164:167], v[4:7]
	v_mfma_f32_16x16x32_bf16 v[0:3], v[112:115], v[164:167], v[0:3]
	v_mfma_f32_16x16x32_bf16 v[28:31], v[104:107], v[72:75], v[28:31]
	v_mfma_f32_16x16x32_bf16 v[144:147], v[120:123], v[72:75], v[24:27]
	v_mfma_f32_16x16x32_bf16 v[20:23], v[104:107], v[88:91], v[20:23]
	v_mfma_f32_16x16x32_bf16 v[148:151], v[120:123], v[88:91], v[16:19]
	v_mfma_f32_16x16x32_bf16 v[12:15], v[104:107], v[160:163], v[12:15]
	v_mfma_f32_16x16x32_bf16 v[152:155], v[120:123], v[160:163], v[8:11]
	v_mfma_f32_16x16x32_bf16 v[4:7], v[104:107], v[168:171], v[4:7]
	v_mfma_f32_16x16x32_bf16 v[156:159], v[120:123], v[168:171], v[0:3]
	s_barrier
	ds_read_b128 v[0:3], v226 offset:0
	ds_read_b128 v[8:11], v226 offset:0x400
	ds_read_b128 v[16:19], v226 offset:0x800
	ds_read_b128 v[24:27], v226 offset:0xc00
	ds_read_b128 v[32:35], v227 offset:0
	ds_read_b128 v[40:43], v227 offset:0x400
	ds_read_b128 v[48:51], v227 offset:0x800
	ds_read_b128 v[56:59], v227 offset:0xc00
	ds_read_b128 v[64:67], v227 offset:0x1000
	ds_read_b128 v[218:221], v227 offset:0x1400
	ds_read_b128 v[236:239], v227 offset:0x1800
	ds_read_b128 v[240:243], v227 offset:0x1c00
	s_waitcnt vmcnt(2)
	s_barrier
; #define WAIT_V(n) asm volatile("s_waitcnt vmcnt(%0)" ::"n"(n) : "memory")
; #define SCHED() __builtin_amdgcn_sched_barrier(0)
; #define LGKM(n) asm volatile("s_waitcnt lgkmcnt(%0)" ::"n"(n) : "memory")
; #define STAGE_AX(AG, b, h, kt) do { _Pragma("unroll") for (int i = 0; i < 2; ++i)                                    \
;       __builtin_amdgcn_global_load_lds((const unsigned*)(((AG) + ((size_t)(kt) * (BK * 2) + (size_t)((h) * 2 + i) * 128 * lda)) + aoff), \
;                                        (unsigned*)(shm + SLOTA(b, h) + wid * 1024 + i * 8192), 16, 0, 0); } while (0)
; #define STAGE_BX(BG, b, h, kt) do { _Pragma("unroll") for (int i = 0; i < 2; ++i)                                    \
;       __builtin_amdgcn_global_load_lds((const unsigned*)(((BG) + ((size_t)(kt) * (BK * 2) + (size_t)((h) * 2 + i) * 128 * K)) + boff),   \
;                                        (unsigned*)(shm + SLOTB(b, h) + wid * 1024 + i * 8192), 16, 0, 0); } while (0)
; #define LDA(b, h) do { const unsigned pa_ = lds0 + SLOTA(b, h) + wr * 8192 + laneoff; _Pragma("unroll") for (int m = 0; m < 4; ++m)   \
;       _Pragma("unroll") for (int k = 0; k < 2; ++k) DSR(At[m][k], pa_, m * 2048 + k * 1024); } while (0)
; #define LDB(dst, b, h) do { const unsigned pb_ = lds0 + SLOTB(b, h) + wc * 4096 + laneoff; _Pragma("unroll") for (int n = 0; n < 2; ++n) \
;       _Pragma("unroll") for (int k = 0; k < 2; ++k) DSR(dst[n][k], pb_, n * 2048 + k * 1024); } while (0)
; #define BAR __builtin_amdgcn_s_barrier()
; #define LGKM(n) asm volatile("s_waitcnt lgkmcnt(%0)" ::"n"(n) : "memory")
; template <int EPI, bool SWP> ...
;     ...
;   { LDB(B0, 1, 0); LDA(1, 0); WAIT_V(2); BAR; LGKM(0); SCHED(); MMA(0, 0, B0); BAR; SCHED();
;     LDB(B1, 1, 1); WAIT_V(0); BAR; LGKM(0); SCHED(); MMA(0, 1, B1); BAR; SCHED();
;     LDA(1, 1);
;     if (has_next) { STAGE_BX(Bg_n, 0, 0, 0); STAGE_AX(Ag_n, 0, 0, 0); STAGE_BX(Bg_n, 0, 1, 0); STAGE_AX(Ag_n, 0, 1, 0); }
	s_waitcnt lgkmcnt(0)
	v_mfma_f32_16x16x32_bf16 v[72:75], v[0:3], v[32:35], v[124:127]
	v_mfma_f32_16x16x32_bf16 v[120:123], v[8:11], v[40:43], v[72:75]
	v_mfma_f32_16x16x32_bf16 v[72:75], v[16:19], v[32:35], v[180:183]
	v_mfma_f32_16x16x32_bf16 v[124:127], v[24:27], v[40:43], v[72:75]
	v_mfma_f32_16x16x32_bf16 v[72:75], v[0:3], v[48:51], v[116:119]
	v_mfma_f32_16x16x32_bf16 v[112:115], v[8:11], v[56:59], v[72:75]
	v_mfma_f32_16x16x32_bf16 v[72:75], v[16:19], v[48:51], v[184:187]
	v_mfma_f32_16x16x32_bf16 v[116:119], v[24:27], v[56:59], v[72:75]
	v_mfma_f32_16x16x32_bf16 v[72:75], v[0:3], v[64:67], v[108:111]
	v_mfma_f32_16x16x32_bf16 v[104:107], v[8:11], v[218:221], v[72:75]
	v_mfma_f32_16x16x32_bf16 v[72:75], v[16:19], v[64:67], v[188:191]
	v_mfma_f32_16x16x32_bf16 v[108:111], v[24:27], v[218:221], v[72:75]
	v_mfma_f32_16x16x32_bf16 v[72:75], v[0:3], v[236:239], v[100:103]
	v_mfma_f32_16x16x32_bf16 v[96:99], v[8:11], v[240:243], v[72:75]
	v_mfma_f32_16x16x32_bf16 v[72:75], v[16:19], v[236:239], v[192:195]
	v_mfma_f32_16x16x32_bf16 v[100:103], v[24:27], v[240:243], v[72:75]
	s_barrier
	ds_read_b128 v[160:163], v229 offset:0
	ds_read_b128 v[164:167], v229 offset:0x400
	ds_read_b128 v[168:171], v229 offset:0x800
	ds_read_b128 v[172:175], v229 offset:0xc00
	s_waitcnt vmcnt(0)
	s_barrier
	s_waitcnt lgkmcnt(0)
	v_mfma_f32_16x16x32_bf16 v[72:75], v[160:163], v[32:35], v[92:95]
	v_mfma_f32_16x16x32_bf16 v[32:35], v[168:171], v[32:35], v[196:199]
	v_mfma_f32_16x16x32_bf16 v[92:95], v[172:175], v[40:43], v[32:35]
	v_mfma_f32_16x16x32_bf16 v[32:35], v[160:163], v[48:51], v[84:87]
	v_mfma_f32_16x16x32_bf16 v[80:83], v[164:167], v[56:59], v[32:35]
	v_mfma_f32_16x16x32_bf16 v[32:35], v[168:171], v[48:51], v[200:203]
	v_mfma_f32_16x16x32_bf16 v[84:87], v[172:175], v[56:59], v[32:35]
	v_mfma_f32_16x16x32_bf16 v[32:35], v[160:163], v[64:67], v[76:79]
	v_mfma_f32_16x16x32_bf16 v[88:91], v[164:167], v[40:43], v[72:75]
	v_mfma_f32_16x16x32_bf16 v[72:75], v[164:167], v[218:221], v[32:35]
	v_mfma_f32_16x16x32_bf16 v[32:35], v[168:171], v[64:67], v[204:207]
	v_mfma_f32_16x16x32_bf16 v[76:79], v[172:175], v[218:221], v[32:35]
	v_mfma_f32_16x16x32_bf16 v[32:35], v[160:163], v[236:239], v[68:71]
	v_mfma_f32_16x16x32_bf16 v[64:67], v[164:167], v[240:243], v[32:35]
	v_mfma_f32_16x16x32_bf16 v[32:35], v[168:171], v[236:239], v[176:179]
	v_mfma_f32_16x16x32_bf16 v[68:71], v[172:175], v[240:243], v[32:35]
	s_barrier
	ds_read_b128 v[200:203], v230 offset:0
	ds_read_b128 v[204:207], v230 offset:0x400
	ds_read_b128 v[192:195], v230 offset:0x800
	ds_read_b128 v[196:199], v230 offset:0xc00
	ds_read_b128 v[184:187], v230 offset:0x1000
	ds_read_b128 v[188:191], v230 offset:0x1400
	ds_read_b128 v[176:179], v230 offset:0x1800
	ds_read_b128 v[180:183], v230 offset:0x1c00
	s_and_b64 vcc, exec, s[44:45]
	v_lshl_add_u64 v[218:219], s[50:51], 0, v[208:209]
	v_lshl_add_u64 v[220:221], s[48:49], 0, v[208:209]
	s_cbranch_vccz .LBB0_357
	s_mov_b32 m0, s16
	v_lshl_add_u64 v[32:33], v[218:219], 0, s[4:5]
	global_load_lds_dwordx4 v[218:219], off
	s_mov_b32 m0, s17
	s_nop 0
	global_load_lds_dwordx4 v[32:33], off
	s_mov_b32 m0, s3
	v_lshl_add_u64 v[32:33], v[220:221], 0, s[4:5]
	global_load_lds_dwordx4 v[220:221], off
	s_mov_b32 m0, s18
	s_nop 0
	global_load_lds_dwordx4 v[32:33], off
	v_lshl_add_u64 v[32:33], v[218:219], 0, s[10:11]
	s_mov_b32 m0, s19
	s_nop 0
	global_load_lds_dwordx4 v[32:33], off
	v_lshl_add_u64 v[32:33], v[218:219], 0, s[12:13]
	s_mov_b32 m0, s60
	s_nop 0
	global_load_lds_dwordx4 v[32:33], off
	v_lshl_add_u64 v[32:33], v[220:221], 0, s[10:11]
	s_mov_b32 m0, s61
	s_nop 0
	global_load_lds_dwordx4 v[32:33], off
	v_lshl_add_u64 v[32:33], v[220:221], 0, s[12:13]
	s_mov_b32 m0, s62
	s_nop 0
	global_load_lds_dwordx4 v[32:33], off

; #define WAIT_V(n) asm volatile("s_waitcnt vmcnt(%0)" ::"n"(n) : "memory")
; #define SCHED() __builtin_amdgcn_sched_barrier(0)
; #define LGKM(n) asm volatile("s_waitcnt lgkmcnt(%0)" ::"n"(n) : "memory")
; #define STAGE_A(b, h, kt) STAGE_AX(Ag, b, h, kt)
; #define STAGE_B(b, h, kt) STAGE_BX(Bg, b, h, kt)
; #define LDA(b, h) do { const unsigned pa_ = lds0 + SLOTA(b, h) + wr * 8192 + laneoff; _Pragma("unroll") for (int m = 0; m < 4; ++m)   \
;       _Pragma("unroll") for (int k = 0; k < 2; ++k) DSR(At[m][k], pa_, m * 2048 + k * 1024); } while (0)
; #define LDB(dst, b, h) do { const unsigned pb_ = lds0 + SLOTB(b, h) + wc * 4096 + laneoff; _Pragma("unroll") for (int n = 0; n < 2; ++n) \
;       _Pragma("unroll") for (int k = 0; k < 2; ++k) DSR(dst[n][k], pb_, n * 2048 + k * 1024); } while (0)
; #define BAR __builtin_amdgcn_s_barrier()
; #define LGKM(n) asm volatile("s_waitcnt lgkmcnt(%0)" ::"n"(n) : "memory")
; template <int EPI, bool SWP> ...
;     ...
;     LDB(B0, 0, 0); LDA(0, 0); STAGE_A(1, 1, t + 1);
;     LGKM(8); BAR; LGKM(0); SCHED(); MMA(0, 0, B0); BAR; SCHED();
;     LDB(B1, 0, 1); STAGE_B(0, 0, t + 2);
;     BAR; LGKM(0); SCHED(); MMA(0, 1, B1); BAR; SCHED();
;     LDA(0, 1); STAGE_A(0, 0, t + 2);
;     BAR; LGKM(0); SCHED(); MMA(1, 0, B0); BAR; SCHED();
;     STAGE_B(0, 1, t + 2);
;     WAIT_V(6); BAR; SCHED(); MMA(1, 1, B1); BAR; SCHED();
.LBB0_385:
	ds_read_b128 v[130:133], v224 offset:0
	ds_read_b128 v[134:137], v224 offset:0x400
	ds_read_b128 v[138:141], v224 offset:0x800
	ds_read_b128 v[142:145], v224 offset:0xc00
	ds_read_b128 v[146:149], v225 offset:0
	ds_read_b128 v[150:153], v225 offset:0x400
	ds_read_b128 v[154:157], v225 offset:0x800
	ds_read_b128 v[158:161], v225 offset:0xc00
	ds_read_b128 v[162:165], v225 offset:0x1000
	ds_read_b128 v[166:169], v225 offset:0x1400
	ds_read_b128 v[170:173], v225 offset:0x1800
	v_lshl_add_u64 v[194:195], s[50:51], 0, v[218:219]
	s_mov_b64 s[58:59], 0xf140080
	s_mov_b32 m0, s69
	ds_read_b128 v[174:177], v225 offset:0x1c00
	v_lshl_add_u64 v[178:179], v[194:195], 0, s[58:59]
	s_mov_b64 s[58:59], 0xf160080
	global_load_lds_dwordx4 v[178:179], off
	v_lshl_add_u64 v[178:179], v[194:195], 0, s[58:59]
	s_mov_b32 m0, s70
	s_nop 0
	global_load_lds_dwordx4 v[178:179], off
	s_waitcnt lgkmcnt(8)
	s_barrier
	s_waitcnt lgkmcnt(0)
	v_mfma_f32_16x16x32_bf16 v[124:127], v[130:133], v[146:149], v[124:127]
	v_mfma_f32_16x16x32_bf16 v[120:123], v[138:141], v[146:149], v[120:123]
	v_mfma_f32_16x16x32_bf16 v[116:119], v[130:133], v[154:157], v[116:119]
	v_mfma_f32_16x16x32_bf16 v[112:115], v[138:141], v[154:157], v[112:115]
	v_mfma_f32_16x16x32_bf16 v[108:111], v[130:133], v[162:165], v[108:111]
	v_mfma_f32_16x16x32_bf16 v[104:107], v[138:141], v[162:165], v[104:107]
	v_mfma_f32_16x16x32_bf16 v[100:103], v[130:133], v[170:173], v[100:103]
	v_mfma_f32_16x16x32_bf16 v[96:99], v[138:141], v[170:173], v[96:99]
	v_mfma_f32_16x16x32_bf16 v[124:127], v[134:137], v[150:153], v[124:127]
	v_mfma_f32_16x16x32_bf16 v[120:123], v[142:145], v[150:153], v[120:123]
	v_mfma_f32_16x16x32_bf16 v[116:119], v[134:137], v[158:161], v[116:119]
	v_mfma_f32_16x16x32_bf16 v[112:115], v[142:145], v[158:161], v[112:115]
	v_mfma_f32_16x16x32_bf16 v[108:111], v[134:137], v[166:169], v[108:111]
	v_mfma_f32_16x16x32_bf16 v[104:107], v[142:145], v[166:169], v[104:107]
	v_mfma_f32_16x16x32_bf16 v[100:103], v[134:137], v[174:177], v[100:103]
	v_mfma_f32_16x16x32_bf16 v[96:99], v[142:145], v[174:177], v[96:99]
	s_barrier
	ds_read_b128 v[178:181], v226 offset:0
	ds_read_b128 v[182:185], v226 offset:0x400
	ds_read_b128 v[186:189], v226 offset:0x800
	v_lshl_add_u64 v[196:197], s[48:49], 0, v[218:219]
	s_mov_b64 s[58:59], 0xe400100
	s_mov_b32 m0, s16
	ds_read_b128 v[190:193], v226 offset:0xc00
	v_lshl_add_u64 v[198:199], v[196:197], 0, s[58:59]
	s_mov_b64 s[58:59], 0xe420100
	global_load_lds_dwordx4 v[198:199], off
	v_lshl_add_u64 v[198:199], v[196:197], 0, s[58:59]
	s_mov_b32 m0, s17
	s_nop 0
	global_load_lds_dwordx4 v[198:199], off
	s_barrier
	s_waitcnt lgkmcnt(0)
	v_mfma_f32_16x16x32_bf16 v[92:95], v[178:181], v[146:149], v[92:95]
	v_mfma_f32_16x16x32_bf16 v[88:91], v[186:189], v[146:149], v[88:91]
	v_mfma_f32_16x16x32_bf16 v[84:87], v[178:181], v[154:157], v[84:87]
	v_mfma_f32_16x16x32_bf16 v[80:83], v[186:189], v[154:157], v[80:83]
	v_mfma_f32_16x16x32_bf16 v[76:79], v[178:181], v[162:165], v[76:79]
	v_mfma_f32_16x16x32_bf16 v[72:75], v[186:189], v[162:165], v[72:75]
	v_mfma_f32_16x16x32_bf16 v[68:71], v[178:181], v[170:173], v[68:71]
	v_mfma_f32_16x16x32_bf16 v[64:67], v[186:189], v[170:173], v[64:67]
	v_mfma_f32_16x16x32_bf16 v[92:95], v[182:185], v[150:153], v[92:95]
	v_mfma_f32_16x16x32_bf16 v[88:91], v[190:193], v[150:153], v[88:91]
	v_mfma_f32_16x16x32_bf16 v[84:87], v[182:185], v[158:161], v[84:87]
	v_mfma_f32_16x16x32_bf16 v[80:83], v[190:193], v[158:161], v[80:83]
	v_mfma_f32_16x16x32_bf16 v[76:79], v[182:185], v[166:169], v[76:79]
	v_mfma_f32_16x16x32_bf16 v[72:75], v[190:193], v[166:169], v[72:75]
	v_mfma_f32_16x16x32_bf16 v[68:71], v[182:185], v[174:177], v[68:71]
	v_mfma_f32_16x16x32_bf16 v[64:67], v[190:193], v[174:177], v[64:67]
	s_barrier
	ds_read_b128 v[146:149], v227 offset:0
	ds_read_b128 v[150:153], v227 offset:0x400
	ds_read_b128 v[154:157], v227 offset:0x800
	ds_read_b128 v[158:161], v227 offset:0xc00
	ds_read_b128 v[162:165], v227 offset:0x1000
	ds_read_b128 v[166:169], v227 offset:0x1400
	ds_read_b128 v[170:173], v227 offset:0x1800
	s_mov_b64 s[58:59], 0xf100100
	s_mov_b32 m0, s3
	ds_read_b128 v[174:177], v227 offset:0x1c00
	v_lshl_add_u64 v[198:199], v[194:195], 0, s[58:59]
	s_mov_b64 s[58:59], 0xf120100
	global_load_lds_dwordx4 v[198:199], off
	v_lshl_add_u64 v[198:199], v[194:195], 0, s[58:59]
	s_mov_b32 m0, s18
	s_nop 0
	global_load_lds_dwordx4 v[198:199], off
	s_barrier
	s_waitcnt lgkmcnt(0)
	v_mfma_f32_16x16x32_bf16 v[60:63], v[130:133], v[146:149], v[60:63]
	v_mfma_f32_16x16x32_bf16 v[56:59], v[138:141], v[146:149], v[56:59]
	v_mfma_f32_16x16x32_bf16 v[52:55], v[130:133], v[154:157], v[52:55]
	v_mfma_f32_16x16x32_bf16 v[48:51], v[138:141], v[154:157], v[48:51]
	v_mfma_f32_16x16x32_bf16 v[44:47], v[130:133], v[162:165], v[44:47]
	v_mfma_f32_16x16x32_bf16 v[40:43], v[138:141], v[162:165], v[40:43]
	v_mfma_f32_16x16x32_bf16 v[36:39], v[130:133], v[170:173], v[36:39]
	v_mfma_f32_16x16x32_bf16 v[32:35], v[138:141], v[170:173], v[32:35]
	v_mfma_f32_16x16x32_bf16 v[60:63], v[134:137], v[150:153], v[60:63]
	v_mfma_f32_16x16x32_bf16 v[56:59], v[142:145], v[150:153], v[56:59]
	v_mfma_f32_16x16x32_bf16 v[52:55], v[134:137], v[158:161], v[52:55]
	v_mfma_f32_16x16x32_bf16 v[48:51], v[142:145], v[158:161], v[48:51]
	v_mfma_f32_16x16x32_bf16 v[44:47], v[134:137], v[166:169], v[44:47]
	v_mfma_f32_16x16x32_bf16 v[40:43], v[142:145], v[166:169], v[40:43]
	v_mfma_f32_16x16x32_bf16 v[36:39], v[134:137], v[174:177], v[36:39]
	v_mfma_f32_16x16x32_bf16 v[32:35], v[142:145], v[174:177], v[32:35]
	s_barrier
; #define WAIT_V(n) asm volatile("s_waitcnt vmcnt(%0)" ::"n"(n) : "memory")
; #define SCHED() __builtin_amdgcn_sched_barrier(0)
; #define LGKM(n) asm volatile("s_waitcnt lgkmcnt(%0)" ::"n"(n) : "memory")
; #define STAGE_A(b, h, kt) STAGE_AX(Ag, b, h, kt)
; #define STAGE_B(b, h, kt) STAGE_BX(Bg, b, h, kt)
; #define LDA(b, h) do { const unsigned pa_ = lds0 + SLOTA(b, h) + wr * 8192 + laneoff; _Pragma("unroll") for (int m = 0; m < 4; ++m)   \
;       _Pragma("unroll") for (int k = 0; k < 2; ++k) DSR(At[m][k], pa_, m * 2048 + k * 1024); } while (0)
; #define LDB(dst, b, h) do { const unsigned pb_ = lds0 + SLOTB(b, h) + wc * 4096 + laneoff; _Pragma("unroll") for (int n = 0; n < 2; ++n) \
;       _Pragma("unroll") for (int k = 0; k < 2; ++k) DSR(dst[n][k], pb_, n * 2048 + k * 1024); } while (0)
; #define BAR __builtin_amdgcn_s_barrier()
; #define LGKM(n) asm volatile("s_waitcnt lgkmcnt(%0)" ::"n"(n) : "memory")
; template <int EPI, bool SWP> ...
;     ...
;     WAIT_V(6); BAR; SCHED(); MMA(1, 1, B1); BAR; SCHED();
;     LDB(B0, 1, 0); LDA(1, 0); STAGE_A(0, 1, t + 2);
;     LGKM(8); BAR; LGKM(0); SCHED(); MMA(0, 0, B0); BAR; SCHED();
;     LDB(B1, 1, 1); STAGE_B(1, 0, t + 3);
;     BAR; LGKM(0); SCHED(); MMA(0, 1, B1); BAR; SCHED();
;     LDA(1, 1); STAGE_A(1, 0, t + 3);
	s_mov_b64 s[58:59], 0xe440100
	s_mov_b32 m0, s19
	v_lshl_add_u64 v[130:131], v[196:197], 0, s[58:59]
	s_mov_b64 s[58:59], 0xe460100
	global_load_lds_dwordx4 v[130:131], off
	v_lshl_add_u64 v[130:131], v[196:197], 0, s[58:59]
	s_mov_b32 m0, s60
	s_nop 0
	global_load_lds_dwordx4 v[130:131], off
	s_waitcnt vmcnt(6)
	s_barrier
	v_mfma_f32_16x16x32_bf16 v[28:31], v[178:181], v[146:149], v[28:31]
	v_mfma_f32_16x16x32_bf16 v[24:27], v[186:189], v[146:149], v[24:27]
	v_mfma_f32_16x16x32_bf16 v[20:23], v[178:181], v[154:157], v[20:23]
	v_mfma_f32_16x16x32_bf16 v[16:19], v[186:189], v[154:157], v[16:19]
	v_mfma_f32_16x16x32_bf16 v[12:15], v[178:181], v[162:165], v[12:15]
	v_mfma_f32_16x16x32_bf16 v[8:11], v[186:189], v[162:165], v[8:11]
	v_mfma_f32_16x16x32_bf16 v[4:7], v[178:181], v[170:173], v[4:7]
	v_mfma_f32_16x16x32_bf16 v[0:3], v[186:189], v[170:173], v[0:3]
	v_mfma_f32_16x16x32_bf16 v[28:31], v[182:185], v[150:153], v[28:31]
	v_mfma_f32_16x16x32_bf16 v[24:27], v[190:193], v[150:153], v[24:27]
	v_mfma_f32_16x16x32_bf16 v[20:23], v[182:185], v[158:161], v[20:23]
	v_mfma_f32_16x16x32_bf16 v[16:19], v[190:193], v[158:161], v[16:19]
	v_mfma_f32_16x16x32_bf16 v[12:15], v[182:185], v[166:169], v[12:15]
	v_mfma_f32_16x16x32_bf16 v[8:11], v[190:193], v[166:169], v[8:11]
	v_mfma_f32_16x16x32_bf16 v[4:7], v[182:185], v[174:177], v[4:7]
	v_mfma_f32_16x16x32_bf16 v[0:3], v[190:193], v[174:177], v[0:3]
	s_barrier
	ds_read_b128 v[130:133], v229 offset:0
	ds_read_b128 v[134:137], v229 offset:0x400
	ds_read_b128 v[138:141], v229 offset:0x800
	ds_read_b128 v[142:145], v229 offset:0xc00
	ds_read_b128 v[146:149], v230 offset:0
	ds_read_b128 v[150:153], v230 offset:0x400
	ds_read_b128 v[154:157], v230 offset:0x800
	ds_read_b128 v[158:161], v230 offset:0xc00
	ds_read_b128 v[162:165], v230 offset:0x1000
	ds_read_b128 v[166:169], v230 offset:0x1400
	ds_read_b128 v[170:173], v230 offset:0x1800
	s_mov_b64 s[58:59], 0xf140100
	s_mov_b32 m0, s61
	ds_read_b128 v[174:177], v230 offset:0x1c00
	v_lshl_add_u64 v[178:179], v[194:195], 0, s[58:59]
	s_mov_b64 s[58:59], 0xf160100
	global_load_lds_dwordx4 v[178:179], off
	v_lshl_add_u64 v[178:179], v[194:195], 0, s[58:59]
	s_mov_b32 m0, s62
	s_nop 0
	global_load_lds_dwordx4 v[178:179], off
	s_waitcnt lgkmcnt(8)
	s_barrier
	s_waitcnt lgkmcnt(0)
	v_mfma_f32_16x16x32_bf16 v[124:127], v[130:133], v[146:149], v[124:127]
	v_mfma_f32_16x16x32_bf16 v[120:123], v[138:141], v[146:149], v[120:123]
	v_mfma_f32_16x16x32_bf16 v[116:119], v[130:133], v[154:157], v[116:119]
	v_mfma_f32_16x16x32_bf16 v[112:115], v[138:141], v[154:157], v[112:115]
	v_mfma_f32_16x16x32_bf16 v[108:111], v[130:133], v[162:165], v[108:111]
	v_mfma_f32_16x16x32_bf16 v[104:107], v[138:141], v[162:165], v[104:107]
	v_mfma_f32_16x16x32_bf16 v[100:103], v[130:133], v[170:173], v[100:103]
	v_mfma_f32_16x16x32_bf16 v[96:99], v[138:141], v[170:173], v[96:99]
	v_mfma_f32_16x16x32_bf16 v[124:127], v[134:137], v[150:153], v[124:127]
	v_mfma_f32_16x16x32_bf16 v[120:123], v[142:145], v[150:153], v[120:123]
	v_mfma_f32_16x16x32_bf16 v[116:119], v[134:137], v[158:161], v[116:119]
	v_mfma_f32_16x16x32_bf16 v[112:115], v[142:145], v[158:161], v[112:115]
	v_mfma_f32_16x16x32_bf16 v[108:111], v[134:137], v[166:169], v[108:111]
	v_mfma_f32_16x16x32_bf16 v[104:107], v[142:145], v[166:169], v[104:107]
	v_mfma_f32_16x16x32_bf16 v[100:103], v[134:137], v[174:177], v[100:103]
	v_mfma_f32_16x16x32_bf16 v[96:99], v[142:145], v[174:177], v[96:99]
	s_barrier
	ds_read_b128 v[178:181], v231 offset:0
	ds_read_b128 v[182:185], v231 offset:0x400
	ds_read_b128 v[186:189], v231 offset:0x800
	s_mov_b64 s[58:59], 0xe400180
	s_mov_b32 m0, s63
	ds_read_b128 v[190:193], v231 offset:0xc00
	v_lshl_add_u64 v[198:199], v[196:197], 0, s[58:59]
	s_mov_b64 s[58:59], 0xe420180
	global_load_lds_dwordx4 v[198:199], off
	v_lshl_add_u64 v[198:199], v[196:197], 0, s[58:59]
	s_mov_b32 m0, s64
	s_nop 0
	global_load_lds_dwordx4 v[198:199], off
	s_barrier
	s_waitcnt lgkmcnt(0)
	v_mfma_f32_16x16x32_bf16 v[92:95], v[178:181], v[146:149], v[92:95]
	v_mfma_f32_16x16x32_bf16 v[88:91], v[186:189], v[146:149], v[88:91]
	v_mfma_f32_16x16x32_bf16 v[84:87], v[178:181], v[154:157], v[84:87]
	v_mfma_f32_16x16x32_bf16 v[80:83], v[186:189], v[154:157], v[80:83]
	v_mfma_f32_16x16x32_bf16 v[76:79], v[178:181], v[162:165], v[76:79]
	v_mfma_f32_16x16x32_bf16 v[72:75], v[186:189], v[162:165], v[72:75]
	v_mfma_f32_16x16x32_bf16 v[68:71], v[178:181], v[170:173], v[68:71]
	v_mfma_f32_16x16x32_bf16 v[64:67], v[186:189], v[170:173], v[64:67]
	v_mfma_f32_16x16x32_bf16 v[92:95], v[182:185], v[150:153], v[92:95]
	v_mfma_f32_16x16x32_bf16 v[88:91], v[190:193], v[150:153], v[88:91]
	v_mfma_f32_16x16x32_bf16 v[84:87], v[182:185], v[158:161], v[84:87]
	v_mfma_f32_16x16x32_bf16 v[80:83], v[190:193], v[158:161], v[80:83]
	v_mfma_f32_16x16x32_bf16 v[76:79], v[182:185], v[166:169], v[76:79]
	v_mfma_f32_16x16x32_bf16 v[72:75], v[190:193], v[166:169], v[72:75]
	v_mfma_f32_16x16x32_bf16 v[68:71], v[182:185], v[174:177], v[68:71]
	v_mfma_f32_16x16x32_bf16 v[64:67], v[190:193], v[174:177], v[64:67]
	s_barrier
	ds_read_b128 v[146:149], v232 offset:0
	ds_read_b128 v[150:153], v232 offset:0x400
	ds_read_b128 v[154:157], v232 offset:0x800
	ds_read_b128 v[158:161], v232 offset:0xc00
	ds_read_b128 v[162:165], v232 offset:0x1000
	ds_read_b128 v[166:169], v232 offset:0x1400
	ds_read_b128 v[170:173], v232 offset:0x1800
	s_mov_b64 s[58:59], 0xf100180
	s_mov_b32 m0, s65
	ds_read_b128 v[174:177], v232 offset:0x1c00
	v_lshl_add_u64 v[198:199], v[194:195], 0, s[58:59]
	s_mov_b64 s[58:59], 0xf120180
	global_load_lds_dwordx4 v[198:199], off
	v_lshl_add_u64 v[194:195], v[194:195], 0, s[58:59]
	s_mov_b32 m0, s66
	s_nop 0
	global_load_lds_dwordx4 v[194:195], off
	s_barrier
; #define WAIT_V(n) asm volatile("s_waitcnt vmcnt(%0)" ::"n"(n) : "memory")
; #define SCHED() __builtin_amdgcn_sched_barrier(0)
; #define LGKM(n) asm volatile("s_waitcnt lgkmcnt(%0)" ::"n"(n) : "memory")
; #define STAGE_A(b, h, kt) STAGE_AX(Ag, b, h, kt)
; #define STAGE_B(b, h, kt) STAGE_BX(Bg, b, h, kt)
; #define LDA(b, h) do { const unsigned pa_ = lds0 + SLOTA(b, h) + wr * 8192 + laneoff; _Pragma("unroll") for (int m = 0; m < 4; ++m)   \
;       _Pragma("unroll") for (int k = 0; k < 2; ++k) DSR(At[m][k], pa_, m * 2048 + k * 1024); } while (0)
; #define LDB(dst, b, h) do { const unsigned pb_ = lds0 + SLOTB(b, h) + wc * 4096 + laneoff; _Pragma("unroll") for (int n = 0; n < 2; ++n) \
;       _Pragma("unroll") for (int k = 0; k < 2; ++k) DSR(dst[n][k], pb_, n * 2048 + k * 1024); } while (0)
; #define BAR __builtin_amdgcn_s_barrier()
; #define LGKM(n) asm volatile("s_waitcnt lgkmcnt(%0)" ::"n"(n) : "memory")
; template <int EPI, bool SWP> ...
;     ...
;     BAR; LGKM(0); SCHED(); MMA(1, 0, B0); BAR; SCHED();
;     STAGE_B(1, 1, t + 3);
;     WAIT_V(6); BAR; SCHED(); MMA(1, 1, B1); BAR; SCHED();
;   }
;   { LDB(B0, 0, 0); LDA(0, 0); STAGE_A(1, 1, nt - 1);
;     BAR; LGKM(0); SCHED(); MMA(0, 0, B0); BAR; SCHED();
;     LDB(B1, 0, 1); BAR; LGKM(0); SCHED(); MMA(0, 1, B1); BAR; SCHED();
	s_waitcnt lgkmcnt(0)
	v_mfma_f32_16x16x32_bf16 v[60:63], v[130:133], v[146:149], v[60:63]
	v_mfma_f32_16x16x32_bf16 v[56:59], v[138:141], v[146:149], v[56:59]
	v_mfma_f32_16x16x32_bf16 v[52:55], v[130:133], v[154:157], v[52:55]
	v_mfma_f32_16x16x32_bf16 v[48:51], v[138:141], v[154:157], v[48:51]
	v_mfma_f32_16x16x32_bf16 v[44:47], v[130:133], v[162:165], v[44:47]
	v_mfma_f32_16x16x32_bf16 v[40:43], v[138:141], v[162:165], v[40:43]
	v_mfma_f32_16x16x32_bf16 v[36:39], v[130:133], v[170:173], v[36:39]
	v_mfma_f32_16x16x32_bf16 v[32:35], v[138:141], v[170:173], v[32:35]
	v_mfma_f32_16x16x32_bf16 v[60:63], v[134:137], v[150:153], v[60:63]
	v_mfma_f32_16x16x32_bf16 v[56:59], v[142:145], v[150:153], v[56:59]
	v_mfma_f32_16x16x32_bf16 v[52:55], v[134:137], v[158:161], v[52:55]
	v_mfma_f32_16x16x32_bf16 v[48:51], v[142:145], v[158:161], v[48:51]
	v_mfma_f32_16x16x32_bf16 v[44:47], v[134:137], v[166:169], v[44:47]
	v_mfma_f32_16x16x32_bf16 v[40:43], v[142:145], v[166:169], v[40:43]
	v_mfma_f32_16x16x32_bf16 v[36:39], v[134:137], v[174:177], v[36:39]
	v_mfma_f32_16x16x32_bf16 v[32:35], v[142:145], v[174:177], v[32:35]
	s_barrier
	s_mov_b64 s[58:59], 0xe440180
	s_mov_b32 m0, s67
	v_lshl_add_u64 v[130:131], v[196:197], 0, s[58:59]
	s_mov_b64 s[58:59], 0xe460180
	global_load_lds_dwordx4 v[130:131], off
	v_lshl_add_u64 v[130:131], v[196:197], 0, s[58:59]
	s_mov_b32 m0, s68
	s_nop 0
	global_load_lds_dwordx4 v[130:131], off
	s_waitcnt vmcnt(6)
	s_barrier
	v_mfma_f32_16x16x32_bf16 v[28:31], v[178:181], v[146:149], v[28:31]
	v_mfma_f32_16x16x32_bf16 v[24:27], v[186:189], v[146:149], v[24:27]
	v_mfma_f32_16x16x32_bf16 v[20:23], v[178:181], v[154:157], v[20:23]
	v_mfma_f32_16x16x32_bf16 v[16:19], v[186:189], v[154:157], v[16:19]
	v_mfma_f32_16x16x32_bf16 v[12:15], v[178:181], v[162:165], v[12:15]
	v_mfma_f32_16x16x32_bf16 v[8:11], v[186:189], v[162:165], v[8:11]
	v_mfma_f32_16x16x32_bf16 v[4:7], v[178:181], v[170:173], v[4:7]
	v_mfma_f32_16x16x32_bf16 v[0:3], v[186:189], v[170:173], v[0:3]
	v_mfma_f32_16x16x32_bf16 v[28:31], v[182:185], v[150:153], v[28:31]
	v_mfma_f32_16x16x32_bf16 v[24:27], v[190:193], v[150:153], v[24:27]
	v_mfma_f32_16x16x32_bf16 v[20:23], v[182:185], v[158:161], v[20:23]
	v_mfma_f32_16x16x32_bf16 v[16:19], v[190:193], v[158:161], v[16:19]
	v_mfma_f32_16x16x32_bf16 v[12:15], v[182:185], v[166:169], v[12:15]
	v_mfma_f32_16x16x32_bf16 v[8:11], v[190:193], v[166:169], v[8:11]
	v_mfma_f32_16x16x32_bf16 v[4:7], v[182:185], v[174:177], v[4:7]
	v_mfma_f32_16x16x32_bf16 v[0:3], v[190:193], v[174:177], v[0:3]
	s_add_i32 s35, s35, 2
	s_add_u32 s48, s48, 0x100
	s_addc_u32 s49, s49, 0
	s_add_u32 s50, s50, 0x100
	s_addc_u32 s51, s51, 0
	s_cmp_gt_u32 s35, 11
	s_barrier
	s_cbranch_scc0 .LBB0_385
	ds_read_b128 v[140:143], v224 offset:0
	ds_read_b128 v[144:147], v224 offset:0x400
	ds_read_b128 v[148:151], v224 offset:0x800
	ds_read_b128 v[152:155], v224 offset:0xc00
	ds_read_b128 v[130:133], v225 offset:0
	ds_read_b128 v[134:137], v225 offset:0x400
	ds_read_b128 v[156:159], v225 offset:0x800
	ds_read_b128 v[160:163], v225 offset:0xc00
	ds_read_b128 v[164:167], v225 offset:0x1000
	ds_read_b128 v[168:171], v225 offset:0x1400
	ds_read_b128 v[172:175], v225 offset:0x1800
	s_mov_b32 m0, s69
	ds_read_b128 v[176:179], v225 offset:0x1c00
	v_lshl_add_u64 v[138:139], v[128:129], 0, s[24:25]
	global_load_lds_dwordx4 v[138:139], off
	v_lshl_add_u64 v[128:129], v[128:129], 0, s[26:27]
	s_mov_b32 m0, s70
	s_ashr_i32 s39, s38, 31
	global_load_lds_dwordx4 v[128:129], off
	s_lshl_b64 s[48:49], s[38:39], 19
	s_add_u32 s48, s46, s48
	s_addc_u32 s49, s47, s49
	s_ashr_i32 s35, s34, 31
	s_barrier
	s_waitcnt lgkmcnt(0)
	s_lshl_b64 s[50:51], s[34:35], 19
	v_readlane_b32 s58, v254, 32
	v_readlane_b32 s59, v254, 33
	s_add_u32 s50, s58, s50
	s_addc_u32 s51, s59, s51
	v_mfma_f32_16x16x32_bf16 v[124:127], v[140:143], v[130:133], v[124:127]
	v_mfma_f32_16x16x32_bf16 v[120:123], v[148:151], v[130:133], v[120:123]
	v_mfma_f32_16x16x32_bf16 v[116:119], v[140:143], v[156:159], v[116:119]
	v_mfma_f32_16x16x32_bf16 v[112:115], v[148:151], v[156:159], v[112:115]
	v_mfma_f32_16x16x32_bf16 v[108:111], v[140:143], v[164:167], v[108:111]
	v_mfma_f32_16x16x32_bf16 v[104:107], v[148:151], v[164:167], v[104:107]
	v_mfma_f32_16x16x32_bf16 v[100:103], v[140:143], v[172:175], v[100:103]
	v_mfma_f32_16x16x32_bf16 v[96:99], v[148:151], v[172:175], v[96:99]
	v_mfma_f32_16x16x32_bf16 v[124:127], v[144:147], v[134:137], v[124:127]
	v_mfma_f32_16x16x32_bf16 v[180:183], v[152:155], v[134:137], v[120:123]
	v_mfma_f32_16x16x32_bf16 v[116:119], v[144:147], v[160:163], v[116:119]
	v_mfma_f32_16x16x32_bf16 v[184:187], v[152:155], v[160:163], v[112:115]
	v_mfma_f32_16x16x32_bf16 v[108:111], v[144:147], v[168:171], v[108:111]
	v_mfma_f32_16x16x32_bf16 v[188:191], v[152:155], v[168:171], v[104:107]
	v_mfma_f32_16x16x32_bf16 v[100:103], v[144:147], v[176:179], v[100:103]
	v_mfma_f32_16x16x32_bf16 v[192:195], v[152:155], v[176:179], v[96:99]
	s_barrier
	ds_read_b128 v[96:99], v226 offset:0
	ds_read_b128 v[104:107], v226 offset:0x400
	ds_read_b128 v[112:115], v226 offset:0x800
	ds_read_b128 v[120:123], v226 offset:0xc00
	s_barrier
; #define WAIT_V(n) asm volatile("s_waitcnt vmcnt(%0)" ::"n"(n) : "memory")
; #define SCHED() __builtin_amdgcn_sched_barrier(0)
; #define LGKM(n) asm volatile("s_waitcnt lgkmcnt(%0)" ::"n"(n) : "memory")
; #define LDA(b, h) do { const unsigned pa_ = lds0 + SLOTA(b, h) + wr * 8192 + laneoff; _Pragma("unroll") for (int m = 0; m < 4; ++m)   \
;       _Pragma("unroll") for (int k = 0; k < 2; ++k) DSR(At[m][k], pa_, m * 2048 + k * 1024); } while (0)
; #define LDB(dst, b, h) do { const unsigned pb_ = lds0 + SLOTB(b, h) + wc * 4096 + laneoff; _Pragma("unroll") for (int n = 0; n < 2; ++n) \
;       _Pragma("unroll") for (int k = 0; k < 2; ++k) DSR(dst[n][k], pb_, n * 2048 + k * 1024); } while (0)
; #define BAR __builtin_amdgcn_s_barrier()
; #define LGKM(n) asm volatile("s_waitcnt lgkmcnt(%0)" ::"n"(n) : "memory")
; template <int EPI, bool SWP> ...
;     ...
;     LDA(0, 1); WAIT_V(4); BAR; LGKM(0); SCHED(); MMA(1, 0, B0); MMA(1, 1, B1); BAR; SCHED(); }
;   { LDB(B0, 1, 0); LDA(1, 0); WAIT_V(2); BAR; LGKM(0); SCHED(); MMA(0, 0, B0); BAR; SCHED();
	s_waitcnt lgkmcnt(0)
	v_mfma_f32_16x16x32_bf16 v[92:95], v[96:99], v[130:133], v[92:95]
	v_mfma_f32_16x16x32_bf16 v[88:91], v[112:115], v[130:133], v[88:91]
	v_mfma_f32_16x16x32_bf16 v[84:87], v[96:99], v[156:159], v[84:87]
	v_mfma_f32_16x16x32_bf16 v[80:83], v[112:115], v[156:159], v[80:83]
	v_mfma_f32_16x16x32_bf16 v[76:79], v[96:99], v[164:167], v[76:79]
	v_mfma_f32_16x16x32_bf16 v[72:75], v[112:115], v[164:167], v[72:75]
	v_mfma_f32_16x16x32_bf16 v[68:71], v[96:99], v[172:175], v[68:71]
	v_mfma_f32_16x16x32_bf16 v[64:67], v[112:115], v[172:175], v[64:67]
	v_mfma_f32_16x16x32_bf16 v[92:95], v[104:107], v[134:137], v[92:95]
	v_mfma_f32_16x16x32_bf16 v[196:199], v[120:123], v[134:137], v[88:91]
	v_mfma_f32_16x16x32_bf16 v[84:87], v[104:107], v[160:163], v[84:87]
	v_mfma_f32_16x16x32_bf16 v[200:203], v[120:123], v[160:163], v[80:83]
	v_mfma_f32_16x16x32_bf16 v[76:79], v[104:107], v[168:171], v[76:79]
	v_mfma_f32_16x16x32_bf16 v[204:207], v[120:123], v[168:171], v[72:75]
	v_mfma_f32_16x16x32_bf16 v[68:71], v[104:107], v[176:179], v[68:71]
	v_mfma_f32_16x16x32_bf16 v[176:179], v[120:123], v[176:179], v[64:67]
	s_barrier
	ds_read_b128 v[64:67], v227 offset:0
	ds_read_b128 v[72:75], v227 offset:0x400
	ds_read_b128 v[80:83], v227 offset:0x800
	ds_read_b128 v[88:91], v227 offset:0xc00
	ds_read_b128 v[156:159], v227 offset:0x1000
	ds_read_b128 v[160:163], v227 offset:0x1400
	ds_read_b128 v[164:167], v227 offset:0x1800
	ds_read_b128 v[168:171], v227 offset:0x1c00
	s_waitcnt vmcnt(4)
	s_barrier
	s_waitcnt lgkmcnt(0)
	v_mfma_f32_16x16x32_bf16 v[60:63], v[140:143], v[64:67], v[60:63]
	v_mfma_f32_16x16x32_bf16 v[56:59], v[148:151], v[64:67], v[56:59]
	v_mfma_f32_16x16x32_bf16 v[52:55], v[140:143], v[80:83], v[52:55]
	v_mfma_f32_16x16x32_bf16 v[48:51], v[148:151], v[80:83], v[48:51]
	v_mfma_f32_16x16x32_bf16 v[44:47], v[140:143], v[156:159], v[44:47]
	v_mfma_f32_16x16x32_bf16 v[40:43], v[148:151], v[156:159], v[40:43]
	v_mfma_f32_16x16x32_bf16 v[36:39], v[140:143], v[164:167], v[36:39]
	v_mfma_f32_16x16x32_bf16 v[32:35], v[148:151], v[164:167], v[32:35]
	v_mfma_f32_16x16x32_bf16 v[60:63], v[144:147], v[72:75], v[60:63]
	v_mfma_f32_16x16x32_bf16 v[128:131], v[152:155], v[72:75], v[56:59]
	v_mfma_f32_16x16x32_bf16 v[52:55], v[144:147], v[88:91], v[52:55]
	v_mfma_f32_16x16x32_bf16 v[132:135], v[152:155], v[88:91], v[48:51]
	v_mfma_f32_16x16x32_bf16 v[44:47], v[144:147], v[160:163], v[44:47]
	v_mfma_f32_16x16x32_bf16 v[136:139], v[152:155], v[160:163], v[40:43]
	v_mfma_f32_16x16x32_bf16 v[36:39], v[144:147], v[168:171], v[36:39]
	v_mfma_f32_16x16x32_bf16 v[140:143], v[152:155], v[168:171], v[32:35]
	v_mfma_f32_16x16x32_bf16 v[28:31], v[96:99], v[64:67], v[28:31]
	v_mfma_f32_16x16x32_bf16 v[24:27], v[112:115], v[64:67], v[24:27]
	v_mfma_f32_16x16x32_bf16 v[20:23], v[96:99], v[80:83], v[20:23]
	v_mfma_f32_16x16x32_bf16 v[16:19], v[112:115], v[80:83], v[16:19]
	v_mfma_f32_16x16x32_bf16 v[12:15], v[96:99], v[156:159], v[12:15]
	v_mfma_f32_16x16x32_bf16 v[8:11], v[112:115], v[156:159], v[8:11]
	v_mfma_f32_16x16x32_bf16 v[4:7], v[96:99], v[164:167], v[4:7]
	v_mfma_f32_16x16x32_bf16 v[0:3], v[112:115], v[164:167], v[0:3]
	v_mfma_f32_16x16x32_bf16 v[28:31], v[104:107], v[72:75], v[28:31]
	v_mfma_f32_16x16x32_bf16 v[144:147], v[120:123], v[72:75], v[24:27]
	v_mfma_f32_16x16x32_bf16 v[20:23], v[104:107], v[88:91], v[20:23]
	v_mfma_f32_16x16x32_bf16 v[148:151], v[120:123], v[88:91], v[16:19]
	v_mfma_f32_16x16x32_bf16 v[12:15], v[104:107], v[160:163], v[12:15]
	v_mfma_f32_16x16x32_bf16 v[152:155], v[120:123], v[160:163], v[8:11]
	v_mfma_f32_16x16x32_bf16 v[4:7], v[104:107], v[168:171], v[4:7]
	v_mfma_f32_16x16x32_bf16 v[156:159], v[120:123], v[168:171], v[0:3]
	s_barrier
	ds_read_b128 v[0:3], v229 offset:0
	ds_read_b128 v[8:11], v229 offset:0x400
	ds_read_b128 v[16:19], v229 offset:0x800
	ds_read_b128 v[24:27], v229 offset:0xc00
	ds_read_b128 v[32:35], v230 offset:0
	ds_read_b128 v[40:43], v230 offset:0x400
	ds_read_b128 v[48:51], v230 offset:0x800
	ds_read_b128 v[56:59], v230 offset:0xc00
	ds_read_b128 v[64:67], v230 offset:0x1000
	ds_read_b128 v[220:223], v230 offset:0x1400
	ds_read_b128 v[238:241], v230 offset:0x1800
	ds_read_b128 v[242:245], v230 offset:0x1c00
	s_waitcnt vmcnt(2)
	s_barrier
; #define WAIT_V(n) asm volatile("s_waitcnt vmcnt(%0)" ::"n"(n) : "memory")
; #define SCHED() __builtin_amdgcn_sched_barrier(0)
; #define LGKM(n) asm volatile("s_waitcnt lgkmcnt(%0)" ::"n"(n) : "memory")
; #define STAGE_AX(AG, b, h, kt) do { _Pragma("unroll") for (int i = 0; i < 2; ++i)                                    \
;       __builtin_amdgcn_global_load_lds((const unsigned*)(((AG) + ((size_t)(kt) * (BK * 2) + (size_t)((h) * 2 + i) * 128 * lda)) + aoff), \
;                                        (unsigned*)(shm + SLOTA(b, h) + wid * 1024 + i * 8192), 16, 0, 0); } while (0)
; #define STAGE_BX(BG, b, h, kt) do { _Pragma("unroll") for (int i = 0; i < 2; ++i)                                    \
;       __builtin_amdgcn_global_load_lds((const unsigned*)(((BG) + ((size_t)(kt) * (BK * 2) + (size_t)((h) * 2 + i) * 128 * K)) + boff),   \
;                                        (unsigned*)(shm + SLOTB(b, h) + wid * 1024 + i * 8192), 16, 0, 0); } while (0)
; #define LDA(b, h) do { const unsigned pa_ = lds0 + SLOTA(b, h) + wr * 8192 + laneoff; _Pragma("unroll") for (int m = 0; m < 4; ++m)   \
;       _Pragma("unroll") for (int k = 0; k < 2; ++k) DSR(At[m][k], pa_, m * 2048 + k * 1024); } while (0)
; #define LDB(dst, b, h) do { const unsigned pb_ = lds0 + SLOTB(b, h) + wc * 4096 + laneoff; _Pragma("unroll") for (int n = 0; n < 2; ++n) \
;       _Pragma("unroll") for (int k = 0; k < 2; ++k) DSR(dst[n][k], pb_, n * 2048 + k * 1024); } while (0)
; #define BAR __builtin_amdgcn_s_barrier()
; #define LGKM(n) asm volatile("s_waitcnt lgkmcnt(%0)" ::"n"(n) : "memory")
; template <int EPI, bool SWP> ...
;     ...
;   { LDB(B0, 1, 0); LDA(1, 0); WAIT_V(2); BAR; LGKM(0); SCHED(); MMA(0, 0, B0); BAR; SCHED();
;     LDB(B1, 1, 1); WAIT_V(0); BAR; LGKM(0); SCHED(); MMA(0, 1, B1); BAR; SCHED();
;     LDA(1, 1);
;     if (has_next) { STAGE_BX(Bg_n, 0, 0, 0); STAGE_AX(Ag_n, 0, 0, 0); STAGE_BX(Bg_n, 0, 1, 0); STAGE_AX(Ag_n, 0, 1, 0); }
	s_waitcnt lgkmcnt(0)
	v_mfma_f32_16x16x32_bf16 v[72:75], v[0:3], v[32:35], v[124:127]
	v_mfma_f32_16x16x32_bf16 v[120:123], v[8:11], v[40:43], v[72:75]
	v_mfma_f32_16x16x32_bf16 v[72:75], v[16:19], v[32:35], v[180:183]
	v_mfma_f32_16x16x32_bf16 v[124:127], v[24:27], v[40:43], v[72:75]
	v_mfma_f32_16x16x32_bf16 v[72:75], v[0:3], v[48:51], v[116:119]
	v_mfma_f32_16x16x32_bf16 v[112:115], v[8:11], v[56:59], v[72:75]
	v_mfma_f32_16x16x32_bf16 v[72:75], v[16:19], v[48:51], v[184:187]
	v_mfma_f32_16x16x32_bf16 v[116:119], v[24:27], v[56:59], v[72:75]
	v_mfma_f32_16x16x32_bf16 v[72:75], v[0:3], v[64:67], v[108:111]
	v_mfma_f32_16x16x32_bf16 v[104:107], v[8:11], v[220:223], v[72:75]
	v_mfma_f32_16x16x32_bf16 v[72:75], v[16:19], v[64:67], v[188:191]
	v_mfma_f32_16x16x32_bf16 v[108:111], v[24:27], v[220:223], v[72:75]
	v_mfma_f32_16x16x32_bf16 v[72:75], v[0:3], v[238:241], v[100:103]
	v_mfma_f32_16x16x32_bf16 v[96:99], v[8:11], v[242:245], v[72:75]
	v_mfma_f32_16x16x32_bf16 v[72:75], v[16:19], v[238:241], v[192:195]
	v_mfma_f32_16x16x32_bf16 v[100:103], v[24:27], v[242:245], v[72:75]
	s_barrier
	ds_read_b128 v[160:163], v231 offset:0
	ds_read_b128 v[164:167], v231 offset:0x400
	ds_read_b128 v[168:171], v231 offset:0x800
	ds_read_b128 v[172:175], v231 offset:0xc00
	s_waitcnt vmcnt(0)
	s_barrier
	s_waitcnt lgkmcnt(0)
	v_mfma_f32_16x16x32_bf16 v[72:75], v[160:163], v[32:35], v[92:95]
	v_mfma_f32_16x16x32_bf16 v[32:35], v[168:171], v[32:35], v[196:199]
	v_mfma_f32_16x16x32_bf16 v[92:95], v[172:175], v[40:43], v[32:35]
	v_mfma_f32_16x16x32_bf16 v[32:35], v[160:163], v[48:51], v[84:87]
	v_mfma_f32_16x16x32_bf16 v[80:83], v[164:167], v[56:59], v[32:35]
	v_mfma_f32_16x16x32_bf16 v[32:35], v[168:171], v[48:51], v[200:203]
	v_mfma_f32_16x16x32_bf16 v[84:87], v[172:175], v[56:59], v[32:35]
	v_mfma_f32_16x16x32_bf16 v[32:35], v[160:163], v[64:67], v[76:79]
	v_mfma_f32_16x16x32_bf16 v[88:91], v[164:167], v[40:43], v[72:75]
	v_mfma_f32_16x16x32_bf16 v[72:75], v[164:167], v[220:223], v[32:35]
	v_mfma_f32_16x16x32_bf16 v[32:35], v[168:171], v[64:67], v[204:207]
	v_mfma_f32_16x16x32_bf16 v[76:79], v[172:175], v[220:223], v[32:35]
	v_mfma_f32_16x16x32_bf16 v[32:35], v[160:163], v[238:241], v[68:71]
	v_mfma_f32_16x16x32_bf16 v[64:67], v[164:167], v[242:245], v[32:35]
	v_mfma_f32_16x16x32_bf16 v[32:35], v[168:171], v[238:241], v[176:179]
	v_mfma_f32_16x16x32_bf16 v[68:71], v[172:175], v[242:245], v[32:35]
	s_barrier
	ds_read_b128 v[200:203], v232 offset:0
	ds_read_b128 v[204:207], v232 offset:0x400
	ds_read_b128 v[192:195], v232 offset:0x800
	ds_read_b128 v[196:199], v232 offset:0xc00
	ds_read_b128 v[184:187], v232 offset:0x1000
	ds_read_b128 v[188:191], v232 offset:0x1400
	ds_read_b128 v[176:179], v232 offset:0x1800
	ds_read_b128 v[180:183], v232 offset:0x1c00
	s_and_b64 vcc, exec, s[44:45]
	v_lshl_add_u64 v[220:221], s[50:51], 0, v[208:209]
	v_lshl_add_u64 v[222:223], s[48:49], 0, v[208:209]
	s_cbranch_vccz .LBB0_388
	s_mov_b32 m0, s16
	v_lshl_add_u64 v[32:33], v[220:221], 0, s[4:5]
	global_load_lds_dwordx4 v[220:221], off
	s_mov_b32 m0, s17
	s_nop 0
	global_load_lds_dwordx4 v[32:33], off
	s_mov_b32 m0, s3
	v_lshl_add_u64 v[32:33], v[222:223], 0, s[4:5]
	global_load_lds_dwordx4 v[222:223], off
	s_mov_b32 m0, s18
	s_nop 0
	global_load_lds_dwordx4 v[32:33], off
	v_lshl_add_u64 v[32:33], v[220:221], 0, s[8:9]
	s_mov_b32 m0, s19
	s_nop 0
	global_load_lds_dwordx4 v[32:33], off
	v_lshl_add_u64 v[32:33], v[220:221], 0, s[10:11]
	s_mov_b32 m0, s60
	s_nop 0
	global_load_lds_dwordx4 v[32:33], off
	v_lshl_add_u64 v[32:33], v[222:223], 0, s[8:9]
	s_mov_b32 m0, s61
	s_nop 0
	global_load_lds_dwordx4 v[32:33], off
	v_lshl_add_u64 v[32:33], v[222:223], 0, s[10:11]
	s_mov_b32 m0, s62
	s_nop 0
	global_load_lds_dwordx4 v[32:33], off

; #define WAIT_V(n) asm volatile("s_waitcnt vmcnt(%0)" ::"n"(n) : "memory")
; #define SCHED() __builtin_amdgcn_sched_barrier(0)
; #define LGKM(n) asm volatile("s_waitcnt lgkmcnt(%0)" ::"n"(n) : "memory")
; #define STAGE_A(b, h, kt) STAGE_AX(Ag, b, h, kt)
; #define STAGE_B(b, h, kt) STAGE_BX(Bg, b, h, kt)
; #define LDA(b, h) do { const unsigned pa_ = lds0 + SLOTA(b, h) + wr * 8192 + laneoff; _Pragma("unroll") for (int m = 0; m < 4; ++m)   \
;       _Pragma("unroll") for (int k = 0; k < 2; ++k) DSR(At[m][k], pa_, m * 2048 + k * 1024); } while (0)
; #define LDB(dst, b, h) do { const unsigned pb_ = lds0 + SLOTB(b, h) + wc * 4096 + laneoff; _Pragma("unroll") for (int n = 0; n < 2; ++n) \
;       _Pragma("unroll") for (int k = 0; k < 2; ++k) DSR(dst[n][k], pb_, n * 2048 + k * 1024); } while (0)
; #define BAR __builtin_amdgcn_s_barrier()
; #define LGKM(n) asm volatile("s_waitcnt lgkmcnt(%0)" ::"n"(n) : "memory")
; template <int EPI, bool SWP> ...
;     ...
;     LDB(B0, 0, 0); LDA(0, 0); STAGE_A(1, 1, t + 1);
;     LGKM(8); BAR; LGKM(0); SCHED(); MMA(0, 0, B0); BAR; SCHED();
;     LDB(B1, 0, 1); STAGE_B(0, 0, t + 2);
;     BAR; LGKM(0); SCHED(); MMA(0, 1, B1); BAR; SCHED();
;     LDA(0, 1); STAGE_A(0, 0, t + 2);
;     BAR; LGKM(0); SCHED(); MMA(1, 0, B0); BAR; SCHED();
;     STAGE_B(0, 1, t + 2);
;     WAIT_V(6); BAR; SCHED(); MMA(1, 1, B1); BAR; SCHED();
.LBB0_428:
	ds_read_b128 v[130:133], v201 offset:0
	ds_read_b128 v[134:137], v201 offset:0x400
	ds_read_b128 v[138:141], v201 offset:0x800
	ds_read_b128 v[142:145], v201 offset:0xc00
	ds_read_b128 v[146:149], v202 offset:0
	ds_read_b128 v[150:153], v202 offset:0x400
	ds_read_b128 v[154:157], v202 offset:0x800
	ds_read_b128 v[158:161], v202 offset:0xc00
	ds_read_b128 v[162:165], v202 offset:0x1000
	ds_read_b128 v[166:169], v202 offset:0x1400
	ds_read_b128 v[170:173], v202 offset:0x1800
	v_lshl_add_u64 v[198:199], s[68:69], 0, v[196:197]
	s_add_i32 s63, s3, 0xc000
	ds_read_b128 v[174:177], v202 offset:0x1c00
	v_lshl_add_u64 v[178:179], v[198:199], 0, s[40:41]
	s_mov_b32 m0, s63
	s_nop 0
	global_load_lds_dwordx4 v[178:179], off
	v_lshl_add_u64 v[178:179], v[198:199], 0, s[42:43]
	s_mov_b32 m0, s81
	s_nop 0
	global_load_lds_dwordx4 v[178:179], off
	s_waitcnt lgkmcnt(8)
	s_barrier
	s_waitcnt lgkmcnt(0)
	v_mfma_f32_16x16x32_bf16 v[124:127], v[130:133], v[146:149], v[124:127]
	v_mfma_f32_16x16x32_bf16 v[120:123], v[138:141], v[146:149], v[120:123]
	v_mfma_f32_16x16x32_bf16 v[116:119], v[130:133], v[154:157], v[116:119]
	v_mfma_f32_16x16x32_bf16 v[112:115], v[138:141], v[154:157], v[112:115]
	v_mfma_f32_16x16x32_bf16 v[108:111], v[130:133], v[162:165], v[108:111]
	v_mfma_f32_16x16x32_bf16 v[104:107], v[138:141], v[162:165], v[104:107]
	v_mfma_f32_16x16x32_bf16 v[100:103], v[130:133], v[170:173], v[100:103]
	v_mfma_f32_16x16x32_bf16 v[96:99], v[138:141], v[170:173], v[96:99]
	v_mfma_f32_16x16x32_bf16 v[124:127], v[134:137], v[150:153], v[124:127]
	v_mfma_f32_16x16x32_bf16 v[120:123], v[142:145], v[150:153], v[120:123]
	v_mfma_f32_16x16x32_bf16 v[116:119], v[134:137], v[158:161], v[116:119]
	v_mfma_f32_16x16x32_bf16 v[112:115], v[142:145], v[158:161], v[112:115]
	v_mfma_f32_16x16x32_bf16 v[108:111], v[134:137], v[166:169], v[108:111]
	v_mfma_f32_16x16x32_bf16 v[104:107], v[142:145], v[166:169], v[104:107]
	v_mfma_f32_16x16x32_bf16 v[100:103], v[134:137], v[174:177], v[100:103]
	v_mfma_f32_16x16x32_bf16 v[96:99], v[142:145], v[174:177], v[96:99]
	s_barrier
	ds_read_b128 v[178:181], v203 offset:0
	ds_read_b128 v[182:185], v203 offset:0x400
	ds_read_b128 v[186:189], v203 offset:0x800
	v_lshl_add_u64 v[218:219], s[70:71], 0, v[196:197]
	s_mov_b64 s[72:73], 0xe800100
	s_mov_b32 m0, s17
	ds_read_b128 v[190:193], v203 offset:0xc00
	v_lshl_add_u64 v[220:221], v[218:219], 0, s[72:73]
	s_mov_b64 s[72:73], 0xe840100
	global_load_lds_dwordx4 v[220:221], off
	v_lshl_add_u64 v[220:221], v[218:219], 0, s[72:73]
	s_mov_b32 m0, s18
	s_nop 0
	global_load_lds_dwordx4 v[220:221], off
	s_barrier
	s_waitcnt lgkmcnt(0)
	v_mfma_f32_16x16x32_bf16 v[92:95], v[178:181], v[146:149], v[92:95]
	v_mfma_f32_16x16x32_bf16 v[88:91], v[186:189], v[146:149], v[88:91]
	v_mfma_f32_16x16x32_bf16 v[84:87], v[178:181], v[154:157], v[84:87]
	v_mfma_f32_16x16x32_bf16 v[80:83], v[186:189], v[154:157], v[80:83]
	v_mfma_f32_16x16x32_bf16 v[76:79], v[178:181], v[162:165], v[76:79]
	v_mfma_f32_16x16x32_bf16 v[72:75], v[186:189], v[162:165], v[72:75]
	v_mfma_f32_16x16x32_bf16 v[68:71], v[178:181], v[170:173], v[68:71]
	v_mfma_f32_16x16x32_bf16 v[64:67], v[186:189], v[170:173], v[64:67]
	v_mfma_f32_16x16x32_bf16 v[92:95], v[182:185], v[150:153], v[92:95]
	v_mfma_f32_16x16x32_bf16 v[88:91], v[190:193], v[150:153], v[88:91]
	v_mfma_f32_16x16x32_bf16 v[84:87], v[182:185], v[158:161], v[84:87]
	v_mfma_f32_16x16x32_bf16 v[80:83], v[190:193], v[158:161], v[80:83]
	v_mfma_f32_16x16x32_bf16 v[76:79], v[182:185], v[166:169], v[76:79]
	v_mfma_f32_16x16x32_bf16 v[72:75], v[190:193], v[166:169], v[72:75]
	v_mfma_f32_16x16x32_bf16 v[68:71], v[182:185], v[174:177], v[68:71]
	v_mfma_f32_16x16x32_bf16 v[64:67], v[190:193], v[174:177], v[64:67]
	s_barrier
	ds_read_b128 v[146:149], v204 offset:0
	ds_read_b128 v[150:153], v204 offset:0x400
	ds_read_b128 v[154:157], v204 offset:0x800
	ds_read_b128 v[158:161], v204 offset:0xc00
	ds_read_b128 v[162:165], v204 offset:0x1000
	ds_read_b128 v[166:169], v204 offset:0x1400
	ds_read_b128 v[170:173], v204 offset:0x1800
	s_mov_b64 s[72:73], 0x100
	s_mov_b32 m0, s3
	ds_read_b128 v[174:177], v204 offset:0x1c00
	v_lshl_add_u64 v[220:221], v[198:199], 0, s[72:73]
	s_mov_b64 s[72:73], 0x40100
	global_load_lds_dwordx4 v[220:221], off
	v_lshl_add_u64 v[220:221], v[198:199], 0, s[72:73]
	s_mov_b32 m0, s19
	s_nop 0
	global_load_lds_dwordx4 v[220:221], off
	s_barrier
	s_waitcnt lgkmcnt(0)
	v_mfma_f32_16x16x32_bf16 v[60:63], v[130:133], v[146:149], v[60:63]
	v_mfma_f32_16x16x32_bf16 v[56:59], v[138:141], v[146:149], v[56:59]
	v_mfma_f32_16x16x32_bf16 v[52:55], v[130:133], v[154:157], v[52:55]
	v_mfma_f32_16x16x32_bf16 v[48:51], v[138:141], v[154:157], v[48:51]
	v_mfma_f32_16x16x32_bf16 v[44:47], v[130:133], v[162:165], v[44:47]
	v_mfma_f32_16x16x32_bf16 v[40:43], v[138:141], v[162:165], v[40:43]
	v_mfma_f32_16x16x32_bf16 v[36:39], v[130:133], v[170:173], v[36:39]
	v_mfma_f32_16x16x32_bf16 v[32:35], v[138:141], v[170:173], v[32:35]
	v_mfma_f32_16x16x32_bf16 v[60:63], v[134:137], v[150:153], v[60:63]
	v_mfma_f32_16x16x32_bf16 v[56:59], v[142:145], v[150:153], v[56:59]
	v_mfma_f32_16x16x32_bf16 v[52:55], v[134:137], v[158:161], v[52:55]
	v_mfma_f32_16x16x32_bf16 v[48:51], v[142:145], v[158:161], v[48:51]
	v_mfma_f32_16x16x32_bf16 v[44:47], v[134:137], v[166:169], v[44:47]
	v_mfma_f32_16x16x32_bf16 v[40:43], v[142:145], v[166:169], v[40:43]
	v_mfma_f32_16x16x32_bf16 v[36:39], v[134:137], v[174:177], v[36:39]
	v_mfma_f32_16x16x32_bf16 v[32:35], v[142:145], v[174:177], v[32:35]
	s_barrier
; #define WAIT_V(n) asm volatile("s_waitcnt vmcnt(%0)" ::"n"(n) : "memory")
; #define SCHED() __builtin_amdgcn_sched_barrier(0)
; #define LGKM(n) asm volatile("s_waitcnt lgkmcnt(%0)" ::"n"(n) : "memory")
; #define STAGE_A(b, h, kt) STAGE_AX(Ag, b, h, kt)
; #define STAGE_B(b, h, kt) STAGE_BX(Bg, b, h, kt)
; #define LDA(b, h) do { const unsigned pa_ = lds0 + SLOTA(b, h) + wr * 8192 + laneoff; _Pragma("unroll") for (int m = 0; m < 4; ++m)   \
;       _Pragma("unroll") for (int k = 0; k < 2; ++k) DSR(At[m][k], pa_, m * 2048 + k * 1024); } while (0)
; #define LDB(dst, b, h) do { const unsigned pb_ = lds0 + SLOTB(b, h) + wc * 4096 + laneoff; _Pragma("unroll") for (int n = 0; n < 2; ++n) \
;       _Pragma("unroll") for (int k = 0; k < 2; ++k) DSR(dst[n][k], pb_, n * 2048 + k * 1024); } while (0)
; #define BAR __builtin_amdgcn_s_barrier()
; #define LGKM(n) asm volatile("s_waitcnt lgkmcnt(%0)" ::"n"(n) : "memory")
; template <int EPI, bool SWP> ...
;     ...
;     WAIT_V(6); BAR; SCHED(); MMA(1, 1, B1); BAR; SCHED();
;     LDB(B0, 1, 0); LDA(1, 0); STAGE_A(0, 1, t + 2);
;     LGKM(8); BAR; LGKM(0); SCHED(); MMA(0, 0, B0); BAR; SCHED();
;     LDB(B1, 1, 1); STAGE_B(1, 0, t + 3);
;     BAR; LGKM(0); SCHED(); MMA(0, 1, B1); BAR; SCHED();
;     LDA(1, 1); STAGE_A(1, 0, t + 3);
	s_mov_b64 s[72:73], 0xe880100
	s_mov_b32 m0, s74
	v_lshl_add_u64 v[130:131], v[218:219], 0, s[72:73]
	s_mov_b64 s[72:73], 0xe8c0100
	global_load_lds_dwordx4 v[130:131], off
	v_lshl_add_u64 v[130:131], v[218:219], 0, s[72:73]
	s_mov_b32 m0, s75
	s_nop 0
	global_load_lds_dwordx4 v[130:131], off
	s_waitcnt vmcnt(6)
	s_barrier
	v_mfma_f32_16x16x32_bf16 v[28:31], v[178:181], v[146:149], v[28:31]
	v_mfma_f32_16x16x32_bf16 v[24:27], v[186:189], v[146:149], v[24:27]
	v_mfma_f32_16x16x32_bf16 v[20:23], v[178:181], v[154:157], v[20:23]
	v_mfma_f32_16x16x32_bf16 v[16:19], v[186:189], v[154:157], v[16:19]
	v_mfma_f32_16x16x32_bf16 v[12:15], v[178:181], v[162:165], v[12:15]
	v_mfma_f32_16x16x32_bf16 v[8:11], v[186:189], v[162:165], v[8:11]
	v_mfma_f32_16x16x32_bf16 v[4:7], v[178:181], v[170:173], v[4:7]
	v_mfma_f32_16x16x32_bf16 v[0:3], v[186:189], v[170:173], v[0:3]
	v_mfma_f32_16x16x32_bf16 v[28:31], v[182:185], v[150:153], v[28:31]
	v_mfma_f32_16x16x32_bf16 v[24:27], v[190:193], v[150:153], v[24:27]
	v_mfma_f32_16x16x32_bf16 v[20:23], v[182:185], v[158:161], v[20:23]
	v_mfma_f32_16x16x32_bf16 v[16:19], v[190:193], v[158:161], v[16:19]
	v_mfma_f32_16x16x32_bf16 v[12:15], v[182:185], v[166:169], v[12:15]
	v_mfma_f32_16x16x32_bf16 v[8:11], v[190:193], v[166:169], v[8:11]
	v_mfma_f32_16x16x32_bf16 v[4:7], v[182:185], v[174:177], v[4:7]
	v_mfma_f32_16x16x32_bf16 v[0:3], v[190:193], v[174:177], v[0:3]
	s_barrier
	ds_read_b128 v[130:133], v205 offset:0
	ds_read_b128 v[134:137], v205 offset:0x400
	ds_read_b128 v[138:141], v205 offset:0x800
	ds_read_b128 v[142:145], v205 offset:0xc00
	ds_read_b128 v[146:149], v206 offset:0
	ds_read_b128 v[150:153], v206 offset:0x400
	ds_read_b128 v[154:157], v206 offset:0x800
	ds_read_b128 v[158:161], v206 offset:0xc00
	ds_read_b128 v[162:165], v206 offset:0x1000
	ds_read_b128 v[166:169], v206 offset:0x1400
	ds_read_b128 v[170:173], v206 offset:0x1800
	s_mov_b64 s[72:73], 0x80100
	s_mov_b32 m0, s76
	ds_read_b128 v[174:177], v206 offset:0x1c00
	v_lshl_add_u64 v[178:179], v[198:199], 0, s[72:73]
	s_mov_b64 s[72:73], 0xc0100
	global_load_lds_dwordx4 v[178:179], off
	v_lshl_add_u64 v[178:179], v[198:199], 0, s[72:73]
	s_mov_b32 m0, s77
	s_nop 0
	global_load_lds_dwordx4 v[178:179], off
	s_waitcnt lgkmcnt(8)
	s_barrier
	s_waitcnt lgkmcnt(0)
	v_mfma_f32_16x16x32_bf16 v[124:127], v[130:133], v[146:149], v[124:127]
	v_mfma_f32_16x16x32_bf16 v[120:123], v[138:141], v[146:149], v[120:123]
	v_mfma_f32_16x16x32_bf16 v[116:119], v[130:133], v[154:157], v[116:119]
	v_mfma_f32_16x16x32_bf16 v[112:115], v[138:141], v[154:157], v[112:115]
	v_mfma_f32_16x16x32_bf16 v[108:111], v[130:133], v[162:165], v[108:111]
	v_mfma_f32_16x16x32_bf16 v[104:107], v[138:141], v[162:165], v[104:107]
	v_mfma_f32_16x16x32_bf16 v[100:103], v[130:133], v[170:173], v[100:103]
	v_mfma_f32_16x16x32_bf16 v[96:99], v[138:141], v[170:173], v[96:99]
	v_mfma_f32_16x16x32_bf16 v[124:127], v[134:137], v[150:153], v[124:127]
	v_mfma_f32_16x16x32_bf16 v[120:123], v[142:145], v[150:153], v[120:123]
	v_mfma_f32_16x16x32_bf16 v[116:119], v[134:137], v[158:161], v[116:119]
	v_mfma_f32_16x16x32_bf16 v[112:115], v[142:145], v[158:161], v[112:115]
	v_mfma_f32_16x16x32_bf16 v[108:111], v[134:137], v[166:169], v[108:111]
	v_mfma_f32_16x16x32_bf16 v[104:107], v[142:145], v[166:169], v[104:107]
	v_mfma_f32_16x16x32_bf16 v[100:103], v[134:137], v[174:177], v[100:103]
	v_mfma_f32_16x16x32_bf16 v[96:99], v[142:145], v[174:177], v[96:99]
	s_barrier
	ds_read_b128 v[178:181], v207 offset:0
	ds_read_b128 v[182:185], v207 offset:0x400
	ds_read_b128 v[186:189], v207 offset:0x800
	s_mov_b64 s[72:73], 0xe800180
	s_add_i32 s67, s3, 0x18000
	ds_read_b128 v[190:193], v207 offset:0xc00
	v_lshl_add_u64 v[220:221], v[218:219], 0, s[72:73]
	s_mov_b32 m0, s67
	s_mov_b64 s[72:73], 0xe840180
	global_load_lds_dwordx4 v[220:221], off
	v_lshl_add_u64 v[220:221], v[218:219], 0, s[72:73]
	s_mov_b32 m0, s78
	s_nop 0
	global_load_lds_dwordx4 v[220:221], off
	s_barrier
	s_waitcnt lgkmcnt(0)
	v_mfma_f32_16x16x32_bf16 v[92:95], v[178:181], v[146:149], v[92:95]
	v_mfma_f32_16x16x32_bf16 v[88:91], v[186:189], v[146:149], v[88:91]
	v_mfma_f32_16x16x32_bf16 v[84:87], v[178:181], v[154:157], v[84:87]
	v_mfma_f32_16x16x32_bf16 v[80:83], v[186:189], v[154:157], v[80:83]
	v_mfma_f32_16x16x32_bf16 v[76:79], v[178:181], v[162:165], v[76:79]
	v_mfma_f32_16x16x32_bf16 v[72:75], v[186:189], v[162:165], v[72:75]
	v_mfma_f32_16x16x32_bf16 v[68:71], v[178:181], v[170:173], v[68:71]
	v_mfma_f32_16x16x32_bf16 v[64:67], v[186:189], v[170:173], v[64:67]
	v_mfma_f32_16x16x32_bf16 v[92:95], v[182:185], v[150:153], v[92:95]
	v_mfma_f32_16x16x32_bf16 v[88:91], v[190:193], v[150:153], v[88:91]
	v_mfma_f32_16x16x32_bf16 v[84:87], v[182:185], v[158:161], v[84:87]
	v_mfma_f32_16x16x32_bf16 v[80:83], v[190:193], v[158:161], v[80:83]
	v_mfma_f32_16x16x32_bf16 v[76:79], v[182:185], v[166:169], v[76:79]
	v_mfma_f32_16x16x32_bf16 v[72:75], v[190:193], v[166:169], v[72:75]
	v_mfma_f32_16x16x32_bf16 v[68:71], v[182:185], v[174:177], v[68:71]
	v_mfma_f32_16x16x32_bf16 v[64:67], v[190:193], v[174:177], v[64:67]
	s_barrier
	ds_read_b128 v[146:149], v208 offset:0
	ds_read_b128 v[150:153], v208 offset:0x400
	ds_read_b128 v[154:157], v208 offset:0x800
	ds_read_b128 v[158:161], v208 offset:0xc00
	ds_read_b128 v[162:165], v208 offset:0x1000
	ds_read_b128 v[166:169], v208 offset:0x1400
	s_mov_b64 s[72:73], 0x180
	ds_read_b128 v[170:173], v208 offset:0x1800
	v_lshl_add_u64 v[220:221], v[198:199], 0, s[72:73]
	s_add_i32 s72, s3, 0x8000
	ds_read_b128 v[174:177], v208 offset:0x1c00
	s_mov_b32 m0, s72
	s_mov_b64 s[84:85], 0x40180
	global_load_lds_dwordx4 v[220:221], off
	v_lshl_add_u64 v[198:199], v[198:199], 0, s[84:85]
	s_mov_b32 m0, s79
	s_nop 0
	global_load_lds_dwordx4 v[198:199], off
	s_barrier
; #define WAIT_V(n) asm volatile("s_waitcnt vmcnt(%0)" ::"n"(n) : "memory")
; #define SCHED() __builtin_amdgcn_sched_barrier(0)
; #define LGKM(n) asm volatile("s_waitcnt lgkmcnt(%0)" ::"n"(n) : "memory")
; #define STAGE_A(b, h, kt) STAGE_AX(Ag, b, h, kt)
; #define STAGE_B(b, h, kt) STAGE_BX(Bg, b, h, kt)
; #define LDA(b, h) do { const unsigned pa_ = lds0 + SLOTA(b, h) + wr * 8192 + laneoff; _Pragma("unroll") for (int m = 0; m < 4; ++m)   \
;       _Pragma("unroll") for (int k = 0; k < 2; ++k) DSR(At[m][k], pa_, m * 2048 + k * 1024); } while (0)
; #define LDB(dst, b, h) do { const unsigned pb_ = lds0 + SLOTB(b, h) + wc * 4096 + laneoff; _Pragma("unroll") for (int n = 0; n < 2; ++n) \
;       _Pragma("unroll") for (int k = 0; k < 2; ++k) DSR(dst[n][k], pb_, n * 2048 + k * 1024); } while (0)
; #define BAR __builtin_amdgcn_s_barrier()
; #define LGKM(n) asm volatile("s_waitcnt lgkmcnt(%0)" ::"n"(n) : "memory")
; template <int EPI, bool SWP> ...
;     ...
;     BAR; LGKM(0); SCHED(); MMA(1, 0, B0); BAR; SCHED();
;     STAGE_B(1, 1, t + 3);
;     WAIT_V(6); BAR; SCHED(); MMA(1, 1, B1); BAR; SCHED();
;   }
;   { LDB(B0, 0, 0); LDA(0, 0); STAGE_A(1, 1, nt - 1);
;     BAR; LGKM(0); SCHED(); MMA(0, 0, B0); BAR; SCHED();
;     LDB(B1, 0, 1); BAR; LGKM(0); SCHED(); MMA(0, 1, B1); BAR; SCHED();
	s_waitcnt lgkmcnt(0)
	v_mfma_f32_16x16x32_bf16 v[60:63], v[130:133], v[146:149], v[60:63]
	v_mfma_f32_16x16x32_bf16 v[56:59], v[138:141], v[146:149], v[56:59]
	v_mfma_f32_16x16x32_bf16 v[52:55], v[130:133], v[154:157], v[52:55]
	v_mfma_f32_16x16x32_bf16 v[48:51], v[138:141], v[154:157], v[48:51]
	v_mfma_f32_16x16x32_bf16 v[44:47], v[130:133], v[162:165], v[44:47]
	v_mfma_f32_16x16x32_bf16 v[40:43], v[138:141], v[162:165], v[40:43]
	v_mfma_f32_16x16x32_bf16 v[36:39], v[130:133], v[170:173], v[36:39]
	v_mfma_f32_16x16x32_bf16 v[32:35], v[138:141], v[170:173], v[32:35]
	v_mfma_f32_16x16x32_bf16 v[60:63], v[134:137], v[150:153], v[60:63]
	v_mfma_f32_16x16x32_bf16 v[56:59], v[142:145], v[150:153], v[56:59]
	v_mfma_f32_16x16x32_bf16 v[52:55], v[134:137], v[158:161], v[52:55]
	v_mfma_f32_16x16x32_bf16 v[48:51], v[142:145], v[158:161], v[48:51]
	v_mfma_f32_16x16x32_bf16 v[44:47], v[134:137], v[166:169], v[44:47]
	v_mfma_f32_16x16x32_bf16 v[40:43], v[142:145], v[166:169], v[40:43]
	v_mfma_f32_16x16x32_bf16 v[36:39], v[134:137], v[174:177], v[36:39]
	v_mfma_f32_16x16x32_bf16 v[32:35], v[142:145], v[174:177], v[32:35]
	s_barrier
	s_add_i32 s73, s3, 0x1c000
	v_lshl_add_u64 v[130:131], v[218:219], 0, s[44:45]
	s_mov_b32 m0, s73
	s_nop 0
	global_load_lds_dwordx4 v[130:131], off
	v_lshl_add_u64 v[130:131], v[218:219], 0, s[46:47]
	s_mov_b32 m0, s80
	s_nop 0
	global_load_lds_dwordx4 v[130:131], off
	s_waitcnt vmcnt(6)
	s_barrier
	v_mfma_f32_16x16x32_bf16 v[28:31], v[178:181], v[146:149], v[28:31]
	v_mfma_f32_16x16x32_bf16 v[24:27], v[186:189], v[146:149], v[24:27]
	v_mfma_f32_16x16x32_bf16 v[20:23], v[178:181], v[154:157], v[20:23]
	v_mfma_f32_16x16x32_bf16 v[16:19], v[186:189], v[154:157], v[16:19]
	v_mfma_f32_16x16x32_bf16 v[12:15], v[178:181], v[162:165], v[12:15]
	v_mfma_f32_16x16x32_bf16 v[8:11], v[186:189], v[162:165], v[8:11]
	v_mfma_f32_16x16x32_bf16 v[4:7], v[178:181], v[170:173], v[4:7]
	v_mfma_f32_16x16x32_bf16 v[0:3], v[186:189], v[170:173], v[0:3]
	v_mfma_f32_16x16x32_bf16 v[28:31], v[182:185], v[150:153], v[28:31]
	v_mfma_f32_16x16x32_bf16 v[24:27], v[190:193], v[150:153], v[24:27]
	v_mfma_f32_16x16x32_bf16 v[20:23], v[182:185], v[158:161], v[20:23]
	v_mfma_f32_16x16x32_bf16 v[16:19], v[190:193], v[158:161], v[16:19]
	v_mfma_f32_16x16x32_bf16 v[12:15], v[182:185], v[166:169], v[12:15]
	v_mfma_f32_16x16x32_bf16 v[8:11], v[190:193], v[166:169], v[8:11]
	v_mfma_f32_16x16x32_bf16 v[4:7], v[182:185], v[174:177], v[4:7]
	v_mfma_f32_16x16x32_bf16 v[0:3], v[190:193], v[174:177], v[0:3]
	s_add_i32 s61, s61, 2
	s_add_u32 s70, s70, 0x100
	s_addc_u32 s71, s71, 0
	s_add_u32 s68, s68, 0x100
	s_addc_u32 s69, s69, 0
	s_cmp_gt_u32 s61, 27
	s_barrier
	s_cbranch_scc0 .LBB0_428
	ds_read_b128 v[130:133], v201 offset:0
	ds_read_b128 v[134:137], v201 offset:0x400
	ds_read_b128 v[138:141], v201 offset:0x800
	ds_read_b128 v[142:145], v201 offset:0xc00
	ds_read_b128 v[146:149], v202 offset:0
	ds_read_b128 v[150:153], v202 offset:0x400
	ds_read_b128 v[154:157], v202 offset:0x800
	ds_read_b128 v[158:161], v202 offset:0xc00
	ds_read_b128 v[162:165], v202 offset:0x1000
	ds_read_b128 v[166:169], v202 offset:0x1400
	ds_read_b128 v[170:173], v202 offset:0x1800
	s_mov_b32 m0, s63
	ds_read_b128 v[174:177], v202 offset:0x1c00
	v_lshl_add_u64 v[178:179], v[128:129], 0, s[88:89]
	global_load_lds_dwordx4 v[178:179], off
	v_lshl_add_u64 v[128:129], v[128:129], 0, s[90:91]
	s_mov_b32 m0, s81
	s_ashr_i32 s95, s94, 31
	global_load_lds_dwordx4 v[128:129], off
	s_lshl_b64 s[68:69], s[94:95], 20
	s_add_u32 s68, s56, s68
	s_addc_u32 s69, s57, s69
	s_ashr_i32 s87, s86, 31
	s_barrier
	s_waitcnt lgkmcnt(0)
	s_lshl_b64 s[70:71], s[86:87], 20
	v_readlane_b32 s48, v254, 34
	v_readlane_b32 s49, v254, 35
	s_add_u32 s70, s48, s70
	s_addc_u32 s71, s49, s71
	v_mfma_f32_16x16x32_bf16 v[124:127], v[130:133], v[146:149], v[124:127]
	v_mfma_f32_16x16x32_bf16 v[120:123], v[138:141], v[146:149], v[120:123]
	v_mfma_f32_16x16x32_bf16 v[116:119], v[130:133], v[154:157], v[116:119]
	v_mfma_f32_16x16x32_bf16 v[112:115], v[138:141], v[154:157], v[112:115]
	v_mfma_f32_16x16x32_bf16 v[108:111], v[130:133], v[162:165], v[108:111]
	v_mfma_f32_16x16x32_bf16 v[104:107], v[138:141], v[162:165], v[104:107]
	v_mfma_f32_16x16x32_bf16 v[100:103], v[130:133], v[170:173], v[100:103]
	v_mfma_f32_16x16x32_bf16 v[96:99], v[138:141], v[170:173], v[96:99]
	v_mfma_f32_16x16x32_bf16 v[124:127], v[134:137], v[150:153], v[124:127]
	v_mfma_f32_16x16x32_bf16 v[120:123], v[142:145], v[150:153], v[120:123]
	v_mfma_f32_16x16x32_bf16 v[116:119], v[134:137], v[158:161], v[116:119]
	v_mfma_f32_16x16x32_bf16 v[178:181], v[142:145], v[158:161], v[112:115]
	v_mfma_f32_16x16x32_bf16 v[108:111], v[134:137], v[166:169], v[108:111]
	v_mfma_f32_16x16x32_bf16 v[104:107], v[142:145], v[166:169], v[104:107]
	v_mfma_f32_16x16x32_bf16 v[100:103], v[134:137], v[174:177], v[100:103]
	v_mfma_f32_16x16x32_bf16 v[96:99], v[142:145], v[174:177], v[96:99]
	s_barrier
	ds_read_b128 v[112:115], v203 offset:0
	ds_read_b128 v[182:185], v203 offset:0x400
	ds_read_b128 v[186:189], v203 offset:0x800
	ds_read_b128 v[190:193], v203 offset:0xc00
	s_barrier
; #define WAIT_V(n) asm volatile("s_waitcnt vmcnt(%0)" ::"n"(n) : "memory")
; #define SCHED() __builtin_amdgcn_sched_barrier(0)
; #define LGKM(n) asm volatile("s_waitcnt lgkmcnt(%0)" ::"n"(n) : "memory")
; #define LDA(b, h) do { const unsigned pa_ = lds0 + SLOTA(b, h) + wr * 8192 + laneoff; _Pragma("unroll") for (int m = 0; m < 4; ++m)   \
;       _Pragma("unroll") for (int k = 0; k < 2; ++k) DSR(At[m][k], pa_, m * 2048 + k * 1024); } while (0)
; #define LDB(dst, b, h) do { const unsigned pb_ = lds0 + SLOTB(b, h) + wc * 4096 + laneoff; _Pragma("unroll") for (int n = 0; n < 2; ++n) \
;       _Pragma("unroll") for (int k = 0; k < 2; ++k) DSR(dst[n][k], pb_, n * 2048 + k * 1024); } while (0)
; #define BAR __builtin_amdgcn_s_barrier()
; #define LGKM(n) asm volatile("s_waitcnt lgkmcnt(%0)" ::"n"(n) : "memory")
; template <int EPI, bool SWP> ...
;     ...
;     LDA(0, 1); WAIT_V(4); BAR; LGKM(0); SCHED(); MMA(1, 0, B0); MMA(1, 1, B1); BAR; SCHED(); }
;   { LDB(B0, 1, 0); LDA(1, 0); WAIT_V(2); BAR; LGKM(0); SCHED(); MMA(0, 0, B0); BAR; SCHED();
	s_waitcnt lgkmcnt(0)
	v_mfma_f32_16x16x32_bf16 v[92:95], v[112:115], v[146:149], v[92:95]
	v_mfma_f32_16x16x32_bf16 v[88:91], v[186:189], v[146:149], v[88:91]
	v_mfma_f32_16x16x32_bf16 v[84:87], v[112:115], v[154:157], v[84:87]
	v_mfma_f32_16x16x32_bf16 v[80:83], v[186:189], v[154:157], v[80:83]
	v_mfma_f32_16x16x32_bf16 v[76:79], v[112:115], v[162:165], v[76:79]
	v_mfma_f32_16x16x32_bf16 v[72:75], v[186:189], v[162:165], v[72:75]
	v_mfma_f32_16x16x32_bf16 v[68:71], v[112:115], v[170:173], v[68:71]
	v_mfma_f32_16x16x32_bf16 v[64:67], v[186:189], v[170:173], v[64:67]
	v_mfma_f32_16x16x32_bf16 v[92:95], v[182:185], v[150:153], v[92:95]
	v_mfma_f32_16x16x32_bf16 v[88:91], v[190:193], v[150:153], v[88:91]
	v_mfma_f32_16x16x32_bf16 v[84:87], v[182:185], v[158:161], v[84:87]
	v_mfma_f32_16x16x32_bf16 v[80:83], v[190:193], v[158:161], v[80:83]
	v_mfma_f32_16x16x32_bf16 v[76:79], v[182:185], v[166:169], v[76:79]
	v_mfma_f32_16x16x32_bf16 v[72:75], v[190:193], v[166:169], v[72:75]
	v_mfma_f32_16x16x32_bf16 v[68:71], v[182:185], v[174:177], v[68:71]
	v_mfma_f32_16x16x32_bf16 v[64:67], v[190:193], v[174:177], v[64:67]
	s_barrier
	ds_read_b128 v[146:149], v204 offset:0
	ds_read_b128 v[150:153], v204 offset:0x400
	ds_read_b128 v[154:157], v204 offset:0x800
	ds_read_b128 v[158:161], v204 offset:0xc00
	ds_read_b128 v[162:165], v204 offset:0x1000
	ds_read_b128 v[166:169], v204 offset:0x1400
	ds_read_b128 v[170:173], v204 offset:0x1800
	ds_read_b128 v[174:177], v204 offset:0x1c00
	s_waitcnt vmcnt(4)
	s_barrier
	s_waitcnt lgkmcnt(0)
	v_mfma_f32_16x16x32_bf16 v[60:63], v[130:133], v[146:149], v[60:63]
	v_mfma_f32_16x16x32_bf16 v[56:59], v[138:141], v[146:149], v[56:59]
	v_mfma_f32_16x16x32_bf16 v[52:55], v[130:133], v[154:157], v[52:55]
	v_mfma_f32_16x16x32_bf16 v[48:51], v[138:141], v[154:157], v[48:51]
	v_mfma_f32_16x16x32_bf16 v[44:47], v[130:133], v[162:165], v[44:47]
	v_mfma_f32_16x16x32_bf16 v[40:43], v[138:141], v[162:165], v[40:43]
	v_mfma_f32_16x16x32_bf16 v[36:39], v[130:133], v[170:173], v[36:39]
	v_mfma_f32_16x16x32_bf16 v[32:35], v[138:141], v[170:173], v[32:35]
	v_mfma_f32_16x16x32_bf16 v[60:63], v[134:137], v[150:153], v[60:63]
	v_mfma_f32_16x16x32_bf16 v[56:59], v[142:145], v[150:153], v[56:59]
	v_mfma_f32_16x16x32_bf16 v[52:55], v[134:137], v[158:161], v[52:55]
	v_mfma_f32_16x16x32_bf16 v[48:51], v[142:145], v[158:161], v[48:51]
	v_mfma_f32_16x16x32_bf16 v[44:47], v[134:137], v[166:169], v[44:47]
	v_mfma_f32_16x16x32_bf16 v[40:43], v[142:145], v[166:169], v[40:43]
	v_mfma_f32_16x16x32_bf16 v[36:39], v[134:137], v[174:177], v[36:39]
	v_mfma_f32_16x16x32_bf16 v[32:35], v[142:145], v[174:177], v[32:35]
	v_mfma_f32_16x16x32_bf16 v[28:31], v[112:115], v[146:149], v[28:31]
	v_mfma_f32_16x16x32_bf16 v[24:27], v[186:189], v[146:149], v[24:27]
	v_mfma_f32_16x16x32_bf16 v[20:23], v[112:115], v[154:157], v[20:23]
	v_mfma_f32_16x16x32_bf16 v[16:19], v[186:189], v[154:157], v[16:19]
	v_mfma_f32_16x16x32_bf16 v[12:15], v[112:115], v[162:165], v[12:15]
	v_mfma_f32_16x16x32_bf16 v[8:11], v[186:189], v[162:165], v[8:11]
	v_mfma_f32_16x16x32_bf16 v[4:7], v[112:115], v[170:173], v[4:7]
	v_mfma_f32_16x16x32_bf16 v[0:3], v[186:189], v[170:173], v[0:3]
	v_mfma_f32_16x16x32_bf16 v[28:31], v[182:185], v[150:153], v[28:31]
	v_mfma_f32_16x16x32_bf16 v[24:27], v[190:193], v[150:153], v[24:27]
	v_mfma_f32_16x16x32_bf16 v[20:23], v[182:185], v[158:161], v[20:23]
	v_mfma_f32_16x16x32_bf16 v[16:19], v[190:193], v[158:161], v[16:19]
	v_mfma_f32_16x16x32_bf16 v[12:15], v[182:185], v[166:169], v[12:15]
	v_mfma_f32_16x16x32_bf16 v[8:11], v[190:193], v[166:169], v[8:11]
	v_mfma_f32_16x16x32_bf16 v[4:7], v[182:185], v[174:177], v[4:7]
	v_mfma_f32_16x16x32_bf16 v[0:3], v[190:193], v[174:177], v[0:3]
	s_barrier
	ds_read_b128 v[112:115], v205 offset:0
	ds_read_b128 v[134:137], v205 offset:0x400
	ds_read_b128 v[138:141], v205 offset:0x800
	ds_read_b128 v[142:145], v205 offset:0xc00
	ds_read_b128 v[162:165], v206 offset:0
	ds_read_b128 v[166:169], v206 offset:0x400
	ds_read_b128 v[170:173], v206 offset:0x800
	ds_read_b128 v[174:177], v206 offset:0xc00
	ds_read_b128 v[182:185], v206 offset:0x1000
	ds_read_b128 v[186:189], v206 offset:0x1400
	ds_read_b128 v[190:193], v206 offset:0x1800
	ds_read_b128 v[218:221], v206 offset:0x1c00
	s_waitcnt vmcnt(2)
	s_barrier
; #define WAIT_V(n) asm volatile("s_waitcnt vmcnt(%0)" ::"n"(n) : "memory")
; #define SCHED() __builtin_amdgcn_sched_barrier(0)
; #define LGKM(n) asm volatile("s_waitcnt lgkmcnt(%0)" ::"n"(n) : "memory")
; #define STAGE_AX(AG, b, h, kt) do { _Pragma("unroll") for (int i = 0; i < 2; ++i)                                    \
;       __builtin_amdgcn_global_load_lds((const unsigned*)(((AG) + ((size_t)(kt) * (BK * 2) + (size_t)((h) * 2 + i) * 128 * lda)) + aoff), \
;                                        (unsigned*)(shm + SLOTA(b, h) + wid * 1024 + i * 8192), 16, 0, 0); } while (0)
; #define STAGE_BX(BG, b, h, kt) do { _Pragma("unroll") for (int i = 0; i < 2; ++i)                                    \
;       __builtin_amdgcn_global_load_lds((const unsigned*)(((BG) + ((size_t)(kt) * (BK * 2) + (size_t)((h) * 2 + i) * 128 * K)) + boff),   \
;                                        (unsigned*)(shm + SLOTB(b, h) + wid * 1024 + i * 8192), 16, 0, 0); } while (0)
; #define LDA(b, h) do { const unsigned pa_ = lds0 + SLOTA(b, h) + wr * 8192 + laneoff; _Pragma("unroll") for (int m = 0; m < 4; ++m)   \
;       _Pragma("unroll") for (int k = 0; k < 2; ++k) DSR(At[m][k], pa_, m * 2048 + k * 1024); } while (0)
; #define LDB(dst, b, h) do { const unsigned pb_ = lds0 + SLOTB(b, h) + wc * 4096 + laneoff; _Pragma("unroll") for (int n = 0; n < 2; ++n) \
;       _Pragma("unroll") for (int k = 0; k < 2; ++k) DSR(dst[n][k], pb_, n * 2048 + k * 1024); } while (0)
; #define BAR __builtin_amdgcn_s_barrier()
; #define LGKM(n) asm volatile("s_waitcnt lgkmcnt(%0)" ::"n"(n) : "memory")
; template <int EPI, bool SWP> ...
;     ...
;   { LDB(B0, 1, 0); LDA(1, 0); WAIT_V(2); BAR; LGKM(0); SCHED(); MMA(0, 0, B0); BAR; SCHED();
;     LDB(B1, 1, 1); WAIT_V(0); BAR; LGKM(0); SCHED(); MMA(0, 1, B1); BAR; SCHED();
;     LDA(1, 1);
;     if (has_next) { STAGE_BX(Bg_n, 0, 0, 0); STAGE_AX(Ag_n, 0, 0, 0); STAGE_BX(Bg_n, 0, 1, 0); STAGE_AX(Ag_n, 0, 1, 0); }
	s_waitcnt lgkmcnt(0)
	v_mfma_f32_16x16x32_bf16 v[124:127], v[112:115], v[162:165], v[124:127]
	v_mfma_f32_16x16x32_bf16 v[120:123], v[138:141], v[162:165], v[120:123]
	v_mfma_f32_16x16x32_bf16 v[116:119], v[112:115], v[170:173], v[116:119]
	v_mfma_f32_16x16x32_bf16 v[130:133], v[134:137], v[166:169], v[124:127]
	v_mfma_f32_16x16x32_bf16 v[126:129], v[142:145], v[166:169], v[120:123]
	v_mfma_f32_16x16x32_bf16 v[122:125], v[134:137], v[174:177], v[116:119]
	v_mfma_f32_16x16x32_bf16 v[116:119], v[138:141], v[170:173], v[178:181]
	v_mfma_f32_16x16x32_bf16 v[108:111], v[112:115], v[182:185], v[108:111]
	v_mfma_f32_16x16x32_bf16 v[104:107], v[138:141], v[182:185], v[104:107]
	v_mfma_f32_16x16x32_bf16 v[100:103], v[112:115], v[190:193], v[100:103]
	v_mfma_f32_16x16x32_bf16 v[96:99], v[138:141], v[190:193], v[96:99]
	v_mfma_f32_16x16x32_bf16 v[118:121], v[142:145], v[174:177], v[116:119]
	v_mfma_f32_16x16x32_bf16 v[108:111], v[134:137], v[186:189], v[108:111]
	v_mfma_f32_16x16x32_bf16 v[104:107], v[142:145], v[186:189], v[104:107]
	v_mfma_f32_16x16x32_bf16 v[100:103], v[134:137], v[218:221], v[100:103]
	v_mfma_f32_16x16x32_bf16 v[96:99], v[142:145], v[218:221], v[96:99]
	s_barrier
	ds_read_b128 v[146:149], v207 offset:0
	ds_read_b128 v[150:153], v207 offset:0x400
	ds_read_b128 v[154:157], v207 offset:0x800
	ds_read_b128 v[158:161], v207 offset:0xc00
	s_waitcnt vmcnt(0)
	s_barrier
	s_waitcnt lgkmcnt(0)
	v_mfma_f32_16x16x32_bf16 v[92:95], v[146:149], v[162:165], v[92:95]
	v_mfma_f32_16x16x32_bf16 v[88:91], v[154:157], v[162:165], v[88:91]
	v_mfma_f32_16x16x32_bf16 v[84:87], v[146:149], v[170:173], v[84:87]
	v_mfma_f32_16x16x32_bf16 v[80:83], v[154:157], v[170:173], v[80:83]
	v_mfma_f32_16x16x32_bf16 v[76:79], v[146:149], v[182:185], v[76:79]
	v_mfma_f32_16x16x32_bf16 v[72:75], v[154:157], v[182:185], v[72:75]
	v_mfma_f32_16x16x32_bf16 v[68:71], v[146:149], v[190:193], v[68:71]
	v_mfma_f32_16x16x32_bf16 v[64:67], v[154:157], v[190:193], v[64:67]
	v_mfma_f32_16x16x32_bf16 v[92:95], v[150:153], v[166:169], v[92:95]
	v_mfma_f32_16x16x32_bf16 v[88:91], v[158:161], v[166:169], v[88:91]
	v_mfma_f32_16x16x32_bf16 v[84:87], v[150:153], v[174:177], v[84:87]
	v_mfma_f32_16x16x32_bf16 v[80:83], v[158:161], v[174:177], v[80:83]
	v_mfma_f32_16x16x32_bf16 v[76:79], v[150:153], v[186:189], v[76:79]
	v_mfma_f32_16x16x32_bf16 v[72:75], v[158:161], v[186:189], v[72:75]
	v_mfma_f32_16x16x32_bf16 v[68:71], v[150:153], v[218:221], v[68:71]
	v_mfma_f32_16x16x32_bf16 v[64:67], v[158:161], v[218:221], v[64:67]
	s_barrier
	ds_read_b128 v[186:189], v208 offset:0
	ds_read_b128 v[190:193], v208 offset:0x400
	ds_read_b128 v[178:181], v208 offset:0x800
	ds_read_b128 v[182:185], v208 offset:0xc00
	ds_read_b128 v[170:173], v208 offset:0x1000
	ds_read_b128 v[174:177], v208 offset:0x1400
	ds_read_b128 v[162:165], v208 offset:0x1800
	ds_read_b128 v[166:169], v208 offset:0x1c00
	s_and_b64 vcc, exec, s[12:13]
	v_lshl_add_u64 v[116:117], s[70:71], 0, v[194:195]
	v_lshl_add_u64 v[198:199], s[68:69], 0, v[194:195]
	s_cbranch_vccz .LBB0_431
	s_mov_b32 m0, s17
	v_lshl_add_u64 v[218:219], v[116:117], 0, s[20:21]
	global_load_lds_dwordx4 v[116:117], off
	s_mov_b32 m0, s18
	s_nop 0
	global_load_lds_dwordx4 v[218:219], off
	s_mov_b32 m0, s3
	v_lshl_add_u64 v[218:219], v[198:199], 0, s[20:21]
	global_load_lds_dwordx4 v[198:199], off
	s_mov_b32 m0, s19
	s_nop 0
	global_load_lds_dwordx4 v[218:219], off
	v_lshl_add_u64 v[218:219], v[116:117], 0, s[28:29]
	s_mov_b32 m0, s74
	s_nop 0
	global_load_lds_dwordx4 v[218:219], off
	v_lshl_add_u64 v[218:219], v[116:117], 0, s[34:35]
	s_mov_b32 m0, s75
	s_nop 0
	global_load_lds_dwordx4 v[218:219], off
	v_lshl_add_u64 v[218:219], v[198:199], 0, s[28:29]
	s_mov_b32 m0, s76
	s_nop 0
	global_load_lds_dwordx4 v[218:219], off
	v_lshl_add_u64 v[218:219], v[198:199], 0, s[34:35]
	s_mov_b32 m0, s77
	s_nop 0
	global_load_lds_dwordx4 v[218:219], off

; #define WAIT_V(n) asm volatile("s_waitcnt vmcnt(%0)" ::"n"(n) : "memory")
; #define SCHED() __builtin_amdgcn_sched_barrier(0)
; #define LGKM(n) asm volatile("s_waitcnt lgkmcnt(%0)" ::"n"(n) : "memory")
; #define STAGE_A(b, h, kt) STAGE_AX(Ag, b, h, kt)
; #define STAGE_B(b, h, kt) STAGE_BX(Bg, b, h, kt)
; #define LDA(b, h) do { const unsigned pa_ = lds0 + SLOTA(b, h) + wr * 8192 + laneoff; _Pragma("unroll") for (int m = 0; m < 4; ++m)   \
;       _Pragma("unroll") for (int k = 0; k < 2; ++k) DSR(At[m][k], pa_, m * 2048 + k * 1024); } while (0)
; #define LDB(dst, b, h) do { const unsigned pb_ = lds0 + SLOTB(b, h) + wc * 4096 + laneoff; _Pragma("unroll") for (int n = 0; n < 2; ++n) \
;       _Pragma("unroll") for (int k = 0; k < 2; ++k) DSR(dst[n][k], pb_, n * 2048 + k * 1024); } while (0)
; #define BAR __builtin_amdgcn_s_barrier()
; #define LGKM(n) asm volatile("s_waitcnt lgkmcnt(%0)" ::"n"(n) : "memory")
; template <int EPI, bool SWP> ...
;     ...
;     LDB(B0, 0, 0); LDA(0, 0); STAGE_A(1, 1, t + 1);
;     LGKM(8); BAR; LGKM(0); SCHED(); MMA(0, 0, B0); BAR; SCHED();
;     LDB(B1, 0, 1); STAGE_B(0, 0, t + 2);
;     BAR; LGKM(0); SCHED(); MMA(0, 1, B1); BAR; SCHED();
;     LDA(0, 1); STAGE_A(0, 0, t + 2);
;     BAR; LGKM(0); SCHED(); MMA(1, 0, B0); BAR; SCHED();
;     STAGE_B(0, 1, t + 2);
;     WAIT_V(6); BAR; SCHED(); MMA(1, 1, B1); BAR; SCHED();
.LBB0_667:
	ds_read_b128 v[128:131], v219 offset:0
	ds_read_b128 v[132:135], v219 offset:0x400
	ds_read_b128 v[136:139], v219 offset:0x800
	ds_read_b128 v[140:143], v219 offset:0xc00
	ds_read_b128 v[144:147], v220 offset:0
	ds_read_b128 v[148:151], v220 offset:0x400
	ds_read_b128 v[152:155], v220 offset:0x800
	ds_read_b128 v[156:159], v220 offset:0xc00
	ds_read_b128 v[160:163], v220 offset:0x1000
	ds_read_b128 v[164:167], v220 offset:0x1400
	ds_read_b128 v[168:171], v220 offset:0x1800
	v_lshl_add_u64 v[192:193], s[68:69], 0, v[210:211]
	s_mov_b64 s[70:71], 0xc080080
	s_mov_b32 m0, s87
	ds_read_b128 v[172:175], v220 offset:0x1c00
	v_lshl_add_u64 v[176:177], v[192:193], 0, s[70:71]
	s_mov_b64 s[70:71], 0xc0c0080
	global_load_lds_dwordx4 v[176:177], off
	v_lshl_add_u64 v[176:177], v[192:193], 0, s[70:71]
	s_mov_b32 m0, s88
	s_nop 0
	global_load_lds_dwordx4 v[176:177], off
	s_waitcnt lgkmcnt(8)
	s_barrier
	s_waitcnt lgkmcnt(0)
	v_mfma_f32_16x16x32_bf16 v[124:127], v[128:131], v[144:147], v[124:127]
	v_mfma_f32_16x16x32_bf16 v[120:123], v[136:139], v[144:147], v[120:123]
	v_mfma_f32_16x16x32_bf16 v[116:119], v[128:131], v[152:155], v[116:119]
	v_mfma_f32_16x16x32_bf16 v[112:115], v[136:139], v[152:155], v[112:115]
	v_mfma_f32_16x16x32_bf16 v[108:111], v[128:131], v[160:163], v[108:111]
	v_mfma_f32_16x16x32_bf16 v[104:107], v[136:139], v[160:163], v[104:107]
	v_mfma_f32_16x16x32_bf16 v[100:103], v[128:131], v[168:171], v[100:103]
	v_mfma_f32_16x16x32_bf16 v[96:99], v[136:139], v[168:171], v[96:99]
	v_mfma_f32_16x16x32_bf16 v[124:127], v[132:135], v[148:151], v[124:127]
	v_mfma_f32_16x16x32_bf16 v[120:123], v[140:143], v[148:151], v[120:123]
	v_mfma_f32_16x16x32_bf16 v[116:119], v[132:135], v[156:159], v[116:119]
	v_mfma_f32_16x16x32_bf16 v[112:115], v[140:143], v[156:159], v[112:115]
	v_mfma_f32_16x16x32_bf16 v[108:111], v[132:135], v[164:167], v[108:111]
	v_mfma_f32_16x16x32_bf16 v[104:107], v[140:143], v[164:167], v[104:107]
	v_mfma_f32_16x16x32_bf16 v[100:103], v[132:135], v[172:175], v[100:103]
	v_mfma_f32_16x16x32_bf16 v[96:99], v[140:143], v[172:175], v[96:99]
	s_barrier
	ds_read_b128 v[176:179], v221 offset:0
	ds_read_b128 v[180:183], v221 offset:0x400
	ds_read_b128 v[184:187], v221 offset:0x800
	v_lshl_add_u64 v[194:195], s[66:67], 0, v[210:211]
	s_mov_b64 s[70:71], 0x2d100100
	s_mov_b32 m0, s75
	ds_read_b128 v[188:191], v221 offset:0xc00
	v_lshl_add_u64 v[196:197], v[194:195], 0, s[70:71]
	s_mov_b64 s[70:71], 0x2d140100
	global_load_lds_dwordx4 v[196:197], off
	v_lshl_add_u64 v[196:197], v[194:195], 0, s[70:71]
	s_mov_b32 m0, s76
	s_nop 0
	global_load_lds_dwordx4 v[196:197], off
	s_barrier
	s_waitcnt lgkmcnt(0)
	v_mfma_f32_16x16x32_bf16 v[92:95], v[176:179], v[144:147], v[92:95]
	v_mfma_f32_16x16x32_bf16 v[88:91], v[184:187], v[144:147], v[88:91]
	v_mfma_f32_16x16x32_bf16 v[84:87], v[176:179], v[152:155], v[84:87]
	v_mfma_f32_16x16x32_bf16 v[80:83], v[184:187], v[152:155], v[80:83]
	v_mfma_f32_16x16x32_bf16 v[76:79], v[176:179], v[160:163], v[76:79]
	v_mfma_f32_16x16x32_bf16 v[72:75], v[184:187], v[160:163], v[72:75]
	v_mfma_f32_16x16x32_bf16 v[68:71], v[176:179], v[168:171], v[68:71]
	v_mfma_f32_16x16x32_bf16 v[64:67], v[184:187], v[168:171], v[64:67]
	v_mfma_f32_16x16x32_bf16 v[92:95], v[180:183], v[148:151], v[92:95]
	v_mfma_f32_16x16x32_bf16 v[88:91], v[188:191], v[148:151], v[88:91]
	v_mfma_f32_16x16x32_bf16 v[84:87], v[180:183], v[156:159], v[84:87]
	v_mfma_f32_16x16x32_bf16 v[80:83], v[188:191], v[156:159], v[80:83]
	v_mfma_f32_16x16x32_bf16 v[76:79], v[180:183], v[164:167], v[76:79]
	v_mfma_f32_16x16x32_bf16 v[72:75], v[188:191], v[164:167], v[72:75]
	v_mfma_f32_16x16x32_bf16 v[68:71], v[180:183], v[172:175], v[68:71]
	v_mfma_f32_16x16x32_bf16 v[64:67], v[188:191], v[172:175], v[64:67]
	s_barrier
	ds_read_b128 v[144:147], v222 offset:0
	ds_read_b128 v[148:151], v222 offset:0x400
	ds_read_b128 v[152:155], v222 offset:0x800
	ds_read_b128 v[156:159], v222 offset:0xc00
	ds_read_b128 v[160:163], v222 offset:0x1000
	ds_read_b128 v[164:167], v222 offset:0x1400
	ds_read_b128 v[168:171], v222 offset:0x1800
	s_mov_b64 s[70:71], 0xc000100
	s_mov_b32 m0, s3
	ds_read_b128 v[172:175], v222 offset:0x1c00
	v_lshl_add_u64 v[196:197], v[192:193], 0, s[70:71]
	s_mov_b64 s[70:71], 0xc040100
	global_load_lds_dwordx4 v[196:197], off
	v_lshl_add_u64 v[196:197], v[192:193], 0, s[70:71]
	s_mov_b32 m0, s77
	s_nop 0
	global_load_lds_dwordx4 v[196:197], off
	s_barrier
	s_waitcnt lgkmcnt(0)
	v_mfma_f32_16x16x32_bf16 v[60:63], v[128:131], v[144:147], v[60:63]
	v_mfma_f32_16x16x32_bf16 v[56:59], v[136:139], v[144:147], v[56:59]
	v_mfma_f32_16x16x32_bf16 v[52:55], v[128:131], v[152:155], v[52:55]
	v_mfma_f32_16x16x32_bf16 v[48:51], v[136:139], v[152:155], v[48:51]
	v_mfma_f32_16x16x32_bf16 v[44:47], v[128:131], v[160:163], v[44:47]
	v_mfma_f32_16x16x32_bf16 v[40:43], v[136:139], v[160:163], v[40:43]
	v_mfma_f32_16x16x32_bf16 v[36:39], v[128:131], v[168:171], v[36:39]
	v_mfma_f32_16x16x32_bf16 v[32:35], v[136:139], v[168:171], v[32:35]
	v_mfma_f32_16x16x32_bf16 v[60:63], v[132:135], v[148:151], v[60:63]
	v_mfma_f32_16x16x32_bf16 v[56:59], v[140:143], v[148:151], v[56:59]
	v_mfma_f32_16x16x32_bf16 v[52:55], v[132:135], v[156:159], v[52:55]
	v_mfma_f32_16x16x32_bf16 v[48:51], v[140:143], v[156:159], v[48:51]
	v_mfma_f32_16x16x32_bf16 v[44:47], v[132:135], v[164:167], v[44:47]
	v_mfma_f32_16x16x32_bf16 v[40:43], v[140:143], v[164:167], v[40:43]
	v_mfma_f32_16x16x32_bf16 v[36:39], v[132:135], v[172:175], v[36:39]
	v_mfma_f32_16x16x32_bf16 v[32:35], v[140:143], v[172:175], v[32:35]
	s_barrier
; #define WAIT_V(n) asm volatile("s_waitcnt vmcnt(%0)" ::"n"(n) : "memory")
; #define SCHED() __builtin_amdgcn_sched_barrier(0)
; #define LGKM(n) asm volatile("s_waitcnt lgkmcnt(%0)" ::"n"(n) : "memory")
; #define STAGE_A(b, h, kt) STAGE_AX(Ag, b, h, kt)
; #define STAGE_B(b, h, kt) STAGE_BX(Bg, b, h, kt)
; #define LDA(b, h) do { const unsigned pa_ = lds0 + SLOTA(b, h) + wr * 8192 + laneoff; _Pragma("unroll") for (int m = 0; m < 4; ++m)   \
;       _Pragma("unroll") for (int k = 0; k < 2; ++k) DSR(At[m][k], pa_, m * 2048 + k * 1024); } while (0)
; #define LDB(dst, b, h) do { const unsigned pb_ = lds0 + SLOTB(b, h) + wc * 4096 + laneoff; _Pragma("unroll") for (int n = 0; n < 2; ++n) \
;       _Pragma("unroll") for (int k = 0; k < 2; ++k) DSR(dst[n][k], pb_, n * 2048 + k * 1024); } while (0)
; #define BAR __builtin_amdgcn_s_barrier()
; #define LGKM(n) asm volatile("s_waitcnt lgkmcnt(%0)" ::"n"(n) : "memory")
; template <int EPI, bool SWP> ...
;     ...
;     WAIT_V(6); BAR; SCHED(); MMA(1, 1, B1); BAR; SCHED();
;     LDB(B0, 1, 0); LDA(1, 0); STAGE_A(0, 1, t + 2);
;     LGKM(8); BAR; LGKM(0); SCHED(); MMA(0, 0, B0); BAR; SCHED();
;     LDB(B1, 1, 1); STAGE_B(1, 0, t + 3);
;     BAR; LGKM(0); SCHED(); MMA(0, 1, B1); BAR; SCHED();
;     LDA(1, 1); STAGE_A(1, 0, t + 3);
	s_mov_b64 s[70:71], 0x2d180100
	s_mov_b32 m0, s78
	v_lshl_add_u64 v[128:129], v[194:195], 0, s[70:71]
	s_mov_b64 s[70:71], 0x2d1c0100
	global_load_lds_dwordx4 v[128:129], off
	v_lshl_add_u64 v[128:129], v[194:195], 0, s[70:71]
	s_mov_b32 m0, s79
	s_nop 0
	global_load_lds_dwordx4 v[128:129], off
	s_waitcnt vmcnt(6)
	s_barrier
	v_mfma_f32_16x16x32_bf16 v[28:31], v[176:179], v[144:147], v[28:31]
	v_mfma_f32_16x16x32_bf16 v[24:27], v[184:187], v[144:147], v[24:27]
	v_mfma_f32_16x16x32_bf16 v[20:23], v[176:179], v[152:155], v[20:23]
	v_mfma_f32_16x16x32_bf16 v[16:19], v[184:187], v[152:155], v[16:19]
	v_mfma_f32_16x16x32_bf16 v[12:15], v[176:179], v[160:163], v[12:15]
	v_mfma_f32_16x16x32_bf16 v[8:11], v[184:187], v[160:163], v[8:11]
	v_mfma_f32_16x16x32_bf16 v[4:7], v[176:179], v[168:171], v[4:7]
	v_mfma_f32_16x16x32_bf16 v[0:3], v[184:187], v[168:171], v[0:3]
	v_mfma_f32_16x16x32_bf16 v[28:31], v[180:183], v[148:151], v[28:31]
	v_mfma_f32_16x16x32_bf16 v[24:27], v[188:191], v[148:151], v[24:27]
	v_mfma_f32_16x16x32_bf16 v[20:23], v[180:183], v[156:159], v[20:23]
	v_mfma_f32_16x16x32_bf16 v[16:19], v[188:191], v[156:159], v[16:19]
	v_mfma_f32_16x16x32_bf16 v[12:15], v[180:183], v[164:167], v[12:15]
	v_mfma_f32_16x16x32_bf16 v[8:11], v[188:191], v[164:167], v[8:11]
	v_mfma_f32_16x16x32_bf16 v[4:7], v[180:183], v[172:175], v[4:7]
	v_mfma_f32_16x16x32_bf16 v[0:3], v[188:191], v[172:175], v[0:3]
	s_barrier
	ds_read_b128 v[128:131], v223 offset:0
	ds_read_b128 v[132:135], v223 offset:0x400
	ds_read_b128 v[136:139], v223 offset:0x800
	ds_read_b128 v[140:143], v223 offset:0xc00
	ds_read_b128 v[144:147], v224 offset:0
	ds_read_b128 v[148:151], v224 offset:0x400
	ds_read_b128 v[152:155], v224 offset:0x800
	ds_read_b128 v[156:159], v224 offset:0xc00
	ds_read_b128 v[160:163], v224 offset:0x1000
	ds_read_b128 v[164:167], v224 offset:0x1400
	ds_read_b128 v[168:171], v224 offset:0x1800
	s_mov_b64 s[70:71], 0xc080100
	s_mov_b32 m0, s80
	ds_read_b128 v[172:175], v224 offset:0x1c00
	v_lshl_add_u64 v[176:177], v[192:193], 0, s[70:71]
	s_mov_b64 s[70:71], 0xc0c0100
	global_load_lds_dwordx4 v[176:177], off
	v_lshl_add_u64 v[176:177], v[192:193], 0, s[70:71]
	s_mov_b32 m0, s81
	s_nop 0
	global_load_lds_dwordx4 v[176:177], off
	s_waitcnt lgkmcnt(8)
	s_barrier
	s_waitcnt lgkmcnt(0)
	v_mfma_f32_16x16x32_bf16 v[124:127], v[128:131], v[144:147], v[124:127]
	v_mfma_f32_16x16x32_bf16 v[120:123], v[136:139], v[144:147], v[120:123]
	v_mfma_f32_16x16x32_bf16 v[116:119], v[128:131], v[152:155], v[116:119]
	v_mfma_f32_16x16x32_bf16 v[112:115], v[136:139], v[152:155], v[112:115]
	v_mfma_f32_16x16x32_bf16 v[108:111], v[128:131], v[160:163], v[108:111]
	v_mfma_f32_16x16x32_bf16 v[104:107], v[136:139], v[160:163], v[104:107]
	v_mfma_f32_16x16x32_bf16 v[100:103], v[128:131], v[168:171], v[100:103]
	v_mfma_f32_16x16x32_bf16 v[96:99], v[136:139], v[168:171], v[96:99]
	v_mfma_f32_16x16x32_bf16 v[124:127], v[132:135], v[148:151], v[124:127]
	v_mfma_f32_16x16x32_bf16 v[120:123], v[140:143], v[148:151], v[120:123]
	v_mfma_f32_16x16x32_bf16 v[116:119], v[132:135], v[156:159], v[116:119]
	v_mfma_f32_16x16x32_bf16 v[112:115], v[140:143], v[156:159], v[112:115]
	v_mfma_f32_16x16x32_bf16 v[108:111], v[132:135], v[164:167], v[108:111]
	v_mfma_f32_16x16x32_bf16 v[104:107], v[140:143], v[164:167], v[104:107]
	v_mfma_f32_16x16x32_bf16 v[100:103], v[132:135], v[172:175], v[100:103]
	v_mfma_f32_16x16x32_bf16 v[96:99], v[140:143], v[172:175], v[96:99]
	s_barrier
	ds_read_b128 v[176:179], v225 offset:0
	ds_read_b128 v[180:183], v225 offset:0x400
	ds_read_b128 v[184:187], v225 offset:0x800
	s_mov_b64 s[70:71], 0x2d100180
	s_mov_b32 m0, s82
	ds_read_b128 v[188:191], v225 offset:0xc00
	v_lshl_add_u64 v[196:197], v[194:195], 0, s[70:71]
	s_mov_b64 s[70:71], 0x2d140180
	global_load_lds_dwordx4 v[196:197], off
	v_lshl_add_u64 v[196:197], v[194:195], 0, s[70:71]
	s_mov_b32 m0, s83
	s_nop 0
	global_load_lds_dwordx4 v[196:197], off
	s_barrier
	s_waitcnt lgkmcnt(0)
	v_mfma_f32_16x16x32_bf16 v[92:95], v[176:179], v[144:147], v[92:95]
	v_mfma_f32_16x16x32_bf16 v[88:91], v[184:187], v[144:147], v[88:91]
	v_mfma_f32_16x16x32_bf16 v[84:87], v[176:179], v[152:155], v[84:87]
	v_mfma_f32_16x16x32_bf16 v[80:83], v[184:187], v[152:155], v[80:83]
	v_mfma_f32_16x16x32_bf16 v[76:79], v[176:179], v[160:163], v[76:79]
	v_mfma_f32_16x16x32_bf16 v[72:75], v[184:187], v[160:163], v[72:75]
	v_mfma_f32_16x16x32_bf16 v[68:71], v[176:179], v[168:171], v[68:71]
	v_mfma_f32_16x16x32_bf16 v[64:67], v[184:187], v[168:171], v[64:67]
	v_mfma_f32_16x16x32_bf16 v[92:95], v[180:183], v[148:151], v[92:95]
	v_mfma_f32_16x16x32_bf16 v[88:91], v[188:191], v[148:151], v[88:91]
	v_mfma_f32_16x16x32_bf16 v[84:87], v[180:183], v[156:159], v[84:87]
	v_mfma_f32_16x16x32_bf16 v[80:83], v[188:191], v[156:159], v[80:83]
	v_mfma_f32_16x16x32_bf16 v[76:79], v[180:183], v[164:167], v[76:79]
	v_mfma_f32_16x16x32_bf16 v[72:75], v[188:191], v[164:167], v[72:75]
	v_mfma_f32_16x16x32_bf16 v[68:71], v[180:183], v[172:175], v[68:71]
	v_mfma_f32_16x16x32_bf16 v[64:67], v[188:191], v[172:175], v[64:67]
	s_barrier
	ds_read_b128 v[144:147], v226 offset:0
	ds_read_b128 v[148:151], v226 offset:0x400
	ds_read_b128 v[152:155], v226 offset:0x800
	ds_read_b128 v[156:159], v226 offset:0xc00
	ds_read_b128 v[160:163], v226 offset:0x1000
	ds_read_b128 v[164:167], v226 offset:0x1400
	ds_read_b128 v[168:171], v226 offset:0x1800
	s_mov_b32 m0, s84
	ds_read_b128 v[172:175], v226 offset:0x1c00
	v_lshl_add_u64 v[196:197], v[192:193], 0, s[36:37]
	global_load_lds_dwordx4 v[196:197], off
	v_lshl_add_u64 v[192:193], v[192:193], 0, s[38:39]
	s_mov_b32 m0, s85
	s_nop 0
	global_load_lds_dwordx4 v[192:193], off
	s_barrier
; #define WAIT_V(n) asm volatile("s_waitcnt vmcnt(%0)" ::"n"(n) : "memory")
; #define SCHED() __builtin_amdgcn_sched_barrier(0)
; #define LGKM(n) asm volatile("s_waitcnt lgkmcnt(%0)" ::"n"(n) : "memory")
; #define STAGE_A(b, h, kt) STAGE_AX(Ag, b, h, kt)
; #define STAGE_B(b, h, kt) STAGE_BX(Bg, b, h, kt)
; #define LDA(b, h) do { const unsigned pa_ = lds0 + SLOTA(b, h) + wr * 8192 + laneoff; _Pragma("unroll") for (int m = 0; m < 4; ++m)   \
;       _Pragma("unroll") for (int k = 0; k < 2; ++k) DSR(At[m][k], pa_, m * 2048 + k * 1024); } while (0)
; #define LDB(dst, b, h) do { const unsigned pb_ = lds0 + SLOTB(b, h) + wc * 4096 + laneoff; _Pragma("unroll") for (int n = 0; n < 2; ++n) \
;       _Pragma("unroll") for (int k = 0; k < 2; ++k) DSR(dst[n][k], pb_, n * 2048 + k * 1024); } while (0)
; #define BAR __builtin_amdgcn_s_barrier()
; #define LGKM(n) asm volatile("s_waitcnt lgkmcnt(%0)" ::"n"(n) : "memory")
; template <int EPI, bool SWP> ...
;     ...
;     BAR; LGKM(0); SCHED(); MMA(1, 0, B0); BAR; SCHED();
;     STAGE_B(1, 1, t + 3);
;     WAIT_V(6); BAR; SCHED(); MMA(1, 1, B1); BAR; SCHED();
;   }
;   { LDB(B0, 0, 0); LDA(0, 0); STAGE_A(1, 1, nt - 1);
;     BAR; LGKM(0); SCHED(); MMA(0, 0, B0); BAR; SCHED();
;     LDB(B1, 0, 1); BAR; LGKM(0); SCHED(); MMA(0, 1, B1); BAR; SCHED();
	s_waitcnt lgkmcnt(0)
	v_mfma_f32_16x16x32_bf16 v[60:63], v[128:131], v[144:147], v[60:63]
	v_mfma_f32_16x16x32_bf16 v[56:59], v[136:139], v[144:147], v[56:59]
	v_mfma_f32_16x16x32_bf16 v[52:55], v[128:131], v[152:155], v[52:55]
	v_mfma_f32_16x16x32_bf16 v[48:51], v[136:139], v[152:155], v[48:51]
	v_mfma_f32_16x16x32_bf16 v[44:47], v[128:131], v[160:163], v[44:47]
	v_mfma_f32_16x16x32_bf16 v[40:43], v[136:139], v[160:163], v[40:43]
	v_mfma_f32_16x16x32_bf16 v[36:39], v[128:131], v[168:171], v[36:39]
	v_mfma_f32_16x16x32_bf16 v[32:35], v[136:139], v[168:171], v[32:35]
	v_mfma_f32_16x16x32_bf16 v[60:63], v[132:135], v[148:151], v[60:63]
	v_mfma_f32_16x16x32_bf16 v[56:59], v[140:143], v[148:151], v[56:59]
	v_mfma_f32_16x16x32_bf16 v[52:55], v[132:135], v[156:159], v[52:55]
	v_mfma_f32_16x16x32_bf16 v[48:51], v[140:143], v[156:159], v[48:51]
	v_mfma_f32_16x16x32_bf16 v[44:47], v[132:135], v[164:167], v[44:47]
	v_mfma_f32_16x16x32_bf16 v[40:43], v[140:143], v[164:167], v[40:43]
	v_mfma_f32_16x16x32_bf16 v[36:39], v[132:135], v[172:175], v[36:39]
	v_mfma_f32_16x16x32_bf16 v[32:35], v[140:143], v[172:175], v[32:35]
	s_barrier
	s_add_i32 s70, s3, 0x1c000
	v_lshl_add_u64 v[128:129], v[194:195], 0, s[40:41]
	s_mov_b32 m0, s70
	s_nop 0
	global_load_lds_dwordx4 v[128:129], off
	v_lshl_add_u64 v[128:129], v[194:195], 0, s[42:43]
	s_mov_b32 m0, s86
	s_nop 0
	global_load_lds_dwordx4 v[128:129], off
	s_waitcnt vmcnt(6)
	s_barrier
	v_mfma_f32_16x16x32_bf16 v[28:31], v[176:179], v[144:147], v[28:31]
	v_mfma_f32_16x16x32_bf16 v[24:27], v[184:187], v[144:147], v[24:27]
	v_mfma_f32_16x16x32_bf16 v[20:23], v[176:179], v[152:155], v[20:23]
	v_mfma_f32_16x16x32_bf16 v[16:19], v[184:187], v[152:155], v[16:19]
	v_mfma_f32_16x16x32_bf16 v[12:15], v[176:179], v[160:163], v[12:15]
	v_mfma_f32_16x16x32_bf16 v[8:11], v[184:187], v[160:163], v[8:11]
	v_mfma_f32_16x16x32_bf16 v[4:7], v[176:179], v[168:171], v[4:7]
	v_mfma_f32_16x16x32_bf16 v[0:3], v[184:187], v[168:171], v[0:3]
	v_mfma_f32_16x16x32_bf16 v[28:31], v[180:183], v[148:151], v[28:31]
	v_mfma_f32_16x16x32_bf16 v[24:27], v[188:191], v[148:151], v[24:27]
	v_mfma_f32_16x16x32_bf16 v[20:23], v[180:183], v[156:159], v[20:23]
	v_mfma_f32_16x16x32_bf16 v[16:19], v[188:191], v[156:159], v[16:19]
	v_mfma_f32_16x16x32_bf16 v[12:15], v[180:183], v[164:167], v[12:15]
	v_mfma_f32_16x16x32_bf16 v[8:11], v[188:191], v[164:167], v[8:11]
	v_mfma_f32_16x16x32_bf16 v[4:7], v[180:183], v[172:175], v[4:7]
	v_mfma_f32_16x16x32_bf16 v[0:3], v[188:191], v[172:175], v[0:3]
	s_add_i32 s1, s1, 2
	s_add_u32 s66, s66, 0x100
	s_addc_u32 s67, s67, 0
	s_add_u32 s68, s68, 0x100
	s_addc_u32 s69, s69, 0
	s_cmp_gt_u32 s1, 27
	s_barrier
	s_cbranch_scc0 .LBB0_667
	ds_read_b128 v[136:139], v219 offset:0
	ds_read_b128 v[140:143], v219 offset:0x400
	ds_read_b128 v[144:147], v219 offset:0x800
	ds_read_b128 v[148:151], v219 offset:0xc00
	ds_read_b128 v[128:131], v220 offset:0
	ds_read_b128 v[132:135], v220 offset:0x400
	ds_read_b128 v[152:155], v220 offset:0x800
	ds_read_b128 v[156:159], v220 offset:0xc00
	ds_read_b128 v[160:163], v220 offset:0x1000
	ds_read_b128 v[164:167], v220 offset:0x1400
	v_lshl_add_u64 v[176:177], s[64:65], 0, v[208:209]
	ds_read_b128 v[168:171], v220 offset:0x1800
	s_mov_b32 m0, s87
	ds_read_b128 v[172:175], v220 offset:0x1c00
	v_lshl_add_u64 v[178:179], v[176:177], 0, s[44:45]
	global_load_lds_dwordx4 v[178:179], off
	v_lshl_add_u64 v[176:177], v[176:177], 0, s[46:47]
	s_mov_b32 m0, s88
	s_ashr_i32 s1, s0, 31
	global_load_lds_dwordx4 v[176:177], off
	s_lshl_b64 s[64:65], s[0:1], 20
	s_add_u32 s64, s24, s64
	s_addc_u32 s65, s25, s65
	s_ashr_i32 s51, s50, 31
	s_barrier
	s_waitcnt lgkmcnt(0)
	s_lshl_b64 s[66:67], s[50:51], 20
	s_add_u32 s66, s30, s66
	s_addc_u32 s67, s31, s67
	v_mfma_f32_16x16x32_bf16 v[124:127], v[136:139], v[128:131], v[124:127]
	v_mfma_f32_16x16x32_bf16 v[120:123], v[144:147], v[128:131], v[120:123]
	v_mfma_f32_16x16x32_bf16 v[116:119], v[136:139], v[152:155], v[116:119]
	v_mfma_f32_16x16x32_bf16 v[112:115], v[144:147], v[152:155], v[112:115]
	v_mfma_f32_16x16x32_bf16 v[108:111], v[136:139], v[160:163], v[108:111]
	v_mfma_f32_16x16x32_bf16 v[104:107], v[144:147], v[160:163], v[104:107]
	v_mfma_f32_16x16x32_bf16 v[100:103], v[136:139], v[168:171], v[100:103]
	v_mfma_f32_16x16x32_bf16 v[96:99], v[144:147], v[168:171], v[96:99]
	v_mfma_f32_16x16x32_bf16 v[124:127], v[140:143], v[132:135], v[124:127]
	v_mfma_f32_16x16x32_bf16 v[120:123], v[148:151], v[132:135], v[120:123]
	v_mfma_f32_16x16x32_bf16 v[116:119], v[140:143], v[156:159], v[116:119]
	v_mfma_f32_16x16x32_bf16 v[112:115], v[148:151], v[156:159], v[112:115]
	v_mfma_f32_16x16x32_bf16 v[176:179], v[140:143], v[164:167], v[108:111]
	v_mfma_f32_16x16x32_bf16 v[180:183], v[148:151], v[164:167], v[104:107]
	v_mfma_f32_16x16x32_bf16 v[100:103], v[140:143], v[172:175], v[100:103]
	v_mfma_f32_16x16x32_bf16 v[96:99], v[148:151], v[172:175], v[96:99]
	s_barrier
	ds_read_b128 v[104:107], v221 offset:0
	ds_read_b128 v[108:111], v221 offset:0x400
	ds_read_b128 v[184:187], v221 offset:0x800
	ds_read_b128 v[188:191], v221 offset:0xc00
	s_barrier
; #define WAIT_V(n) asm volatile("s_waitcnt vmcnt(%0)" ::"n"(n) : "memory")
; #define SCHED() __builtin_amdgcn_sched_barrier(0)
; #define LGKM(n) asm volatile("s_waitcnt lgkmcnt(%0)" ::"n"(n) : "memory")
; #define LDA(b, h) do { const unsigned pa_ = lds0 + SLOTA(b, h) + wr * 8192 + laneoff; _Pragma("unroll") for (int m = 0; m < 4; ++m)   \
;       _Pragma("unroll") for (int k = 0; k < 2; ++k) DSR(At[m][k], pa_, m * 2048 + k * 1024); } while (0)
; #define LDB(dst, b, h) do { const unsigned pb_ = lds0 + SLOTB(b, h) + wc * 4096 + laneoff; _Pragma("unroll") for (int n = 0; n < 2; ++n) \
;       _Pragma("unroll") for (int k = 0; k < 2; ++k) DSR(dst[n][k], pb_, n * 2048 + k * 1024); } while (0)
; #define BAR __builtin_amdgcn_s_barrier()
; #define LGKM(n) asm volatile("s_waitcnt lgkmcnt(%0)" ::"n"(n) : "memory")
; template <int EPI, bool SWP> ...
;     ...
;     LDB(B1, 0, 1); BAR; LGKM(0); SCHED(); MMA(0, 1, B1); BAR; SCHED();
;     LDA(0, 1); WAIT_V(4); BAR; LGKM(0); SCHED(); MMA(1, 0, B0); MMA(1, 1, B1); BAR; SCHED(); }
;   { LDB(B0, 1, 0); LDA(1, 0); WAIT_V(2); BAR; LGKM(0); SCHED(); MMA(0, 0, B0); BAR; SCHED();
	s_waitcnt lgkmcnt(0)
	v_mfma_f32_16x16x32_bf16 v[92:95], v[104:107], v[128:131], v[92:95]
	v_mfma_f32_16x16x32_bf16 v[88:91], v[184:187], v[128:131], v[88:91]
	v_mfma_f32_16x16x32_bf16 v[84:87], v[104:107], v[152:155], v[84:87]
	v_mfma_f32_16x16x32_bf16 v[80:83], v[184:187], v[152:155], v[80:83]
	v_mfma_f32_16x16x32_bf16 v[76:79], v[104:107], v[160:163], v[76:79]
	v_mfma_f32_16x16x32_bf16 v[72:75], v[184:187], v[160:163], v[72:75]
	v_mfma_f32_16x16x32_bf16 v[68:71], v[104:107], v[168:171], v[68:71]
	v_mfma_f32_16x16x32_bf16 v[64:67], v[184:187], v[168:171], v[64:67]
	v_mfma_f32_16x16x32_bf16 v[192:195], v[108:111], v[132:135], v[92:95]
	v_mfma_f32_16x16x32_bf16 v[196:199], v[188:191], v[132:135], v[88:91]
	v_mfma_f32_16x16x32_bf16 v[84:87], v[108:111], v[156:159], v[84:87]
	v_mfma_f32_16x16x32_bf16 v[80:83], v[188:191], v[156:159], v[80:83]
	v_mfma_f32_16x16x32_bf16 v[200:203], v[108:111], v[164:167], v[76:79]
	v_mfma_f32_16x16x32_bf16 v[204:207], v[188:191], v[164:167], v[72:75]
	v_mfma_f32_16x16x32_bf16 v[68:71], v[108:111], v[172:175], v[68:71]
	v_mfma_f32_16x16x32_bf16 v[64:67], v[188:191], v[172:175], v[64:67]
	s_barrier
	ds_read_b128 v[72:75], v222 offset:0
	ds_read_b128 v[76:79], v222 offset:0x400
	ds_read_b128 v[88:91], v222 offset:0x800
	ds_read_b128 v[92:95], v222 offset:0xc00
	ds_read_b128 v[152:155], v222 offset:0x1000
	ds_read_b128 v[156:159], v222 offset:0x1400
	ds_read_b128 v[160:163], v222 offset:0x1800
	ds_read_b128 v[164:167], v222 offset:0x1c00
	s_waitcnt vmcnt(4)
	s_barrier
	s_waitcnt lgkmcnt(0)
	v_mfma_f32_16x16x32_bf16 v[60:63], v[136:139], v[72:75], v[60:63]
	v_mfma_f32_16x16x32_bf16 v[56:59], v[144:147], v[72:75], v[56:59]
	v_mfma_f32_16x16x32_bf16 v[52:55], v[136:139], v[88:91], v[52:55]
	v_mfma_f32_16x16x32_bf16 v[48:51], v[144:147], v[88:91], v[48:51]
	v_mfma_f32_16x16x32_bf16 v[44:47], v[136:139], v[152:155], v[44:47]
	v_mfma_f32_16x16x32_bf16 v[40:43], v[144:147], v[152:155], v[40:43]
	v_mfma_f32_16x16x32_bf16 v[36:39], v[136:139], v[160:163], v[36:39]
	v_mfma_f32_16x16x32_bf16 v[32:35], v[144:147], v[160:163], v[32:35]
	v_mfma_f32_16x16x32_bf16 v[60:63], v[140:143], v[76:79], v[60:63]
	v_mfma_f32_16x16x32_bf16 v[56:59], v[148:151], v[76:79], v[56:59]
	v_mfma_f32_16x16x32_bf16 v[52:55], v[140:143], v[92:95], v[52:55]
	v_mfma_f32_16x16x32_bf16 v[48:51], v[148:151], v[92:95], v[48:51]
	v_mfma_f32_16x16x32_bf16 v[128:131], v[140:143], v[156:159], v[44:47]
	v_mfma_f32_16x16x32_bf16 v[132:135], v[148:151], v[156:159], v[40:43]
	v_mfma_f32_16x16x32_bf16 v[36:39], v[140:143], v[164:167], v[36:39]
	v_mfma_f32_16x16x32_bf16 v[32:35], v[148:151], v[164:167], v[32:35]
	v_mfma_f32_16x16x32_bf16 v[28:31], v[104:107], v[72:75], v[28:31]
	v_mfma_f32_16x16x32_bf16 v[24:27], v[184:187], v[72:75], v[24:27]
	v_mfma_f32_16x16x32_bf16 v[20:23], v[104:107], v[88:91], v[20:23]
	v_mfma_f32_16x16x32_bf16 v[16:19], v[184:187], v[88:91], v[16:19]
	v_mfma_f32_16x16x32_bf16 v[12:15], v[104:107], v[152:155], v[12:15]
	v_mfma_f32_16x16x32_bf16 v[8:11], v[184:187], v[152:155], v[8:11]
	v_mfma_f32_16x16x32_bf16 v[4:7], v[104:107], v[160:163], v[4:7]
	v_mfma_f32_16x16x32_bf16 v[0:3], v[184:187], v[160:163], v[0:3]
	v_mfma_f32_16x16x32_bf16 v[136:139], v[108:111], v[76:79], v[28:31]
	v_mfma_f32_16x16x32_bf16 v[140:143], v[188:191], v[76:79], v[24:27]
	v_mfma_f32_16x16x32_bf16 v[20:23], v[108:111], v[92:95], v[20:23]
	v_mfma_f32_16x16x32_bf16 v[16:19], v[188:191], v[92:95], v[16:19]
	v_mfma_f32_16x16x32_bf16 v[144:147], v[108:111], v[156:159], v[12:15]
	v_mfma_f32_16x16x32_bf16 v[148:151], v[188:191], v[156:159], v[8:11]
	v_mfma_f32_16x16x32_bf16 v[4:7], v[108:111], v[164:167], v[4:7]
	v_mfma_f32_16x16x32_bf16 v[0:3], v[188:191], v[164:167], v[0:3]
	s_barrier
	ds_read_b128 v[8:11], v223 offset:0
	ds_read_b128 v[12:15], v223 offset:0x400
	ds_read_b128 v[152:155], v223 offset:0x800
	ds_read_b128 v[156:159], v223 offset:0xc00
	ds_read_b128 v[24:27], v224 offset:0
	ds_read_b128 v[28:31], v224 offset:0x400
	ds_read_b128 v[40:43], v224 offset:0x800
	ds_read_b128 v[44:47], v224 offset:0xc00
	ds_read_b128 v[184:187], v224 offset:0x1000
	ds_read_b128 v[188:191], v224 offset:0x1400
	ds_read_b128 v[212:215], v224 offset:0x1800
	ds_read_b128 v[236:239], v224 offset:0x1c00
	s_waitcnt vmcnt(2)
	s_barrier
; #define WAIT_V(n) asm volatile("s_waitcnt vmcnt(%0)" ::"n"(n) : "memory")
; #define SCHED() __builtin_amdgcn_sched_barrier(0)
; #define LGKM(n) asm volatile("s_waitcnt lgkmcnt(%0)" ::"n"(n) : "memory")
; #define STAGE_AX(AG, b, h, kt) do { _Pragma("unroll") for (int i = 0; i < 2; ++i)                                    \
;       __builtin_amdgcn_global_load_lds((const unsigned*)(((AG) + ((size_t)(kt) * (BK * 2) + (size_t)((h) * 2 + i) * 128 * lda)) + aoff), \
;                                        (unsigned*)(shm + SLOTA(b, h) + wid * 1024 + i * 8192), 16, 0, 0); } while (0)
; #define STAGE_BX(BG, b, h, kt) do { _Pragma("unroll") for (int i = 0; i < 2; ++i)                                    \
;       __builtin_amdgcn_global_load_lds((const unsigned*)(((BG) + ((size_t)(kt) * (BK * 2) + (size_t)((h) * 2 + i) * 128 * K)) + boff),   \
;                                        (unsigned*)(shm + SLOTB(b, h) + wid * 1024 + i * 8192), 16, 0, 0); } while (0)
; #define LDA(b, h) do { const unsigned pa_ = lds0 + SLOTA(b, h) + wr * 8192 + laneoff; _Pragma("unroll") for (int m = 0; m < 4; ++m)   \
;       _Pragma("unroll") for (int k = 0; k < 2; ++k) DSR(At[m][k], pa_, m * 2048 + k * 1024); } while (0)
; #define LDB(dst, b, h) do { const unsigned pb_ = lds0 + SLOTB(b, h) + wc * 4096 + laneoff; _Pragma("unroll") for (int n = 0; n < 2; ++n) \
;       _Pragma("unroll") for (int k = 0; k < 2; ++k) DSR(dst[n][k], pb_, n * 2048 + k * 1024); } while (0)
; #define BAR __builtin_amdgcn_s_barrier()
; #define LGKM(n) asm volatile("s_waitcnt lgkmcnt(%0)" ::"n"(n) : "memory")
; template <int EPI, bool SWP> ...
;     ...
;   { LDB(B0, 1, 0); LDA(1, 0); WAIT_V(2); BAR; LGKM(0); SCHED(); MMA(0, 0, B0); BAR; SCHED();
;     LDB(B1, 1, 1); WAIT_V(0); BAR; LGKM(0); SCHED(); MMA(0, 1, B1); BAR; SCHED();
;     LDA(1, 1);
;     if (has_next) { STAGE_BX(Bg_n, 0, 0, 0); STAGE_AX(Ag_n, 0, 0, 0); STAGE_BX(Bg_n, 0, 1, 0); STAGE_AX(Ag_n, 0, 1, 0); }
	s_waitcnt lgkmcnt(0)
	v_mfma_f32_16x16x32_bf16 v[72:75], v[8:11], v[24:27], v[124:127]
	v_mfma_f32_16x16x32_bf16 v[124:127], v[12:15], v[28:31], v[72:75]
	v_mfma_f32_16x16x32_bf16 v[72:75], v[152:155], v[24:27], v[120:123]
	v_mfma_f32_16x16x32_bf16 v[120:123], v[156:159], v[28:31], v[72:75]
	v_mfma_f32_16x16x32_bf16 v[72:75], v[8:11], v[40:43], v[116:119]
	v_mfma_f32_16x16x32_bf16 v[108:111], v[12:15], v[44:47], v[72:75]
	v_mfma_f32_16x16x32_bf16 v[72:75], v[152:155], v[40:43], v[112:115]
	v_mfma_f32_16x16x32_bf16 v[104:107], v[156:159], v[44:47], v[72:75]
	v_mfma_f32_16x16x32_bf16 v[72:75], v[8:11], v[184:187], v[176:179]
	v_mfma_f32_16x16x32_bf16 v[92:95], v[12:15], v[188:191], v[72:75]
	v_mfma_f32_16x16x32_bf16 v[72:75], v[152:155], v[184:187], v[180:183]
	v_mfma_f32_16x16x32_bf16 v[88:91], v[156:159], v[188:191], v[72:75]
	v_mfma_f32_16x16x32_bf16 v[72:75], v[8:11], v[212:215], v[100:103]
	v_mfma_f32_16x16x32_bf16 v[76:79], v[12:15], v[236:239], v[72:75]
	v_mfma_f32_16x16x32_bf16 v[72:75], v[152:155], v[212:215], v[96:99]
	v_mfma_f32_16x16x32_bf16 v[72:75], v[156:159], v[236:239], v[72:75]
	s_barrier
	ds_read_b128 v[160:163], v225 offset:0
	ds_read_b128 v[164:167], v225 offset:0x400
	ds_read_b128 v[168:171], v225 offset:0x800
	ds_read_b128 v[172:175], v225 offset:0xc00
	s_waitcnt vmcnt(0)
	s_barrier
	s_waitcnt lgkmcnt(0)
	v_mfma_f32_16x16x32_bf16 v[96:99], v[160:163], v[24:27], v[192:195]
	v_mfma_f32_16x16x32_bf16 v[24:27], v[168:171], v[24:27], v[196:199]
	v_mfma_f32_16x16x32_bf16 v[112:115], v[172:175], v[28:31], v[24:27]
	v_mfma_f32_16x16x32_bf16 v[24:27], v[160:163], v[40:43], v[84:87]
	v_mfma_f32_16x16x32_bf16 v[100:103], v[164:167], v[44:47], v[24:27]
	v_mfma_f32_16x16x32_bf16 v[24:27], v[168:171], v[40:43], v[80:83]
	v_mfma_f32_16x16x32_bf16 v[116:119], v[164:167], v[28:31], v[96:99]
	v_mfma_f32_16x16x32_bf16 v[96:99], v[172:175], v[44:47], v[24:27]
	v_mfma_f32_16x16x32_bf16 v[24:27], v[160:163], v[184:187], v[200:203]
	v_mfma_f32_16x16x32_bf16 v[84:87], v[164:167], v[188:191], v[24:27]
	v_mfma_f32_16x16x32_bf16 v[24:27], v[168:171], v[184:187], v[204:207]
	v_mfma_f32_16x16x32_bf16 v[80:83], v[172:175], v[188:191], v[24:27]
	v_mfma_f32_16x16x32_bf16 v[24:27], v[160:163], v[212:215], v[68:71]
	v_mfma_f32_16x16x32_bf16 v[68:71], v[164:167], v[236:239], v[24:27]
	v_mfma_f32_16x16x32_bf16 v[24:27], v[168:171], v[212:215], v[64:67]
	v_mfma_f32_16x16x32_bf16 v[64:67], v[172:175], v[236:239], v[24:27]
	s_barrier
	ds_read_b128 v[200:203], v226 offset:0
	ds_read_b128 v[204:207], v226 offset:0x400
	ds_read_b128 v[192:195], v226 offset:0x800
	ds_read_b128 v[196:199], v226 offset:0xc00
	ds_read_b128 v[184:187], v226 offset:0x1000
	ds_read_b128 v[188:191], v226 offset:0x1400
	ds_read_b128 v[176:179], v226 offset:0x1800
	ds_read_b128 v[180:183], v226 offset:0x1c00
	s_and_b64 vcc, exec, s[62:63]
	v_lshl_add_u64 v[212:213], s[66:67], 0, v[208:209]
	v_lshl_add_u64 v[214:215], s[64:65], 0, v[208:209]
	s_cbranch_vccz .LBB0_670
	s_mov_b32 m0, s75
	v_lshl_add_u64 v[24:25], v[212:213], 0, s[12:13]
	global_load_lds_dwordx4 v[212:213], off
	s_mov_b32 m0, s76
	s_nop 0
	global_load_lds_dwordx4 v[24:25], off
	s_mov_b32 m0, s3
	v_lshl_add_u64 v[24:25], v[214:215], 0, s[12:13]
	global_load_lds_dwordx4 v[214:215], off
	s_mov_b32 m0, s77
	s_nop 0
	global_load_lds_dwordx4 v[24:25], off
	v_lshl_add_u64 v[24:25], v[212:213], 0, s[14:15]
	s_mov_b32 m0, s78
	s_nop 0
	global_load_lds_dwordx4 v[24:25], off
	v_lshl_add_u64 v[24:25], v[212:213], 0, s[16:17]
	s_mov_b32 m0, s79
	s_nop 0
	global_load_lds_dwordx4 v[24:25], off
	v_lshl_add_u64 v[24:25], v[214:215], 0, s[14:15]
	s_mov_b32 m0, s80
	s_nop 0
	global_load_lds_dwordx4 v[24:25], off
	v_lshl_add_u64 v[24:25], v[214:215], 0, s[16:17]
	s_mov_b32 m0, s81
	s_nop 0
	global_load_lds_dwordx4 v[24:25], off

; #define WAIT_V(n) asm volatile("s_waitcnt vmcnt(%0)" ::"n"(n) : "memory")
; #define SCHED() __builtin_amdgcn_sched_barrier(0)
; #define LGKM(n) asm volatile("s_waitcnt lgkmcnt(%0)" ::"n"(n) : "memory")
; #define STAGE_A(b, h, kt) STAGE_AX(Ag, b, h, kt)
; #define STAGE_B(b, h, kt) STAGE_BX(Bg, b, h, kt)
; #define LDA(b, h) do { const unsigned pa_ = lds0 + SLOTA(b, h) + wr * 8192 + laneoff; _Pragma("unroll") for (int m = 0; m < 4; ++m)   \
;       _Pragma("unroll") for (int k = 0; k < 2; ++k) DSR(At[m][k], pa_, m * 2048 + k * 1024); } while (0)
; #define LDB(dst, b, h) do { const unsigned pb_ = lds0 + SLOTB(b, h) + wc * 4096 + laneoff; _Pragma("unroll") for (int n = 0; n < 2; ++n) \
;       _Pragma("unroll") for (int k = 0; k < 2; ++k) DSR(dst[n][k], pb_, n * 2048 + k * 1024); } while (0)
; #define BAR __builtin_amdgcn_s_barrier()
; #define LGKM(n) asm volatile("s_waitcnt lgkmcnt(%0)" ::"n"(n) : "memory")
; template <int EPI, bool SWP> ...
;     ...
;     LDB(B0, 0, 0); LDA(0, 0); STAGE_A(1, 1, t + 1);
;     LGKM(8); BAR; LGKM(0); SCHED(); MMA(0, 0, B0); BAR; SCHED();
;     LDB(B1, 0, 1); STAGE_B(0, 0, t + 2);
;     BAR; LGKM(0); SCHED(); MMA(0, 1, B1); BAR; SCHED();
;     LDA(0, 1); STAGE_A(0, 0, t + 2);
;     BAR; LGKM(0); SCHED(); MMA(1, 0, B0); BAR; SCHED();
;     STAGE_B(0, 1, t + 2);
;     WAIT_V(6); BAR; SCHED(); MMA(1, 1, B1); BAR; SCHED();
.LBB0_709:
	ds_read_b128 v[130:133], v201 offset:0
	ds_read_b128 v[134:137], v201 offset:0x400
	ds_read_b128 v[138:141], v201 offset:0x800
	ds_read_b128 v[142:145], v201 offset:0xc00
	ds_read_b128 v[146:149], v202 offset:0
	ds_read_b128 v[150:153], v202 offset:0x400
	ds_read_b128 v[154:157], v202 offset:0x800
	ds_read_b128 v[158:161], v202 offset:0xc00
	ds_read_b128 v[162:165], v202 offset:0x1000
	ds_read_b128 v[166:169], v202 offset:0x1400
	ds_read_b128 v[170:173], v202 offset:0x1800
	v_lshl_add_u64 v[190:191], s[68:69], 0, v[194:195]
	s_mov_b32 m0, s86
	ds_read_b128 v[174:177], v202 offset:0x1c00
	v_lshl_add_u64 v[178:179], v[190:191], 0, s[28:29]
	global_load_lds_dwordx4 v[178:179], off
	v_lshl_add_u64 v[178:179], v[190:191], 0, s[30:31]
	s_mov_b32 m0, s87
	s_nop 0
	global_load_lds_dwordx4 v[178:179], off
	s_waitcnt lgkmcnt(8)
	s_barrier
	s_waitcnt lgkmcnt(0)
	v_mfma_f32_16x16x32_bf16 v[124:127], v[130:133], v[146:149], v[124:127]
	v_mfma_f32_16x16x32_bf16 v[120:123], v[138:141], v[146:149], v[120:123]
	v_mfma_f32_16x16x32_bf16 v[116:119], v[130:133], v[154:157], v[116:119]
	v_mfma_f32_16x16x32_bf16 v[112:115], v[138:141], v[154:157], v[112:115]
	v_mfma_f32_16x16x32_bf16 v[108:111], v[130:133], v[162:165], v[108:111]
	v_mfma_f32_16x16x32_bf16 v[104:107], v[138:141], v[162:165], v[104:107]
	v_mfma_f32_16x16x32_bf16 v[100:103], v[130:133], v[170:173], v[100:103]
	v_mfma_f32_16x16x32_bf16 v[96:99], v[138:141], v[170:173], v[96:99]
	v_mfma_f32_16x16x32_bf16 v[124:127], v[134:137], v[150:153], v[124:127]
	v_mfma_f32_16x16x32_bf16 v[120:123], v[142:145], v[150:153], v[120:123]
	v_mfma_f32_16x16x32_bf16 v[116:119], v[134:137], v[158:161], v[116:119]
	v_mfma_f32_16x16x32_bf16 v[112:115], v[142:145], v[158:161], v[112:115]
	v_mfma_f32_16x16x32_bf16 v[108:111], v[134:137], v[166:169], v[108:111]
	v_mfma_f32_16x16x32_bf16 v[104:107], v[142:145], v[166:169], v[104:107]
	v_mfma_f32_16x16x32_bf16 v[100:103], v[134:137], v[174:177], v[100:103]
	v_mfma_f32_16x16x32_bf16 v[96:99], v[142:145], v[174:177], v[96:99]
	s_barrier
	ds_read_b128 v[178:181], v203 offset:0
	ds_read_b128 v[182:185], v203 offset:0x400
	ds_read_b128 v[186:189], v203 offset:0x800
	v_lshl_add_u64 v[218:219], s[70:71], 0, v[194:195]
	s_mov_b64 s[92:93], 0x2fd00100
	s_mov_b32 m0, s73
	ds_read_b128 v[196:199], v203 offset:0xc00
	v_lshl_add_u64 v[220:221], v[218:219], 0, s[92:93]
	s_mov_b64 s[92:93], 0x2fdb0100
	global_load_lds_dwordx4 v[220:221], off
	v_lshl_add_u64 v[220:221], v[218:219], 0, s[92:93]
	s_mov_b32 m0, s74
	s_nop 0
	global_load_lds_dwordx4 v[220:221], off
	s_barrier
	s_waitcnt lgkmcnt(0)
	v_mfma_f32_16x16x32_bf16 v[92:95], v[178:181], v[146:149], v[92:95]
	v_mfma_f32_16x16x32_bf16 v[88:91], v[186:189], v[146:149], v[88:91]
	v_mfma_f32_16x16x32_bf16 v[84:87], v[178:181], v[154:157], v[84:87]
	v_mfma_f32_16x16x32_bf16 v[80:83], v[186:189], v[154:157], v[80:83]
	v_mfma_f32_16x16x32_bf16 v[76:79], v[178:181], v[162:165], v[76:79]
	v_mfma_f32_16x16x32_bf16 v[72:75], v[186:189], v[162:165], v[72:75]
	v_mfma_f32_16x16x32_bf16 v[68:71], v[178:181], v[170:173], v[68:71]
	v_mfma_f32_16x16x32_bf16 v[64:67], v[186:189], v[170:173], v[64:67]
	v_mfma_f32_16x16x32_bf16 v[92:95], v[182:185], v[150:153], v[92:95]
	v_mfma_f32_16x16x32_bf16 v[88:91], v[196:199], v[150:153], v[88:91]
	v_mfma_f32_16x16x32_bf16 v[84:87], v[182:185], v[158:161], v[84:87]
	v_mfma_f32_16x16x32_bf16 v[80:83], v[196:199], v[158:161], v[80:83]
	v_mfma_f32_16x16x32_bf16 v[76:79], v[182:185], v[166:169], v[76:79]
	v_mfma_f32_16x16x32_bf16 v[72:75], v[196:199], v[166:169], v[72:75]
	v_mfma_f32_16x16x32_bf16 v[68:71], v[182:185], v[174:177], v[68:71]
	v_mfma_f32_16x16x32_bf16 v[64:67], v[196:199], v[174:177], v[64:67]
	s_barrier
	ds_read_b128 v[146:149], v204 offset:0
	ds_read_b128 v[150:153], v204 offset:0x400
	ds_read_b128 v[154:157], v204 offset:0x800
	ds_read_b128 v[158:161], v204 offset:0xc00
	ds_read_b128 v[162:165], v204 offset:0x1000
	ds_read_b128 v[166:169], v204 offset:0x1400
	ds_read_b128 v[170:173], v204 offset:0x1800
	s_mov_b64 s[92:93], 0x100
	s_mov_b32 m0, s3
	ds_read_b128 v[174:177], v204 offset:0x1c00
	v_lshl_add_u64 v[220:221], v[190:191], 0, s[92:93]
	s_mov_b64 s[92:93], 0xb0100
	global_load_lds_dwordx4 v[220:221], off
	v_lshl_add_u64 v[220:221], v[190:191], 0, s[92:93]
	s_mov_b32 m0, s75
	s_nop 0
	global_load_lds_dwordx4 v[220:221], off
	s_barrier
	s_waitcnt lgkmcnt(0)
	v_mfma_f32_16x16x32_bf16 v[60:63], v[130:133], v[146:149], v[60:63]
	v_mfma_f32_16x16x32_bf16 v[56:59], v[138:141], v[146:149], v[56:59]
	v_mfma_f32_16x16x32_bf16 v[52:55], v[130:133], v[154:157], v[52:55]
	v_mfma_f32_16x16x32_bf16 v[48:51], v[138:141], v[154:157], v[48:51]
	v_mfma_f32_16x16x32_bf16 v[44:47], v[130:133], v[162:165], v[44:47]
	v_mfma_f32_16x16x32_bf16 v[40:43], v[138:141], v[162:165], v[40:43]
	v_mfma_f32_16x16x32_bf16 v[36:39], v[130:133], v[170:173], v[36:39]
	v_mfma_f32_16x16x32_bf16 v[32:35], v[138:141], v[170:173], v[32:35]
	v_mfma_f32_16x16x32_bf16 v[60:63], v[134:137], v[150:153], v[60:63]
	v_mfma_f32_16x16x32_bf16 v[56:59], v[142:145], v[150:153], v[56:59]
	v_mfma_f32_16x16x32_bf16 v[52:55], v[134:137], v[158:161], v[52:55]
	v_mfma_f32_16x16x32_bf16 v[48:51], v[142:145], v[158:161], v[48:51]
	v_mfma_f32_16x16x32_bf16 v[44:47], v[134:137], v[166:169], v[44:47]
	v_mfma_f32_16x16x32_bf16 v[40:43], v[142:145], v[166:169], v[40:43]
	v_mfma_f32_16x16x32_bf16 v[36:39], v[134:137], v[174:177], v[36:39]
	v_mfma_f32_16x16x32_bf16 v[32:35], v[142:145], v[174:177], v[32:35]
	s_barrier
	s_mov_b32 m0, s76
	v_lshl_add_u64 v[130:131], v[218:219], 0, s[34:35]
	global_load_lds_dwordx4 v[130:131], off
	v_lshl_add_u64 v[130:131], v[218:219], 0, s[36:37]
	s_mov_b32 m0, s77
	s_nop 0
	global_load_lds_dwordx4 v[130:131], off
	s_waitcnt vmcnt(6)
	s_barrier
; #define WAIT_V(n) asm volatile("s_waitcnt vmcnt(%0)" ::"n"(n) : "memory")
; #define SCHED() __builtin_amdgcn_sched_barrier(0)
; #define LGKM(n) asm volatile("s_waitcnt lgkmcnt(%0)" ::"n"(n) : "memory")
; #define STAGE_A(b, h, kt) STAGE_AX(Ag, b, h, kt)
; #define STAGE_B(b, h, kt) STAGE_BX(Bg, b, h, kt)
; #define LDA(b, h) do { const unsigned pa_ = lds0 + SLOTA(b, h) + wr * 8192 + laneoff; _Pragma("unroll") for (int m = 0; m < 4; ++m)   \
;       _Pragma("unroll") for (int k = 0; k < 2; ++k) DSR(At[m][k], pa_, m * 2048 + k * 1024); } while (0)
; #define LDB(dst, b, h) do { const unsigned pb_ = lds0 + SLOTB(b, h) + wc * 4096 + laneoff; _Pragma("unroll") for (int n = 0; n < 2; ++n) \
;       _Pragma("unroll") for (int k = 0; k < 2; ++k) DSR(dst[n][k], pb_, n * 2048 + k * 1024); } while (0)
; #define BAR __builtin_amdgcn_s_barrier()
; #define LGKM(n) asm volatile("s_waitcnt lgkmcnt(%0)" ::"n"(n) : "memory")
; template <int EPI, bool SWP> ...
;     ...
;     WAIT_V(6); BAR; SCHED(); MMA(1, 1, B1); BAR; SCHED();
;     LDB(B0, 1, 0); LDA(1, 0); STAGE_A(0, 1, t + 2);
;     LGKM(8); BAR; LGKM(0); SCHED(); MMA(0, 0, B0); BAR; SCHED();
;     LDB(B1, 1, 1); STAGE_B(1, 0, t + 3);
;     BAR; LGKM(0); SCHED(); MMA(0, 1, B1); BAR; SCHED();
;     LDA(1, 1); STAGE_A(1, 0, t + 3);
	v_mfma_f32_16x16x32_bf16 v[28:31], v[178:181], v[146:149], v[28:31]
	v_mfma_f32_16x16x32_bf16 v[24:27], v[186:189], v[146:149], v[24:27]
	v_mfma_f32_16x16x32_bf16 v[20:23], v[178:181], v[154:157], v[20:23]
	v_mfma_f32_16x16x32_bf16 v[16:19], v[186:189], v[154:157], v[16:19]
	v_mfma_f32_16x16x32_bf16 v[12:15], v[178:181], v[162:165], v[12:15]
	v_mfma_f32_16x16x32_bf16 v[8:11], v[186:189], v[162:165], v[8:11]
	v_mfma_f32_16x16x32_bf16 v[4:7], v[178:181], v[170:173], v[4:7]
	v_mfma_f32_16x16x32_bf16 v[0:3], v[186:189], v[170:173], v[0:3]
	v_mfma_f32_16x16x32_bf16 v[28:31], v[182:185], v[150:153], v[28:31]
	v_mfma_f32_16x16x32_bf16 v[24:27], v[196:199], v[150:153], v[24:27]
	v_mfma_f32_16x16x32_bf16 v[20:23], v[182:185], v[158:161], v[20:23]
	v_mfma_f32_16x16x32_bf16 v[16:19], v[196:199], v[158:161], v[16:19]
	v_mfma_f32_16x16x32_bf16 v[12:15], v[182:185], v[166:169], v[12:15]
	v_mfma_f32_16x16x32_bf16 v[8:11], v[196:199], v[166:169], v[8:11]
	v_mfma_f32_16x16x32_bf16 v[4:7], v[182:185], v[174:177], v[4:7]
	v_mfma_f32_16x16x32_bf16 v[0:3], v[196:199], v[174:177], v[0:3]
	s_barrier
	ds_read_b128 v[130:133], v205 offset:0
	ds_read_b128 v[134:137], v205 offset:0x400
	ds_read_b128 v[138:141], v205 offset:0x800
	ds_read_b128 v[142:145], v205 offset:0xc00
	ds_read_b128 v[146:149], v206 offset:0
	ds_read_b128 v[150:153], v206 offset:0x400
	ds_read_b128 v[154:157], v206 offset:0x800
	ds_read_b128 v[158:161], v206 offset:0xc00
	ds_read_b128 v[162:165], v206 offset:0x1000
	ds_read_b128 v[166:169], v206 offset:0x1400
	ds_read_b128 v[170:173], v206 offset:0x1800
	s_mov_b32 m0, s78
	ds_read_b128 v[174:177], v206 offset:0x1c00
	v_lshl_add_u64 v[178:179], v[190:191], 0, s[38:39]
	global_load_lds_dwordx4 v[178:179], off
	v_lshl_add_u64 v[178:179], v[190:191], 0, s[40:41]
	s_mov_b32 m0, s79
	s_nop 0
	global_load_lds_dwordx4 v[178:179], off
	s_waitcnt lgkmcnt(8)
	s_barrier
	s_waitcnt lgkmcnt(0)
	v_mfma_f32_16x16x32_bf16 v[124:127], v[130:133], v[146:149], v[124:127]
	v_mfma_f32_16x16x32_bf16 v[120:123], v[138:141], v[146:149], v[120:123]
	v_mfma_f32_16x16x32_bf16 v[116:119], v[130:133], v[154:157], v[116:119]
	v_mfma_f32_16x16x32_bf16 v[112:115], v[138:141], v[154:157], v[112:115]
	v_mfma_f32_16x16x32_bf16 v[108:111], v[130:133], v[162:165], v[108:111]
	v_mfma_f32_16x16x32_bf16 v[104:107], v[138:141], v[162:165], v[104:107]
	v_mfma_f32_16x16x32_bf16 v[100:103], v[130:133], v[170:173], v[100:103]
	v_mfma_f32_16x16x32_bf16 v[96:99], v[138:141], v[170:173], v[96:99]
	v_mfma_f32_16x16x32_bf16 v[124:127], v[134:137], v[150:153], v[124:127]
	v_mfma_f32_16x16x32_bf16 v[120:123], v[142:145], v[150:153], v[120:123]
	v_mfma_f32_16x16x32_bf16 v[116:119], v[134:137], v[158:161], v[116:119]
	v_mfma_f32_16x16x32_bf16 v[112:115], v[142:145], v[158:161], v[112:115]
	v_mfma_f32_16x16x32_bf16 v[108:111], v[134:137], v[166:169], v[108:111]
	v_mfma_f32_16x16x32_bf16 v[104:107], v[142:145], v[166:169], v[104:107]
	v_mfma_f32_16x16x32_bf16 v[100:103], v[134:137], v[174:177], v[100:103]
	v_mfma_f32_16x16x32_bf16 v[96:99], v[142:145], v[174:177], v[96:99]
	s_barrier
	ds_read_b128 v[178:181], v207 offset:0
	ds_read_b128 v[182:185], v207 offset:0x400
	ds_read_b128 v[186:189], v207 offset:0x800
	s_mov_b32 m0, s80
	ds_read_b128 v[196:199], v207 offset:0xc00
	v_lshl_add_u64 v[220:221], v[218:219], 0, s[42:43]
	global_load_lds_dwordx4 v[220:221], off
	v_lshl_add_u64 v[220:221], v[218:219], 0, s[44:45]
	s_mov_b32 m0, s81
	s_nop 0
	global_load_lds_dwordx4 v[220:221], off
	s_barrier
	s_waitcnt lgkmcnt(0)
	v_mfma_f32_16x16x32_bf16 v[92:95], v[178:181], v[146:149], v[92:95]
	v_mfma_f32_16x16x32_bf16 v[88:91], v[186:189], v[146:149], v[88:91]
	v_mfma_f32_16x16x32_bf16 v[84:87], v[178:181], v[154:157], v[84:87]
	v_mfma_f32_16x16x32_bf16 v[80:83], v[186:189], v[154:157], v[80:83]
	v_mfma_f32_16x16x32_bf16 v[76:79], v[178:181], v[162:165], v[76:79]
	v_mfma_f32_16x16x32_bf16 v[72:75], v[186:189], v[162:165], v[72:75]
	v_mfma_f32_16x16x32_bf16 v[68:71], v[178:181], v[170:173], v[68:71]
	v_mfma_f32_16x16x32_bf16 v[64:67], v[186:189], v[170:173], v[64:67]
	v_mfma_f32_16x16x32_bf16 v[92:95], v[182:185], v[150:153], v[92:95]
	v_mfma_f32_16x16x32_bf16 v[88:91], v[196:199], v[150:153], v[88:91]
	v_mfma_f32_16x16x32_bf16 v[84:87], v[182:185], v[158:161], v[84:87]
	v_mfma_f32_16x16x32_bf16 v[80:83], v[196:199], v[158:161], v[80:83]
	v_mfma_f32_16x16x32_bf16 v[76:79], v[182:185], v[166:169], v[76:79]
	v_mfma_f32_16x16x32_bf16 v[72:75], v[196:199], v[166:169], v[72:75]
	v_mfma_f32_16x16x32_bf16 v[68:71], v[182:185], v[174:177], v[68:71]
	v_mfma_f32_16x16x32_bf16 v[64:67], v[196:199], v[174:177], v[64:67]
	s_barrier
	ds_read_b128 v[146:149], v208 offset:0
	ds_read_b128 v[150:153], v208 offset:0x400
	ds_read_b128 v[154:157], v208 offset:0x800
	ds_read_b128 v[158:161], v208 offset:0xc00
	ds_read_b128 v[162:165], v208 offset:0x1000
	ds_read_b128 v[166:169], v208 offset:0x1400
	ds_read_b128 v[170:173], v208 offset:0x1800
	s_mov_b32 m0, s82
	ds_read_b128 v[174:177], v208 offset:0x1c00
	v_lshl_add_u64 v[220:221], v[190:191], 0, s[46:47]
	global_load_lds_dwordx4 v[220:221], off
	v_lshl_add_u64 v[190:191], v[190:191], 0, s[48:49]
	s_mov_b32 m0, s83
	s_nop 0
	global_load_lds_dwordx4 v[190:191], off
	s_barrier
; #define WAIT_V(n) asm volatile("s_waitcnt vmcnt(%0)" ::"n"(n) : "memory")
; #define SCHED() __builtin_amdgcn_sched_barrier(0)
; #define LGKM(n) asm volatile("s_waitcnt lgkmcnt(%0)" ::"n"(n) : "memory")
; #define STAGE_A(b, h, kt) STAGE_AX(Ag, b, h, kt)
; #define STAGE_B(b, h, kt) STAGE_BX(Bg, b, h, kt)
; #define LDA(b, h) do { const unsigned pa_ = lds0 + SLOTA(b, h) + wr * 8192 + laneoff; _Pragma("unroll") for (int m = 0; m < 4; ++m)   \
;       _Pragma("unroll") for (int k = 0; k < 2; ++k) DSR(At[m][k], pa_, m * 2048 + k * 1024); } while (0)
; #define LDB(dst, b, h) do { const unsigned pb_ = lds0 + SLOTB(b, h) + wc * 4096 + laneoff; _Pragma("unroll") for (int n = 0; n < 2; ++n) \
;       _Pragma("unroll") for (int k = 0; k < 2; ++k) DSR(dst[n][k], pb_, n * 2048 + k * 1024); } while (0)
; #define BAR __builtin_amdgcn_s_barrier()
; #define LGKM(n) asm volatile("s_waitcnt lgkmcnt(%0)" ::"n"(n) : "memory")
; template <int EPI, bool SWP> ...
;     ...
;     BAR; LGKM(0); SCHED(); MMA(1, 0, B0); BAR; SCHED();
;     STAGE_B(1, 1, t + 3);
;     WAIT_V(6); BAR; SCHED(); MMA(1, 1, B1); BAR; SCHED();
;   }
;   { LDB(B0, 0, 0); LDA(0, 0); STAGE_A(1, 1, nt - 1);
;     BAR; LGKM(0); SCHED(); MMA(0, 0, B0); BAR; SCHED();
;     LDB(B1, 0, 1); BAR; LGKM(0); SCHED(); MMA(0, 1, B1); BAR; SCHED();
	s_waitcnt lgkmcnt(0)
	v_mfma_f32_16x16x32_bf16 v[60:63], v[130:133], v[146:149], v[60:63]
	v_mfma_f32_16x16x32_bf16 v[56:59], v[138:141], v[146:149], v[56:59]
	v_mfma_f32_16x16x32_bf16 v[52:55], v[130:133], v[154:157], v[52:55]
	v_mfma_f32_16x16x32_bf16 v[48:51], v[138:141], v[154:157], v[48:51]
	v_mfma_f32_16x16x32_bf16 v[44:47], v[130:133], v[162:165], v[44:47]
	v_mfma_f32_16x16x32_bf16 v[40:43], v[138:141], v[162:165], v[40:43]
	v_mfma_f32_16x16x32_bf16 v[36:39], v[130:133], v[170:173], v[36:39]
	v_mfma_f32_16x16x32_bf16 v[32:35], v[138:141], v[170:173], v[32:35]
	v_mfma_f32_16x16x32_bf16 v[60:63], v[134:137], v[150:153], v[60:63]
	v_mfma_f32_16x16x32_bf16 v[56:59], v[142:145], v[150:153], v[56:59]
	v_mfma_f32_16x16x32_bf16 v[52:55], v[134:137], v[158:161], v[52:55]
	v_mfma_f32_16x16x32_bf16 v[48:51], v[142:145], v[158:161], v[48:51]
	v_mfma_f32_16x16x32_bf16 v[44:47], v[134:137], v[166:169], v[44:47]
	v_mfma_f32_16x16x32_bf16 v[40:43], v[142:145], v[166:169], v[40:43]
	v_mfma_f32_16x16x32_bf16 v[36:39], v[134:137], v[174:177], v[36:39]
	v_mfma_f32_16x16x32_bf16 v[32:35], v[142:145], v[174:177], v[32:35]
	s_barrier
	s_mov_b32 m0, s84
	v_lshl_add_u64 v[130:131], v[218:219], 0, s[50:51]
	global_load_lds_dwordx4 v[130:131], off
	v_lshl_add_u64 v[130:131], v[218:219], 0, s[58:59]
	s_mov_b32 m0, s85
	s_nop 0
	global_load_lds_dwordx4 v[130:131], off
	s_waitcnt vmcnt(6)
	s_barrier
	v_mfma_f32_16x16x32_bf16 v[28:31], v[178:181], v[146:149], v[28:31]
	v_mfma_f32_16x16x32_bf16 v[24:27], v[186:189], v[146:149], v[24:27]
	v_mfma_f32_16x16x32_bf16 v[20:23], v[178:181], v[154:157], v[20:23]
	v_mfma_f32_16x16x32_bf16 v[16:19], v[186:189], v[154:157], v[16:19]
	v_mfma_f32_16x16x32_bf16 v[12:15], v[178:181], v[162:165], v[12:15]
	v_mfma_f32_16x16x32_bf16 v[8:11], v[186:189], v[162:165], v[8:11]
	v_mfma_f32_16x16x32_bf16 v[4:7], v[178:181], v[170:173], v[4:7]
	v_mfma_f32_16x16x32_bf16 v[0:3], v[186:189], v[170:173], v[0:3]
	v_mfma_f32_16x16x32_bf16 v[28:31], v[182:185], v[150:153], v[28:31]
	v_mfma_f32_16x16x32_bf16 v[24:27], v[196:199], v[150:153], v[24:27]
	v_mfma_f32_16x16x32_bf16 v[20:23], v[182:185], v[158:161], v[20:23]
	v_mfma_f32_16x16x32_bf16 v[16:19], v[196:199], v[158:161], v[16:19]
	v_mfma_f32_16x16x32_bf16 v[12:15], v[182:185], v[166:169], v[12:15]
	v_mfma_f32_16x16x32_bf16 v[8:11], v[196:199], v[166:169], v[8:11]
	v_mfma_f32_16x16x32_bf16 v[4:7], v[182:185], v[174:177], v[4:7]
	v_mfma_f32_16x16x32_bf16 v[0:3], v[196:199], v[174:177], v[0:3]
	s_add_i32 s91, s91, 2
	s_add_u32 s70, s70, 0x100
	s_addc_u32 s71, s71, 0
	s_add_u32 s68, s68, 0x100
	s_addc_u32 s69, s69, 0
	s_cmpk_gt_u32 s91, 0x53
	s_barrier
	s_cbranch_scc0 .LBB0_709
	ds_read_b128 v[130:133], v201 offset:0
	ds_read_b128 v[134:137], v201 offset:0x400
	ds_read_b128 v[138:141], v201 offset:0x800
	ds_read_b128 v[142:145], v201 offset:0xc00
	ds_read_b128 v[146:149], v202 offset:0
	ds_read_b128 v[150:153], v202 offset:0x400
	ds_read_b128 v[154:157], v202 offset:0x800
	ds_read_b128 v[158:161], v202 offset:0xc00
	ds_read_b128 v[162:165], v202 offset:0x1000
	ds_read_b128 v[166:169], v202 offset:0x1400
	ds_read_b128 v[170:173], v202 offset:0x1800
	s_mov_b32 m0, s86
	ds_read_b128 v[174:177], v202 offset:0x1c00
	v_lshl_add_u64 v[178:179], v[128:129], 0, s[60:61]
	global_load_lds_dwordx4 v[178:179], off
	v_lshl_add_u64 v[128:129], v[128:129], 0, s[62:63]
	s_mov_b32 m0, s87
	s_mul_i32 s68, s88, 0x2c0000
	global_load_lds_dwordx4 v[128:129], off
	s_mul_hi_i32 s69, s88, 0x2c0000
	s_add_u32 s68, s56, s68
	s_barrier
	s_waitcnt lgkmcnt(0)
	s_addc_u32 s69, s57, s69
	s_mul_i32 s70, s89, 0x2c0000
	s_mul_hi_i32 s71, s89, 0x2c0000
	s_add_u32 s70, s22, s70
	s_addc_u32 s71, s23, s71
	v_mfma_f32_16x16x32_bf16 v[124:127], v[130:133], v[146:149], v[124:127]
	v_mfma_f32_16x16x32_bf16 v[120:123], v[138:141], v[146:149], v[120:123]
	v_mfma_f32_16x16x32_bf16 v[116:119], v[130:133], v[154:157], v[116:119]
	v_mfma_f32_16x16x32_bf16 v[112:115], v[138:141], v[154:157], v[112:115]
	v_mfma_f32_16x16x32_bf16 v[108:111], v[130:133], v[162:165], v[108:111]
	v_mfma_f32_16x16x32_bf16 v[104:107], v[138:141], v[162:165], v[104:107]
	v_mfma_f32_16x16x32_bf16 v[100:103], v[130:133], v[170:173], v[100:103]
	v_mfma_f32_16x16x32_bf16 v[96:99], v[138:141], v[170:173], v[96:99]
	v_mfma_f32_16x16x32_bf16 v[124:127], v[134:137], v[150:153], v[124:127]
	v_mfma_f32_16x16x32_bf16 v[120:123], v[142:145], v[150:153], v[120:123]
	v_mfma_f32_16x16x32_bf16 v[116:119], v[134:137], v[158:161], v[116:119]
	v_mfma_f32_16x16x32_bf16 v[112:115], v[142:145], v[158:161], v[112:115]
	v_mfma_f32_16x16x32_bf16 v[108:111], v[134:137], v[166:169], v[108:111]
	v_mfma_f32_16x16x32_bf16 v[104:107], v[142:145], v[166:169], v[104:107]
	v_mfma_f32_16x16x32_bf16 v[100:103], v[134:137], v[174:177], v[100:103]
	v_mfma_f32_16x16x32_bf16 v[96:99], v[142:145], v[174:177], v[96:99]
	s_barrier
	ds_read_b128 v[178:181], v203 offset:0
	ds_read_b128 v[182:185], v203 offset:0x400
	ds_read_b128 v[186:189], v203 offset:0x800
	ds_read_b128 v[196:199], v203 offset:0xc00
	s_barrier
	s_waitcnt lgkmcnt(0)
	v_mfma_f32_16x16x32_bf16 v[92:95], v[178:181], v[146:149], v[92:95]
	v_mfma_f32_16x16x32_bf16 v[88:91], v[186:189], v[146:149], v[88:91]
	v_mfma_f32_16x16x32_bf16 v[84:87], v[178:181], v[154:157], v[84:87]
	v_mfma_f32_16x16x32_bf16 v[80:83], v[186:189], v[154:157], v[80:83]
	v_mfma_f32_16x16x32_bf16 v[76:79], v[178:181], v[162:165], v[76:79]
	v_mfma_f32_16x16x32_bf16 v[72:75], v[186:189], v[162:165], v[72:75]
	v_mfma_f32_16x16x32_bf16 v[68:71], v[178:181], v[170:173], v[68:71]
	v_mfma_f32_16x16x32_bf16 v[64:67], v[186:189], v[170:173], v[64:67]
	v_mfma_f32_16x16x32_bf16 v[92:95], v[182:185], v[150:153], v[92:95]
	v_mfma_f32_16x16x32_bf16 v[88:91], v[196:199], v[150:153], v[88:91]
	v_mfma_f32_16x16x32_bf16 v[84:87], v[182:185], v[158:161], v[84:87]
	v_mfma_f32_16x16x32_bf16 v[80:83], v[196:199], v[158:161], v[80:83]
	v_mfma_f32_16x16x32_bf16 v[76:79], v[182:185], v[166:169], v[76:79]
	v_mfma_f32_16x16x32_bf16 v[72:75], v[196:199], v[166:169], v[72:75]
	v_mfma_f32_16x16x32_bf16 v[68:71], v[182:185], v[174:177], v[68:71]
	v_mfma_f32_16x16x32_bf16 v[64:67], v[196:199], v[174:177], v[64:67]
	s_barrier
; #define WAIT_V(n) asm volatile("s_waitcnt vmcnt(%0)" ::"n"(n) : "memory")
; #define SCHED() __builtin_amdgcn_sched_barrier(0)
; #define LGKM(n) asm volatile("s_waitcnt lgkmcnt(%0)" ::"n"(n) : "memory")
; #define STAGE_AX(AG, b, h, kt) do { _Pragma("unroll") for (int i = 0; i < 2; ++i)                                    \
;       __builtin_amdgcn_global_load_lds((const unsigned*)(((AG) + ((size_t)(kt) * (BK * 2) + (size_t)((h) * 2 + i) * 128 * lda)) + aoff), \
;                                        (unsigned*)(shm + SLOTA(b, h) + wid * 1024 + i * 8192), 16, 0, 0); } while (0)
; #define STAGE_BX(BG, b, h, kt) do { _Pragma("unroll") for (int i = 0; i < 2; ++i)                                    \
;       __builtin_amdgcn_global_load_lds((const unsigned*)(((BG) + ((size_t)(kt) * (BK * 2) + (size_t)((h) * 2 + i) * 128 * K)) + boff),   \
;                                        (unsigned*)(shm + SLOTB(b, h) + wid * 1024 + i * 8192), 16, 0, 0); } while (0)
; #define LDA(b, h) do { const unsigned pa_ = lds0 + SLOTA(b, h) + wr * 8192 + laneoff; _Pragma("unroll") for (int m = 0; m < 4; ++m)   \
;       _Pragma("unroll") for (int k = 0; k < 2; ++k) DSR(At[m][k], pa_, m * 2048 + k * 1024); } while (0)
; #define LDB(dst, b, h) do { const unsigned pb_ = lds0 + SLOTB(b, h) + wc * 4096 + laneoff; _Pragma("unroll") for (int n = 0; n < 2; ++n) \
;       _Pragma("unroll") for (int k = 0; k < 2; ++k) DSR(dst[n][k], pb_, n * 2048 + k * 1024); } while (0)
; #define BAR __builtin_amdgcn_s_barrier()
; #define LGKM(n) asm volatile("s_waitcnt lgkmcnt(%0)" ::"n"(n) : "memory")
; template <int EPI, bool SWP> ...
;     ...
;     LDA(0, 1); WAIT_V(4); BAR; LGKM(0); SCHED(); MMA(1, 0, B0); MMA(1, 1, B1); BAR; SCHED(); }
;   { LDB(B0, 1, 0); LDA(1, 0); WAIT_V(2); BAR; LGKM(0); SCHED(); MMA(0, 0, B0); BAR; SCHED();
;     LDB(B1, 1, 1); WAIT_V(0); BAR; LGKM(0); SCHED(); MMA(0, 1, B1); BAR; SCHED();
;     LDA(1, 1);
;     if (has_next) { STAGE_BX(Bg_n, 0, 0, 0); STAGE_AX(Ag_n, 0, 0, 0); STAGE_BX(Bg_n, 0, 1, 0); STAGE_AX(Ag_n, 0, 1, 0); }
	ds_read_b128 v[146:149], v204 offset:0
	ds_read_b128 v[150:153], v204 offset:0x400
	ds_read_b128 v[154:157], v204 offset:0x800
	ds_read_b128 v[158:161], v204 offset:0xc00
	ds_read_b128 v[162:165], v204 offset:0x1000
	ds_read_b128 v[166:169], v204 offset:0x1400
	ds_read_b128 v[170:173], v204 offset:0x1800
	ds_read_b128 v[174:177], v204 offset:0x1c00
	s_waitcnt vmcnt(4)
	s_barrier
	s_waitcnt lgkmcnt(0)
	v_mfma_f32_16x16x32_bf16 v[60:63], v[130:133], v[146:149], v[60:63]
	v_mfma_f32_16x16x32_bf16 v[56:59], v[138:141], v[146:149], v[56:59]
	v_mfma_f32_16x16x32_bf16 v[52:55], v[130:133], v[154:157], v[52:55]
	v_mfma_f32_16x16x32_bf16 v[48:51], v[138:141], v[154:157], v[48:51]
	v_mfma_f32_16x16x32_bf16 v[44:47], v[130:133], v[162:165], v[44:47]
	v_mfma_f32_16x16x32_bf16 v[40:43], v[138:141], v[162:165], v[40:43]
	v_mfma_f32_16x16x32_bf16 v[36:39], v[130:133], v[170:173], v[36:39]
	v_mfma_f32_16x16x32_bf16 v[32:35], v[138:141], v[170:173], v[32:35]
	v_mfma_f32_16x16x32_bf16 v[60:63], v[134:137], v[150:153], v[60:63]
	v_mfma_f32_16x16x32_bf16 v[56:59], v[142:145], v[150:153], v[56:59]
	v_mfma_f32_16x16x32_bf16 v[52:55], v[134:137], v[158:161], v[52:55]
	v_mfma_f32_16x16x32_bf16 v[48:51], v[142:145], v[158:161], v[48:51]
	v_mfma_f32_16x16x32_bf16 v[44:47], v[134:137], v[166:169], v[44:47]
	v_mfma_f32_16x16x32_bf16 v[40:43], v[142:145], v[166:169], v[40:43]
	v_mfma_f32_16x16x32_bf16 v[36:39], v[134:137], v[174:177], v[36:39]
	v_mfma_f32_16x16x32_bf16 v[32:35], v[142:145], v[174:177], v[32:35]
	v_mfma_f32_16x16x32_bf16 v[28:31], v[178:181], v[146:149], v[28:31]
	v_mfma_f32_16x16x32_bf16 v[24:27], v[186:189], v[146:149], v[24:27]
	v_mfma_f32_16x16x32_bf16 v[20:23], v[178:181], v[154:157], v[20:23]
	v_mfma_f32_16x16x32_bf16 v[16:19], v[186:189], v[154:157], v[16:19]
	v_mfma_f32_16x16x32_bf16 v[12:15], v[178:181], v[162:165], v[12:15]
	v_mfma_f32_16x16x32_bf16 v[8:11], v[186:189], v[162:165], v[8:11]
	v_mfma_f32_16x16x32_bf16 v[4:7], v[178:181], v[170:173], v[4:7]
	v_mfma_f32_16x16x32_bf16 v[0:3], v[186:189], v[170:173], v[0:3]
	v_mfma_f32_16x16x32_bf16 v[28:31], v[182:185], v[150:153], v[28:31]
	v_mfma_f32_16x16x32_bf16 v[24:27], v[196:199], v[150:153], v[24:27]
	v_mfma_f32_16x16x32_bf16 v[20:23], v[182:185], v[158:161], v[20:23]
	v_mfma_f32_16x16x32_bf16 v[16:19], v[196:199], v[158:161], v[16:19]
	v_mfma_f32_16x16x32_bf16 v[12:15], v[182:185], v[166:169], v[12:15]
	v_mfma_f32_16x16x32_bf16 v[8:11], v[196:199], v[166:169], v[8:11]
	v_mfma_f32_16x16x32_bf16 v[4:7], v[182:185], v[174:177], v[4:7]
	v_mfma_f32_16x16x32_bf16 v[0:3], v[196:199], v[174:177], v[0:3]
	s_barrier
	ds_read_b128 v[128:131], v205 offset:0
	ds_read_b128 v[132:135], v205 offset:0x400
	ds_read_b128 v[136:139], v205 offset:0x800
	ds_read_b128 v[140:143], v205 offset:0xc00
	ds_read_b128 v[160:163], v206 offset:0
	ds_read_b128 v[164:167], v206 offset:0x400
	ds_read_b128 v[168:171], v206 offset:0x800
	ds_read_b128 v[172:175], v206 offset:0xc00
	ds_read_b128 v[176:179], v206 offset:0x1000
	ds_read_b128 v[180:183], v206 offset:0x1400
	ds_read_b128 v[184:187], v206 offset:0x1800
	ds_read_b128 v[188:191], v206 offset:0x1c00
	s_waitcnt vmcnt(2)
	s_barrier
	s_waitcnt lgkmcnt(0)
	v_mfma_f32_16x16x32_bf16 v[124:127], v[128:131], v[160:163], v[124:127]
	v_mfma_f32_16x16x32_bf16 v[120:123], v[136:139], v[160:163], v[120:123]
	v_mfma_f32_16x16x32_bf16 v[116:119], v[128:131], v[168:171], v[116:119]
	v_mfma_f32_16x16x32_bf16 v[112:115], v[136:139], v[168:171], v[112:115]
	v_mfma_f32_16x16x32_bf16 v[108:111], v[128:131], v[176:179], v[108:111]
	v_mfma_f32_16x16x32_bf16 v[104:107], v[136:139], v[176:179], v[104:107]
	v_mfma_f32_16x16x32_bf16 v[100:103], v[128:131], v[184:187], v[100:103]
	v_mfma_f32_16x16x32_bf16 v[96:99], v[136:139], v[184:187], v[96:99]
	v_mfma_f32_16x16x32_bf16 v[124:127], v[132:135], v[164:167], v[124:127]
	v_mfma_f32_16x16x32_bf16 v[120:123], v[140:143], v[164:167], v[120:123]
	v_mfma_f32_16x16x32_bf16 v[116:119], v[132:135], v[172:175], v[116:119]
	v_mfma_f32_16x16x32_bf16 v[112:115], v[140:143], v[172:175], v[112:115]
	v_mfma_f32_16x16x32_bf16 v[108:111], v[132:135], v[180:183], v[108:111]
	v_mfma_f32_16x16x32_bf16 v[104:107], v[140:143], v[180:183], v[104:107]
	v_mfma_f32_16x16x32_bf16 v[100:103], v[132:135], v[188:191], v[100:103]
	v_mfma_f32_16x16x32_bf16 v[96:99], v[140:143], v[188:191], v[96:99]
	s_barrier
	ds_read_b128 v[144:147], v207 offset:0
	ds_read_b128 v[148:151], v207 offset:0x400
	ds_read_b128 v[152:155], v207 offset:0x800
	ds_read_b128 v[156:159], v207 offset:0xc00
	s_waitcnt vmcnt(0)
	s_barrier
	s_waitcnt lgkmcnt(0)
	v_mfma_f32_16x16x32_bf16 v[92:95], v[144:147], v[160:163], v[92:95]
	v_mfma_f32_16x16x32_bf16 v[88:91], v[152:155], v[160:163], v[88:91]
	v_mfma_f32_16x16x32_bf16 v[84:87], v[144:147], v[168:171], v[84:87]
	v_mfma_f32_16x16x32_bf16 v[80:83], v[152:155], v[168:171], v[80:83]
	v_mfma_f32_16x16x32_bf16 v[76:79], v[144:147], v[176:179], v[76:79]
	v_mfma_f32_16x16x32_bf16 v[72:75], v[152:155], v[176:179], v[72:75]
	v_mfma_f32_16x16x32_bf16 v[68:71], v[144:147], v[184:187], v[68:71]
	v_mfma_f32_16x16x32_bf16 v[64:67], v[152:155], v[184:187], v[64:67]
	v_mfma_f32_16x16x32_bf16 v[92:95], v[148:151], v[164:167], v[92:95]
	v_mfma_f32_16x16x32_bf16 v[88:91], v[156:159], v[164:167], v[88:91]
	v_mfma_f32_16x16x32_bf16 v[84:87], v[148:151], v[172:175], v[84:87]
	v_mfma_f32_16x16x32_bf16 v[80:83], v[156:159], v[172:175], v[80:83]
	v_mfma_f32_16x16x32_bf16 v[76:79], v[148:151], v[180:183], v[76:79]
	v_mfma_f32_16x16x32_bf16 v[72:75], v[156:159], v[180:183], v[72:75]
	v_mfma_f32_16x16x32_bf16 v[68:71], v[148:151], v[188:191], v[68:71]
	v_mfma_f32_16x16x32_bf16 v[64:67], v[156:159], v[188:191], v[64:67]
	s_barrier
	ds_read_b128 v[184:187], v208 offset:0
	ds_read_b128 v[188:191], v208 offset:0x400
	ds_read_b128 v[176:179], v208 offset:0x800
	ds_read_b128 v[180:183], v208 offset:0xc00
	ds_read_b128 v[168:171], v208 offset:0x1000
	ds_read_b128 v[172:175], v208 offset:0x1400
	ds_read_b128 v[160:163], v208 offset:0x1800
	ds_read_b128 v[164:167], v208 offset:0x1c00
	s_and_b64 vcc, exec, s[66:67]
	v_lshl_add_u64 v[196:197], s[70:71], 0, v[192:193]
	v_lshl_add_u64 v[198:199], s[68:69], 0, v[192:193]
	s_cbranch_vccz .LBB0_712
	s_mov_b32 m0, s73
	v_lshl_add_u64 v[218:219], v[196:197], 0, s[14:15]
	global_load_lds_dwordx4 v[196:197], off
	s_mov_b32 m0, s74
	s_nop 0
	global_load_lds_dwordx4 v[218:219], off
	s_mov_b32 m0, s3
	v_lshl_add_u64 v[218:219], v[198:199], 0, s[14:15]
	global_load_lds_dwordx4 v[198:199], off
	s_mov_b32 m0, s75
	s_nop 0
	global_load_lds_dwordx4 v[218:219], off
	v_lshl_add_u64 v[218:219], v[196:197], 0, s[16:17]
	s_mov_b32 m0, s76
	s_nop 0
	global_load_lds_dwordx4 v[218:219], off
	v_lshl_add_u64 v[218:219], v[196:197], 0, s[18:19]
	s_mov_b32 m0, s77
	s_nop 0
	global_load_lds_dwordx4 v[218:219], off
	v_lshl_add_u64 v[218:219], v[198:199], 0, s[16:17]
	s_mov_b32 m0, s78
	s_nop 0
	global_load_lds_dwordx4 v[218:219], off
	v_lshl_add_u64 v[218:219], v[198:199], 0, s[18:19]
	s_mov_b32 m0, s79
	s_nop 0
	global_load_lds_dwordx4 v[218:219], off
